# 5/8 of the fp6 table encode hosted in the attention phase (rows stored to the dead Wt_in / modpart regions, gather selects the table base by expert id); rest stays in the routing phase
# baseline (speedup 1.0000x reference)
; DEV unsigned pack2(float a, float b) { float2v v = {a, b}; return __builtin_bit_cast(unsigned, __builtin_convertvector(v, bf16x2v)); }
; DEV float bflo(unsigned u) { return __uint_as_float(u << 16); }
; DEV float bfhi(unsigned u) { return __uint_as_float(u & 0xffff0000u); }
; DEV float gelu_exact(float v) { return 0.5f * v * (1.f + erff(v * 0.7071067811865476f)); }
; DEV void ph_scan2(const Params& p, int item) {
;     ...
;   for (int t = 0; t < CHL; ++t) {
;     float4 a = *(const float4*)(p.a_arr + (row0 + t) * 1024 + ch);
;     float4 bb = *(const float4*)(p.b_arr + (row0 + t) * 1024 + ch);
;     u32x2 xg = *(const u32x2*)(p.z + (row0 + t) * ZLD + CXG + ch);
;     H[0] = a.x * H[0] + bb.x; H[1] = a.y * H[1] + bb.y; H[2] = a.z * H[2] + bb.z; H[3] = a.w * H[3] + bb.w;
;     u32x2 pk;
;     pk[0] = pack2(gelu_exact(bflo(xg[0])) * H[0], gelu_exact(bfhi(xg[0])) * H[1]);
;     pk[1] = pack2(gelu_exact(bflo(xg[1])) * H[2], gelu_exact(bfhi(xg[1])) * H[3]);
;     *(u32x2*)(p.orn + (row0 + t) * 1024 + ch) = pk;
;   }
.Lsc_main:
	global_load_dwordx4 v[80:83], v1, s[2:3] sc0 sc1 nt
	global_load_dwordx4 v[84:87], v1, s[4:5] sc0 sc1 nt
	global_load_dwordx2 v[88:89], v2, s[6:7] sc0 sc1 nt
	s_add_u32 s2, s2, 0x1000
	s_addc_u32 s3, s3, 0
	s_add_u32 s4, s4, 0x1000
	s_addc_u32 s5, s5, 0
	s_add_u32 s6, s6, 0x2500
	s_addc_u32 s7, s7, 0
	global_load_dwordx4 v[90:93], v1, s[2:3] sc0 sc1 nt
	global_load_dwordx4 v[94:97], v1, s[4:5] sc0 sc1 nt
	global_load_dwordx2 v[98:99], v2, s[6:7] sc0 sc1 nt
	s_add_u32 s2, s2, 0x1000
	s_addc_u32 s3, s3, 0
	s_add_u32 s4, s4, 0x1000
	s_addc_u32 s5, s5, 0
	s_add_u32 s6, s6, 0x2500
	s_addc_u32 s7, s7, 0
	global_load_dwordx4 v[100:103], v1, s[2:3] sc0 sc1 nt
	global_load_dwordx4 v[104:107], v1, s[4:5] sc0 sc1 nt
	global_load_dwordx2 v[108:109], v2, s[6:7] sc0 sc1 nt
	s_add_u32 s2, s2, 0x1000
	s_addc_u32 s3, s3, 0
	s_add_u32 s4, s4, 0x1000
	s_addc_u32 s5, s5, 0
	s_add_u32 s6, s6, 0x2500
	s_addc_u32 s7, s7, 0
	global_load_dwordx4 v[110:113], v1, s[2:3] sc0 sc1 nt
	global_load_dwordx4 v[114:117], v1, s[4:5] sc0 sc1 nt
	global_load_dwordx2 v[118:119], v2, s[6:7] sc0 sc1 nt
	s_add_u32 s2, s2, 0x1000
	s_addc_u32 s3, s3, 0
	s_add_u32 s4, s4, 0x1000
	s_addc_u32 s5, s5, 0
	s_add_u32 s6, s6, 0x2500
	s_addc_u32 s7, s7, 0
	global_load_dwordx4 v[120:123], v1, s[2:3] sc0 sc1 nt
	global_load_dwordx4 v[124:127], v1, s[4:5] sc0 sc1 nt
	global_load_dwordx2 v[128:129], v2, s[6:7] sc0 sc1 nt
	s_add_u32 s2, s2, 0x1000
	s_addc_u32 s3, s3, 0
	s_add_u32 s4, s4, 0x1000
	s_addc_u32 s5, s5, 0
	s_add_u32 s6, s6, 0x2500
	s_addc_u32 s7, s7, 0
	global_load_dwordx4 v[130:133], v1, s[2:3] sc0 sc1 nt
	global_load_dwordx4 v[134:137], v1, s[4:5] sc0 sc1 nt
	global_load_dwordx2 v[138:139], v2, s[6:7] sc0 sc1 nt
	s_add_u32 s2, s2, 0x1000
	s_addc_u32 s3, s3, 0
	s_add_u32 s4, s4, 0x1000
	s_addc_u32 s5, s5, 0
	s_add_u32 s6, s6, 0x2500
	s_addc_u32 s7, s7, 0
	global_load_dwordx4 v[140:143], v1, s[2:3] sc0 sc1 nt
	global_load_dwordx4 v[144:147], v1, s[4:5] sc0 sc1 nt
	global_load_dwordx2 v[148:149], v2, s[6:7] sc0 sc1 nt
	s_add_u32 s2, s2, 0x1000
	s_addc_u32 s3, s3, 0
	s_add_u32 s4, s4, 0x1000
	s_addc_u32 s5, s5, 0
	s_add_u32 s6, s6, 0x2500
	s_addc_u32 s7, s7, 0
	global_load_dwordx4 v[150:153], v1, s[2:3] sc0 sc1 nt
	global_load_dwordx4 v[154:157], v1, s[4:5] sc0 sc1 nt
	global_load_dwordx2 v[158:159], v2, s[6:7] sc0 sc1 nt
	s_add_u32 s2, s2, 0x1000
	s_addc_u32 s3, s3, 0
	s_add_u32 s4, s4, 0x1000
	s_addc_u32 s5, s5, 0
	s_add_u32 s6, s6, 0x2500
	s_addc_u32 s7, s7, 0
	s_waitcnt vmcnt(21)
	v_fma_f32 v4, v80, v4, v84
	v_fma_f32 v5, v81, v5, v85
	v_fma_f32 v6, v82, v6, v86
	v_fma_f32 v7, v83, v7, v87
	v_lshlrev_b32_e32 v168, 16, v88
	v_and_b32_e32 v169, 0xffff0000, v88
	v_lshlrev_b32_e32 v170, 16, v89
	v_and_b32_e32 v171, 0xffff0000, v89
	v_mul_f32_e32 v160, 0x3f3504f3, v168
	v_mul_f32_e32 v161, v160, v160
	v_fmamk_f32 v162, v161, 0xba1345e1, v8
	v_fmaak_f32 v162, v161, v162, 0xbcdac9b8
	v_fmaak_f32 v162, v161, v162, 0x3de703be
	v_fmaak_f32 v162, v161, v162, 0xbec09330
	v_fmaak_f32 v161, v161, v162, 0x3e0375d0
	v_fma_f32 v165, |v160|, v161, |v160|
	v_fma_f32 v161, |v160|, s72, v9
	v_fma_f32 v161, |v160|, v161, s73
	v_fma_f32 v161, |v160|, v161, s74
	v_fma_f32 v161, |v160|, v161, s75
	v_fma_f32 v161, |v160|, v161, s76
	v_fma_f32 v161, |v160|, v161, s77
	v_fma_f32 v161, |v160|, v161, |v160|
	v_mul_f32_e32 v162, 0xbfb8aa3b, v161
	v_fma_f32 v163, v161, s78, -v162
	v_rndne_f32_e32 v164, v162
	v_fmac_f32_e32 v163, 0xb2a5705f, v161
	v_sub_f32_e32 v162, v162, v164
	v_add_f32_e32 v162, v162, v163
	v_cvt_i32_f32_e32 v163, v164
	v_exp_f32_e32 v162, v162
	v_cmp_nlt_f32_e32 vcc, s79, v161
	v_ldexp_f32 v162, v162, v163
	s_nop 0
	v_cndmask_b32_e32 v162, 0, v162, vcc
	v_cmp_ngt_f32_e32 vcc, s80, v161
	s_nop 1
	v_cndmask_b32_e32 v161, v3, v162, vcc
	v_sub_f32_e32 v166, 1.0, v161
	v_cmp_lt_f32_e64 vcc, |v160|, 1.0
	s_nop 1
	v_cndmask_b32_e32 v165, v166, v165, vcc
	v_bfi_b32 v165, s81, v165, v160
	v_mul_f32_e32 v161, 0.5, v168
	v_add_f32_e32 v165, 1.0, v165
	v_mul_f32_e32 v161, v161, v165
	v_mul_f32_e32 v176, v161, v4
	v_mul_f32_e32 v160, 0x3f3504f3, v169
	v_mul_f32_e32 v161, v160, v160
	v_fmamk_f32 v162, v161, 0xba1345e1, v8
	v_fmaak_f32 v162, v161, v162, 0xbcdac9b8
	v_fmaak_f32 v162, v161, v162, 0x3de703be
	v_fmaak_f32 v162, v161, v162, 0xbec09330
	v_fmaak_f32 v161, v161, v162, 0x3e0375d0
	v_fma_f32 v165, |v160|, v161, |v160|
	v_fma_f32 v161, |v160|, s72, v9
	v_fma_f32 v161, |v160|, v161, s73
	v_fma_f32 v161, |v160|, v161, s74
	v_fma_f32 v161, |v160|, v161, s75
	v_fma_f32 v161, |v160|, v161, s76
	v_fma_f32 v161, |v160|, v161, s77
	v_fma_f32 v161, |v160|, v161, |v160|
	v_mul_f32_e32 v162, 0xbfb8aa3b, v161
	v_fma_f32 v163, v161, s78, -v162
	v_rndne_f32_e32 v164, v162
	v_fmac_f32_e32 v163, 0xb2a5705f, v161
	v_sub_f32_e32 v162, v162, v164
	v_add_f32_e32 v162, v162, v163
	v_cvt_i32_f32_e32 v163, v164
	v_exp_f32_e32 v162, v162
	v_cmp_nlt_f32_e32 vcc, s79, v161
	v_ldexp_f32 v162, v162, v163
	s_nop 0
	v_cndmask_b32_e32 v162, 0, v162, vcc
	v_cmp_ngt_f32_e32 vcc, s80, v161
	s_nop 1
	v_cndmask_b32_e32 v161, v3, v162, vcc
	v_sub_f32_e32 v166, 1.0, v161
	v_cmp_lt_f32_e64 vcc, |v160|, 1.0
	s_nop 1
	v_cndmask_b32_e32 v165, v166, v165, vcc
	v_bfi_b32 v165, s81, v165, v160
	v_mul_f32_e32 v161, 0.5, v169
	v_add_f32_e32 v165, 1.0, v165
	v_mul_f32_e32 v161, v161, v165
	v_mul_f32_e32 v177, v161, v5
	v_mul_f32_e32 v160, 0x3f3504f3, v170
	v_mul_f32_e32 v161, v160, v160
	v_fmamk_f32 v162, v161, 0xba1345e1, v8
	v_fmaak_f32 v162, v161, v162, 0xbcdac9b8
	v_fmaak_f32 v162, v161, v162, 0x3de703be
	v_fmaak_f32 v162, v161, v162, 0xbec09330
	v_fmaak_f32 v161, v161, v162, 0x3e0375d0
	v_fma_f32 v165, |v160|, v161, |v160|
; DEV unsigned pack2(float a, float b) { float2v v = {a, b}; return __builtin_bit_cast(unsigned, __builtin_convertvector(v, bf16x2v)); }
; DEV float bflo(unsigned u) { return __uint_as_float(u << 16); }
; DEV float bfhi(unsigned u) { return __uint_as_float(u & 0xffff0000u); }
; DEV float gelu_exact(float v) { return 0.5f * v * (1.f + erff(v * 0.7071067811865476f)); }
; DEV void ph_scan2(const Params& p, int item) {
;     ...
;   for (int t = 0; t < CHL; ++t) {
;     float4 a = *(const float4*)(p.a_arr + (row0 + t) * 1024 + ch);
;     float4 bb = *(const float4*)(p.b_arr + (row0 + t) * 1024 + ch);
;     u32x2 xg = *(const u32x2*)(p.z + (row0 + t) * ZLD + CXG + ch);
;     H[0] = a.x * H[0] + bb.x; H[1] = a.y * H[1] + bb.y; H[2] = a.z * H[2] + bb.z; H[3] = a.w * H[3] + bb.w;
;     u32x2 pk;
;     pk[0] = pack2(gelu_exact(bflo(xg[0])) * H[0], gelu_exact(bfhi(xg[0])) * H[1]);
;     pk[1] = pack2(gelu_exact(bflo(xg[1])) * H[2], gelu_exact(bfhi(xg[1])) * H[3]);
;     *(u32x2*)(p.orn + (row0 + t) * 1024 + ch) = pk;
;   }
	v_fma_f32 v161, |v160|, s72, v9
	v_fma_f32 v161, |v160|, v161, s73
	v_fma_f32 v161, |v160|, v161, s74
	v_fma_f32 v161, |v160|, v161, s75
	v_fma_f32 v161, |v160|, v161, s76
	v_fma_f32 v161, |v160|, v161, s77
	v_fma_f32 v161, |v160|, v161, |v160|
	v_mul_f32_e32 v162, 0xbfb8aa3b, v161
	v_fma_f32 v163, v161, s78, -v162
	v_rndne_f32_e32 v164, v162
	v_fmac_f32_e32 v163, 0xb2a5705f, v161
	v_sub_f32_e32 v162, v162, v164
	v_add_f32_e32 v162, v162, v163
	v_cvt_i32_f32_e32 v163, v164
	v_exp_f32_e32 v162, v162
	v_cmp_nlt_f32_e32 vcc, s79, v161
	v_ldexp_f32 v162, v162, v163
	s_nop 0
	v_cndmask_b32_e32 v162, 0, v162, vcc
	v_cmp_ngt_f32_e32 vcc, s80, v161
	s_nop 1
	v_cndmask_b32_e32 v161, v3, v162, vcc
	v_sub_f32_e32 v166, 1.0, v161
	v_cmp_lt_f32_e64 vcc, |v160|, 1.0
	s_nop 1
	v_cndmask_b32_e32 v165, v166, v165, vcc
	v_bfi_b32 v165, s81, v165, v160
	v_mul_f32_e32 v161, 0.5, v170
	v_add_f32_e32 v165, 1.0, v165
	v_mul_f32_e32 v161, v161, v165
	v_mul_f32_e32 v178, v161, v6
	v_mul_f32_e32 v160, 0x3f3504f3, v171
	v_mul_f32_e32 v161, v160, v160
	v_fmamk_f32 v162, v161, 0xba1345e1, v8
	v_fmaak_f32 v162, v161, v162, 0xbcdac9b8
	v_fmaak_f32 v162, v161, v162, 0x3de703be
	v_fmaak_f32 v162, v161, v162, 0xbec09330
	v_fmaak_f32 v161, v161, v162, 0x3e0375d0
	v_fma_f32 v165, |v160|, v161, |v160|
	v_fma_f32 v161, |v160|, s72, v9
	v_fma_f32 v161, |v160|, v161, s73
	v_fma_f32 v161, |v160|, v161, s74
	v_fma_f32 v161, |v160|, v161, s75
	v_fma_f32 v161, |v160|, v161, s76
	v_fma_f32 v161, |v160|, v161, s77
	v_fma_f32 v161, |v160|, v161, |v160|
	v_mul_f32_e32 v162, 0xbfb8aa3b, v161
	v_fma_f32 v163, v161, s78, -v162
	v_rndne_f32_e32 v164, v162
	v_fmac_f32_e32 v163, 0xb2a5705f, v161
	v_sub_f32_e32 v162, v162, v164
	v_add_f32_e32 v162, v162, v163
	v_cvt_i32_f32_e32 v163, v164
	v_exp_f32_e32 v162, v162
	v_cmp_nlt_f32_e32 vcc, s79, v161
	v_ldexp_f32 v162, v162, v163
	s_nop 0
	v_cndmask_b32_e32 v162, 0, v162, vcc
	v_cmp_ngt_f32_e32 vcc, s80, v161
	s_nop 1
	v_cndmask_b32_e32 v161, v3, v162, vcc
	v_sub_f32_e32 v166, 1.0, v161
	v_cmp_lt_f32_e64 vcc, |v160|, 1.0
	s_nop 1
	v_cndmask_b32_e32 v165, v166, v165, vcc
	v_bfi_b32 v165, s81, v165, v160
	v_mul_f32_e32 v161, 0.5, v171
	v_add_f32_e32 v165, 1.0, v165
	v_mul_f32_e32 v161, v161, v165
	v_mul_f32_e32 v179, v161, v7
	v_cvt_pk_bf16_f32 v180, v176, v177
	v_cvt_pk_bf16_f32 v181, v178, v179
	global_store_dwordx2 v2, v[180:181], s[34:35]
	s_add_u32 s34, s34, 0x800
	s_addc_u32 s35, s35, 0
	s_waitcnt vmcnt(19)
	v_fma_f32 v4, v90, v4, v94
	v_fma_f32 v5, v91, v5, v95
	v_fma_f32 v6, v92, v6, v96
	v_fma_f32 v7, v93, v7, v97
	v_lshlrev_b32_e32 v168, 16, v98
	v_and_b32_e32 v169, 0xffff0000, v98
	v_lshlrev_b32_e32 v170, 16, v99
	v_and_b32_e32 v171, 0xffff0000, v99
	v_mul_f32_e32 v160, 0x3f3504f3, v168
	v_mul_f32_e32 v161, v160, v160
	v_fmamk_f32 v162, v161, 0xba1345e1, v8
	v_fmaak_f32 v162, v161, v162, 0xbcdac9b8
	v_fmaak_f32 v162, v161, v162, 0x3de703be
	v_fmaak_f32 v162, v161, v162, 0xbec09330
	v_fmaak_f32 v161, v161, v162, 0x3e0375d0
	v_fma_f32 v165, |v160|, v161, |v160|
	v_fma_f32 v161, |v160|, s72, v9
	v_fma_f32 v161, |v160|, v161, s73
	v_fma_f32 v161, |v160|, v161, s74
	v_fma_f32 v161, |v160|, v161, s75
	v_fma_f32 v161, |v160|, v161, s76
	v_fma_f32 v161, |v160|, v161, s77
	v_fma_f32 v161, |v160|, v161, |v160|
	v_mul_f32_e32 v162, 0xbfb8aa3b, v161
	v_fma_f32 v163, v161, s78, -v162
	v_rndne_f32_e32 v164, v162
	v_fmac_f32_e32 v163, 0xb2a5705f, v161
	v_sub_f32_e32 v162, v162, v164
	v_add_f32_e32 v162, v162, v163
	v_cvt_i32_f32_e32 v163, v164
	v_exp_f32_e32 v162, v162
	v_cmp_nlt_f32_e32 vcc, s79, v161
	v_ldexp_f32 v162, v162, v163
	s_nop 0
	v_cndmask_b32_e32 v162, 0, v162, vcc
	v_cmp_ngt_f32_e32 vcc, s80, v161
	s_nop 1
	v_cndmask_b32_e32 v161, v3, v162, vcc
	v_sub_f32_e32 v166, 1.0, v161
	v_cmp_lt_f32_e64 vcc, |v160|, 1.0
	s_nop 1
	v_cndmask_b32_e32 v165, v166, v165, vcc
	v_bfi_b32 v165, s81, v165, v160
	v_mul_f32_e32 v161, 0.5, v168
	v_add_f32_e32 v165, 1.0, v165
	v_mul_f32_e32 v161, v161, v165
	v_mul_f32_e32 v176, v161, v4
	v_mul_f32_e32 v160, 0x3f3504f3, v169
	v_mul_f32_e32 v161, v160, v160
	v_fmamk_f32 v162, v161, 0xba1345e1, v8
	v_fmaak_f32 v162, v161, v162, 0xbcdac9b8
	v_fmaak_f32 v162, v161, v162, 0x3de703be
	v_fmaak_f32 v162, v161, v162, 0xbec09330
	v_fmaak_f32 v161, v161, v162, 0x3e0375d0
	v_fma_f32 v165, |v160|, v161, |v160|
	v_fma_f32 v161, |v160|, s72, v9
	v_fma_f32 v161, |v160|, v161, s73
	v_fma_f32 v161, |v160|, v161, s74
	v_fma_f32 v161, |v160|, v161, s75
	v_fma_f32 v161, |v160|, v161, s76
	v_fma_f32 v161, |v160|, v161, s77
	v_fma_f32 v161, |v160|, v161, |v160|
	v_mul_f32_e32 v162, 0xbfb8aa3b, v161
	v_fma_f32 v163, v161, s78, -v162
	v_rndne_f32_e32 v164, v162
	v_fmac_f32_e32 v163, 0xb2a5705f, v161
	v_sub_f32_e32 v162, v162, v164
	v_add_f32_e32 v162, v162, v163
	v_cvt_i32_f32_e32 v163, v164
	v_exp_f32_e32 v162, v162
	v_cmp_nlt_f32_e32 vcc, s79, v161
	v_ldexp_f32 v162, v162, v163
	s_nop 0
	v_cndmask_b32_e32 v162, 0, v162, vcc
	v_cmp_ngt_f32_e32 vcc, s80, v161
	s_nop 1
	v_cndmask_b32_e32 v161, v3, v162, vcc
	v_sub_f32_e32 v166, 1.0, v161
	v_cmp_lt_f32_e64 vcc, |v160|, 1.0
	s_nop 1
	v_cndmask_b32_e32 v165, v166, v165, vcc
	v_bfi_b32 v165, s81, v165, v160
	v_mul_f32_e32 v161, 0.5, v169
	v_add_f32_e32 v165, 1.0, v165
	v_mul_f32_e32 v161, v161, v165
	v_mul_f32_e32 v177, v161, v5
	v_mul_f32_e32 v160, 0x3f3504f3, v170
	v_mul_f32_e32 v161, v160, v160
	v_fmamk_f32 v162, v161, 0xba1345e1, v8
	v_fmaak_f32 v162, v161, v162, 0xbcdac9b8
	v_fmaak_f32 v162, v161, v162, 0x3de703be
	v_fmaak_f32 v162, v161, v162, 0xbec09330
	v_fmaak_f32 v161, v161, v162, 0x3e0375d0
	v_fma_f32 v165, |v160|, v161, |v160|
	v_fma_f32 v161, |v160|, s72, v9
; DEV unsigned pack2(float a, float b) { float2v v = {a, b}; return __builtin_bit_cast(unsigned, __builtin_convertvector(v, bf16x2v)); }
; DEV float bflo(unsigned u) { return __uint_as_float(u << 16); }
; DEV float bfhi(unsigned u) { return __uint_as_float(u & 0xffff0000u); }
; DEV float gelu_exact(float v) { return 0.5f * v * (1.f + erff(v * 0.7071067811865476f)); }
; DEV void ph_scan2(const Params& p, int item) {
;     ...
;   for (int t = 0; t < CHL; ++t) {
;     float4 a = *(const float4*)(p.a_arr + (row0 + t) * 1024 + ch);
;     float4 bb = *(const float4*)(p.b_arr + (row0 + t) * 1024 + ch);
;     u32x2 xg = *(const u32x2*)(p.z + (row0 + t) * ZLD + CXG + ch);
;     H[0] = a.x * H[0] + bb.x; H[1] = a.y * H[1] + bb.y; H[2] = a.z * H[2] + bb.z; H[3] = a.w * H[3] + bb.w;
;     u32x2 pk;
;     pk[0] = pack2(gelu_exact(bflo(xg[0])) * H[0], gelu_exact(bfhi(xg[0])) * H[1]);
;     pk[1] = pack2(gelu_exact(bflo(xg[1])) * H[2], gelu_exact(bfhi(xg[1])) * H[3]);
;     *(u32x2*)(p.orn + (row0 + t) * 1024 + ch) = pk;
;   }
	v_fma_f32 v161, |v160|, v161, s73
	v_fma_f32 v161, |v160|, v161, s74
	v_fma_f32 v161, |v160|, v161, s75
	v_fma_f32 v161, |v160|, v161, s76
	v_fma_f32 v161, |v160|, v161, s77
	v_fma_f32 v161, |v160|, v161, |v160|
	v_mul_f32_e32 v162, 0xbfb8aa3b, v161
	v_fma_f32 v163, v161, s78, -v162
	v_rndne_f32_e32 v164, v162
	v_fmac_f32_e32 v163, 0xb2a5705f, v161
	v_sub_f32_e32 v162, v162, v164
	v_add_f32_e32 v162, v162, v163
	v_cvt_i32_f32_e32 v163, v164
	v_exp_f32_e32 v162, v162
	v_cmp_nlt_f32_e32 vcc, s79, v161
	v_ldexp_f32 v162, v162, v163
	s_nop 0
	v_cndmask_b32_e32 v162, 0, v162, vcc
	v_cmp_ngt_f32_e32 vcc, s80, v161
	s_nop 1
	v_cndmask_b32_e32 v161, v3, v162, vcc
	v_sub_f32_e32 v166, 1.0, v161
	v_cmp_lt_f32_e64 vcc, |v160|, 1.0
	s_nop 1
	v_cndmask_b32_e32 v165, v166, v165, vcc
	v_bfi_b32 v165, s81, v165, v160
	v_mul_f32_e32 v161, 0.5, v170
	v_add_f32_e32 v165, 1.0, v165
	v_mul_f32_e32 v161, v161, v165
	v_mul_f32_e32 v178, v161, v6
	v_mul_f32_e32 v160, 0x3f3504f3, v171
	v_mul_f32_e32 v161, v160, v160
	v_fmamk_f32 v162, v161, 0xba1345e1, v8
	v_fmaak_f32 v162, v161, v162, 0xbcdac9b8
	v_fmaak_f32 v162, v161, v162, 0x3de703be
	v_fmaak_f32 v162, v161, v162, 0xbec09330
	v_fmaak_f32 v161, v161, v162, 0x3e0375d0
	v_fma_f32 v165, |v160|, v161, |v160|
	v_fma_f32 v161, |v160|, s72, v9
	v_fma_f32 v161, |v160|, v161, s73
	v_fma_f32 v161, |v160|, v161, s74
	v_fma_f32 v161, |v160|, v161, s75
	v_fma_f32 v161, |v160|, v161, s76
	v_fma_f32 v161, |v160|, v161, s77
	v_fma_f32 v161, |v160|, v161, |v160|
	v_mul_f32_e32 v162, 0xbfb8aa3b, v161
	v_fma_f32 v163, v161, s78, -v162
	v_rndne_f32_e32 v164, v162
	v_fmac_f32_e32 v163, 0xb2a5705f, v161
	v_sub_f32_e32 v162, v162, v164
	v_add_f32_e32 v162, v162, v163
	v_cvt_i32_f32_e32 v163, v164
	v_exp_f32_e32 v162, v162
	v_cmp_nlt_f32_e32 vcc, s79, v161
	v_ldexp_f32 v162, v162, v163
	s_nop 0
	v_cndmask_b32_e32 v162, 0, v162, vcc
	v_cmp_ngt_f32_e32 vcc, s80, v161
	s_nop 1
	v_cndmask_b32_e32 v161, v3, v162, vcc
	v_sub_f32_e32 v166, 1.0, v161
	v_cmp_lt_f32_e64 vcc, |v160|, 1.0
	s_nop 1
	v_cndmask_b32_e32 v165, v166, v165, vcc
	v_bfi_b32 v165, s81, v165, v160
	v_mul_f32_e32 v161, 0.5, v171
	v_add_f32_e32 v165, 1.0, v165
	v_mul_f32_e32 v161, v161, v165
	v_mul_f32_e32 v179, v161, v7
	v_cvt_pk_bf16_f32 v180, v176, v177
	v_cvt_pk_bf16_f32 v181, v178, v179
	global_store_dwordx2 v2, v[180:181], s[34:35]
	s_add_u32 s34, s34, 0x800
	s_addc_u32 s35, s35, 0
	s_waitcnt vmcnt(17)
	v_fma_f32 v4, v100, v4, v104
	v_fma_f32 v5, v101, v5, v105
	v_fma_f32 v6, v102, v6, v106
	v_fma_f32 v7, v103, v7, v107
	v_lshlrev_b32_e32 v168, 16, v108
	v_and_b32_e32 v169, 0xffff0000, v108
	v_lshlrev_b32_e32 v170, 16, v109
	v_and_b32_e32 v171, 0xffff0000, v109
	v_mul_f32_e32 v160, 0x3f3504f3, v168
	v_mul_f32_e32 v161, v160, v160
	v_fmamk_f32 v162, v161, 0xba1345e1, v8
	v_fmaak_f32 v162, v161, v162, 0xbcdac9b8
	v_fmaak_f32 v162, v161, v162, 0x3de703be
	v_fmaak_f32 v162, v161, v162, 0xbec09330
	v_fmaak_f32 v161, v161, v162, 0x3e0375d0
	v_fma_f32 v165, |v160|, v161, |v160|
	v_fma_f32 v161, |v160|, s72, v9
	v_fma_f32 v161, |v160|, v161, s73
	v_fma_f32 v161, |v160|, v161, s74
	v_fma_f32 v161, |v160|, v161, s75
	v_fma_f32 v161, |v160|, v161, s76
	v_fma_f32 v161, |v160|, v161, s77
	v_fma_f32 v161, |v160|, v161, |v160|
	v_mul_f32_e32 v162, 0xbfb8aa3b, v161
	v_fma_f32 v163, v161, s78, -v162
	v_rndne_f32_e32 v164, v162
	v_fmac_f32_e32 v163, 0xb2a5705f, v161
	v_sub_f32_e32 v162, v162, v164
	v_add_f32_e32 v162, v162, v163
	v_cvt_i32_f32_e32 v163, v164
	v_exp_f32_e32 v162, v162
	v_cmp_nlt_f32_e32 vcc, s79, v161
	v_ldexp_f32 v162, v162, v163
	s_nop 0
	v_cndmask_b32_e32 v162, 0, v162, vcc
	v_cmp_ngt_f32_e32 vcc, s80, v161
	s_nop 1
	v_cndmask_b32_e32 v161, v3, v162, vcc
	v_sub_f32_e32 v166, 1.0, v161
	v_cmp_lt_f32_e64 vcc, |v160|, 1.0
	s_nop 1
	v_cndmask_b32_e32 v165, v166, v165, vcc
	v_bfi_b32 v165, s81, v165, v160
	v_mul_f32_e32 v161, 0.5, v168
	v_add_f32_e32 v165, 1.0, v165
	v_mul_f32_e32 v161, v161, v165
	v_mul_f32_e32 v176, v161, v4
	v_mul_f32_e32 v160, 0x3f3504f3, v169
	v_mul_f32_e32 v161, v160, v160
	v_fmamk_f32 v162, v161, 0xba1345e1, v8
	v_fmaak_f32 v162, v161, v162, 0xbcdac9b8
	v_fmaak_f32 v162, v161, v162, 0x3de703be
	v_fmaak_f32 v162, v161, v162, 0xbec09330
	v_fmaak_f32 v161, v161, v162, 0x3e0375d0
	v_fma_f32 v165, |v160|, v161, |v160|
	v_fma_f32 v161, |v160|, s72, v9
	v_fma_f32 v161, |v160|, v161, s73
	v_fma_f32 v161, |v160|, v161, s74
	v_fma_f32 v161, |v160|, v161, s75
	v_fma_f32 v161, |v160|, v161, s76
	v_fma_f32 v161, |v160|, v161, s77
	v_fma_f32 v161, |v160|, v161, |v160|
	v_mul_f32_e32 v162, 0xbfb8aa3b, v161
	v_fma_f32 v163, v161, s78, -v162
	v_rndne_f32_e32 v164, v162
	v_fmac_f32_e32 v163, 0xb2a5705f, v161
	v_sub_f32_e32 v162, v162, v164
	v_add_f32_e32 v162, v162, v163
	v_cvt_i32_f32_e32 v163, v164
	v_exp_f32_e32 v162, v162
	v_cmp_nlt_f32_e32 vcc, s79, v161
	v_ldexp_f32 v162, v162, v163
	s_nop 0
	v_cndmask_b32_e32 v162, 0, v162, vcc
	v_cmp_ngt_f32_e32 vcc, s80, v161
	s_nop 1
	v_cndmask_b32_e32 v161, v3, v162, vcc
	v_sub_f32_e32 v166, 1.0, v161
	v_cmp_lt_f32_e64 vcc, |v160|, 1.0
	s_nop 1
	v_cndmask_b32_e32 v165, v166, v165, vcc
	v_bfi_b32 v165, s81, v165, v160
	v_mul_f32_e32 v161, 0.5, v169
	v_add_f32_e32 v165, 1.0, v165
	v_mul_f32_e32 v161, v161, v165
	v_mul_f32_e32 v177, v161, v5
	v_mul_f32_e32 v160, 0x3f3504f3, v170
	v_mul_f32_e32 v161, v160, v160
	v_fmamk_f32 v162, v161, 0xba1345e1, v8
	v_fmaak_f32 v162, v161, v162, 0xbcdac9b8
	v_fmaak_f32 v162, v161, v162, 0x3de703be
	v_fmaak_f32 v162, v161, v162, 0xbec09330
	v_fmaak_f32 v161, v161, v162, 0x3e0375d0
	v_fma_f32 v165, |v160|, v161, |v160|
	v_fma_f32 v161, |v160|, s72, v9
	v_fma_f32 v161, |v160|, v161, s73
; DEV unsigned pack2(float a, float b) { float2v v = {a, b}; return __builtin_bit_cast(unsigned, __builtin_convertvector(v, bf16x2v)); }
; DEV float bflo(unsigned u) { return __uint_as_float(u << 16); }
; DEV float bfhi(unsigned u) { return __uint_as_float(u & 0xffff0000u); }
; DEV float gelu_exact(float v) { return 0.5f * v * (1.f + erff(v * 0.7071067811865476f)); }
; DEV void ph_scan2(const Params& p, int item) {
;     ...
;   for (int t = 0; t < CHL; ++t) {
;     float4 a = *(const float4*)(p.a_arr + (row0 + t) * 1024 + ch);
;     float4 bb = *(const float4*)(p.b_arr + (row0 + t) * 1024 + ch);
;     u32x2 xg = *(const u32x2*)(p.z + (row0 + t) * ZLD + CXG + ch);
;     H[0] = a.x * H[0] + bb.x; H[1] = a.y * H[1] + bb.y; H[2] = a.z * H[2] + bb.z; H[3] = a.w * H[3] + bb.w;
;     u32x2 pk;
;     pk[0] = pack2(gelu_exact(bflo(xg[0])) * H[0], gelu_exact(bfhi(xg[0])) * H[1]);
;     pk[1] = pack2(gelu_exact(bflo(xg[1])) * H[2], gelu_exact(bfhi(xg[1])) * H[3]);
;     *(u32x2*)(p.orn + (row0 + t) * 1024 + ch) = pk;
;   }
	v_fma_f32 v161, |v160|, v161, s74
	v_fma_f32 v161, |v160|, v161, s75
	v_fma_f32 v161, |v160|, v161, s76
	v_fma_f32 v161, |v160|, v161, s77
	v_fma_f32 v161, |v160|, v161, |v160|
	v_mul_f32_e32 v162, 0xbfb8aa3b, v161
	v_fma_f32 v163, v161, s78, -v162
	v_rndne_f32_e32 v164, v162
	v_fmac_f32_e32 v163, 0xb2a5705f, v161
	v_sub_f32_e32 v162, v162, v164
	v_add_f32_e32 v162, v162, v163
	v_cvt_i32_f32_e32 v163, v164
	v_exp_f32_e32 v162, v162
	v_cmp_nlt_f32_e32 vcc, s79, v161
	v_ldexp_f32 v162, v162, v163
	s_nop 0
	v_cndmask_b32_e32 v162, 0, v162, vcc
	v_cmp_ngt_f32_e32 vcc, s80, v161
	s_nop 1
	v_cndmask_b32_e32 v161, v3, v162, vcc
	v_sub_f32_e32 v166, 1.0, v161
	v_cmp_lt_f32_e64 vcc, |v160|, 1.0
	s_nop 1
	v_cndmask_b32_e32 v165, v166, v165, vcc
	v_bfi_b32 v165, s81, v165, v160
	v_mul_f32_e32 v161, 0.5, v170
	v_add_f32_e32 v165, 1.0, v165
	v_mul_f32_e32 v161, v161, v165
	v_mul_f32_e32 v178, v161, v6
	v_mul_f32_e32 v160, 0x3f3504f3, v171
	v_mul_f32_e32 v161, v160, v160
	v_fmamk_f32 v162, v161, 0xba1345e1, v8
	v_fmaak_f32 v162, v161, v162, 0xbcdac9b8
	v_fmaak_f32 v162, v161, v162, 0x3de703be
	v_fmaak_f32 v162, v161, v162, 0xbec09330
	v_fmaak_f32 v161, v161, v162, 0x3e0375d0
	v_fma_f32 v165, |v160|, v161, |v160|
	v_fma_f32 v161, |v160|, s72, v9
	v_fma_f32 v161, |v160|, v161, s73
	v_fma_f32 v161, |v160|, v161, s74
	v_fma_f32 v161, |v160|, v161, s75
	v_fma_f32 v161, |v160|, v161, s76
	v_fma_f32 v161, |v160|, v161, s77
	v_fma_f32 v161, |v160|, v161, |v160|
	v_mul_f32_e32 v162, 0xbfb8aa3b, v161
	v_fma_f32 v163, v161, s78, -v162
	v_rndne_f32_e32 v164, v162
	v_fmac_f32_e32 v163, 0xb2a5705f, v161
	v_sub_f32_e32 v162, v162, v164
	v_add_f32_e32 v162, v162, v163
	v_cvt_i32_f32_e32 v163, v164
	v_exp_f32_e32 v162, v162
	v_cmp_nlt_f32_e32 vcc, s79, v161
	v_ldexp_f32 v162, v162, v163
	s_nop 0
	v_cndmask_b32_e32 v162, 0, v162, vcc
	v_cmp_ngt_f32_e32 vcc, s80, v161
	s_nop 1
	v_cndmask_b32_e32 v161, v3, v162, vcc
	v_sub_f32_e32 v166, 1.0, v161
	v_cmp_lt_f32_e64 vcc, |v160|, 1.0
	s_nop 1
	v_cndmask_b32_e32 v165, v166, v165, vcc
	v_bfi_b32 v165, s81, v165, v160
	v_mul_f32_e32 v161, 0.5, v171
	v_add_f32_e32 v165, 1.0, v165
	v_mul_f32_e32 v161, v161, v165
	v_mul_f32_e32 v179, v161, v7
	v_cvt_pk_bf16_f32 v180, v176, v177
	v_cvt_pk_bf16_f32 v181, v178, v179
	global_store_dwordx2 v2, v[180:181], s[34:35]
	s_add_u32 s34, s34, 0x800
	s_addc_u32 s35, s35, 0
	s_waitcnt vmcnt(15)
	v_fma_f32 v4, v110, v4, v114
	v_fma_f32 v5, v111, v5, v115
	v_fma_f32 v6, v112, v6, v116
	v_fma_f32 v7, v113, v7, v117
	v_lshlrev_b32_e32 v168, 16, v118
	v_and_b32_e32 v169, 0xffff0000, v118
	v_lshlrev_b32_e32 v170, 16, v119
	v_and_b32_e32 v171, 0xffff0000, v119
	v_mul_f32_e32 v160, 0x3f3504f3, v168
	v_mul_f32_e32 v161, v160, v160
	v_fmamk_f32 v162, v161, 0xba1345e1, v8
	v_fmaak_f32 v162, v161, v162, 0xbcdac9b8
	v_fmaak_f32 v162, v161, v162, 0x3de703be
	v_fmaak_f32 v162, v161, v162, 0xbec09330
	v_fmaak_f32 v161, v161, v162, 0x3e0375d0
	v_fma_f32 v165, |v160|, v161, |v160|
	v_fma_f32 v161, |v160|, s72, v9
	v_fma_f32 v161, |v160|, v161, s73
	v_fma_f32 v161, |v160|, v161, s74
	v_fma_f32 v161, |v160|, v161, s75
	v_fma_f32 v161, |v160|, v161, s76
	v_fma_f32 v161, |v160|, v161, s77
	v_fma_f32 v161, |v160|, v161, |v160|
	v_mul_f32_e32 v162, 0xbfb8aa3b, v161
	v_fma_f32 v163, v161, s78, -v162
	v_rndne_f32_e32 v164, v162
	v_fmac_f32_e32 v163, 0xb2a5705f, v161
	v_sub_f32_e32 v162, v162, v164
	v_add_f32_e32 v162, v162, v163
	v_cvt_i32_f32_e32 v163, v164
	v_exp_f32_e32 v162, v162
	v_cmp_nlt_f32_e32 vcc, s79, v161
	v_ldexp_f32 v162, v162, v163
	s_nop 0
	v_cndmask_b32_e32 v162, 0, v162, vcc
	v_cmp_ngt_f32_e32 vcc, s80, v161
	s_nop 1
	v_cndmask_b32_e32 v161, v3, v162, vcc
	v_sub_f32_e32 v166, 1.0, v161
	v_cmp_lt_f32_e64 vcc, |v160|, 1.0
	s_nop 1
	v_cndmask_b32_e32 v165, v166, v165, vcc
	v_bfi_b32 v165, s81, v165, v160
	v_mul_f32_e32 v161, 0.5, v168
	v_add_f32_e32 v165, 1.0, v165
	v_mul_f32_e32 v161, v161, v165
	v_mul_f32_e32 v176, v161, v4
	v_mul_f32_e32 v160, 0x3f3504f3, v169
	v_mul_f32_e32 v161, v160, v160
	v_fmamk_f32 v162, v161, 0xba1345e1, v8
	v_fmaak_f32 v162, v161, v162, 0xbcdac9b8
	v_fmaak_f32 v162, v161, v162, 0x3de703be
	v_fmaak_f32 v162, v161, v162, 0xbec09330
	v_fmaak_f32 v161, v161, v162, 0x3e0375d0
	v_fma_f32 v165, |v160|, v161, |v160|
	v_fma_f32 v161, |v160|, s72, v9
	v_fma_f32 v161, |v160|, v161, s73
	v_fma_f32 v161, |v160|, v161, s74
	v_fma_f32 v161, |v160|, v161, s75
	v_fma_f32 v161, |v160|, v161, s76
	v_fma_f32 v161, |v160|, v161, s77
	v_fma_f32 v161, |v160|, v161, |v160|
	v_mul_f32_e32 v162, 0xbfb8aa3b, v161
	v_fma_f32 v163, v161, s78, -v162
	v_rndne_f32_e32 v164, v162
	v_fmac_f32_e32 v163, 0xb2a5705f, v161
	v_sub_f32_e32 v162, v162, v164
	v_add_f32_e32 v162, v162, v163
	v_cvt_i32_f32_e32 v163, v164
	v_exp_f32_e32 v162, v162
	v_cmp_nlt_f32_e32 vcc, s79, v161
	v_ldexp_f32 v162, v162, v163
	s_nop 0
	v_cndmask_b32_e32 v162, 0, v162, vcc
	v_cmp_ngt_f32_e32 vcc, s80, v161
	s_nop 1
	v_cndmask_b32_e32 v161, v3, v162, vcc
	v_sub_f32_e32 v166, 1.0, v161
	v_cmp_lt_f32_e64 vcc, |v160|, 1.0
	s_nop 1
	v_cndmask_b32_e32 v165, v166, v165, vcc
	v_bfi_b32 v165, s81, v165, v160
	v_mul_f32_e32 v161, 0.5, v169
	v_add_f32_e32 v165, 1.0, v165
	v_mul_f32_e32 v161, v161, v165
	v_mul_f32_e32 v177, v161, v5
	v_mul_f32_e32 v160, 0x3f3504f3, v170
	v_mul_f32_e32 v161, v160, v160
	v_fmamk_f32 v162, v161, 0xba1345e1, v8
	v_fmaak_f32 v162, v161, v162, 0xbcdac9b8
	v_fmaak_f32 v162, v161, v162, 0x3de703be
	v_fmaak_f32 v162, v161, v162, 0xbec09330
	v_fmaak_f32 v161, v161, v162, 0x3e0375d0
	v_fma_f32 v165, |v160|, v161, |v160|
	v_fma_f32 v161, |v160|, s72, v9
	v_fma_f32 v161, |v160|, v161, s73
	v_fma_f32 v161, |v160|, v161, s74
; DEV unsigned pack2(float a, float b) { float2v v = {a, b}; return __builtin_bit_cast(unsigned, __builtin_convertvector(v, bf16x2v)); }
; DEV float bflo(unsigned u) { return __uint_as_float(u << 16); }
; DEV float bfhi(unsigned u) { return __uint_as_float(u & 0xffff0000u); }
; DEV float gelu_exact(float v) { return 0.5f * v * (1.f + erff(v * 0.7071067811865476f)); }
; DEV void ph_scan2(const Params& p, int item) {
;     ...
;   for (int t = 0; t < CHL; ++t) {
;     float4 a = *(const float4*)(p.a_arr + (row0 + t) * 1024 + ch);
;     float4 bb = *(const float4*)(p.b_arr + (row0 + t) * 1024 + ch);
;     u32x2 xg = *(const u32x2*)(p.z + (row0 + t) * ZLD + CXG + ch);
;     H[0] = a.x * H[0] + bb.x; H[1] = a.y * H[1] + bb.y; H[2] = a.z * H[2] + bb.z; H[3] = a.w * H[3] + bb.w;
;     u32x2 pk;
;     pk[0] = pack2(gelu_exact(bflo(xg[0])) * H[0], gelu_exact(bfhi(xg[0])) * H[1]);
;     pk[1] = pack2(gelu_exact(bflo(xg[1])) * H[2], gelu_exact(bfhi(xg[1])) * H[3]);
;     *(u32x2*)(p.orn + (row0 + t) * 1024 + ch) = pk;
;   }
	v_fma_f32 v161, |v160|, v161, s75
	v_fma_f32 v161, |v160|, v161, s76
	v_fma_f32 v161, |v160|, v161, s77
	v_fma_f32 v161, |v160|, v161, |v160|
	v_mul_f32_e32 v162, 0xbfb8aa3b, v161
	v_fma_f32 v163, v161, s78, -v162
	v_rndne_f32_e32 v164, v162
	v_fmac_f32_e32 v163, 0xb2a5705f, v161
	v_sub_f32_e32 v162, v162, v164
	v_add_f32_e32 v162, v162, v163
	v_cvt_i32_f32_e32 v163, v164
	v_exp_f32_e32 v162, v162
	v_cmp_nlt_f32_e32 vcc, s79, v161
	v_ldexp_f32 v162, v162, v163
	s_nop 0
	v_cndmask_b32_e32 v162, 0, v162, vcc
	v_cmp_ngt_f32_e32 vcc, s80, v161
	s_nop 1
	v_cndmask_b32_e32 v161, v3, v162, vcc
	v_sub_f32_e32 v166, 1.0, v161
	v_cmp_lt_f32_e64 vcc, |v160|, 1.0
	s_nop 1
	v_cndmask_b32_e32 v165, v166, v165, vcc
	v_bfi_b32 v165, s81, v165, v160
	v_mul_f32_e32 v161, 0.5, v170
	v_add_f32_e32 v165, 1.0, v165
	v_mul_f32_e32 v161, v161, v165
	v_mul_f32_e32 v178, v161, v6
	v_mul_f32_e32 v160, 0x3f3504f3, v171
	v_mul_f32_e32 v161, v160, v160
	v_fmamk_f32 v162, v161, 0xba1345e1, v8
	v_fmaak_f32 v162, v161, v162, 0xbcdac9b8
	v_fmaak_f32 v162, v161, v162, 0x3de703be
	v_fmaak_f32 v162, v161, v162, 0xbec09330
	v_fmaak_f32 v161, v161, v162, 0x3e0375d0
	v_fma_f32 v165, |v160|, v161, |v160|
	v_fma_f32 v161, |v160|, s72, v9
	v_fma_f32 v161, |v160|, v161, s73
	v_fma_f32 v161, |v160|, v161, s74
	v_fma_f32 v161, |v160|, v161, s75
	v_fma_f32 v161, |v160|, v161, s76
	v_fma_f32 v161, |v160|, v161, s77
	v_fma_f32 v161, |v160|, v161, |v160|
	v_mul_f32_e32 v162, 0xbfb8aa3b, v161
	v_fma_f32 v163, v161, s78, -v162
	v_rndne_f32_e32 v164, v162
	v_fmac_f32_e32 v163, 0xb2a5705f, v161
	v_sub_f32_e32 v162, v162, v164
	v_add_f32_e32 v162, v162, v163
	v_cvt_i32_f32_e32 v163, v164
	v_exp_f32_e32 v162, v162
	v_cmp_nlt_f32_e32 vcc, s79, v161
	v_ldexp_f32 v162, v162, v163
	s_nop 0
	v_cndmask_b32_e32 v162, 0, v162, vcc
	v_cmp_ngt_f32_e32 vcc, s80, v161
	s_nop 1
	v_cndmask_b32_e32 v161, v3, v162, vcc
	v_sub_f32_e32 v166, 1.0, v161
	v_cmp_lt_f32_e64 vcc, |v160|, 1.0
	s_nop 1
	v_cndmask_b32_e32 v165, v166, v165, vcc
	v_bfi_b32 v165, s81, v165, v160
	v_mul_f32_e32 v161, 0.5, v171
	v_add_f32_e32 v165, 1.0, v165
	v_mul_f32_e32 v161, v161, v165
	v_mul_f32_e32 v179, v161, v7
	v_cvt_pk_bf16_f32 v180, v176, v177
	v_cvt_pk_bf16_f32 v181, v178, v179
	global_store_dwordx2 v2, v[180:181], s[34:35]
	s_add_u32 s34, s34, 0x800
	s_addc_u32 s35, s35, 0
	s_waitcnt vmcnt(13)
	v_fma_f32 v4, v120, v4, v124
	v_fma_f32 v5, v121, v5, v125
	v_fma_f32 v6, v122, v6, v126
	v_fma_f32 v7, v123, v7, v127
	v_lshlrev_b32_e32 v168, 16, v128
	v_and_b32_e32 v169, 0xffff0000, v128
	v_lshlrev_b32_e32 v170, 16, v129
	v_and_b32_e32 v171, 0xffff0000, v129
	v_mul_f32_e32 v160, 0x3f3504f3, v168
	v_mul_f32_e32 v161, v160, v160
	v_fmamk_f32 v162, v161, 0xba1345e1, v8
	v_fmaak_f32 v162, v161, v162, 0xbcdac9b8
	v_fmaak_f32 v162, v161, v162, 0x3de703be
	v_fmaak_f32 v162, v161, v162, 0xbec09330
	v_fmaak_f32 v161, v161, v162, 0x3e0375d0
	v_fma_f32 v165, |v160|, v161, |v160|
	v_fma_f32 v161, |v160|, s72, v9
	v_fma_f32 v161, |v160|, v161, s73
	v_fma_f32 v161, |v160|, v161, s74
	v_fma_f32 v161, |v160|, v161, s75
	v_fma_f32 v161, |v160|, v161, s76
	v_fma_f32 v161, |v160|, v161, s77
	v_fma_f32 v161, |v160|, v161, |v160|
	v_mul_f32_e32 v162, 0xbfb8aa3b, v161
	v_fma_f32 v163, v161, s78, -v162
	v_rndne_f32_e32 v164, v162
	v_fmac_f32_e32 v163, 0xb2a5705f, v161
	v_sub_f32_e32 v162, v162, v164
	v_add_f32_e32 v162, v162, v163
	v_cvt_i32_f32_e32 v163, v164
	v_exp_f32_e32 v162, v162
	v_cmp_nlt_f32_e32 vcc, s79, v161
	v_ldexp_f32 v162, v162, v163
	s_nop 0
	v_cndmask_b32_e32 v162, 0, v162, vcc
	v_cmp_ngt_f32_e32 vcc, s80, v161
	s_nop 1
	v_cndmask_b32_e32 v161, v3, v162, vcc
	v_sub_f32_e32 v166, 1.0, v161
	v_cmp_lt_f32_e64 vcc, |v160|, 1.0
	s_nop 1
	v_cndmask_b32_e32 v165, v166, v165, vcc
	v_bfi_b32 v165, s81, v165, v160
	v_mul_f32_e32 v161, 0.5, v168
	v_add_f32_e32 v165, 1.0, v165
	v_mul_f32_e32 v161, v161, v165
	v_mul_f32_e32 v176, v161, v4
	v_mul_f32_e32 v160, 0x3f3504f3, v169
	v_mul_f32_e32 v161, v160, v160
	v_fmamk_f32 v162, v161, 0xba1345e1, v8
	v_fmaak_f32 v162, v161, v162, 0xbcdac9b8
	v_fmaak_f32 v162, v161, v162, 0x3de703be
	v_fmaak_f32 v162, v161, v162, 0xbec09330
	v_fmaak_f32 v161, v161, v162, 0x3e0375d0
	v_fma_f32 v165, |v160|, v161, |v160|
	v_fma_f32 v161, |v160|, s72, v9
	v_fma_f32 v161, |v160|, v161, s73
	v_fma_f32 v161, |v160|, v161, s74
	v_fma_f32 v161, |v160|, v161, s75
	v_fma_f32 v161, |v160|, v161, s76
	v_fma_f32 v161, |v160|, v161, s77
	v_fma_f32 v161, |v160|, v161, |v160|
	v_mul_f32_e32 v162, 0xbfb8aa3b, v161
	v_fma_f32 v163, v161, s78, -v162
	v_rndne_f32_e32 v164, v162
	v_fmac_f32_e32 v163, 0xb2a5705f, v161
	v_sub_f32_e32 v162, v162, v164
	v_add_f32_e32 v162, v162, v163
	v_cvt_i32_f32_e32 v163, v164
	v_exp_f32_e32 v162, v162
	v_cmp_nlt_f32_e32 vcc, s79, v161
	v_ldexp_f32 v162, v162, v163
	s_nop 0
	v_cndmask_b32_e32 v162, 0, v162, vcc
	v_cmp_ngt_f32_e32 vcc, s80, v161
	s_nop 1
	v_cndmask_b32_e32 v161, v3, v162, vcc
	v_sub_f32_e32 v166, 1.0, v161
	v_cmp_lt_f32_e64 vcc, |v160|, 1.0
	s_nop 1
	v_cndmask_b32_e32 v165, v166, v165, vcc
	v_bfi_b32 v165, s81, v165, v160
	v_mul_f32_e32 v161, 0.5, v169
	v_add_f32_e32 v165, 1.0, v165
	v_mul_f32_e32 v161, v161, v165
	v_mul_f32_e32 v177, v161, v5
	v_mul_f32_e32 v160, 0x3f3504f3, v170
	v_mul_f32_e32 v161, v160, v160
	v_fmamk_f32 v162, v161, 0xba1345e1, v8
	v_fmaak_f32 v162, v161, v162, 0xbcdac9b8
	v_fmaak_f32 v162, v161, v162, 0x3de703be
	v_fmaak_f32 v162, v161, v162, 0xbec09330
	v_fmaak_f32 v161, v161, v162, 0x3e0375d0
	v_fma_f32 v165, |v160|, v161, |v160|
	v_fma_f32 v161, |v160|, s72, v9
	v_fma_f32 v161, |v160|, v161, s73
	v_fma_f32 v161, |v160|, v161, s74
	v_fma_f32 v161, |v160|, v161, s75
; DEV unsigned pack2(float a, float b) { float2v v = {a, b}; return __builtin_bit_cast(unsigned, __builtin_convertvector(v, bf16x2v)); }
; DEV float bflo(unsigned u) { return __uint_as_float(u << 16); }
; DEV float bfhi(unsigned u) { return __uint_as_float(u & 0xffff0000u); }
; DEV float gelu_exact(float v) { return 0.5f * v * (1.f + erff(v * 0.7071067811865476f)); }
; DEV void ph_scan2(const Params& p, int item) {
;     ...
;   for (int t = 0; t < CHL; ++t) {
;     float4 a = *(const float4*)(p.a_arr + (row0 + t) * 1024 + ch);
;     float4 bb = *(const float4*)(p.b_arr + (row0 + t) * 1024 + ch);
;     u32x2 xg = *(const u32x2*)(p.z + (row0 + t) * ZLD + CXG + ch);
;     H[0] = a.x * H[0] + bb.x; H[1] = a.y * H[1] + bb.y; H[2] = a.z * H[2] + bb.z; H[3] = a.w * H[3] + bb.w;
;     u32x2 pk;
;     pk[0] = pack2(gelu_exact(bflo(xg[0])) * H[0], gelu_exact(bfhi(xg[0])) * H[1]);
;     pk[1] = pack2(gelu_exact(bflo(xg[1])) * H[2], gelu_exact(bfhi(xg[1])) * H[3]);
;     *(u32x2*)(p.orn + (row0 + t) * 1024 + ch) = pk;
;   }
	v_fma_f32 v161, |v160|, v161, s76
	v_fma_f32 v161, |v160|, v161, s77
	v_fma_f32 v161, |v160|, v161, |v160|
	v_mul_f32_e32 v162, 0xbfb8aa3b, v161
	v_fma_f32 v163, v161, s78, -v162
	v_rndne_f32_e32 v164, v162
	v_fmac_f32_e32 v163, 0xb2a5705f, v161
	v_sub_f32_e32 v162, v162, v164
	v_add_f32_e32 v162, v162, v163
	v_cvt_i32_f32_e32 v163, v164
	v_exp_f32_e32 v162, v162
	v_cmp_nlt_f32_e32 vcc, s79, v161
	v_ldexp_f32 v162, v162, v163
	s_nop 0
	v_cndmask_b32_e32 v162, 0, v162, vcc
	v_cmp_ngt_f32_e32 vcc, s80, v161
	s_nop 1
	v_cndmask_b32_e32 v161, v3, v162, vcc
	v_sub_f32_e32 v166, 1.0, v161
	v_cmp_lt_f32_e64 vcc, |v160|, 1.0
	s_nop 1
	v_cndmask_b32_e32 v165, v166, v165, vcc
	v_bfi_b32 v165, s81, v165, v160
	v_mul_f32_e32 v161, 0.5, v170
	v_add_f32_e32 v165, 1.0, v165
	v_mul_f32_e32 v161, v161, v165
	v_mul_f32_e32 v178, v161, v6
	v_mul_f32_e32 v160, 0x3f3504f3, v171
	v_mul_f32_e32 v161, v160, v160
	v_fmamk_f32 v162, v161, 0xba1345e1, v8
	v_fmaak_f32 v162, v161, v162, 0xbcdac9b8
	v_fmaak_f32 v162, v161, v162, 0x3de703be
	v_fmaak_f32 v162, v161, v162, 0xbec09330
	v_fmaak_f32 v161, v161, v162, 0x3e0375d0
	v_fma_f32 v165, |v160|, v161, |v160|
	v_fma_f32 v161, |v160|, s72, v9
	v_fma_f32 v161, |v160|, v161, s73
	v_fma_f32 v161, |v160|, v161, s74
	v_fma_f32 v161, |v160|, v161, s75
	v_fma_f32 v161, |v160|, v161, s76
	v_fma_f32 v161, |v160|, v161, s77
	v_fma_f32 v161, |v160|, v161, |v160|
	v_mul_f32_e32 v162, 0xbfb8aa3b, v161
	v_fma_f32 v163, v161, s78, -v162
	v_rndne_f32_e32 v164, v162
	v_fmac_f32_e32 v163, 0xb2a5705f, v161
	v_sub_f32_e32 v162, v162, v164
	v_add_f32_e32 v162, v162, v163
	v_cvt_i32_f32_e32 v163, v164
	v_exp_f32_e32 v162, v162
	v_cmp_nlt_f32_e32 vcc, s79, v161
	v_ldexp_f32 v162, v162, v163
	s_nop 0
	v_cndmask_b32_e32 v162, 0, v162, vcc
	v_cmp_ngt_f32_e32 vcc, s80, v161
	s_nop 1
	v_cndmask_b32_e32 v161, v3, v162, vcc
	v_sub_f32_e32 v166, 1.0, v161
	v_cmp_lt_f32_e64 vcc, |v160|, 1.0
	s_nop 1
	v_cndmask_b32_e32 v165, v166, v165, vcc
	v_bfi_b32 v165, s81, v165, v160
	v_mul_f32_e32 v161, 0.5, v171
	v_add_f32_e32 v165, 1.0, v165
	v_mul_f32_e32 v161, v161, v165
	v_mul_f32_e32 v179, v161, v7
	v_cvt_pk_bf16_f32 v180, v176, v177
	v_cvt_pk_bf16_f32 v181, v178, v179
	global_store_dwordx2 v2, v[180:181], s[34:35]
	s_add_u32 s34, s34, 0x800
	s_addc_u32 s35, s35, 0
	s_waitcnt vmcnt(11)
	v_fma_f32 v4, v130, v4, v134
	v_fma_f32 v5, v131, v5, v135
	v_fma_f32 v6, v132, v6, v136
	v_fma_f32 v7, v133, v7, v137
	v_lshlrev_b32_e32 v168, 16, v138
	v_and_b32_e32 v169, 0xffff0000, v138
	v_lshlrev_b32_e32 v170, 16, v139
	v_and_b32_e32 v171, 0xffff0000, v139
	v_mul_f32_e32 v160, 0x3f3504f3, v168
	v_mul_f32_e32 v161, v160, v160
	v_fmamk_f32 v162, v161, 0xba1345e1, v8
	v_fmaak_f32 v162, v161, v162, 0xbcdac9b8
	v_fmaak_f32 v162, v161, v162, 0x3de703be
	v_fmaak_f32 v162, v161, v162, 0xbec09330
	v_fmaak_f32 v161, v161, v162, 0x3e0375d0
	v_fma_f32 v165, |v160|, v161, |v160|
	v_fma_f32 v161, |v160|, s72, v9
	v_fma_f32 v161, |v160|, v161, s73
	v_fma_f32 v161, |v160|, v161, s74
	v_fma_f32 v161, |v160|, v161, s75
	v_fma_f32 v161, |v160|, v161, s76
	v_fma_f32 v161, |v160|, v161, s77
	v_fma_f32 v161, |v160|, v161, |v160|
	v_mul_f32_e32 v162, 0xbfb8aa3b, v161
	v_fma_f32 v163, v161, s78, -v162
	v_rndne_f32_e32 v164, v162
	v_fmac_f32_e32 v163, 0xb2a5705f, v161
	v_sub_f32_e32 v162, v162, v164
	v_add_f32_e32 v162, v162, v163
	v_cvt_i32_f32_e32 v163, v164
	v_exp_f32_e32 v162, v162
	v_cmp_nlt_f32_e32 vcc, s79, v161
	v_ldexp_f32 v162, v162, v163
	s_nop 0
	v_cndmask_b32_e32 v162, 0, v162, vcc
	v_cmp_ngt_f32_e32 vcc, s80, v161
	s_nop 1
	v_cndmask_b32_e32 v161, v3, v162, vcc
	v_sub_f32_e32 v166, 1.0, v161
	v_cmp_lt_f32_e64 vcc, |v160|, 1.0
	s_nop 1
	v_cndmask_b32_e32 v165, v166, v165, vcc
	v_bfi_b32 v165, s81, v165, v160
	v_mul_f32_e32 v161, 0.5, v168
	v_add_f32_e32 v165, 1.0, v165
	v_mul_f32_e32 v161, v161, v165
	v_mul_f32_e32 v176, v161, v4
	v_mul_f32_e32 v160, 0x3f3504f3, v169
	v_mul_f32_e32 v161, v160, v160
	v_fmamk_f32 v162, v161, 0xba1345e1, v8
	v_fmaak_f32 v162, v161, v162, 0xbcdac9b8
	v_fmaak_f32 v162, v161, v162, 0x3de703be
	v_fmaak_f32 v162, v161, v162, 0xbec09330
	v_fmaak_f32 v161, v161, v162, 0x3e0375d0
	v_fma_f32 v165, |v160|, v161, |v160|
	v_fma_f32 v161, |v160|, s72, v9
	v_fma_f32 v161, |v160|, v161, s73
	v_fma_f32 v161, |v160|, v161, s74
	v_fma_f32 v161, |v160|, v161, s75
	v_fma_f32 v161, |v160|, v161, s76
	v_fma_f32 v161, |v160|, v161, s77
	v_fma_f32 v161, |v160|, v161, |v160|
	v_mul_f32_e32 v162, 0xbfb8aa3b, v161
	v_fma_f32 v163, v161, s78, -v162
	v_rndne_f32_e32 v164, v162
	v_fmac_f32_e32 v163, 0xb2a5705f, v161
	v_sub_f32_e32 v162, v162, v164
	v_add_f32_e32 v162, v162, v163
	v_cvt_i32_f32_e32 v163, v164
	v_exp_f32_e32 v162, v162
	v_cmp_nlt_f32_e32 vcc, s79, v161
	v_ldexp_f32 v162, v162, v163
	s_nop 0
	v_cndmask_b32_e32 v162, 0, v162, vcc
	v_cmp_ngt_f32_e32 vcc, s80, v161
	s_nop 1
	v_cndmask_b32_e32 v161, v3, v162, vcc
	v_sub_f32_e32 v166, 1.0, v161
	v_cmp_lt_f32_e64 vcc, |v160|, 1.0
	s_nop 1
	v_cndmask_b32_e32 v165, v166, v165, vcc
	v_bfi_b32 v165, s81, v165, v160
	v_mul_f32_e32 v161, 0.5, v169
	v_add_f32_e32 v165, 1.0, v165
	v_mul_f32_e32 v161, v161, v165
	v_mul_f32_e32 v177, v161, v5
	v_mul_f32_e32 v160, 0x3f3504f3, v170
	v_mul_f32_e32 v161, v160, v160
	v_fmamk_f32 v162, v161, 0xba1345e1, v8
	v_fmaak_f32 v162, v161, v162, 0xbcdac9b8
	v_fmaak_f32 v162, v161, v162, 0x3de703be
	v_fmaak_f32 v162, v161, v162, 0xbec09330
	v_fmaak_f32 v161, v161, v162, 0x3e0375d0
	v_fma_f32 v165, |v160|, v161, |v160|
	v_fma_f32 v161, |v160|, s72, v9
	v_fma_f32 v161, |v160|, v161, s73
	v_fma_f32 v161, |v160|, v161, s74
	v_fma_f32 v161, |v160|, v161, s75
	v_fma_f32 v161, |v160|, v161, s76
; DEV unsigned pack2(float a, float b) { float2v v = {a, b}; return __builtin_bit_cast(unsigned, __builtin_convertvector(v, bf16x2v)); }
; DEV float bflo(unsigned u) { return __uint_as_float(u << 16); }
; DEV float bfhi(unsigned u) { return __uint_as_float(u & 0xffff0000u); }
; DEV float gelu_exact(float v) { return 0.5f * v * (1.f + erff(v * 0.7071067811865476f)); }
; DEV void ph_scan2(const Params& p, int item) {
;     ...
;   for (int t = 0; t < CHL; ++t) {
;     float4 a = *(const float4*)(p.a_arr + (row0 + t) * 1024 + ch);
;     float4 bb = *(const float4*)(p.b_arr + (row0 + t) * 1024 + ch);
;     u32x2 xg = *(const u32x2*)(p.z + (row0 + t) * ZLD + CXG + ch);
;     H[0] = a.x * H[0] + bb.x; H[1] = a.y * H[1] + bb.y; H[2] = a.z * H[2] + bb.z; H[3] = a.w * H[3] + bb.w;
;     u32x2 pk;
;     pk[0] = pack2(gelu_exact(bflo(xg[0])) * H[0], gelu_exact(bfhi(xg[0])) * H[1]);
;     pk[1] = pack2(gelu_exact(bflo(xg[1])) * H[2], gelu_exact(bfhi(xg[1])) * H[3]);
;     *(u32x2*)(p.orn + (row0 + t) * 1024 + ch) = pk;
;   }
	v_fma_f32 v161, |v160|, v161, s77
	v_fma_f32 v161, |v160|, v161, |v160|
	v_mul_f32_e32 v162, 0xbfb8aa3b, v161
	v_fma_f32 v163, v161, s78, -v162
	v_rndne_f32_e32 v164, v162
	v_fmac_f32_e32 v163, 0xb2a5705f, v161
	v_sub_f32_e32 v162, v162, v164
	v_add_f32_e32 v162, v162, v163
	v_cvt_i32_f32_e32 v163, v164
	v_exp_f32_e32 v162, v162
	v_cmp_nlt_f32_e32 vcc, s79, v161
	v_ldexp_f32 v162, v162, v163
	s_nop 0
	v_cndmask_b32_e32 v162, 0, v162, vcc
	v_cmp_ngt_f32_e32 vcc, s80, v161
	s_nop 1
	v_cndmask_b32_e32 v161, v3, v162, vcc
	v_sub_f32_e32 v166, 1.0, v161
	v_cmp_lt_f32_e64 vcc, |v160|, 1.0
	s_nop 1
	v_cndmask_b32_e32 v165, v166, v165, vcc
	v_bfi_b32 v165, s81, v165, v160
	v_mul_f32_e32 v161, 0.5, v170
	v_add_f32_e32 v165, 1.0, v165
	v_mul_f32_e32 v161, v161, v165
	v_mul_f32_e32 v178, v161, v6
	v_mul_f32_e32 v160, 0x3f3504f3, v171
	v_mul_f32_e32 v161, v160, v160
	v_fmamk_f32 v162, v161, 0xba1345e1, v8
	v_fmaak_f32 v162, v161, v162, 0xbcdac9b8
	v_fmaak_f32 v162, v161, v162, 0x3de703be
	v_fmaak_f32 v162, v161, v162, 0xbec09330
	v_fmaak_f32 v161, v161, v162, 0x3e0375d0
	v_fma_f32 v165, |v160|, v161, |v160|
	v_fma_f32 v161, |v160|, s72, v9
	v_fma_f32 v161, |v160|, v161, s73
	v_fma_f32 v161, |v160|, v161, s74
	v_fma_f32 v161, |v160|, v161, s75
	v_fma_f32 v161, |v160|, v161, s76
	v_fma_f32 v161, |v160|, v161, s77
	v_fma_f32 v161, |v160|, v161, |v160|
	v_mul_f32_e32 v162, 0xbfb8aa3b, v161
	v_fma_f32 v163, v161, s78, -v162
	v_rndne_f32_e32 v164, v162
	v_fmac_f32_e32 v163, 0xb2a5705f, v161
	v_sub_f32_e32 v162, v162, v164
	v_add_f32_e32 v162, v162, v163
	v_cvt_i32_f32_e32 v163, v164
	v_exp_f32_e32 v162, v162
	v_cmp_nlt_f32_e32 vcc, s79, v161
	v_ldexp_f32 v162, v162, v163
	s_nop 0
	v_cndmask_b32_e32 v162, 0, v162, vcc
	v_cmp_ngt_f32_e32 vcc, s80, v161
	s_nop 1
	v_cndmask_b32_e32 v161, v3, v162, vcc
	v_sub_f32_e32 v166, 1.0, v161
	v_cmp_lt_f32_e64 vcc, |v160|, 1.0
	s_nop 1
	v_cndmask_b32_e32 v165, v166, v165, vcc
	v_bfi_b32 v165, s81, v165, v160
	v_mul_f32_e32 v161, 0.5, v171
	v_add_f32_e32 v165, 1.0, v165
	v_mul_f32_e32 v161, v161, v165
	v_mul_f32_e32 v179, v161, v7
	v_cvt_pk_bf16_f32 v180, v176, v177
	v_cvt_pk_bf16_f32 v181, v178, v179
	global_store_dwordx2 v2, v[180:181], s[34:35]
	s_add_u32 s34, s34, 0x800
	s_addc_u32 s35, s35, 0
	s_waitcnt vmcnt(9)
	v_fma_f32 v4, v140, v4, v144
	v_fma_f32 v5, v141, v5, v145
	v_fma_f32 v6, v142, v6, v146
	v_fma_f32 v7, v143, v7, v147
	v_lshlrev_b32_e32 v168, 16, v148
	v_and_b32_e32 v169, 0xffff0000, v148
	v_lshlrev_b32_e32 v170, 16, v149
	v_and_b32_e32 v171, 0xffff0000, v149
	v_mul_f32_e32 v160, 0x3f3504f3, v168
	v_mul_f32_e32 v161, v160, v160
	v_fmamk_f32 v162, v161, 0xba1345e1, v8
	v_fmaak_f32 v162, v161, v162, 0xbcdac9b8
	v_fmaak_f32 v162, v161, v162, 0x3de703be
	v_fmaak_f32 v162, v161, v162, 0xbec09330
	v_fmaak_f32 v161, v161, v162, 0x3e0375d0
	v_fma_f32 v165, |v160|, v161, |v160|
	v_fma_f32 v161, |v160|, s72, v9
	v_fma_f32 v161, |v160|, v161, s73
	v_fma_f32 v161, |v160|, v161, s74
	v_fma_f32 v161, |v160|, v161, s75
	v_fma_f32 v161, |v160|, v161, s76
	v_fma_f32 v161, |v160|, v161, s77
	v_fma_f32 v161, |v160|, v161, |v160|
	v_mul_f32_e32 v162, 0xbfb8aa3b, v161
	v_fma_f32 v163, v161, s78, -v162
	v_rndne_f32_e32 v164, v162
	v_fmac_f32_e32 v163, 0xb2a5705f, v161
	v_sub_f32_e32 v162, v162, v164
	v_add_f32_e32 v162, v162, v163
	v_cvt_i32_f32_e32 v163, v164
	v_exp_f32_e32 v162, v162
	v_cmp_nlt_f32_e32 vcc, s79, v161
	v_ldexp_f32 v162, v162, v163
	s_nop 0
	v_cndmask_b32_e32 v162, 0, v162, vcc
	v_cmp_ngt_f32_e32 vcc, s80, v161
	s_nop 1
	v_cndmask_b32_e32 v161, v3, v162, vcc
	v_sub_f32_e32 v166, 1.0, v161
	v_cmp_lt_f32_e64 vcc, |v160|, 1.0
	s_nop 1
	v_cndmask_b32_e32 v165, v166, v165, vcc
	v_bfi_b32 v165, s81, v165, v160
	v_mul_f32_e32 v161, 0.5, v168
	v_add_f32_e32 v165, 1.0, v165
	v_mul_f32_e32 v161, v161, v165
	v_mul_f32_e32 v176, v161, v4
	v_mul_f32_e32 v160, 0x3f3504f3, v169
	v_mul_f32_e32 v161, v160, v160
	v_fmamk_f32 v162, v161, 0xba1345e1, v8
	v_fmaak_f32 v162, v161, v162, 0xbcdac9b8
	v_fmaak_f32 v162, v161, v162, 0x3de703be
	v_fmaak_f32 v162, v161, v162, 0xbec09330
	v_fmaak_f32 v161, v161, v162, 0x3e0375d0
	v_fma_f32 v165, |v160|, v161, |v160|
	v_fma_f32 v161, |v160|, s72, v9
	v_fma_f32 v161, |v160|, v161, s73
	v_fma_f32 v161, |v160|, v161, s74
	v_fma_f32 v161, |v160|, v161, s75
	v_fma_f32 v161, |v160|, v161, s76
	v_fma_f32 v161, |v160|, v161, s77
	v_fma_f32 v161, |v160|, v161, |v160|
	v_mul_f32_e32 v162, 0xbfb8aa3b, v161
	v_fma_f32 v163, v161, s78, -v162
	v_rndne_f32_e32 v164, v162
	v_fmac_f32_e32 v163, 0xb2a5705f, v161
	v_sub_f32_e32 v162, v162, v164
	v_add_f32_e32 v162, v162, v163
	v_cvt_i32_f32_e32 v163, v164
	v_exp_f32_e32 v162, v162
	v_cmp_nlt_f32_e32 vcc, s79, v161
	v_ldexp_f32 v162, v162, v163
	s_nop 0
	v_cndmask_b32_e32 v162, 0, v162, vcc
	v_cmp_ngt_f32_e32 vcc, s80, v161
	s_nop 1
	v_cndmask_b32_e32 v161, v3, v162, vcc
	v_sub_f32_e32 v166, 1.0, v161
	v_cmp_lt_f32_e64 vcc, |v160|, 1.0
	s_nop 1
	v_cndmask_b32_e32 v165, v166, v165, vcc
	v_bfi_b32 v165, s81, v165, v160
	v_mul_f32_e32 v161, 0.5, v169
	v_add_f32_e32 v165, 1.0, v165
	v_mul_f32_e32 v161, v161, v165
	v_mul_f32_e32 v177, v161, v5
	v_mul_f32_e32 v160, 0x3f3504f3, v170
	v_mul_f32_e32 v161, v160, v160
	v_fmamk_f32 v162, v161, 0xba1345e1, v8
	v_fmaak_f32 v162, v161, v162, 0xbcdac9b8
	v_fmaak_f32 v162, v161, v162, 0x3de703be
	v_fmaak_f32 v162, v161, v162, 0xbec09330
	v_fmaak_f32 v161, v161, v162, 0x3e0375d0
	v_fma_f32 v165, |v160|, v161, |v160|
	v_fma_f32 v161, |v160|, s72, v9
	v_fma_f32 v161, |v160|, v161, s73
	v_fma_f32 v161, |v160|, v161, s74
	v_fma_f32 v161, |v160|, v161, s75
	v_fma_f32 v161, |v160|, v161, s76
	v_fma_f32 v161, |v160|, v161, s77
; DEV unsigned pack2(float a, float b) { float2v v = {a, b}; return __builtin_bit_cast(unsigned, __builtin_convertvector(v, bf16x2v)); }
; DEV float bflo(unsigned u) { return __uint_as_float(u << 16); }
; DEV float bfhi(unsigned u) { return __uint_as_float(u & 0xffff0000u); }
; DEV float gelu_exact(float v) { return 0.5f * v * (1.f + erff(v * 0.7071067811865476f)); }
; DEV void ph_scan2(const Params& p, int item) {
;     ...
;   for (int t = 0; t < CHL; ++t) {
;     float4 a = *(const float4*)(p.a_arr + (row0 + t) * 1024 + ch);
;     float4 bb = *(const float4*)(p.b_arr + (row0 + t) * 1024 + ch);
;     u32x2 xg = *(const u32x2*)(p.z + (row0 + t) * ZLD + CXG + ch);
;     H[0] = a.x * H[0] + bb.x; H[1] = a.y * H[1] + bb.y; H[2] = a.z * H[2] + bb.z; H[3] = a.w * H[3] + bb.w;
;     u32x2 pk;
;     pk[0] = pack2(gelu_exact(bflo(xg[0])) * H[0], gelu_exact(bfhi(xg[0])) * H[1]);
;     pk[1] = pack2(gelu_exact(bflo(xg[1])) * H[2], gelu_exact(bfhi(xg[1])) * H[3]);
;     *(u32x2*)(p.orn + (row0 + t) * 1024 + ch) = pk;
;   }
	v_fma_f32 v161, |v160|, v161, |v160|
	v_mul_f32_e32 v162, 0xbfb8aa3b, v161
	v_fma_f32 v163, v161, s78, -v162
	v_rndne_f32_e32 v164, v162
	v_fmac_f32_e32 v163, 0xb2a5705f, v161
	v_sub_f32_e32 v162, v162, v164
	v_add_f32_e32 v162, v162, v163
	v_cvt_i32_f32_e32 v163, v164
	v_exp_f32_e32 v162, v162
	v_cmp_nlt_f32_e32 vcc, s79, v161
	v_ldexp_f32 v162, v162, v163
	s_nop 0
	v_cndmask_b32_e32 v162, 0, v162, vcc
	v_cmp_ngt_f32_e32 vcc, s80, v161
	s_nop 1
	v_cndmask_b32_e32 v161, v3, v162, vcc
	v_sub_f32_e32 v166, 1.0, v161
	v_cmp_lt_f32_e64 vcc, |v160|, 1.0
	s_nop 1
	v_cndmask_b32_e32 v165, v166, v165, vcc
	v_bfi_b32 v165, s81, v165, v160
	v_mul_f32_e32 v161, 0.5, v170
	v_add_f32_e32 v165, 1.0, v165
	v_mul_f32_e32 v161, v161, v165
	v_mul_f32_e32 v178, v161, v6
	v_mul_f32_e32 v160, 0x3f3504f3, v171
	v_mul_f32_e32 v161, v160, v160
	v_fmamk_f32 v162, v161, 0xba1345e1, v8
	v_fmaak_f32 v162, v161, v162, 0xbcdac9b8
	v_fmaak_f32 v162, v161, v162, 0x3de703be
	v_fmaak_f32 v162, v161, v162, 0xbec09330
	v_fmaak_f32 v161, v161, v162, 0x3e0375d0
	v_fma_f32 v165, |v160|, v161, |v160|
	v_fma_f32 v161, |v160|, s72, v9
	v_fma_f32 v161, |v160|, v161, s73
	v_fma_f32 v161, |v160|, v161, s74
	v_fma_f32 v161, |v160|, v161, s75
	v_fma_f32 v161, |v160|, v161, s76
	v_fma_f32 v161, |v160|, v161, s77
	v_fma_f32 v161, |v160|, v161, |v160|
	v_mul_f32_e32 v162, 0xbfb8aa3b, v161
	v_fma_f32 v163, v161, s78, -v162
	v_rndne_f32_e32 v164, v162
	v_fmac_f32_e32 v163, 0xb2a5705f, v161
	v_sub_f32_e32 v162, v162, v164
	v_add_f32_e32 v162, v162, v163
	v_cvt_i32_f32_e32 v163, v164
	v_exp_f32_e32 v162, v162
	v_cmp_nlt_f32_e32 vcc, s79, v161
	v_ldexp_f32 v162, v162, v163
	s_nop 0
	v_cndmask_b32_e32 v162, 0, v162, vcc
	v_cmp_ngt_f32_e32 vcc, s80, v161
	s_nop 1
	v_cndmask_b32_e32 v161, v3, v162, vcc
	v_sub_f32_e32 v166, 1.0, v161
	v_cmp_lt_f32_e64 vcc, |v160|, 1.0
	s_nop 1
	v_cndmask_b32_e32 v165, v166, v165, vcc
	v_bfi_b32 v165, s81, v165, v160
	v_mul_f32_e32 v161, 0.5, v171
	v_add_f32_e32 v165, 1.0, v165
	v_mul_f32_e32 v161, v161, v165
	v_mul_f32_e32 v179, v161, v7
	v_cvt_pk_bf16_f32 v180, v176, v177
	v_cvt_pk_bf16_f32 v181, v178, v179
	global_store_dwordx2 v2, v[180:181], s[34:35]
	s_add_u32 s34, s34, 0x800
	s_addc_u32 s35, s35, 0
	s_waitcnt vmcnt(7)
	v_fma_f32 v4, v150, v4, v154
	v_fma_f32 v5, v151, v5, v155
	v_fma_f32 v6, v152, v6, v156
	v_fma_f32 v7, v153, v7, v157
	v_lshlrev_b32_e32 v168, 16, v158
	v_and_b32_e32 v169, 0xffff0000, v158
	v_lshlrev_b32_e32 v170, 16, v159
	v_and_b32_e32 v171, 0xffff0000, v159
	v_mul_f32_e32 v160, 0x3f3504f3, v168
	v_mul_f32_e32 v161, v160, v160
	v_fmamk_f32 v162, v161, 0xba1345e1, v8
	v_fmaak_f32 v162, v161, v162, 0xbcdac9b8
	v_fmaak_f32 v162, v161, v162, 0x3de703be
	v_fmaak_f32 v162, v161, v162, 0xbec09330
	v_fmaak_f32 v161, v161, v162, 0x3e0375d0
	v_fma_f32 v165, |v160|, v161, |v160|
	v_fma_f32 v161, |v160|, s72, v9
	v_fma_f32 v161, |v160|, v161, s73
	v_fma_f32 v161, |v160|, v161, s74
	v_fma_f32 v161, |v160|, v161, s75
	v_fma_f32 v161, |v160|, v161, s76
	v_fma_f32 v161, |v160|, v161, s77
	v_fma_f32 v161, |v160|, v161, |v160|
	v_mul_f32_e32 v162, 0xbfb8aa3b, v161
	v_fma_f32 v163, v161, s78, -v162
	v_rndne_f32_e32 v164, v162
	v_fmac_f32_e32 v163, 0xb2a5705f, v161
	v_sub_f32_e32 v162, v162, v164
	v_add_f32_e32 v162, v162, v163
	v_cvt_i32_f32_e32 v163, v164
	v_exp_f32_e32 v162, v162
	v_cmp_nlt_f32_e32 vcc, s79, v161
	v_ldexp_f32 v162, v162, v163
	s_nop 0
	v_cndmask_b32_e32 v162, 0, v162, vcc
	v_cmp_ngt_f32_e32 vcc, s80, v161
	s_nop 1
	v_cndmask_b32_e32 v161, v3, v162, vcc
	v_sub_f32_e32 v166, 1.0, v161
	v_cmp_lt_f32_e64 vcc, |v160|, 1.0
	s_nop 1
	v_cndmask_b32_e32 v165, v166, v165, vcc
	v_bfi_b32 v165, s81, v165, v160
	v_mul_f32_e32 v161, 0.5, v168
	v_add_f32_e32 v165, 1.0, v165
	v_mul_f32_e32 v161, v161, v165
	v_mul_f32_e32 v176, v161, v4
	v_mul_f32_e32 v160, 0x3f3504f3, v169
	v_mul_f32_e32 v161, v160, v160
	v_fmamk_f32 v162, v161, 0xba1345e1, v8
	v_fmaak_f32 v162, v161, v162, 0xbcdac9b8
	v_fmaak_f32 v162, v161, v162, 0x3de703be
	v_fmaak_f32 v162, v161, v162, 0xbec09330
	v_fmaak_f32 v161, v161, v162, 0x3e0375d0
	v_fma_f32 v165, |v160|, v161, |v160|
	v_fma_f32 v161, |v160|, s72, v9
	v_fma_f32 v161, |v160|, v161, s73
	v_fma_f32 v161, |v160|, v161, s74
	v_fma_f32 v161, |v160|, v161, s75
	v_fma_f32 v161, |v160|, v161, s76
	v_fma_f32 v161, |v160|, v161, s77
	v_fma_f32 v161, |v160|, v161, |v160|
	v_mul_f32_e32 v162, 0xbfb8aa3b, v161
	v_fma_f32 v163, v161, s78, -v162
	v_rndne_f32_e32 v164, v162
	v_fmac_f32_e32 v163, 0xb2a5705f, v161
	v_sub_f32_e32 v162, v162, v164
	v_add_f32_e32 v162, v162, v163
	v_cvt_i32_f32_e32 v163, v164
	v_exp_f32_e32 v162, v162
	v_cmp_nlt_f32_e32 vcc, s79, v161
	v_ldexp_f32 v162, v162, v163
	s_nop 0
	v_cndmask_b32_e32 v162, 0, v162, vcc
	v_cmp_ngt_f32_e32 vcc, s80, v161
	s_nop 1
	v_cndmask_b32_e32 v161, v3, v162, vcc
	v_sub_f32_e32 v166, 1.0, v161
	v_cmp_lt_f32_e64 vcc, |v160|, 1.0
	s_nop 1
	v_cndmask_b32_e32 v165, v166, v165, vcc
	v_bfi_b32 v165, s81, v165, v160
	v_mul_f32_e32 v161, 0.5, v169
	v_add_f32_e32 v165, 1.0, v165
	v_mul_f32_e32 v161, v161, v165
	v_mul_f32_e32 v177, v161, v5
	v_mul_f32_e32 v160, 0x3f3504f3, v170
	v_mul_f32_e32 v161, v160, v160
	v_fmamk_f32 v162, v161, 0xba1345e1, v8
	v_fmaak_f32 v162, v161, v162, 0xbcdac9b8
	v_fmaak_f32 v162, v161, v162, 0x3de703be
	v_fmaak_f32 v162, v161, v162, 0xbec09330
	v_fmaak_f32 v161, v161, v162, 0x3e0375d0
	v_fma_f32 v165, |v160|, v161, |v160|
	v_fma_f32 v161, |v160|, s72, v9
	v_fma_f32 v161, |v160|, v161, s73
	v_fma_f32 v161, |v160|, v161, s74
	v_fma_f32 v161, |v160|, v161, s75
	v_fma_f32 v161, |v160|, v161, s76
	v_fma_f32 v161, |v160|, v161, s77
	v_fma_f32 v161, |v160|, v161, |v160|
; DEV unsigned pack2(float a, float b) { float2v v = {a, b}; return __builtin_bit_cast(unsigned, __builtin_convertvector(v, bf16x2v)); }
; DEV float bflo(unsigned u) { return __uint_as_float(u << 16); }
; DEV float bfhi(unsigned u) { return __uint_as_float(u & 0xffff0000u); }
; DEV float gelu_exact(float v) { return 0.5f * v * (1.f + erff(v * 0.7071067811865476f)); }
; DEV void ph_scan2(const Params& p, int item) {
;     ...
;   for (int t = 0; t < CHL; ++t) {
;     float4 a = *(const float4*)(p.a_arr + (row0 + t) * 1024 + ch);
;     float4 bb = *(const float4*)(p.b_arr + (row0 + t) * 1024 + ch);
;     u32x2 xg = *(const u32x2*)(p.z + (row0 + t) * ZLD + CXG + ch);
;     H[0] = a.x * H[0] + bb.x; H[1] = a.y * H[1] + bb.y; H[2] = a.z * H[2] + bb.z; H[3] = a.w * H[3] + bb.w;
;     u32x2 pk;
;     pk[0] = pack2(gelu_exact(bflo(xg[0])) * H[0], gelu_exact(bfhi(xg[0])) * H[1]);
;     pk[1] = pack2(gelu_exact(bflo(xg[1])) * H[2], gelu_exact(bfhi(xg[1])) * H[3]);
;     *(u32x2*)(p.orn + (row0 + t) * 1024 + ch) = pk;
;   }
; __global__ void __launch_bounds__(256, 2) fwd_megakernel(Params p) {
;     ...
;   for (size_t blk = (size_t)bid * 256 + tid; blk < (size_t)16384 * 64; blk += (size_t)nb * 256) {
; #pragma unroll
;     for (int tb = 0; tb < 2; ++tb) {
;       const float* src = (tb ? p.peer_up : p.peer_down) + blk * 32;
;       const float sc = tb ? UP_SCALE : DOWN_SCALE;
;       v16f va, vb;
; #pragma unroll
;       for (int q = 0; q < 4; ++q) {
;         const float4 x = *(const float4*)(src + q * 8), y = *(const float4*)(src + q * 8 + 4);
;         va[q * 4] = x.x * sc; vb[q * 4] = x.y * sc; va[q * 4 + 1] = x.z * sc; vb[q * 4 + 1] = x.w * sc;
;         va[q * 4 + 2] = y.x * sc; vb[q * 4 + 2] = y.y * sc; va[q * 4 + 3] = y.z * sc; vb[q * 4 + 3] = y.w * sc;
;       }
;       const v6u o = __builtin_amdgcn_cvt_scalef32_2xpk16_fp6_f32(va, vb, 1.0f);
;       unsigned char* dst = (tb ? p.up8 : p.down8) + blk * 24;
;       *(u32x2*)dst = u32x2{o[0], o[1]}; *(u32x2*)(dst + 8) = u32x2{o[2], o[3]}; *(u32x2*)(dst + 16) = u32x2{o[4], o[5]};
;     }
	v_mul_f32_e32 v162, 0xbfb8aa3b, v161
	v_fma_f32 v163, v161, s78, -v162
	v_rndne_f32_e32 v164, v162
	v_fmac_f32_e32 v163, 0xb2a5705f, v161
	v_sub_f32_e32 v162, v162, v164
	v_add_f32_e32 v162, v162, v163
	v_cvt_i32_f32_e32 v163, v164
	v_exp_f32_e32 v162, v162
	v_cmp_nlt_f32_e32 vcc, s79, v161
	v_ldexp_f32 v162, v162, v163
	s_nop 0
	v_cndmask_b32_e32 v162, 0, v162, vcc
	v_cmp_ngt_f32_e32 vcc, s80, v161
	s_nop 1
	v_cndmask_b32_e32 v161, v3, v162, vcc
	v_sub_f32_e32 v166, 1.0, v161
	v_cmp_lt_f32_e64 vcc, |v160|, 1.0
	s_nop 1
	v_cndmask_b32_e32 v165, v166, v165, vcc
	v_bfi_b32 v165, s81, v165, v160
	v_mul_f32_e32 v161, 0.5, v170
	v_add_f32_e32 v165, 1.0, v165
	v_mul_f32_e32 v161, v161, v165
	v_mul_f32_e32 v178, v161, v6
	v_mul_f32_e32 v160, 0x3f3504f3, v171
	v_mul_f32_e32 v161, v160, v160
	v_fmamk_f32 v162, v161, 0xba1345e1, v8
	v_fmaak_f32 v162, v161, v162, 0xbcdac9b8
	v_fmaak_f32 v162, v161, v162, 0x3de703be
	v_fmaak_f32 v162, v161, v162, 0xbec09330
	v_fmaak_f32 v161, v161, v162, 0x3e0375d0
	v_fma_f32 v165, |v160|, v161, |v160|
	v_fma_f32 v161, |v160|, s72, v9
	v_fma_f32 v161, |v160|, v161, s73
	v_fma_f32 v161, |v160|, v161, s74
	v_fma_f32 v161, |v160|, v161, s75
	v_fma_f32 v161, |v160|, v161, s76
	v_fma_f32 v161, |v160|, v161, s77
	v_fma_f32 v161, |v160|, v161, |v160|
	v_mul_f32_e32 v162, 0xbfb8aa3b, v161
	v_fma_f32 v163, v161, s78, -v162
	v_rndne_f32_e32 v164, v162
	v_fmac_f32_e32 v163, 0xb2a5705f, v161
	v_sub_f32_e32 v162, v162, v164
	v_add_f32_e32 v162, v162, v163
	v_cvt_i32_f32_e32 v163, v164
	v_exp_f32_e32 v162, v162
	v_cmp_nlt_f32_e32 vcc, s79, v161
	v_ldexp_f32 v162, v162, v163
	s_nop 0
	v_cndmask_b32_e32 v162, 0, v162, vcc
	v_cmp_ngt_f32_e32 vcc, s80, v161
	s_nop 1
	v_cndmask_b32_e32 v161, v3, v162, vcc
	v_sub_f32_e32 v166, 1.0, v161
	v_cmp_lt_f32_e64 vcc, |v160|, 1.0
	s_nop 1
	v_cndmask_b32_e32 v165, v166, v165, vcc
	v_bfi_b32 v165, s81, v165, v160
	v_mul_f32_e32 v161, 0.5, v171
	v_add_f32_e32 v165, 1.0, v165
	v_mul_f32_e32 v161, v161, v165
	v_mul_f32_e32 v179, v161, v7
	v_cvt_pk_bf16_f32 v180, v176, v177
	v_cvt_pk_bf16_f32 v181, v178, v179
	global_store_dwordx2 v2, v[180:181], s[34:35]
	s_add_u32 s34, s34, 0x800
	s_addc_u32 s35, s35, 0
	s_add_u32 s41, s41, 1
	s_cmp_lt_u32 s41, 4
	s_cbranch_scc1 .Lsc_main
	s_add_i32 s50, s50, s92
	s_cmpk_lt_i32 s50, 0x200
	s_cbranch_scc1 .Lsc_item
	s_mov_b64 exec, -1
	v_lshrrev_b32_e32 v54, 6, v0
	v_and_b32_e32 v55, 63, v0
	v_lshlrev_b32_e32 v52, 13, v54
	v_lshl_or_b32 v52, v55, 4, v52
	v_mul_u32_u24_e32 v53, 0xc00, v54
	v_lshl_or_b32 v53, v55, 4, v53
	v_add_u32_e32 v54, 0x1000, v52
	v_readlane_b32 s40, v254, 8
	v_readlane_b32 s41, v254, 9
	v_readlane_b32 s42, v254, 10
	v_readlane_b32 s43, v254, 11
	s_lshl_b32 s12, s92, 15
	s_mul_i32 s13, s92, 0x3000
	s_mov_b32 s16, 0x42800000
	s_lshl_b32 s0, s94, 15
	s_mul_i32 s1, s12, 0
	s_add_u32 s0, s0, s1
	s_add_u32 s2, s40, s0
	s_addc_u32 s3, s41, 0
	s_add_u32 s4, s42, s0
	s_addc_u32 s5, s43, 0
	v_readlane_b32 s6, v254, 14
	v_readlane_b32 s7, v254, 15
	s_mul_i32 s0, s94, 0x3000
	s_nop 0
	s_add_u32 s6, s6, s0
	s_addc_u32 s7, s7, 0
	s_nop 3
	global_load_dwordx4 v[56:59], v52, s[2:3] sc0 sc1 nt
	global_load_dwordx4 v[60:63], v52, s[2:3] offset:1024 sc0 sc1 nt
	global_load_dwordx4 v[64:67], v52, s[2:3] offset:2048 sc0 sc1 nt
	global_load_dwordx4 v[68:71], v52, s[2:3] offset:3072 sc0 sc1 nt
	global_load_dwordx4 v[72:75], v54, s[2:3] sc0 sc1 nt
	global_load_dwordx4 v[76:79], v54, s[2:3] offset:1024 sc0 sc1 nt
	global_load_dwordx4 v[80:83], v54, s[2:3] offset:2048 sc0 sc1 nt
	global_load_dwordx4 v[84:87], v54, s[2:3] offset:3072 sc0 sc1 nt
	s_waitcnt vmcnt(0)
	v_mul_f32_e32 v2, s16, v56
	v_mul_f32_e32 v3, s16, v58
	v_mul_f32_e32 v4, s16, v60
	v_mul_f32_e32 v5, s16, v62
	v_mul_f32_e32 v6, s16, v64
	v_mul_f32_e32 v7, s16, v66
	v_mul_f32_e32 v8, s16, v68
	v_mul_f32_e32 v9, s16, v70
	v_mul_f32_e32 v10, s16, v72
	v_mul_f32_e32 v11, s16, v74
	v_mul_f32_e32 v12, s16, v76
	v_mul_f32_e32 v13, s16, v78
	v_mul_f32_e32 v14, s16, v80
	v_mul_f32_e32 v15, s16, v82
	v_mul_f32_e32 v16, s16, v84
	v_mul_f32_e32 v17, s16, v86
	v_mul_f32_e32 v18, s16, v57
	v_mul_f32_e32 v19, s16, v59
	v_mul_f32_e32 v20, s16, v61
	v_mul_f32_e32 v21, s16, v63
	v_mul_f32_e32 v22, s16, v65
	v_mul_f32_e32 v23, s16, v67
	v_mul_f32_e32 v24, s16, v69
	v_mul_f32_e32 v25, s16, v71
	v_mul_f32_e32 v26, s16, v73
	v_mul_f32_e32 v27, s16, v75
	v_mul_f32_e32 v28, s16, v77
	v_mul_f32_e32 v29, s16, v79
	v_mul_f32_e32 v30, s16, v81
	v_mul_f32_e32 v31, s16, v83
	v_mul_f32_e32 v32, s16, v85
	v_mul_f32_e32 v33, s16, v87
	s_nop 0
	v_cvt_scalef32_2xpk16_fp6_f32 v[40:45], v[2:17], v[18:33], 1.0
	global_load_dwordx4 v[56:59], v52, s[4:5] sc0 sc1 nt
	global_load_dwordx4 v[60:63], v52, s[4:5] offset:1024 sc0 sc1 nt
	global_load_dwordx4 v[64:67], v52, s[4:5] offset:2048 sc0 sc1 nt
	global_load_dwordx4 v[68:71], v52, s[4:5] offset:3072 sc0 sc1 nt
	global_load_dwordx4 v[72:75], v54, s[4:5] sc0 sc1 nt
	global_load_dwordx4 v[76:79], v54, s[4:5] offset:1024 sc0 sc1 nt
	global_load_dwordx4 v[80:83], v54, s[4:5] offset:2048 sc0 sc1 nt
	global_load_dwordx4 v[84:87], v54, s[4:5] offset:3072 sc0 sc1 nt
	s_add_u32 s2, s2, s12
	s_addc_u32 s3, s3, 0
	s_add_u32 s4, s4, s12
	s_addc_u32 s5, s5, 0
	s_waitcnt vmcnt(0)
; __global__ void __launch_bounds__(256, 2) fwd_megakernel(Params p) {
;     ...
;   for (size_t blk = (size_t)bid * 256 + tid; blk < (size_t)16384 * 64; blk += (size_t)nb * 256) {
; #pragma unroll
;     for (int tb = 0; tb < 2; ++tb) {
;       const float* src = (tb ? p.peer_up : p.peer_down) + blk * 32;
;       const float sc = tb ? UP_SCALE : DOWN_SCALE;
;       v16f va, vb;
; #pragma unroll
;       for (int q = 0; q < 4; ++q) {
;         const float4 x = *(const float4*)(src + q * 8), y = *(const float4*)(src + q * 8 + 4);
;         va[q * 4] = x.x * sc; vb[q * 4] = x.y * sc; va[q * 4 + 1] = x.z * sc; vb[q * 4 + 1] = x.w * sc;
;         va[q * 4 + 2] = y.x * sc; vb[q * 4 + 2] = y.y * sc; va[q * 4 + 3] = y.z * sc; vb[q * 4 + 3] = y.w * sc;
;       }
;       const v6u o = __builtin_amdgcn_cvt_scalef32_2xpk16_fp6_f32(va, vb, 1.0f);
;       unsigned char* dst = (tb ? p.up8 : p.down8) + blk * 24;
;       *(u32x2*)dst = u32x2{o[0], o[1]}; *(u32x2*)(dst + 8) = u32x2{o[2], o[3]}; *(u32x2*)(dst + 16) = u32x2{o[4], o[5]};
;     }
	v_mul_f32_e32 v2, 4.0, v56
	v_mul_f32_e32 v3, 4.0, v58
	v_mul_f32_e32 v4, 4.0, v60
	v_mul_f32_e32 v5, 4.0, v62
	v_mul_f32_e32 v6, 4.0, v64
	v_mul_f32_e32 v7, 4.0, v66
	v_mul_f32_e32 v8, 4.0, v68
	v_mul_f32_e32 v9, 4.0, v70
	v_mul_f32_e32 v10, 4.0, v72
	v_mul_f32_e32 v11, 4.0, v74
	v_mul_f32_e32 v12, 4.0, v76
	v_mul_f32_e32 v13, 4.0, v78
	v_mul_f32_e32 v14, 4.0, v80
	v_mul_f32_e32 v15, 4.0, v82
	v_mul_f32_e32 v16, 4.0, v84
	v_mul_f32_e32 v17, 4.0, v86
	v_mul_f32_e32 v18, 4.0, v57
	v_mul_f32_e32 v19, 4.0, v59
	v_mul_f32_e32 v20, 4.0, v61
	v_mul_f32_e32 v21, 4.0, v63
	v_mul_f32_e32 v22, 4.0, v65
	v_mul_f32_e32 v23, 4.0, v67
	v_mul_f32_e32 v24, 4.0, v69
	v_mul_f32_e32 v25, 4.0, v71
	v_mul_f32_e32 v26, 4.0, v73
	v_mul_f32_e32 v27, 4.0, v75
	v_mul_f32_e32 v28, 4.0, v77
	v_mul_f32_e32 v29, 4.0, v79
	v_mul_f32_e32 v30, 4.0, v81
	v_mul_f32_e32 v31, 4.0, v83
	v_mul_f32_e32 v32, 4.0, v85
	v_mul_f32_e32 v33, 4.0, v87
	s_nop 0
	v_cvt_scalef32_2xpk16_fp6_f32 v[46:51], v[2:17], v[18:33], 1.0
	global_store_dwordx4 v53, v[40:43], s[6:7]
	global_store_dwordx4 v53, v[48:51], s[6:7] offset:1024
	global_store_dwordx4 v53, v[44:47], s[6:7] offset:2048
	s_add_u32 s6, s6, s13
	s_addc_u32 s7, s7, 0
	global_load_dwordx4 v[56:59], v52, s[2:3] sc0 sc1 nt
	global_load_dwordx4 v[60:63], v52, s[2:3] offset:1024 sc0 sc1 nt
	global_load_dwordx4 v[64:67], v52, s[2:3] offset:2048 sc0 sc1 nt
	global_load_dwordx4 v[68:71], v52, s[2:3] offset:3072 sc0 sc1 nt
	global_load_dwordx4 v[72:75], v54, s[2:3] sc0 sc1 nt
	global_load_dwordx4 v[76:79], v54, s[2:3] offset:1024 sc0 sc1 nt
	global_load_dwordx4 v[80:83], v54, s[2:3] offset:2048 sc0 sc1 nt
	global_load_dwordx4 v[84:87], v54, s[2:3] offset:3072 sc0 sc1 nt
	s_waitcnt vmcnt(0)
	v_mul_f32_e32 v2, s16, v56
	v_mul_f32_e32 v3, s16, v58
	v_mul_f32_e32 v4, s16, v60
	v_mul_f32_e32 v5, s16, v62
	v_mul_f32_e32 v6, s16, v64
	v_mul_f32_e32 v7, s16, v66
	v_mul_f32_e32 v8, s16, v68
	v_mul_f32_e32 v9, s16, v70
	v_mul_f32_e32 v10, s16, v72
	v_mul_f32_e32 v11, s16, v74
	v_mul_f32_e32 v12, s16, v76
	v_mul_f32_e32 v13, s16, v78
	v_mul_f32_e32 v14, s16, v80
	v_mul_f32_e32 v15, s16, v82
	v_mul_f32_e32 v16, s16, v84
	v_mul_f32_e32 v17, s16, v86
	v_mul_f32_e32 v18, s16, v57
	v_mul_f32_e32 v19, s16, v59
	v_mul_f32_e32 v20, s16, v61
	v_mul_f32_e32 v21, s16, v63
	v_mul_f32_e32 v22, s16, v65
	v_mul_f32_e32 v23, s16, v67
	v_mul_f32_e32 v24, s16, v69
	v_mul_f32_e32 v25, s16, v71
	v_mul_f32_e32 v26, s16, v73
	v_mul_f32_e32 v27, s16, v75
	v_mul_f32_e32 v28, s16, v77
	v_mul_f32_e32 v29, s16, v79
	v_mul_f32_e32 v30, s16, v81
	v_mul_f32_e32 v31, s16, v83
	v_mul_f32_e32 v32, s16, v85
	v_mul_f32_e32 v33, s16, v87
	s_nop 0
	v_cvt_scalef32_2xpk16_fp6_f32 v[40:45], v[2:17], v[18:33], 1.0
	global_load_dwordx4 v[56:59], v52, s[4:5] sc0 sc1 nt
	global_load_dwordx4 v[60:63], v52, s[4:5] offset:1024 sc0 sc1 nt
	global_load_dwordx4 v[64:67], v52, s[4:5] offset:2048 sc0 sc1 nt
	global_load_dwordx4 v[68:71], v52, s[4:5] offset:3072 sc0 sc1 nt
	global_load_dwordx4 v[72:75], v54, s[4:5] sc0 sc1 nt
	global_load_dwordx4 v[76:79], v54, s[4:5] offset:1024 sc0 sc1 nt
	global_load_dwordx4 v[80:83], v54, s[4:5] offset:2048 sc0 sc1 nt
	global_load_dwordx4 v[84:87], v54, s[4:5] offset:3072 sc0 sc1 nt
	s_add_u32 s2, s2, s12
	s_addc_u32 s3, s3, 0
	s_add_u32 s4, s4, s12
	s_addc_u32 s5, s5, 0
	s_waitcnt vmcnt(0)
	v_mul_f32_e32 v2, 4.0, v56
	v_mul_f32_e32 v3, 4.0, v58
	v_mul_f32_e32 v4, 4.0, v60
	v_mul_f32_e32 v5, 4.0, v62
	v_mul_f32_e32 v6, 4.0, v64
	v_mul_f32_e32 v7, 4.0, v66
	v_mul_f32_e32 v8, 4.0, v68
	v_mul_f32_e32 v9, 4.0, v70
	v_mul_f32_e32 v10, 4.0, v72
	v_mul_f32_e32 v11, 4.0, v74
	v_mul_f32_e32 v12, 4.0, v76
	v_mul_f32_e32 v13, 4.0, v78
	v_mul_f32_e32 v14, 4.0, v80
	v_mul_f32_e32 v15, 4.0, v82
	v_mul_f32_e32 v16, 4.0, v84
	v_mul_f32_e32 v17, 4.0, v86
	v_mul_f32_e32 v18, 4.0, v57
	v_mul_f32_e32 v19, 4.0, v59
	v_mul_f32_e32 v20, 4.0, v61
	v_mul_f32_e32 v21, 4.0, v63
	v_mul_f32_e32 v22, 4.0, v65
	v_mul_f32_e32 v23, 4.0, v67
	v_mul_f32_e32 v24, 4.0, v69
	v_mul_f32_e32 v25, 4.0, v71
	v_mul_f32_e32 v26, 4.0, v73
	v_mul_f32_e32 v27, 4.0, v75
	v_mul_f32_e32 v28, 4.0, v77
	v_mul_f32_e32 v29, 4.0, v79
	v_mul_f32_e32 v30, 4.0, v81
	v_mul_f32_e32 v31, 4.0, v83
	v_mul_f32_e32 v32, 4.0, v85
	v_mul_f32_e32 v33, 4.0, v87
	s_nop 0
	v_cvt_scalef32_2xpk16_fp6_f32 v[46:51], v[2:17], v[18:33], 1.0
	global_store_dwordx4 v53, v[40:43], s[6:7]
	global_store_dwordx4 v53, v[48:51], s[6:7] offset:1024
	global_store_dwordx4 v53, v[44:47], s[6:7] offset:2048
	s_add_u32 s6, s6, s13
	s_addc_u32 s7, s7, 0
	global_load_dwordx4 v[56:59], v52, s[2:3] sc0 sc1 nt
	global_load_dwordx4 v[60:63], v52, s[2:3] offset:1024 sc0 sc1 nt
	global_load_dwordx4 v[64:67], v52, s[2:3] offset:2048 sc0 sc1 nt
	global_load_dwordx4 v[68:71], v52, s[2:3] offset:3072 sc0 sc1 nt
	global_load_dwordx4 v[72:75], v54, s[2:3] sc0 sc1 nt
	global_load_dwordx4 v[76:79], v54, s[2:3] offset:1024 sc0 sc1 nt
	global_load_dwordx4 v[80:83], v54, s[2:3] offset:2048 sc0 sc1 nt
	global_load_dwordx4 v[84:87], v54, s[2:3] offset:3072 sc0 sc1 nt
	s_waitcnt vmcnt(0)
; __global__ void __launch_bounds__(256, 2) fwd_megakernel(Params p) {
;     ...
;   for (size_t blk = (size_t)bid * 256 + tid; blk < (size_t)16384 * 64; blk += (size_t)nb * 256) {
; #pragma unroll
;     for (int tb = 0; tb < 2; ++tb) {
;       const float* src = (tb ? p.peer_up : p.peer_down) + blk * 32;
;       const float sc = tb ? UP_SCALE : DOWN_SCALE;
;       v16f va, vb;
; #pragma unroll
;       for (int q = 0; q < 4; ++q) {
;         const float4 x = *(const float4*)(src + q * 8), y = *(const float4*)(src + q * 8 + 4);
;         va[q * 4] = x.x * sc; vb[q * 4] = x.y * sc; va[q * 4 + 1] = x.z * sc; vb[q * 4 + 1] = x.w * sc;
;         va[q * 4 + 2] = y.x * sc; vb[q * 4 + 2] = y.y * sc; va[q * 4 + 3] = y.z * sc; vb[q * 4 + 3] = y.w * sc;
;       }
;       const v6u o = __builtin_amdgcn_cvt_scalef32_2xpk16_fp6_f32(va, vb, 1.0f);
;       unsigned char* dst = (tb ? p.up8 : p.down8) + blk * 24;
;       *(u32x2*)dst = u32x2{o[0], o[1]}; *(u32x2*)(dst + 8) = u32x2{o[2], o[3]}; *(u32x2*)(dst + 16) = u32x2{o[4], o[5]};
;     }
	v_mul_f32_e32 v2, s16, v56
	v_mul_f32_e32 v3, s16, v58
	v_mul_f32_e32 v4, s16, v60
	v_mul_f32_e32 v5, s16, v62
	v_mul_f32_e32 v6, s16, v64
	v_mul_f32_e32 v7, s16, v66
	v_mul_f32_e32 v8, s16, v68
	v_mul_f32_e32 v9, s16, v70
	v_mul_f32_e32 v10, s16, v72
	v_mul_f32_e32 v11, s16, v74
	v_mul_f32_e32 v12, s16, v76
	v_mul_f32_e32 v13, s16, v78
	v_mul_f32_e32 v14, s16, v80
	v_mul_f32_e32 v15, s16, v82
	v_mul_f32_e32 v16, s16, v84
	v_mul_f32_e32 v17, s16, v86
	v_mul_f32_e32 v18, s16, v57
	v_mul_f32_e32 v19, s16, v59
	v_mul_f32_e32 v20, s16, v61
	v_mul_f32_e32 v21, s16, v63
	v_mul_f32_e32 v22, s16, v65
	v_mul_f32_e32 v23, s16, v67
	v_mul_f32_e32 v24, s16, v69
	v_mul_f32_e32 v25, s16, v71
	v_mul_f32_e32 v26, s16, v73
	v_mul_f32_e32 v27, s16, v75
	v_mul_f32_e32 v28, s16, v77
	v_mul_f32_e32 v29, s16, v79
	v_mul_f32_e32 v30, s16, v81
	v_mul_f32_e32 v31, s16, v83
	v_mul_f32_e32 v32, s16, v85
	v_mul_f32_e32 v33, s16, v87
	s_nop 0
	v_cvt_scalef32_2xpk16_fp6_f32 v[40:45], v[2:17], v[18:33], 1.0
	global_load_dwordx4 v[56:59], v52, s[4:5] sc0 sc1 nt
	global_load_dwordx4 v[60:63], v52, s[4:5] offset:1024 sc0 sc1 nt
	global_load_dwordx4 v[64:67], v52, s[4:5] offset:2048 sc0 sc1 nt
	global_load_dwordx4 v[68:71], v52, s[4:5] offset:3072 sc0 sc1 nt
	global_load_dwordx4 v[72:75], v54, s[4:5] sc0 sc1 nt
	global_load_dwordx4 v[76:79], v54, s[4:5] offset:1024 sc0 sc1 nt
	global_load_dwordx4 v[80:83], v54, s[4:5] offset:2048 sc0 sc1 nt
	global_load_dwordx4 v[84:87], v54, s[4:5] offset:3072 sc0 sc1 nt
	s_add_u32 s2, s2, s12
	s_addc_u32 s3, s3, 0
	s_add_u32 s4, s4, s12
	s_addc_u32 s5, s5, 0
	s_waitcnt vmcnt(0)
	v_mul_f32_e32 v2, 4.0, v56
	v_mul_f32_e32 v3, 4.0, v58
	v_mul_f32_e32 v4, 4.0, v60
	v_mul_f32_e32 v5, 4.0, v62
	v_mul_f32_e32 v6, 4.0, v64
	v_mul_f32_e32 v7, 4.0, v66
	v_mul_f32_e32 v8, 4.0, v68
	v_mul_f32_e32 v9, 4.0, v70
	v_mul_f32_e32 v10, 4.0, v72
	v_mul_f32_e32 v11, 4.0, v74
	v_mul_f32_e32 v12, 4.0, v76
	v_mul_f32_e32 v13, 4.0, v78
	v_mul_f32_e32 v14, 4.0, v80
	v_mul_f32_e32 v15, 4.0, v82
	v_mul_f32_e32 v16, 4.0, v84
	v_mul_f32_e32 v17, 4.0, v86
	v_mul_f32_e32 v18, 4.0, v57
	v_mul_f32_e32 v19, 4.0, v59
	v_mul_f32_e32 v20, 4.0, v61
	v_mul_f32_e32 v21, 4.0, v63
	v_mul_f32_e32 v22, 4.0, v65
	v_mul_f32_e32 v23, 4.0, v67
	v_mul_f32_e32 v24, 4.0, v69
	v_mul_f32_e32 v25, 4.0, v71
	v_mul_f32_e32 v26, 4.0, v73
	v_mul_f32_e32 v27, 4.0, v75
	v_mul_f32_e32 v28, 4.0, v77
	v_mul_f32_e32 v29, 4.0, v79
	v_mul_f32_e32 v30, 4.0, v81
	v_mul_f32_e32 v31, 4.0, v83
	v_mul_f32_e32 v32, 4.0, v85
	v_mul_f32_e32 v33, 4.0, v87
	s_nop 0
	v_cvt_scalef32_2xpk16_fp6_f32 v[46:51], v[2:17], v[18:33], 1.0
	global_store_dwordx4 v53, v[40:43], s[6:7]
	global_store_dwordx4 v53, v[48:51], s[6:7] offset:1024
	global_store_dwordx4 v53, v[44:47], s[6:7] offset:2048
	s_add_u32 s6, s6, s13
	s_addc_u32 s7, s7, 0
	v_readlane_b32 s6, v255, 9
	v_readlane_b32 s7, v255, 10
	s_mul_i32 s0, s94, 0x3000
	s_nop 0
	s_add_u32 s6, s6, s0
	s_addc_u32 s7, s7, 0
	s_nop 3
	global_load_dwordx4 v[56:59], v52, s[2:3] sc0 sc1 nt
	global_load_dwordx4 v[60:63], v52, s[2:3] offset:1024 sc0 sc1 nt
	global_load_dwordx4 v[64:67], v52, s[2:3] offset:2048 sc0 sc1 nt
	global_load_dwordx4 v[68:71], v52, s[2:3] offset:3072 sc0 sc1 nt
	global_load_dwordx4 v[72:75], v54, s[2:3] sc0 sc1 nt
	global_load_dwordx4 v[76:79], v54, s[2:3] offset:1024 sc0 sc1 nt
	global_load_dwordx4 v[80:83], v54, s[2:3] offset:2048 sc0 sc1 nt
	global_load_dwordx4 v[84:87], v54, s[2:3] offset:3072 sc0 sc1 nt
	s_waitcnt vmcnt(0)
	v_mul_f32_e32 v2, s16, v56
	v_mul_f32_e32 v3, s16, v58
	v_mul_f32_e32 v4, s16, v60
	v_mul_f32_e32 v5, s16, v62
	v_mul_f32_e32 v6, s16, v64
	v_mul_f32_e32 v7, s16, v66
	v_mul_f32_e32 v8, s16, v68
	v_mul_f32_e32 v9, s16, v70
	v_mul_f32_e32 v10, s16, v72
	v_mul_f32_e32 v11, s16, v74
	v_mul_f32_e32 v12, s16, v76
	v_mul_f32_e32 v13, s16, v78
	v_mul_f32_e32 v14, s16, v80
	v_mul_f32_e32 v15, s16, v82
	v_mul_f32_e32 v16, s16, v84
	v_mul_f32_e32 v17, s16, v86
	v_mul_f32_e32 v18, s16, v57
	v_mul_f32_e32 v19, s16, v59
	v_mul_f32_e32 v20, s16, v61
	v_mul_f32_e32 v21, s16, v63
	v_mul_f32_e32 v22, s16, v65
	v_mul_f32_e32 v23, s16, v67
	v_mul_f32_e32 v24, s16, v69
	v_mul_f32_e32 v25, s16, v71
	v_mul_f32_e32 v26, s16, v73
	v_mul_f32_e32 v27, s16, v75
	v_mul_f32_e32 v28, s16, v77
	v_mul_f32_e32 v29, s16, v79
	v_mul_f32_e32 v30, s16, v81
	v_mul_f32_e32 v31, s16, v83
	v_mul_f32_e32 v32, s16, v85
	v_mul_f32_e32 v33, s16, v87
	s_nop 0
	v_cvt_scalef32_2xpk16_fp6_f32 v[40:45], v[2:17], v[18:33], 1.0
	global_load_dwordx4 v[56:59], v52, s[4:5] sc0 sc1 nt
	global_load_dwordx4 v[60:63], v52, s[4:5] offset:1024 sc0 sc1 nt
	global_load_dwordx4 v[64:67], v52, s[4:5] offset:2048 sc0 sc1 nt
	global_load_dwordx4 v[68:71], v52, s[4:5] offset:3072 sc0 sc1 nt
	global_load_dwordx4 v[72:75], v54, s[4:5] sc0 sc1 nt
	global_load_dwordx4 v[76:79], v54, s[4:5] offset:1024 sc0 sc1 nt
	global_load_dwordx4 v[80:83], v54, s[4:5] offset:2048 sc0 sc1 nt
	global_load_dwordx4 v[84:87], v54, s[4:5] offset:3072 sc0 sc1 nt
	s_add_u32 s2, s2, s12
	s_addc_u32 s3, s3, 0
	s_add_u32 s4, s4, s12
	s_addc_u32 s5, s5, 0
	s_waitcnt vmcnt(0)
; __global__ void __launch_bounds__(256, 2) fwd_megakernel(Params p) {
;     ...
;   for (size_t blk = (size_t)bid * 256 + tid; blk < (size_t)16384 * 64; blk += (size_t)nb * 256) {
; #pragma unroll
;     for (int tb = 0; tb < 2; ++tb) {
;       const float* src = (tb ? p.peer_up : p.peer_down) + blk * 32;
;       const float sc = tb ? UP_SCALE : DOWN_SCALE;
;       v16f va, vb;
; #pragma unroll
;       for (int q = 0; q < 4; ++q) {
;         const float4 x = *(const float4*)(src + q * 8), y = *(const float4*)(src + q * 8 + 4);
;         va[q * 4] = x.x * sc; vb[q * 4] = x.y * sc; va[q * 4 + 1] = x.z * sc; vb[q * 4 + 1] = x.w * sc;
;         va[q * 4 + 2] = y.x * sc; vb[q * 4 + 2] = y.y * sc; va[q * 4 + 3] = y.z * sc; vb[q * 4 + 3] = y.w * sc;
;       }
;       const v6u o = __builtin_amdgcn_cvt_scalef32_2xpk16_fp6_f32(va, vb, 1.0f);
;       unsigned char* dst = (tb ? p.up8 : p.down8) + blk * 24;
;       *(u32x2*)dst = u32x2{o[0], o[1]}; *(u32x2*)(dst + 8) = u32x2{o[2], o[3]}; *(u32x2*)(dst + 16) = u32x2{o[4], o[5]};
;     }
	v_mul_f32_e32 v2, 4.0, v56
	v_mul_f32_e32 v3, 4.0, v58
	v_mul_f32_e32 v4, 4.0, v60
	v_mul_f32_e32 v5, 4.0, v62
	v_mul_f32_e32 v6, 4.0, v64
	v_mul_f32_e32 v7, 4.0, v66
	v_mul_f32_e32 v8, 4.0, v68
	v_mul_f32_e32 v9, 4.0, v70
	v_mul_f32_e32 v10, 4.0, v72
	v_mul_f32_e32 v11, 4.0, v74
	v_mul_f32_e32 v12, 4.0, v76
	v_mul_f32_e32 v13, 4.0, v78
	v_mul_f32_e32 v14, 4.0, v80
	v_mul_f32_e32 v15, 4.0, v82
	v_mul_f32_e32 v16, 4.0, v84
	v_mul_f32_e32 v17, 4.0, v86
	v_mul_f32_e32 v18, 4.0, v57
	v_mul_f32_e32 v19, 4.0, v59
	v_mul_f32_e32 v20, 4.0, v61
	v_mul_f32_e32 v21, 4.0, v63
	v_mul_f32_e32 v22, 4.0, v65
	v_mul_f32_e32 v23, 4.0, v67
	v_mul_f32_e32 v24, 4.0, v69
	v_mul_f32_e32 v25, 4.0, v71
	v_mul_f32_e32 v26, 4.0, v73
	v_mul_f32_e32 v27, 4.0, v75
	v_mul_f32_e32 v28, 4.0, v77
	v_mul_f32_e32 v29, 4.0, v79
	v_mul_f32_e32 v30, 4.0, v81
	v_mul_f32_e32 v31, 4.0, v83
	v_mul_f32_e32 v32, 4.0, v85
	v_mul_f32_e32 v33, 4.0, v87
	s_nop 0
	v_cvt_scalef32_2xpk16_fp6_f32 v[46:51], v[2:17], v[18:33], 1.0
	global_store_dwordx4 v53, v[40:43], s[6:7]
	global_store_dwordx4 v53, v[48:51], s[6:7] offset:1024
	global_store_dwordx4 v53, v[44:47], s[6:7] offset:2048
	s_add_u32 s6, s6, s13
	s_addc_u32 s7, s7, 0
	global_load_dwordx4 v[56:59], v52, s[2:3] sc0 sc1 nt
	global_load_dwordx4 v[60:63], v52, s[2:3] offset:1024 sc0 sc1 nt
	global_load_dwordx4 v[64:67], v52, s[2:3] offset:2048 sc0 sc1 nt
	global_load_dwordx4 v[68:71], v52, s[2:3] offset:3072 sc0 sc1 nt
	global_load_dwordx4 v[72:75], v54, s[2:3] sc0 sc1 nt
	global_load_dwordx4 v[76:79], v54, s[2:3] offset:1024 sc0 sc1 nt
	global_load_dwordx4 v[80:83], v54, s[2:3] offset:2048 sc0 sc1 nt
	global_load_dwordx4 v[84:87], v54, s[2:3] offset:3072 sc0 sc1 nt
	s_waitcnt vmcnt(0)
	v_mul_f32_e32 v2, s16, v56
	v_mul_f32_e32 v3, s16, v58
	v_mul_f32_e32 v4, s16, v60
	v_mul_f32_e32 v5, s16, v62
	v_mul_f32_e32 v6, s16, v64
	v_mul_f32_e32 v7, s16, v66
	v_mul_f32_e32 v8, s16, v68
	v_mul_f32_e32 v9, s16, v70
	v_mul_f32_e32 v10, s16, v72
	v_mul_f32_e32 v11, s16, v74
	v_mul_f32_e32 v12, s16, v76
	v_mul_f32_e32 v13, s16, v78
	v_mul_f32_e32 v14, s16, v80
	v_mul_f32_e32 v15, s16, v82
	v_mul_f32_e32 v16, s16, v84
	v_mul_f32_e32 v17, s16, v86
	v_mul_f32_e32 v18, s16, v57
	v_mul_f32_e32 v19, s16, v59
	v_mul_f32_e32 v20, s16, v61
	v_mul_f32_e32 v21, s16, v63
	v_mul_f32_e32 v22, s16, v65
	v_mul_f32_e32 v23, s16, v67
	v_mul_f32_e32 v24, s16, v69
	v_mul_f32_e32 v25, s16, v71
	v_mul_f32_e32 v26, s16, v73
	v_mul_f32_e32 v27, s16, v75
	v_mul_f32_e32 v28, s16, v77
	v_mul_f32_e32 v29, s16, v79
	v_mul_f32_e32 v30, s16, v81
	v_mul_f32_e32 v31, s16, v83
	v_mul_f32_e32 v32, s16, v85
	v_mul_f32_e32 v33, s16, v87
	s_nop 0
	v_cvt_scalef32_2xpk16_fp6_f32 v[40:45], v[2:17], v[18:33], 1.0
	global_load_dwordx4 v[56:59], v52, s[4:5] sc0 sc1 nt
	global_load_dwordx4 v[60:63], v52, s[4:5] offset:1024 sc0 sc1 nt
	global_load_dwordx4 v[64:67], v52, s[4:5] offset:2048 sc0 sc1 nt
	global_load_dwordx4 v[68:71], v52, s[4:5] offset:3072 sc0 sc1 nt
	global_load_dwordx4 v[72:75], v54, s[4:5] sc0 sc1 nt
	global_load_dwordx4 v[76:79], v54, s[4:5] offset:1024 sc0 sc1 nt
	global_load_dwordx4 v[80:83], v54, s[4:5] offset:2048 sc0 sc1 nt
	global_load_dwordx4 v[84:87], v54, s[4:5] offset:3072 sc0 sc1 nt
	s_add_u32 s2, s2, s12
	s_addc_u32 s3, s3, 0
	s_add_u32 s4, s4, s12
	s_addc_u32 s5, s5, 0
	s_waitcnt vmcnt(0)
	v_mul_f32_e32 v2, 4.0, v56
	v_mul_f32_e32 v3, 4.0, v58
	v_mul_f32_e32 v4, 4.0, v60
	v_mul_f32_e32 v5, 4.0, v62
	v_mul_f32_e32 v6, 4.0, v64
	v_mul_f32_e32 v7, 4.0, v66
	v_mul_f32_e32 v8, 4.0, v68
	v_mul_f32_e32 v9, 4.0, v70
	v_mul_f32_e32 v10, 4.0, v72
	v_mul_f32_e32 v11, 4.0, v74
	v_mul_f32_e32 v12, 4.0, v76
	v_mul_f32_e32 v13, 4.0, v78
	v_mul_f32_e32 v14, 4.0, v80
	v_mul_f32_e32 v15, 4.0, v82
	v_mul_f32_e32 v16, 4.0, v84
	v_mul_f32_e32 v17, 4.0, v86
	v_mul_f32_e32 v18, 4.0, v57
	v_mul_f32_e32 v19, 4.0, v59
	v_mul_f32_e32 v20, 4.0, v61
	v_mul_f32_e32 v21, 4.0, v63
	v_mul_f32_e32 v22, 4.0, v65
	v_mul_f32_e32 v23, 4.0, v67
	v_mul_f32_e32 v24, 4.0, v69
	v_mul_f32_e32 v25, 4.0, v71
	v_mul_f32_e32 v26, 4.0, v73
	v_mul_f32_e32 v27, 4.0, v75
	v_mul_f32_e32 v28, 4.0, v77
	v_mul_f32_e32 v29, 4.0, v79
	v_mul_f32_e32 v30, 4.0, v81
	v_mul_f32_e32 v31, 4.0, v83
	v_mul_f32_e32 v32, 4.0, v85
	v_mul_f32_e32 v33, 4.0, v87
	s_nop 0
	v_cvt_scalef32_2xpk16_fp6_f32 v[46:51], v[2:17], v[18:33], 1.0
	global_store_dwordx4 v53, v[40:43], s[6:7]
	global_store_dwordx4 v53, v[48:51], s[6:7] offset:1024
	global_store_dwordx4 v53, v[44:47], s[6:7] offset:2048
	s_add_u32 s6, s6, s13
	s_addc_u32 s7, s7, 0
.Lenc_end_h:
	v_readlane_b32 s2, v254, 0
	s_nop 3
	s_cmp_lt_u32 s2, 0x100
	s_cbranch_scc1 .Lp5_resume

; __global__ void __launch_bounds__(256, 2) fwd_megakernel(Params p) {
;     ...
;   if (bid < (nb >> 1)) {
;   for (size_t blk = (size_t)bid * 256 + tid; blk < (size_t)16384 * 64; blk += (size_t)nb * 256) {
; #pragma unroll
;     for (int tb = 0; tb < 2; ++tb) {
;       const float* src = (tb ? p.peer_up : p.peer_down) + blk * 32;
;       const float sc = tb ? UP_SCALE : DOWN_SCALE;
;       v16f va, vb;
; #pragma unroll
;       for (int q = 0; q < 4; ++q) {
;         const float4 x = *(const float4*)(src + q * 8), y = *(const float4*)(src + q * 8 + 4);
;         va[q * 4] = x.x * sc; vb[q * 4] = x.y * sc; va[q * 4 + 1] = x.z * sc; vb[q * 4 + 1] = x.w * sc;
;         va[q * 4 + 2] = y.x * sc; vb[q * 4 + 2] = y.y * sc; va[q * 4 + 3] = y.z * sc; vb[q * 4 + 3] = y.w * sc;
;       }
;       const v6u o = __builtin_amdgcn_cvt_scalef32_2xpk16_fp6_f32(va, vb, 1.0f);
;       unsigned char* dst = (tb ? p.up8 : p.down8) + blk * 24;
;       *(u32x2*)dst = u32x2{o[0], o[1]}; *(u32x2*)(dst + 8) = u32x2{o[2], o[3]}; *(u32x2*)(dst + 16) = u32x2{o[4], o[5]};
;     }
.LBB0_1436:
	s_or_b64 exec, exec, s[0:1]
	s_ashr_i32 s0, s92, 1
	v_mov_b32_e32 v34, v0
	s_cmp_ge_i32 s94, s0
	s_waitcnt lgkmcnt(0)
	s_barrier
	s_cselect_b64 s[72:73], -1, 0
	s_cmp_lt_i32 s94, s0
	v_ashrrev_i32_e32 v35, 31, v34
	s_cbranch_scc0 .LBB0_1441
	s_mov_b64 exec, -1
	v_lshrrev_b32_e32 v54, 6, v0
	v_and_b32_e32 v55, 63, v0
	v_lshlrev_b32_e32 v52, 13, v54
	v_lshl_or_b32 v52, v55, 4, v52
	v_mul_u32_u24_e32 v53, 0xc00, v54
	v_lshl_or_b32 v53, v55, 4, v53
	v_add_u32_e32 v54, 0x1000, v52
	v_readlane_b32 s40, v254, 8
	v_readlane_b32 s41, v254, 9
	v_readlane_b32 s42, v254, 10
	v_readlane_b32 s43, v254, 11
	s_lshl_b32 s12, s92, 15
	s_mul_i32 s13, s92, 0x3000
	s_mov_b32 s16, 0x42800000
	s_lshl_b32 s0, s94, 15
	s_mul_i32 s1, s12, 5
	s_add_u32 s0, s0, s1
	s_add_u32 s2, s40, s0
	s_addc_u32 s3, s41, 0
	s_add_u32 s4, s42, s0
	s_addc_u32 s5, s43, 0
	s_mul_i32 s0, s94, 0x3000
	s_mul_i32 s1, s13, 5
	s_add_u32 s0, s0, s1
	s_add_u32 s6, s62, s0
	s_addc_u32 s7, s63, 0
	global_load_dwordx4 v[56:59], v52, s[2:3] sc0 sc1 nt
	global_load_dwordx4 v[60:63], v52, s[2:3] offset:1024 sc0 sc1 nt
	global_load_dwordx4 v[64:67], v52, s[2:3] offset:2048 sc0 sc1 nt
	global_load_dwordx4 v[68:71], v52, s[2:3] offset:3072 sc0 sc1 nt
	global_load_dwordx4 v[72:75], v54, s[2:3] sc0 sc1 nt
	global_load_dwordx4 v[76:79], v54, s[2:3] offset:1024 sc0 sc1 nt
	global_load_dwordx4 v[80:83], v54, s[2:3] offset:2048 sc0 sc1 nt
	global_load_dwordx4 v[84:87], v54, s[2:3] offset:3072 sc0 sc1 nt
	s_waitcnt vmcnt(0)
	v_mul_f32_e32 v2, s16, v56
	v_mul_f32_e32 v3, s16, v58
	v_mul_f32_e32 v4, s16, v60
	v_mul_f32_e32 v5, s16, v62
	v_mul_f32_e32 v6, s16, v64
	v_mul_f32_e32 v7, s16, v66
	v_mul_f32_e32 v8, s16, v68
	v_mul_f32_e32 v9, s16, v70
	v_mul_f32_e32 v10, s16, v72
	v_mul_f32_e32 v11, s16, v74
	v_mul_f32_e32 v12, s16, v76
	v_mul_f32_e32 v13, s16, v78
	v_mul_f32_e32 v14, s16, v80
	v_mul_f32_e32 v15, s16, v82
	v_mul_f32_e32 v16, s16, v84
	v_mul_f32_e32 v17, s16, v86
	v_mul_f32_e32 v18, s16, v57
	v_mul_f32_e32 v19, s16, v59
	v_mul_f32_e32 v20, s16, v61
	v_mul_f32_e32 v21, s16, v63
	v_mul_f32_e32 v22, s16, v65
	v_mul_f32_e32 v23, s16, v67
	v_mul_f32_e32 v24, s16, v69
	v_mul_f32_e32 v25, s16, v71
	v_mul_f32_e32 v26, s16, v73
	v_mul_f32_e32 v27, s16, v75
	v_mul_f32_e32 v28, s16, v77
	v_mul_f32_e32 v29, s16, v79
	v_mul_f32_e32 v30, s16, v81
	v_mul_f32_e32 v31, s16, v83
	v_mul_f32_e32 v32, s16, v85
	v_mul_f32_e32 v33, s16, v87
	s_nop 0
	v_cvt_scalef32_2xpk16_fp6_f32 v[40:45], v[2:17], v[18:33], 1.0
	global_load_dwordx4 v[56:59], v52, s[4:5] sc0 sc1 nt
	global_load_dwordx4 v[60:63], v52, s[4:5] offset:1024 sc0 sc1 nt
	global_load_dwordx4 v[64:67], v52, s[4:5] offset:2048 sc0 sc1 nt
	global_load_dwordx4 v[68:71], v52, s[4:5] offset:3072 sc0 sc1 nt
	global_load_dwordx4 v[72:75], v54, s[4:5] sc0 sc1 nt
	global_load_dwordx4 v[76:79], v54, s[4:5] offset:1024 sc0 sc1 nt
	global_load_dwordx4 v[80:83], v54, s[4:5] offset:2048 sc0 sc1 nt
	global_load_dwordx4 v[84:87], v54, s[4:5] offset:3072 sc0 sc1 nt
	s_add_u32 s2, s2, s12
	s_addc_u32 s3, s3, 0
	s_add_u32 s4, s4, s12
	s_addc_u32 s5, s5, 0
	s_waitcnt vmcnt(0)
	v_mul_f32_e32 v2, 4.0, v56
	v_mul_f32_e32 v3, 4.0, v58
	v_mul_f32_e32 v4, 4.0, v60
	v_mul_f32_e32 v5, 4.0, v62
	v_mul_f32_e32 v6, 4.0, v64
	v_mul_f32_e32 v7, 4.0, v66
	v_mul_f32_e32 v8, 4.0, v68
	v_mul_f32_e32 v9, 4.0, v70
	v_mul_f32_e32 v10, 4.0, v72
	v_mul_f32_e32 v11, 4.0, v74
	v_mul_f32_e32 v12, 4.0, v76
	v_mul_f32_e32 v13, 4.0, v78
	v_mul_f32_e32 v14, 4.0, v80
	v_mul_f32_e32 v15, 4.0, v82
	v_mul_f32_e32 v16, 4.0, v84
	v_mul_f32_e32 v17, 4.0, v86
	v_mul_f32_e32 v18, 4.0, v57
	v_mul_f32_e32 v19, 4.0, v59
	v_mul_f32_e32 v20, 4.0, v61
	v_mul_f32_e32 v21, 4.0, v63
	v_mul_f32_e32 v22, 4.0, v65
	v_mul_f32_e32 v23, 4.0, v67
	v_mul_f32_e32 v24, 4.0, v69
	v_mul_f32_e32 v25, 4.0, v71
	v_mul_f32_e32 v26, 4.0, v73
	v_mul_f32_e32 v27, 4.0, v75
	v_mul_f32_e32 v28, 4.0, v77
	v_mul_f32_e32 v29, 4.0, v79
	v_mul_f32_e32 v30, 4.0, v81
	v_mul_f32_e32 v31, 4.0, v83
	v_mul_f32_e32 v32, 4.0, v85
	v_mul_f32_e32 v33, 4.0, v87
	s_nop 0
	v_cvt_scalef32_2xpk16_fp6_f32 v[46:51], v[2:17], v[18:33], 1.0
	global_store_dwordx4 v53, v[40:43], s[6:7]
	global_store_dwordx4 v53, v[48:51], s[6:7] offset:1024
	global_store_dwordx4 v53, v[44:47], s[6:7] offset:2048
	s_add_u32 s6, s6, s13
	s_addc_u32 s7, s7, 0
	global_load_dwordx4 v[56:59], v52, s[2:3] sc0 sc1 nt
	global_load_dwordx4 v[60:63], v52, s[2:3] offset:1024 sc0 sc1 nt
	global_load_dwordx4 v[64:67], v52, s[2:3] offset:2048 sc0 sc1 nt
	global_load_dwordx4 v[68:71], v52, s[2:3] offset:3072 sc0 sc1 nt
	global_load_dwordx4 v[72:75], v54, s[2:3] sc0 sc1 nt
	global_load_dwordx4 v[76:79], v54, s[2:3] offset:1024 sc0 sc1 nt
	global_load_dwordx4 v[80:83], v54, s[2:3] offset:2048 sc0 sc1 nt
	global_load_dwordx4 v[84:87], v54, s[2:3] offset:3072 sc0 sc1 nt
	s_waitcnt vmcnt(0)
; __global__ void __launch_bounds__(256, 2) fwd_megakernel(Params p) {
;     ...
;   if (bid < (nb >> 1)) {
;   for (size_t blk = (size_t)bid * 256 + tid; blk < (size_t)16384 * 64; blk += (size_t)nb * 256) {
; #pragma unroll
;     for (int tb = 0; tb < 2; ++tb) {
;       const float* src = (tb ? p.peer_up : p.peer_down) + blk * 32;
;       const float sc = tb ? UP_SCALE : DOWN_SCALE;
;       v16f va, vb;
; #pragma unroll
;       for (int q = 0; q < 4; ++q) {
;         const float4 x = *(const float4*)(src + q * 8), y = *(const float4*)(src + q * 8 + 4);
;         va[q * 4] = x.x * sc; vb[q * 4] = x.y * sc; va[q * 4 + 1] = x.z * sc; vb[q * 4 + 1] = x.w * sc;
;         va[q * 4 + 2] = y.x * sc; vb[q * 4 + 2] = y.y * sc; va[q * 4 + 3] = y.z * sc; vb[q * 4 + 3] = y.w * sc;
;       }
;       const v6u o = __builtin_amdgcn_cvt_scalef32_2xpk16_fp6_f32(va, vb, 1.0f);
;       unsigned char* dst = (tb ? p.up8 : p.down8) + blk * 24;
;       *(u32x2*)dst = u32x2{o[0], o[1]}; *(u32x2*)(dst + 8) = u32x2{o[2], o[3]}; *(u32x2*)(dst + 16) = u32x2{o[4], o[5]};
;     }
	v_mul_f32_e32 v2, s16, v56
	v_mul_f32_e32 v3, s16, v58
	v_mul_f32_e32 v4, s16, v60
	v_mul_f32_e32 v5, s16, v62
	v_mul_f32_e32 v6, s16, v64
	v_mul_f32_e32 v7, s16, v66
	v_mul_f32_e32 v8, s16, v68
	v_mul_f32_e32 v9, s16, v70
	v_mul_f32_e32 v10, s16, v72
	v_mul_f32_e32 v11, s16, v74
	v_mul_f32_e32 v12, s16, v76
	v_mul_f32_e32 v13, s16, v78
	v_mul_f32_e32 v14, s16, v80
	v_mul_f32_e32 v15, s16, v82
	v_mul_f32_e32 v16, s16, v84
	v_mul_f32_e32 v17, s16, v86
	v_mul_f32_e32 v18, s16, v57
	v_mul_f32_e32 v19, s16, v59
	v_mul_f32_e32 v20, s16, v61
	v_mul_f32_e32 v21, s16, v63
	v_mul_f32_e32 v22, s16, v65
	v_mul_f32_e32 v23, s16, v67
	v_mul_f32_e32 v24, s16, v69
	v_mul_f32_e32 v25, s16, v71
	v_mul_f32_e32 v26, s16, v73
	v_mul_f32_e32 v27, s16, v75
	v_mul_f32_e32 v28, s16, v77
	v_mul_f32_e32 v29, s16, v79
	v_mul_f32_e32 v30, s16, v81
	v_mul_f32_e32 v31, s16, v83
	v_mul_f32_e32 v32, s16, v85
	v_mul_f32_e32 v33, s16, v87
	s_nop 0
	v_cvt_scalef32_2xpk16_fp6_f32 v[40:45], v[2:17], v[18:33], 1.0
	global_load_dwordx4 v[56:59], v52, s[4:5] sc0 sc1 nt
	global_load_dwordx4 v[60:63], v52, s[4:5] offset:1024 sc0 sc1 nt
	global_load_dwordx4 v[64:67], v52, s[4:5] offset:2048 sc0 sc1 nt
	global_load_dwordx4 v[68:71], v52, s[4:5] offset:3072 sc0 sc1 nt
	global_load_dwordx4 v[72:75], v54, s[4:5] sc0 sc1 nt
	global_load_dwordx4 v[76:79], v54, s[4:5] offset:1024 sc0 sc1 nt
	global_load_dwordx4 v[80:83], v54, s[4:5] offset:2048 sc0 sc1 nt
	global_load_dwordx4 v[84:87], v54, s[4:5] offset:3072 sc0 sc1 nt
	s_add_u32 s2, s2, s12
	s_addc_u32 s3, s3, 0
	s_add_u32 s4, s4, s12
	s_addc_u32 s5, s5, 0
	s_waitcnt vmcnt(0)
	v_mul_f32_e32 v2, 4.0, v56
	v_mul_f32_e32 v3, 4.0, v58
	v_mul_f32_e32 v4, 4.0, v60
	v_mul_f32_e32 v5, 4.0, v62
	v_mul_f32_e32 v6, 4.0, v64
	v_mul_f32_e32 v7, 4.0, v66
	v_mul_f32_e32 v8, 4.0, v68
	v_mul_f32_e32 v9, 4.0, v70
	v_mul_f32_e32 v10, 4.0, v72
	v_mul_f32_e32 v11, 4.0, v74
	v_mul_f32_e32 v12, 4.0, v76
	v_mul_f32_e32 v13, 4.0, v78
	v_mul_f32_e32 v14, 4.0, v80
	v_mul_f32_e32 v15, 4.0, v82
	v_mul_f32_e32 v16, 4.0, v84
	v_mul_f32_e32 v17, 4.0, v86
	v_mul_f32_e32 v18, 4.0, v57
	v_mul_f32_e32 v19, 4.0, v59
	v_mul_f32_e32 v20, 4.0, v61
	v_mul_f32_e32 v21, 4.0, v63
	v_mul_f32_e32 v22, 4.0, v65
	v_mul_f32_e32 v23, 4.0, v67
	v_mul_f32_e32 v24, 4.0, v69
	v_mul_f32_e32 v25, 4.0, v71
	v_mul_f32_e32 v26, 4.0, v73
	v_mul_f32_e32 v27, 4.0, v75
	v_mul_f32_e32 v28, 4.0, v77
	v_mul_f32_e32 v29, 4.0, v79
	v_mul_f32_e32 v30, 4.0, v81
	v_mul_f32_e32 v31, 4.0, v83
	v_mul_f32_e32 v32, 4.0, v85
	v_mul_f32_e32 v33, 4.0, v87
	s_nop 0
	v_cvt_scalef32_2xpk16_fp6_f32 v[46:51], v[2:17], v[18:33], 1.0
	global_store_dwordx4 v53, v[40:43], s[6:7]
	global_store_dwordx4 v53, v[48:51], s[6:7] offset:1024
	global_store_dwordx4 v53, v[44:47], s[6:7] offset:2048
	s_add_u32 s6, s6, s13
	s_addc_u32 s7, s7, 0
	global_load_dwordx4 v[56:59], v52, s[2:3] sc0 sc1 nt
	global_load_dwordx4 v[60:63], v52, s[2:3] offset:1024 sc0 sc1 nt
	global_load_dwordx4 v[64:67], v52, s[2:3] offset:2048 sc0 sc1 nt
	global_load_dwordx4 v[68:71], v52, s[2:3] offset:3072 sc0 sc1 nt
	global_load_dwordx4 v[72:75], v54, s[2:3] sc0 sc1 nt
	global_load_dwordx4 v[76:79], v54, s[2:3] offset:1024 sc0 sc1 nt
	global_load_dwordx4 v[80:83], v54, s[2:3] offset:2048 sc0 sc1 nt
	global_load_dwordx4 v[84:87], v54, s[2:3] offset:3072 sc0 sc1 nt
	s_waitcnt vmcnt(0)
	v_mul_f32_e32 v2, s16, v56
	v_mul_f32_e32 v3, s16, v58
	v_mul_f32_e32 v4, s16, v60
	v_mul_f32_e32 v5, s16, v62
	v_mul_f32_e32 v6, s16, v64
	v_mul_f32_e32 v7, s16, v66
	v_mul_f32_e32 v8, s16, v68
	v_mul_f32_e32 v9, s16, v70
	v_mul_f32_e32 v10, s16, v72
	v_mul_f32_e32 v11, s16, v74
	v_mul_f32_e32 v12, s16, v76
	v_mul_f32_e32 v13, s16, v78
	v_mul_f32_e32 v14, s16, v80
	v_mul_f32_e32 v15, s16, v82
	v_mul_f32_e32 v16, s16, v84
	v_mul_f32_e32 v17, s16, v86
	v_mul_f32_e32 v18, s16, v57
	v_mul_f32_e32 v19, s16, v59
	v_mul_f32_e32 v20, s16, v61
	v_mul_f32_e32 v21, s16, v63
	v_mul_f32_e32 v22, s16, v65
	v_mul_f32_e32 v23, s16, v67
	v_mul_f32_e32 v24, s16, v69
	v_mul_f32_e32 v25, s16, v71
	v_mul_f32_e32 v26, s16, v73
	v_mul_f32_e32 v27, s16, v75
	v_mul_f32_e32 v28, s16, v77
	v_mul_f32_e32 v29, s16, v79
	v_mul_f32_e32 v30, s16, v81
	v_mul_f32_e32 v31, s16, v83
	v_mul_f32_e32 v32, s16, v85
	v_mul_f32_e32 v33, s16, v87
	s_nop 0
	v_cvt_scalef32_2xpk16_fp6_f32 v[40:45], v[2:17], v[18:33], 1.0
	global_load_dwordx4 v[56:59], v52, s[4:5] sc0 sc1 nt
	global_load_dwordx4 v[60:63], v52, s[4:5] offset:1024 sc0 sc1 nt
	global_load_dwordx4 v[64:67], v52, s[4:5] offset:2048 sc0 sc1 nt
	global_load_dwordx4 v[68:71], v52, s[4:5] offset:3072 sc0 sc1 nt
	global_load_dwordx4 v[72:75], v54, s[4:5] sc0 sc1 nt
	global_load_dwordx4 v[76:79], v54, s[4:5] offset:1024 sc0 sc1 nt
	global_load_dwordx4 v[80:83], v54, s[4:5] offset:2048 sc0 sc1 nt
	global_load_dwordx4 v[84:87], v54, s[4:5] offset:3072 sc0 sc1 nt
	s_add_u32 s2, s2, s12
	s_addc_u32 s3, s3, 0
	s_add_u32 s4, s4, s12
	s_addc_u32 s5, s5, 0
	s_waitcnt vmcnt(0)
	v_mul_f32_e32 v2, 4.0, v56
	v_mul_f32_e32 v3, 4.0, v58
	v_mul_f32_e32 v4, 4.0, v60
	v_mul_f32_e32 v5, 4.0, v62
	v_mul_f32_e32 v6, 4.0, v64
	v_mul_f32_e32 v7, 4.0, v66
	v_mul_f32_e32 v8, 4.0, v68
	v_mul_f32_e32 v9, 4.0, v70
	v_mul_f32_e32 v10, 4.0, v72
	v_mul_f32_e32 v11, 4.0, v74
	v_mul_f32_e32 v12, 4.0, v76
	v_mul_f32_e32 v13, 4.0, v78
	v_mul_f32_e32 v14, 4.0, v80
	v_mul_f32_e32 v15, 4.0, v82
	v_mul_f32_e32 v16, 4.0, v84
	v_mul_f32_e32 v17, 4.0, v86
	v_mul_f32_e32 v18, 4.0, v57
	v_mul_f32_e32 v19, 4.0, v59
	v_mul_f32_e32 v20, 4.0, v61
	v_mul_f32_e32 v21, 4.0, v63
	v_mul_f32_e32 v22, 4.0, v65
	v_mul_f32_e32 v23, 4.0, v67
	v_mul_f32_e32 v24, 4.0, v69
	v_mul_f32_e32 v25, 4.0, v71
	v_mul_f32_e32 v26, 4.0, v73
	v_mul_f32_e32 v27, 4.0, v75
	v_mul_f32_e32 v28, 4.0, v77
	v_mul_f32_e32 v29, 4.0, v79
	v_mul_f32_e32 v30, 4.0, v81
	v_mul_f32_e32 v31, 4.0, v83
	v_mul_f32_e32 v32, 4.0, v85
	v_mul_f32_e32 v33, 4.0, v87
	s_nop 0
	v_cvt_scalef32_2xpk16_fp6_f32 v[46:51], v[2:17], v[18:33], 1.0
	global_store_dwordx4 v53, v[40:43], s[6:7]
	global_store_dwordx4 v53, v[48:51], s[6:7] offset:1024
	global_store_dwordx4 v53, v[44:47], s[6:7] offset:2048
	s_add_u32 s6, s6, s13
	s_addc_u32 s7, s7, 0

; __global__ void __launch_bounds__(256, 2) fwd_megakernel(Params p) {
;     ...
;   if (bid >= (nb >> 1)) {
;   for (size_t blk = (size_t)bid * 256 + tid; blk < (size_t)16384 * 64; blk += (size_t)nb * 256) {
; #pragma unroll
;     for (int tb = 0; tb < 2; ++tb) {
;       const float* src = (tb ? p.peer_up : p.peer_down) + blk * 32;
;       const float sc = tb ? UP_SCALE : DOWN_SCALE;
;       v16f va, vb;
; #pragma unroll
;       for (int q = 0; q < 4; ++q) {
;         const float4 x = *(const float4*)(src + q * 8), y = *(const float4*)(src + q * 8 + 4);
;         va[q * 4] = x.x * sc; vb[q * 4] = x.y * sc; va[q * 4 + 1] = x.z * sc; vb[q * 4 + 1] = x.w * sc;
;         va[q * 4 + 2] = y.x * sc; vb[q * 4 + 2] = y.y * sc; va[q * 4 + 3] = y.z * sc; vb[q * 4 + 3] = y.w * sc;
;       }
;       const v6u o = __builtin_amdgcn_cvt_scalef32_2xpk16_fp6_f32(va, vb, 1.0f);
;       unsigned char* dst = (tb ? p.up8 : p.down8) + blk * 24;
;       *(u32x2*)dst = u32x2{o[0], o[1]}; *(u32x2*)(dst + 8) = u32x2{o[2], o[3]}; *(u32x2*)(dst + 16) = u32x2{o[4], o[5]};
;     }
.LBB0_1510:
	s_and_b64 vcc, exec, s[72:73]
	s_cbranch_vccz .LBB0_1515
	s_mov_b64 exec, -1
	v_lshrrev_b32_e32 v54, 6, v0
	v_and_b32_e32 v55, 63, v0
	v_lshlrev_b32_e32 v52, 13, v54
	v_lshl_or_b32 v52, v55, 4, v52
	v_mul_u32_u24_e32 v53, 0xc00, v54
	v_lshl_or_b32 v53, v55, 4, v53
	v_add_u32_e32 v54, 0x1000, v52
	v_readlane_b32 s40, v254, 8
	v_readlane_b32 s41, v254, 9
	v_readlane_b32 s42, v254, 10
	v_readlane_b32 s43, v254, 11
	s_lshl_b32 s12, s92, 15
	s_mul_i32 s13, s92, 0x3000
	s_mov_b32 s16, 0x42800000
	s_lshl_b32 s0, s94, 15
	s_mul_i32 s1, s12, 5
	s_add_u32 s0, s0, s1
	s_add_u32 s2, s40, s0
	s_addc_u32 s3, s41, 0
	s_add_u32 s4, s42, s0
	s_addc_u32 s5, s43, 0
	s_mul_i32 s0, s94, 0x3000
	s_mul_i32 s1, s13, 5
	s_add_u32 s0, s0, s1
	s_add_u32 s6, s62, s0
	s_addc_u32 s7, s63, 0
	global_load_dwordx4 v[56:59], v52, s[2:3] sc0 sc1 nt
	global_load_dwordx4 v[60:63], v52, s[2:3] offset:1024 sc0 sc1 nt
	global_load_dwordx4 v[64:67], v52, s[2:3] offset:2048 sc0 sc1 nt
	global_load_dwordx4 v[68:71], v52, s[2:3] offset:3072 sc0 sc1 nt
	global_load_dwordx4 v[72:75], v54, s[2:3] sc0 sc1 nt
	global_load_dwordx4 v[76:79], v54, s[2:3] offset:1024 sc0 sc1 nt
	global_load_dwordx4 v[80:83], v54, s[2:3] offset:2048 sc0 sc1 nt
	global_load_dwordx4 v[84:87], v54, s[2:3] offset:3072 sc0 sc1 nt
	s_waitcnt vmcnt(0)
	v_mul_f32_e32 v2, s16, v56
	v_mul_f32_e32 v3, s16, v58
	v_mul_f32_e32 v4, s16, v60
	v_mul_f32_e32 v5, s16, v62
	v_mul_f32_e32 v6, s16, v64
	v_mul_f32_e32 v7, s16, v66
	v_mul_f32_e32 v8, s16, v68
	v_mul_f32_e32 v9, s16, v70
	v_mul_f32_e32 v10, s16, v72
	v_mul_f32_e32 v11, s16, v74
	v_mul_f32_e32 v12, s16, v76
	v_mul_f32_e32 v13, s16, v78
	v_mul_f32_e32 v14, s16, v80
	v_mul_f32_e32 v15, s16, v82
	v_mul_f32_e32 v16, s16, v84
	v_mul_f32_e32 v17, s16, v86
	v_mul_f32_e32 v18, s16, v57
	v_mul_f32_e32 v19, s16, v59
	v_mul_f32_e32 v20, s16, v61
	v_mul_f32_e32 v21, s16, v63
	v_mul_f32_e32 v22, s16, v65
	v_mul_f32_e32 v23, s16, v67
	v_mul_f32_e32 v24, s16, v69
	v_mul_f32_e32 v25, s16, v71
	v_mul_f32_e32 v26, s16, v73
	v_mul_f32_e32 v27, s16, v75
	v_mul_f32_e32 v28, s16, v77
	v_mul_f32_e32 v29, s16, v79
	v_mul_f32_e32 v30, s16, v81
	v_mul_f32_e32 v31, s16, v83
	v_mul_f32_e32 v32, s16, v85
	v_mul_f32_e32 v33, s16, v87
	s_nop 0
	v_cvt_scalef32_2xpk16_fp6_f32 v[40:45], v[2:17], v[18:33], 1.0
	global_load_dwordx4 v[56:59], v52, s[4:5] sc0 sc1 nt
	global_load_dwordx4 v[60:63], v52, s[4:5] offset:1024 sc0 sc1 nt
	global_load_dwordx4 v[64:67], v52, s[4:5] offset:2048 sc0 sc1 nt
	global_load_dwordx4 v[68:71], v52, s[4:5] offset:3072 sc0 sc1 nt
	global_load_dwordx4 v[72:75], v54, s[4:5] sc0 sc1 nt
	global_load_dwordx4 v[76:79], v54, s[4:5] offset:1024 sc0 sc1 nt
	global_load_dwordx4 v[80:83], v54, s[4:5] offset:2048 sc0 sc1 nt
	global_load_dwordx4 v[84:87], v54, s[4:5] offset:3072 sc0 sc1 nt
	s_add_u32 s2, s2, s12
	s_addc_u32 s3, s3, 0
	s_add_u32 s4, s4, s12
	s_addc_u32 s5, s5, 0
	s_waitcnt vmcnt(0)
	v_mul_f32_e32 v2, 4.0, v56
	v_mul_f32_e32 v3, 4.0, v58
	v_mul_f32_e32 v4, 4.0, v60
	v_mul_f32_e32 v5, 4.0, v62
	v_mul_f32_e32 v6, 4.0, v64
	v_mul_f32_e32 v7, 4.0, v66
	v_mul_f32_e32 v8, 4.0, v68
	v_mul_f32_e32 v9, 4.0, v70
	v_mul_f32_e32 v10, 4.0, v72
	v_mul_f32_e32 v11, 4.0, v74
	v_mul_f32_e32 v12, 4.0, v76
	v_mul_f32_e32 v13, 4.0, v78
	v_mul_f32_e32 v14, 4.0, v80
	v_mul_f32_e32 v15, 4.0, v82
	v_mul_f32_e32 v16, 4.0, v84
	v_mul_f32_e32 v17, 4.0, v86
	v_mul_f32_e32 v18, 4.0, v57
	v_mul_f32_e32 v19, 4.0, v59
	v_mul_f32_e32 v20, 4.0, v61
	v_mul_f32_e32 v21, 4.0, v63
	v_mul_f32_e32 v22, 4.0, v65
	v_mul_f32_e32 v23, 4.0, v67
	v_mul_f32_e32 v24, 4.0, v69
	v_mul_f32_e32 v25, 4.0, v71
	v_mul_f32_e32 v26, 4.0, v73
	v_mul_f32_e32 v27, 4.0, v75
	v_mul_f32_e32 v28, 4.0, v77
	v_mul_f32_e32 v29, 4.0, v79
	v_mul_f32_e32 v30, 4.0, v81
	v_mul_f32_e32 v31, 4.0, v83
	v_mul_f32_e32 v32, 4.0, v85
	v_mul_f32_e32 v33, 4.0, v87
	s_nop 0
	v_cvt_scalef32_2xpk16_fp6_f32 v[46:51], v[2:17], v[18:33], 1.0
	global_store_dwordx4 v53, v[40:43], s[6:7]
	global_store_dwordx4 v53, v[48:51], s[6:7] offset:1024
	global_store_dwordx4 v53, v[44:47], s[6:7] offset:2048
	s_add_u32 s6, s6, s13
	s_addc_u32 s7, s7, 0
	global_load_dwordx4 v[56:59], v52, s[2:3] sc0 sc1 nt
	global_load_dwordx4 v[60:63], v52, s[2:3] offset:1024 sc0 sc1 nt
	global_load_dwordx4 v[64:67], v52, s[2:3] offset:2048 sc0 sc1 nt
	global_load_dwordx4 v[68:71], v52, s[2:3] offset:3072 sc0 sc1 nt
	global_load_dwordx4 v[72:75], v54, s[2:3] sc0 sc1 nt
	global_load_dwordx4 v[76:79], v54, s[2:3] offset:1024 sc0 sc1 nt
	global_load_dwordx4 v[80:83], v54, s[2:3] offset:2048 sc0 sc1 nt
	global_load_dwordx4 v[84:87], v54, s[2:3] offset:3072 sc0 sc1 nt
	s_waitcnt vmcnt(0)
; __global__ void __launch_bounds__(256, 2) fwd_megakernel(Params p) {
;     ...
;   if (bid >= (nb >> 1)) {
;   for (size_t blk = (size_t)bid * 256 + tid; blk < (size_t)16384 * 64; blk += (size_t)nb * 256) {
; #pragma unroll
;     for (int tb = 0; tb < 2; ++tb) {
;       const float* src = (tb ? p.peer_up : p.peer_down) + blk * 32;
;       const float sc = tb ? UP_SCALE : DOWN_SCALE;
;       v16f va, vb;
; #pragma unroll
;       for (int q = 0; q < 4; ++q) {
;         const float4 x = *(const float4*)(src + q * 8), y = *(const float4*)(src + q * 8 + 4);
;         va[q * 4] = x.x * sc; vb[q * 4] = x.y * sc; va[q * 4 + 1] = x.z * sc; vb[q * 4 + 1] = x.w * sc;
;         va[q * 4 + 2] = y.x * sc; vb[q * 4 + 2] = y.y * sc; va[q * 4 + 3] = y.z * sc; vb[q * 4 + 3] = y.w * sc;
;       }
;       const v6u o = __builtin_amdgcn_cvt_scalef32_2xpk16_fp6_f32(va, vb, 1.0f);
;       unsigned char* dst = (tb ? p.up8 : p.down8) + blk * 24;
;       *(u32x2*)dst = u32x2{o[0], o[1]}; *(u32x2*)(dst + 8) = u32x2{o[2], o[3]}; *(u32x2*)(dst + 16) = u32x2{o[4], o[5]};
;     }
	v_mul_f32_e32 v2, s16, v56
	v_mul_f32_e32 v3, s16, v58
	v_mul_f32_e32 v4, s16, v60
	v_mul_f32_e32 v5, s16, v62
	v_mul_f32_e32 v6, s16, v64
	v_mul_f32_e32 v7, s16, v66
	v_mul_f32_e32 v8, s16, v68
	v_mul_f32_e32 v9, s16, v70
	v_mul_f32_e32 v10, s16, v72
	v_mul_f32_e32 v11, s16, v74
	v_mul_f32_e32 v12, s16, v76
	v_mul_f32_e32 v13, s16, v78
	v_mul_f32_e32 v14, s16, v80
	v_mul_f32_e32 v15, s16, v82
	v_mul_f32_e32 v16, s16, v84
	v_mul_f32_e32 v17, s16, v86
	v_mul_f32_e32 v18, s16, v57
	v_mul_f32_e32 v19, s16, v59
	v_mul_f32_e32 v20, s16, v61
	v_mul_f32_e32 v21, s16, v63
	v_mul_f32_e32 v22, s16, v65
	v_mul_f32_e32 v23, s16, v67
	v_mul_f32_e32 v24, s16, v69
	v_mul_f32_e32 v25, s16, v71
	v_mul_f32_e32 v26, s16, v73
	v_mul_f32_e32 v27, s16, v75
	v_mul_f32_e32 v28, s16, v77
	v_mul_f32_e32 v29, s16, v79
	v_mul_f32_e32 v30, s16, v81
	v_mul_f32_e32 v31, s16, v83
	v_mul_f32_e32 v32, s16, v85
	v_mul_f32_e32 v33, s16, v87
	s_nop 0
	v_cvt_scalef32_2xpk16_fp6_f32 v[40:45], v[2:17], v[18:33], 1.0
	global_load_dwordx4 v[56:59], v52, s[4:5] sc0 sc1 nt
	global_load_dwordx4 v[60:63], v52, s[4:5] offset:1024 sc0 sc1 nt
	global_load_dwordx4 v[64:67], v52, s[4:5] offset:2048 sc0 sc1 nt
	global_load_dwordx4 v[68:71], v52, s[4:5] offset:3072 sc0 sc1 nt
	global_load_dwordx4 v[72:75], v54, s[4:5] sc0 sc1 nt
	global_load_dwordx4 v[76:79], v54, s[4:5] offset:1024 sc0 sc1 nt
	global_load_dwordx4 v[80:83], v54, s[4:5] offset:2048 sc0 sc1 nt
	global_load_dwordx4 v[84:87], v54, s[4:5] offset:3072 sc0 sc1 nt
	s_add_u32 s2, s2, s12
	s_addc_u32 s3, s3, 0
	s_add_u32 s4, s4, s12
	s_addc_u32 s5, s5, 0
	s_waitcnt vmcnt(0)
	v_mul_f32_e32 v2, 4.0, v56
	v_mul_f32_e32 v3, 4.0, v58
	v_mul_f32_e32 v4, 4.0, v60
	v_mul_f32_e32 v5, 4.0, v62
	v_mul_f32_e32 v6, 4.0, v64
	v_mul_f32_e32 v7, 4.0, v66
	v_mul_f32_e32 v8, 4.0, v68
	v_mul_f32_e32 v9, 4.0, v70
	v_mul_f32_e32 v10, 4.0, v72
	v_mul_f32_e32 v11, 4.0, v74
	v_mul_f32_e32 v12, 4.0, v76
	v_mul_f32_e32 v13, 4.0, v78
	v_mul_f32_e32 v14, 4.0, v80
	v_mul_f32_e32 v15, 4.0, v82
	v_mul_f32_e32 v16, 4.0, v84
	v_mul_f32_e32 v17, 4.0, v86
	v_mul_f32_e32 v18, 4.0, v57
	v_mul_f32_e32 v19, 4.0, v59
	v_mul_f32_e32 v20, 4.0, v61
	v_mul_f32_e32 v21, 4.0, v63
	v_mul_f32_e32 v22, 4.0, v65
	v_mul_f32_e32 v23, 4.0, v67
	v_mul_f32_e32 v24, 4.0, v69
	v_mul_f32_e32 v25, 4.0, v71
	v_mul_f32_e32 v26, 4.0, v73
	v_mul_f32_e32 v27, 4.0, v75
	v_mul_f32_e32 v28, 4.0, v77
	v_mul_f32_e32 v29, 4.0, v79
	v_mul_f32_e32 v30, 4.0, v81
	v_mul_f32_e32 v31, 4.0, v83
	v_mul_f32_e32 v32, 4.0, v85
	v_mul_f32_e32 v33, 4.0, v87
	s_nop 0
	v_cvt_scalef32_2xpk16_fp6_f32 v[46:51], v[2:17], v[18:33], 1.0
	global_store_dwordx4 v53, v[40:43], s[6:7]
	global_store_dwordx4 v53, v[48:51], s[6:7] offset:1024
	global_store_dwordx4 v53, v[44:47], s[6:7] offset:2048
	s_add_u32 s6, s6, s13
	s_addc_u32 s7, s7, 0
	global_load_dwordx4 v[56:59], v52, s[2:3] sc0 sc1 nt
	global_load_dwordx4 v[60:63], v52, s[2:3] offset:1024 sc0 sc1 nt
	global_load_dwordx4 v[64:67], v52, s[2:3] offset:2048 sc0 sc1 nt
	global_load_dwordx4 v[68:71], v52, s[2:3] offset:3072 sc0 sc1 nt
	global_load_dwordx4 v[72:75], v54, s[2:3] sc0 sc1 nt
	global_load_dwordx4 v[76:79], v54, s[2:3] offset:1024 sc0 sc1 nt
	global_load_dwordx4 v[80:83], v54, s[2:3] offset:2048 sc0 sc1 nt
	global_load_dwordx4 v[84:87], v54, s[2:3] offset:3072 sc0 sc1 nt
	s_waitcnt vmcnt(0)
	v_mul_f32_e32 v2, s16, v56
	v_mul_f32_e32 v3, s16, v58
	v_mul_f32_e32 v4, s16, v60
	v_mul_f32_e32 v5, s16, v62
	v_mul_f32_e32 v6, s16, v64
	v_mul_f32_e32 v7, s16, v66
	v_mul_f32_e32 v8, s16, v68
	v_mul_f32_e32 v9, s16, v70
	v_mul_f32_e32 v10, s16, v72
	v_mul_f32_e32 v11, s16, v74
	v_mul_f32_e32 v12, s16, v76
	v_mul_f32_e32 v13, s16, v78
	v_mul_f32_e32 v14, s16, v80
	v_mul_f32_e32 v15, s16, v82
	v_mul_f32_e32 v16, s16, v84
	v_mul_f32_e32 v17, s16, v86
	v_mul_f32_e32 v18, s16, v57
	v_mul_f32_e32 v19, s16, v59
	v_mul_f32_e32 v20, s16, v61
	v_mul_f32_e32 v21, s16, v63
	v_mul_f32_e32 v22, s16, v65
	v_mul_f32_e32 v23, s16, v67
	v_mul_f32_e32 v24, s16, v69
	v_mul_f32_e32 v25, s16, v71
	v_mul_f32_e32 v26, s16, v73
	v_mul_f32_e32 v27, s16, v75
	v_mul_f32_e32 v28, s16, v77
	v_mul_f32_e32 v29, s16, v79
	v_mul_f32_e32 v30, s16, v81
	v_mul_f32_e32 v31, s16, v83
	v_mul_f32_e32 v32, s16, v85
	v_mul_f32_e32 v33, s16, v87
	s_nop 0
	v_cvt_scalef32_2xpk16_fp6_f32 v[40:45], v[2:17], v[18:33], 1.0
	global_load_dwordx4 v[56:59], v52, s[4:5] sc0 sc1 nt
	global_load_dwordx4 v[60:63], v52, s[4:5] offset:1024 sc0 sc1 nt
	global_load_dwordx4 v[64:67], v52, s[4:5] offset:2048 sc0 sc1 nt
	global_load_dwordx4 v[68:71], v52, s[4:5] offset:3072 sc0 sc1 nt
	global_load_dwordx4 v[72:75], v54, s[4:5] sc0 sc1 nt
	global_load_dwordx4 v[76:79], v54, s[4:5] offset:1024 sc0 sc1 nt
	global_load_dwordx4 v[80:83], v54, s[4:5] offset:2048 sc0 sc1 nt
	global_load_dwordx4 v[84:87], v54, s[4:5] offset:3072 sc0 sc1 nt
	s_add_u32 s2, s2, s12
	s_addc_u32 s3, s3, 0
	s_add_u32 s4, s4, s12
	s_addc_u32 s5, s5, 0
	s_waitcnt vmcnt(0)
	v_mul_f32_e32 v2, 4.0, v56
	v_mul_f32_e32 v3, 4.0, v58
	v_mul_f32_e32 v4, 4.0, v60
	v_mul_f32_e32 v5, 4.0, v62
	v_mul_f32_e32 v6, 4.0, v64
	v_mul_f32_e32 v7, 4.0, v66
	v_mul_f32_e32 v8, 4.0, v68
	v_mul_f32_e32 v9, 4.0, v70
	v_mul_f32_e32 v10, 4.0, v72
	v_mul_f32_e32 v11, 4.0, v74
	v_mul_f32_e32 v12, 4.0, v76
	v_mul_f32_e32 v13, 4.0, v78
	v_mul_f32_e32 v14, 4.0, v80
	v_mul_f32_e32 v15, 4.0, v82
	v_mul_f32_e32 v16, 4.0, v84
	v_mul_f32_e32 v17, 4.0, v86
	v_mul_f32_e32 v18, 4.0, v57
	v_mul_f32_e32 v19, 4.0, v59
	v_mul_f32_e32 v20, 4.0, v61
	v_mul_f32_e32 v21, 4.0, v63
	v_mul_f32_e32 v22, 4.0, v65
	v_mul_f32_e32 v23, 4.0, v67
	v_mul_f32_e32 v24, 4.0, v69
	v_mul_f32_e32 v25, 4.0, v71
	v_mul_f32_e32 v26, 4.0, v73
	v_mul_f32_e32 v27, 4.0, v75
	v_mul_f32_e32 v28, 4.0, v77
	v_mul_f32_e32 v29, 4.0, v79
	v_mul_f32_e32 v30, 4.0, v81
	v_mul_f32_e32 v31, 4.0, v83
	v_mul_f32_e32 v32, 4.0, v85
	v_mul_f32_e32 v33, 4.0, v87
	s_nop 0
	v_cvt_scalef32_2xpk16_fp6_f32 v[46:51], v[2:17], v[18:33], 1.0
	global_store_dwordx4 v53, v[40:43], s[6:7]
	global_store_dwordx4 v53, v[48:51], s[6:7] offset:1024
	global_store_dwordx4 v53, v[44:47], s[6:7] offset:2048
	s_add_u32 s6, s6, s13
	s_addc_u32 s7, s7, 0

; DEV int ltid() { int t = threadIdx.x; asm volatile("" : "+v"(t)); return t; }
; DEV float bflo(unsigned u) { return __uint_as_float(u << 16); }
; DEV float bfhi(unsigned u) { return __uint_as_float(u & 0xffff0000u); }
; DEV void peer_gather_token(const Params& p, int tok) {
;   const int lane = ltid() & 63, b = tok >> 11;
;   float hx[32], acc[32];
;   {
;     const u16* hr = p.h + (size_t)tok * 2048 + lane * 32;
; #pragma unroll
;     for (int q = 0; q < 4; ++q) {
;       u32x4 v = *(const u32x4*)(hr + q * 8);
; #pragma unroll
;       for (int e = 0; e < 4; ++e) { hx[q * 8 + 2 * e] = bflo(v[e]); hx[q * 8 + 2 * e + 1] = bfhi(v[e]); }
;     }
;   }
; #pragma unroll
;   for (int e = 0; e < 32; ++e) acc[e] = 0.f;
;   const int e0 = p.eidx[(size_t)tok * 128 + lane], e1 = p.eidx[(size_t)tok * 128 + 64 + lane];
;   const int g0 = __builtin_bit_cast(int, p.gw[(size_t)tok * 128 + lane]), g1 = __builtin_bit_cast(int, p.gw[(size_t)tok * 128 + 64 + lane]);
;   u32x2 dn[4][3], up[4][3];
;   auto issue = [&](int k, int slot) {
;     const int e = (k < 64) ? __builtin_amdgcn_readlane(e0, k) : __builtin_amdgcn_readlane(e1, k - 64);
;     const unsigned char* dr = p.down8 + (size_t)e * ROW6 + lane * 24;
;     const unsigned char* ur = p.up8 + (size_t)e * ROW6 + lane * 24;
; #pragma unroll
;     for (int i = 0; i < 3; ++i) { dn[slot][i] = *(const u32x2*)(dr + i * 8); up[slot][i] = *(const u32x2*)(ur + i * 8); }
;   };
;   issue(0, 0); issue(1, 1); issue(2, 2);
.LBB0_1567:
	s_or_b64 exec, exec, s[0:1]
	s_waitcnt lgkmcnt(0)
	s_barrier
	s_mov_b64 exec, -1
	v_lshrrev_b32_e32 v2, 6, v0
	v_and_b32_e32 v3, 63, v0
	s_nop 0
	v_readfirstlane_b32 s38, v2
	s_add_i32 s20, s84, s38
	s_mov_b32 s90, s38
	s_lshl_b32 s21, s92, 2
	s_cmpk_lt_u32 s20, 0x4000
	s_cbranch_scc0 .Lp12_end
	v_lshlrev_b32_e32 v1, 4, v3
	v_lshlrev_b32_e32 v242, 2, v3
	v_lshlrev_b32_e32 v243, 3, v3
	v_lshlrev_b32_e32 v244, 4, v3
	v_add_u32_e32 v245, 0x1000, v244
	v_lshrrev_b32_e32 v2, 3, v3
	v_and_b32_e32 v246, 7, v3
	v_lshlrev_b32_e32 v2, 20, v2
	v_lshl_or_b32 v246, v246, 3, v2
	v_add_u32_e32 v247, 0x800000, v246
	v_add_u32_e32 v248, 0x1000000, v246
	v_add_u32_e32 v249, 0x1800000, v246
	v_add_u32_e32 v250, 0x2000000, v246
	v_add_u32_e32 v251, 0x2800000, v246
	v_add_u32_e32 v252, 0x3000000, v246
	v_add_u32_e32 v253, 0x3800000, v246
	v_mov_b32_e32 v212, 0x3c800000
	v_mov_b32_e32 v213, 0x3ba10414
	v_mov_b32_e32 v214, 0xb9c68948
	v_mov_b32_e32 v215, 0x7f800000
	v_mov_b32_e32 v207, 0
	s_mov_b32 s9, 0x378e98ab
	s_mov_b32 s10, 0x3b7cd369
	s_mov_b32 s11, 0xbcc618b2
	s_mov_b32 s12, 0x3dda74e4
	s_mov_b32 s13, 0x3f228afd
	s_mov_b32 s14, 0x3e03c728
	s_mov_b32 s15, 0xbfb8aa3b
	s_mov_b32 s16, 0x42ce8ed0
	s_mov_b32 s17, 0xc2b17218
	s_brev_b32 s18, -2
	s_mov_b32 s43, 1
	s_mov_b32 s19, 0
	v_readlane_b32 s2, v254, 14
	v_readlane_b32 s3, v254, 15
	v_readlane_b32 s4, v255, 9
	v_readlane_b32 s5, v255, 10
	s_nop 3
	s_sub_u32 s4, s4, 0x1200000
	s_subb_u32 s5, s5, 0
	s_lshl_b32 s38, s20, 9
	s_add_u32 s58, s66, s38
	s_addc_u32 s59, s67, 0
	global_load_dword v216, v242, s[58:59]
	global_load_dword v217, v242, s[58:59] offset:256
	s_add_u32 s58, s68, s38
	s_addc_u32 s59, s69, 0
	global_load_dword v218, v242, s[58:59]
	global_load_dword v219, v242, s[58:59] offset:256
	s_lshl_b32 s38, s20, 6
	s_add_u32 s58, s80, s38
	s_addc_u32 s59, s81, 0
	global_load_dwordx2 v[220:221], v246, s[58:59]
	global_load_dwordx2 v[222:223], v247, s[58:59]
	global_load_dwordx2 v[224:225], v248, s[58:59]
	global_load_dwordx2 v[226:227], v249, s[58:59]
	global_load_dwordx2 v[228:229], v250, s[58:59]
	global_load_dwordx2 v[230:231], v251, s[58:59]
	global_load_dwordx2 v[232:233], v252, s[58:59]
	global_load_dwordx2 v[234:235], v253, s[58:59]
	s_waitcnt vmcnt(0) lgkmcnt(0)
	s_mov_b32 s36, 0
	s_mov_b32 s37, 0
	v_and_b32_e32 v236, 63, v0
	v_lshrrev_b32_e32 v241, 6, v0
	v_lshl_or_b32 v237, v216, 7, v236
	v_or_b32_e32 v238, 64, v236
	v_lshl_or_b32 v238, v217, 7, v238
	v_mov_b32_e32 v239, 0
	v_mov_b32_e32 v240, 0
	v_lshlrev_b32_e32 v241, 10, v241
	v_lshl_add_u32 v241, v236, 2, v241
	v_readlane_b32 s46, v237, 0
	v_readlane_b32 s47, v238, 0
	s_nop 1
	v_cmp_lt_u32_e64 s[48:49], s46, v237
	v_cmp_lt_u32_e64 s[50:51], s46, v238
	v_cmp_lt_u32_e64 s[52:53], s47, v237
	v_cmp_lt_u32_e64 s[54:55], s47, v238
	v_readlane_b32 s46, v237, 1
	v_readlane_b32 s47, v238, 1
	v_addc_co_u32_e64 v239, s[56:57], 0, v239, s[48:49]
	v_addc_co_u32_e64 v240, s[56:57], 0, v240, s[50:51]
	v_addc_co_u32_e64 v239, s[56:57], 0, v239, s[52:53]
	v_addc_co_u32_e64 v240, s[56:57], 0, v240, s[54:55]
	v_cmp_lt_u32_e64 s[48:49], s46, v237
	v_cmp_lt_u32_e64 s[50:51], s46, v238
	v_cmp_lt_u32_e64 s[52:53], s47, v237
	v_cmp_lt_u32_e64 s[54:55], s47, v238
	v_readlane_b32 s46, v237, 2
	v_readlane_b32 s47, v238, 2
	v_addc_co_u32_e64 v239, s[56:57], 0, v239, s[48:49]
	v_addc_co_u32_e64 v240, s[56:57], 0, v240, s[50:51]
	v_addc_co_u32_e64 v239, s[56:57], 0, v239, s[52:53]
	v_addc_co_u32_e64 v240, s[56:57], 0, v240, s[54:55]
	v_cmp_lt_u32_e64 s[48:49], s46, v237
	v_cmp_lt_u32_e64 s[50:51], s46, v238
	v_cmp_lt_u32_e64 s[52:53], s47, v237
	v_cmp_lt_u32_e64 s[54:55], s47, v238
	v_readlane_b32 s46, v237, 3
	v_readlane_b32 s47, v238, 3
	v_addc_co_u32_e64 v239, s[56:57], 0, v239, s[48:49]
	v_addc_co_u32_e64 v240, s[56:57], 0, v240, s[50:51]
	v_addc_co_u32_e64 v239, s[56:57], 0, v239, s[52:53]
	v_addc_co_u32_e64 v240, s[56:57], 0, v240, s[54:55]
	v_cmp_lt_u32_e64 s[48:49], s46, v237
	v_cmp_lt_u32_e64 s[50:51], s46, v238
	v_cmp_lt_u32_e64 s[52:53], s47, v237
	v_cmp_lt_u32_e64 s[54:55], s47, v238
	v_readlane_b32 s46, v237, 4
	v_readlane_b32 s47, v238, 4
	v_addc_co_u32_e64 v239, s[56:57], 0, v239, s[48:49]
	v_addc_co_u32_e64 v240, s[56:57], 0, v240, s[50:51]
	v_addc_co_u32_e64 v239, s[56:57], 0, v239, s[52:53]
	v_addc_co_u32_e64 v240, s[56:57], 0, v240, s[54:55]
	v_cmp_lt_u32_e64 s[48:49], s46, v237
	v_cmp_lt_u32_e64 s[50:51], s46, v238
	v_cmp_lt_u32_e64 s[52:53], s47, v237
	v_cmp_lt_u32_e64 s[54:55], s47, v238
	v_readlane_b32 s46, v237, 5
	v_readlane_b32 s47, v238, 5
	v_addc_co_u32_e64 v239, s[56:57], 0, v239, s[48:49]
	v_addc_co_u32_e64 v240, s[56:57], 0, v240, s[50:51]
	v_addc_co_u32_e64 v239, s[56:57], 0, v239, s[52:53]
	v_addc_co_u32_e64 v240, s[56:57], 0, v240, s[54:55]
	v_cmp_lt_u32_e64 s[48:49], s46, v237
	v_cmp_lt_u32_e64 s[50:51], s46, v238
	v_cmp_lt_u32_e64 s[52:53], s47, v237
	v_cmp_lt_u32_e64 s[54:55], s47, v238
	v_readlane_b32 s46, v237, 6
	v_readlane_b32 s47, v238, 6
	v_addc_co_u32_e64 v239, s[56:57], 0, v239, s[48:49]
	v_addc_co_u32_e64 v240, s[56:57], 0, v240, s[50:51]
	v_addc_co_u32_e64 v239, s[56:57], 0, v239, s[52:53]
	v_addc_co_u32_e64 v240, s[56:57], 0, v240, s[54:55]
	v_cmp_lt_u32_e64 s[48:49], s46, v237
	v_cmp_lt_u32_e64 s[50:51], s46, v238
	v_cmp_lt_u32_e64 s[52:53], s47, v237
	v_cmp_lt_u32_e64 s[54:55], s47, v238
	v_readlane_b32 s46, v237, 7
	v_readlane_b32 s47, v238, 7
	v_addc_co_u32_e64 v239, s[56:57], 0, v239, s[48:49]
	v_addc_co_u32_e64 v240, s[56:57], 0, v240, s[50:51]
	v_addc_co_u32_e64 v239, s[56:57], 0, v239, s[52:53]
	v_addc_co_u32_e64 v240, s[56:57], 0, v240, s[54:55]
	v_cmp_lt_u32_e64 s[48:49], s46, v237
; DEV void peer_gather_token(const Params& p, int tok) {
;     ...
;   const int e0 = p.eidx[(size_t)tok * 128 + lane], e1 = p.eidx[(size_t)tok * 128 + 64 + lane];
;   const int g0 = __builtin_bit_cast(int, p.gw[(size_t)tok * 128 + lane]), g1 = __builtin_bit_cast(int, p.gw[(size_t)tok * 128 + 64 + lane]);
;   u32x2 dn[4][3], up[4][3];
;   auto issue = [&](int k, int slot) {
;     const int e = (k < 64) ? __builtin_amdgcn_readlane(e0, k) : __builtin_amdgcn_readlane(e1, k - 64);
	v_cmp_lt_u32_e64 s[50:51], s46, v238
	v_cmp_lt_u32_e64 s[52:53], s47, v237
	v_cmp_lt_u32_e64 s[54:55], s47, v238
	v_readlane_b32 s46, v237, 8
	v_readlane_b32 s47, v238, 8
	v_addc_co_u32_e64 v239, s[56:57], 0, v239, s[48:49]
	v_addc_co_u32_e64 v240, s[56:57], 0, v240, s[50:51]
	v_addc_co_u32_e64 v239, s[56:57], 0, v239, s[52:53]
	v_addc_co_u32_e64 v240, s[56:57], 0, v240, s[54:55]
	v_cmp_lt_u32_e64 s[48:49], s46, v237
	v_cmp_lt_u32_e64 s[50:51], s46, v238
	v_cmp_lt_u32_e64 s[52:53], s47, v237
	v_cmp_lt_u32_e64 s[54:55], s47, v238
	v_readlane_b32 s46, v237, 9
	v_readlane_b32 s47, v238, 9
	v_addc_co_u32_e64 v239, s[56:57], 0, v239, s[48:49]
	v_addc_co_u32_e64 v240, s[56:57], 0, v240, s[50:51]
	v_addc_co_u32_e64 v239, s[56:57], 0, v239, s[52:53]
	v_addc_co_u32_e64 v240, s[56:57], 0, v240, s[54:55]
	v_cmp_lt_u32_e64 s[48:49], s46, v237
	v_cmp_lt_u32_e64 s[50:51], s46, v238
	v_cmp_lt_u32_e64 s[52:53], s47, v237
	v_cmp_lt_u32_e64 s[54:55], s47, v238
	v_readlane_b32 s46, v237, 10
	v_readlane_b32 s47, v238, 10
	v_addc_co_u32_e64 v239, s[56:57], 0, v239, s[48:49]
	v_addc_co_u32_e64 v240, s[56:57], 0, v240, s[50:51]
	v_addc_co_u32_e64 v239, s[56:57], 0, v239, s[52:53]
	v_addc_co_u32_e64 v240, s[56:57], 0, v240, s[54:55]
	v_cmp_lt_u32_e64 s[48:49], s46, v237
	v_cmp_lt_u32_e64 s[50:51], s46, v238
	v_cmp_lt_u32_e64 s[52:53], s47, v237
	v_cmp_lt_u32_e64 s[54:55], s47, v238
	v_readlane_b32 s46, v237, 11
	v_readlane_b32 s47, v238, 11
	v_addc_co_u32_e64 v239, s[56:57], 0, v239, s[48:49]
	v_addc_co_u32_e64 v240, s[56:57], 0, v240, s[50:51]
	v_addc_co_u32_e64 v239, s[56:57], 0, v239, s[52:53]
	v_addc_co_u32_e64 v240, s[56:57], 0, v240, s[54:55]
	v_cmp_lt_u32_e64 s[48:49], s46, v237
	v_cmp_lt_u32_e64 s[50:51], s46, v238
	v_cmp_lt_u32_e64 s[52:53], s47, v237
	v_cmp_lt_u32_e64 s[54:55], s47, v238
	v_readlane_b32 s46, v237, 12
	v_readlane_b32 s47, v238, 12
	v_addc_co_u32_e64 v239, s[56:57], 0, v239, s[48:49]
	v_addc_co_u32_e64 v240, s[56:57], 0, v240, s[50:51]
	v_addc_co_u32_e64 v239, s[56:57], 0, v239, s[52:53]
	v_addc_co_u32_e64 v240, s[56:57], 0, v240, s[54:55]
	v_cmp_lt_u32_e64 s[48:49], s46, v237
	v_cmp_lt_u32_e64 s[50:51], s46, v238
	v_cmp_lt_u32_e64 s[52:53], s47, v237
	v_cmp_lt_u32_e64 s[54:55], s47, v238
	v_readlane_b32 s46, v237, 13
	v_readlane_b32 s47, v238, 13
	v_addc_co_u32_e64 v239, s[56:57], 0, v239, s[48:49]
	v_addc_co_u32_e64 v240, s[56:57], 0, v240, s[50:51]
	v_addc_co_u32_e64 v239, s[56:57], 0, v239, s[52:53]
	v_addc_co_u32_e64 v240, s[56:57], 0, v240, s[54:55]
	v_cmp_lt_u32_e64 s[48:49], s46, v237
	v_cmp_lt_u32_e64 s[50:51], s46, v238
	v_cmp_lt_u32_e64 s[52:53], s47, v237
	v_cmp_lt_u32_e64 s[54:55], s47, v238
	v_readlane_b32 s46, v237, 14
	v_readlane_b32 s47, v238, 14
	v_addc_co_u32_e64 v239, s[56:57], 0, v239, s[48:49]
	v_addc_co_u32_e64 v240, s[56:57], 0, v240, s[50:51]
	v_addc_co_u32_e64 v239, s[56:57], 0, v239, s[52:53]
	v_addc_co_u32_e64 v240, s[56:57], 0, v240, s[54:55]
	v_cmp_lt_u32_e64 s[48:49], s46, v237
	v_cmp_lt_u32_e64 s[50:51], s46, v238
	v_cmp_lt_u32_e64 s[52:53], s47, v237
	v_cmp_lt_u32_e64 s[54:55], s47, v238
	v_readlane_b32 s46, v237, 15
	v_readlane_b32 s47, v238, 15
	v_addc_co_u32_e64 v239, s[56:57], 0, v239, s[48:49]
	v_addc_co_u32_e64 v240, s[56:57], 0, v240, s[50:51]
	v_addc_co_u32_e64 v239, s[56:57], 0, v239, s[52:53]
	v_addc_co_u32_e64 v240, s[56:57], 0, v240, s[54:55]
	v_cmp_lt_u32_e64 s[48:49], s46, v237
	v_cmp_lt_u32_e64 s[50:51], s46, v238
	v_cmp_lt_u32_e64 s[52:53], s47, v237
	v_cmp_lt_u32_e64 s[54:55], s47, v238
	v_readlane_b32 s46, v237, 16
	v_readlane_b32 s47, v238, 16
	v_addc_co_u32_e64 v239, s[56:57], 0, v239, s[48:49]
	v_addc_co_u32_e64 v240, s[56:57], 0, v240, s[50:51]
	v_addc_co_u32_e64 v239, s[56:57], 0, v239, s[52:53]
	v_addc_co_u32_e64 v240, s[56:57], 0, v240, s[54:55]
	v_cmp_lt_u32_e64 s[48:49], s46, v237
	v_cmp_lt_u32_e64 s[50:51], s46, v238
	v_cmp_lt_u32_e64 s[52:53], s47, v237
	v_cmp_lt_u32_e64 s[54:55], s47, v238
	v_readlane_b32 s46, v237, 17
	v_readlane_b32 s47, v238, 17
	v_addc_co_u32_e64 v239, s[56:57], 0, v239, s[48:49]
	v_addc_co_u32_e64 v240, s[56:57], 0, v240, s[50:51]
	v_addc_co_u32_e64 v239, s[56:57], 0, v239, s[52:53]
	v_addc_co_u32_e64 v240, s[56:57], 0, v240, s[54:55]
	v_cmp_lt_u32_e64 s[48:49], s46, v237
	v_cmp_lt_u32_e64 s[50:51], s46, v238
	v_cmp_lt_u32_e64 s[52:53], s47, v237
	v_cmp_lt_u32_e64 s[54:55], s47, v238
	v_readlane_b32 s46, v237, 18
	v_readlane_b32 s47, v238, 18
	v_addc_co_u32_e64 v239, s[56:57], 0, v239, s[48:49]
	v_addc_co_u32_e64 v240, s[56:57], 0, v240, s[50:51]
	v_addc_co_u32_e64 v239, s[56:57], 0, v239, s[52:53]
	v_addc_co_u32_e64 v240, s[56:57], 0, v240, s[54:55]
	v_cmp_lt_u32_e64 s[48:49], s46, v237
	v_cmp_lt_u32_e64 s[50:51], s46, v238
	v_cmp_lt_u32_e64 s[52:53], s47, v237
	v_cmp_lt_u32_e64 s[54:55], s47, v238
	v_readlane_b32 s46, v237, 19
	v_readlane_b32 s47, v238, 19
	v_addc_co_u32_e64 v239, s[56:57], 0, v239, s[48:49]
	v_addc_co_u32_e64 v240, s[56:57], 0, v240, s[50:51]
	v_addc_co_u32_e64 v239, s[56:57], 0, v239, s[52:53]
	v_addc_co_u32_e64 v240, s[56:57], 0, v240, s[54:55]
	v_cmp_lt_u32_e64 s[48:49], s46, v237
	v_cmp_lt_u32_e64 s[50:51], s46, v238
	v_cmp_lt_u32_e64 s[52:53], s47, v237
	v_cmp_lt_u32_e64 s[54:55], s47, v238
	v_readlane_b32 s46, v237, 20
	v_readlane_b32 s47, v238, 20
	v_addc_co_u32_e64 v239, s[56:57], 0, v239, s[48:49]
	v_addc_co_u32_e64 v240, s[56:57], 0, v240, s[50:51]
	v_addc_co_u32_e64 v239, s[56:57], 0, v239, s[52:53]
	v_addc_co_u32_e64 v240, s[56:57], 0, v240, s[54:55]
	v_cmp_lt_u32_e64 s[48:49], s46, v237
	v_cmp_lt_u32_e64 s[50:51], s46, v238
	v_cmp_lt_u32_e64 s[52:53], s47, v237
	v_cmp_lt_u32_e64 s[54:55], s47, v238
	v_readlane_b32 s46, v237, 21
; DEV void peer_gather_token(const Params& p, int tok) {
;     ...
;   const int e0 = p.eidx[(size_t)tok * 128 + lane], e1 = p.eidx[(size_t)tok * 128 + 64 + lane];
;   const int g0 = __builtin_bit_cast(int, p.gw[(size_t)tok * 128 + lane]), g1 = __builtin_bit_cast(int, p.gw[(size_t)tok * 128 + 64 + lane]);
;   u32x2 dn[4][3], up[4][3];
;   auto issue = [&](int k, int slot) {
;     const int e = (k < 64) ? __builtin_amdgcn_readlane(e0, k) : __builtin_amdgcn_readlane(e1, k - 64);
	v_readlane_b32 s47, v238, 21
	v_addc_co_u32_e64 v239, s[56:57], 0, v239, s[48:49]
	v_addc_co_u32_e64 v240, s[56:57], 0, v240, s[50:51]
	v_addc_co_u32_e64 v239, s[56:57], 0, v239, s[52:53]
	v_addc_co_u32_e64 v240, s[56:57], 0, v240, s[54:55]
	v_cmp_lt_u32_e64 s[48:49], s46, v237
	v_cmp_lt_u32_e64 s[50:51], s46, v238
	v_cmp_lt_u32_e64 s[52:53], s47, v237
	v_cmp_lt_u32_e64 s[54:55], s47, v238
	v_readlane_b32 s46, v237, 22
	v_readlane_b32 s47, v238, 22
	v_addc_co_u32_e64 v239, s[56:57], 0, v239, s[48:49]
	v_addc_co_u32_e64 v240, s[56:57], 0, v240, s[50:51]
	v_addc_co_u32_e64 v239, s[56:57], 0, v239, s[52:53]
	v_addc_co_u32_e64 v240, s[56:57], 0, v240, s[54:55]
	v_cmp_lt_u32_e64 s[48:49], s46, v237
	v_cmp_lt_u32_e64 s[50:51], s46, v238
	v_cmp_lt_u32_e64 s[52:53], s47, v237
	v_cmp_lt_u32_e64 s[54:55], s47, v238
	v_readlane_b32 s46, v237, 23
	v_readlane_b32 s47, v238, 23
	v_addc_co_u32_e64 v239, s[56:57], 0, v239, s[48:49]
	v_addc_co_u32_e64 v240, s[56:57], 0, v240, s[50:51]
	v_addc_co_u32_e64 v239, s[56:57], 0, v239, s[52:53]
	v_addc_co_u32_e64 v240, s[56:57], 0, v240, s[54:55]
	v_cmp_lt_u32_e64 s[48:49], s46, v237
	v_cmp_lt_u32_e64 s[50:51], s46, v238
	v_cmp_lt_u32_e64 s[52:53], s47, v237
	v_cmp_lt_u32_e64 s[54:55], s47, v238
	v_readlane_b32 s46, v237, 24
	v_readlane_b32 s47, v238, 24
	v_addc_co_u32_e64 v239, s[56:57], 0, v239, s[48:49]
	v_addc_co_u32_e64 v240, s[56:57], 0, v240, s[50:51]
	v_addc_co_u32_e64 v239, s[56:57], 0, v239, s[52:53]
	v_addc_co_u32_e64 v240, s[56:57], 0, v240, s[54:55]
	v_cmp_lt_u32_e64 s[48:49], s46, v237
	v_cmp_lt_u32_e64 s[50:51], s46, v238
	v_cmp_lt_u32_e64 s[52:53], s47, v237
	v_cmp_lt_u32_e64 s[54:55], s47, v238
	v_readlane_b32 s46, v237, 25
	v_readlane_b32 s47, v238, 25
	v_addc_co_u32_e64 v239, s[56:57], 0, v239, s[48:49]
	v_addc_co_u32_e64 v240, s[56:57], 0, v240, s[50:51]
	v_addc_co_u32_e64 v239, s[56:57], 0, v239, s[52:53]
	v_addc_co_u32_e64 v240, s[56:57], 0, v240, s[54:55]
	v_cmp_lt_u32_e64 s[48:49], s46, v237
	v_cmp_lt_u32_e64 s[50:51], s46, v238
	v_cmp_lt_u32_e64 s[52:53], s47, v237
	v_cmp_lt_u32_e64 s[54:55], s47, v238
	v_readlane_b32 s46, v237, 26
	v_readlane_b32 s47, v238, 26
	v_addc_co_u32_e64 v239, s[56:57], 0, v239, s[48:49]
	v_addc_co_u32_e64 v240, s[56:57], 0, v240, s[50:51]
	v_addc_co_u32_e64 v239, s[56:57], 0, v239, s[52:53]
	v_addc_co_u32_e64 v240, s[56:57], 0, v240, s[54:55]
	v_cmp_lt_u32_e64 s[48:49], s46, v237
	v_cmp_lt_u32_e64 s[50:51], s46, v238
	v_cmp_lt_u32_e64 s[52:53], s47, v237
	v_cmp_lt_u32_e64 s[54:55], s47, v238
	v_readlane_b32 s46, v237, 27
	v_readlane_b32 s47, v238, 27
	v_addc_co_u32_e64 v239, s[56:57], 0, v239, s[48:49]
	v_addc_co_u32_e64 v240, s[56:57], 0, v240, s[50:51]
	v_addc_co_u32_e64 v239, s[56:57], 0, v239, s[52:53]
	v_addc_co_u32_e64 v240, s[56:57], 0, v240, s[54:55]
	v_cmp_lt_u32_e64 s[48:49], s46, v237
	v_cmp_lt_u32_e64 s[50:51], s46, v238
	v_cmp_lt_u32_e64 s[52:53], s47, v237
	v_cmp_lt_u32_e64 s[54:55], s47, v238
	v_readlane_b32 s46, v237, 28
	v_readlane_b32 s47, v238, 28
	v_addc_co_u32_e64 v239, s[56:57], 0, v239, s[48:49]
	v_addc_co_u32_e64 v240, s[56:57], 0, v240, s[50:51]
	v_addc_co_u32_e64 v239, s[56:57], 0, v239, s[52:53]
	v_addc_co_u32_e64 v240, s[56:57], 0, v240, s[54:55]
	v_cmp_lt_u32_e64 s[48:49], s46, v237
	v_cmp_lt_u32_e64 s[50:51], s46, v238
	v_cmp_lt_u32_e64 s[52:53], s47, v237
	v_cmp_lt_u32_e64 s[54:55], s47, v238
	v_readlane_b32 s46, v237, 29
	v_readlane_b32 s47, v238, 29
	v_addc_co_u32_e64 v239, s[56:57], 0, v239, s[48:49]
	v_addc_co_u32_e64 v240, s[56:57], 0, v240, s[50:51]
	v_addc_co_u32_e64 v239, s[56:57], 0, v239, s[52:53]
	v_addc_co_u32_e64 v240, s[56:57], 0, v240, s[54:55]
	v_cmp_lt_u32_e64 s[48:49], s46, v237
	v_cmp_lt_u32_e64 s[50:51], s46, v238
	v_cmp_lt_u32_e64 s[52:53], s47, v237
	v_cmp_lt_u32_e64 s[54:55], s47, v238
	v_readlane_b32 s46, v237, 30
	v_readlane_b32 s47, v238, 30
	v_addc_co_u32_e64 v239, s[56:57], 0, v239, s[48:49]
	v_addc_co_u32_e64 v240, s[56:57], 0, v240, s[50:51]
	v_addc_co_u32_e64 v239, s[56:57], 0, v239, s[52:53]
	v_addc_co_u32_e64 v240, s[56:57], 0, v240, s[54:55]
	v_cmp_lt_u32_e64 s[48:49], s46, v237
	v_cmp_lt_u32_e64 s[50:51], s46, v238
	v_cmp_lt_u32_e64 s[52:53], s47, v237
	v_cmp_lt_u32_e64 s[54:55], s47, v238
	v_readlane_b32 s46, v237, 31
	v_readlane_b32 s47, v238, 31
	v_addc_co_u32_e64 v239, s[56:57], 0, v239, s[48:49]
	v_addc_co_u32_e64 v240, s[56:57], 0, v240, s[50:51]
	v_addc_co_u32_e64 v239, s[56:57], 0, v239, s[52:53]
	v_addc_co_u32_e64 v240, s[56:57], 0, v240, s[54:55]
	v_cmp_lt_u32_e64 s[48:49], s46, v237
	v_cmp_lt_u32_e64 s[50:51], s46, v238
	v_cmp_lt_u32_e64 s[52:53], s47, v237
	v_cmp_lt_u32_e64 s[54:55], s47, v238
	v_readlane_b32 s46, v237, 32
	v_readlane_b32 s47, v238, 32
	v_addc_co_u32_e64 v239, s[56:57], 0, v239, s[48:49]
	v_addc_co_u32_e64 v240, s[56:57], 0, v240, s[50:51]
	v_addc_co_u32_e64 v239, s[56:57], 0, v239, s[52:53]
	v_addc_co_u32_e64 v240, s[56:57], 0, v240, s[54:55]
	v_cmp_lt_u32_e64 s[48:49], s46, v237
	v_cmp_lt_u32_e64 s[50:51], s46, v238
	v_cmp_lt_u32_e64 s[52:53], s47, v237
	v_cmp_lt_u32_e64 s[54:55], s47, v238
	v_readlane_b32 s46, v237, 33
	v_readlane_b32 s47, v238, 33
	v_addc_co_u32_e64 v239, s[56:57], 0, v239, s[48:49]
	v_addc_co_u32_e64 v240, s[56:57], 0, v240, s[50:51]
	v_addc_co_u32_e64 v239, s[56:57], 0, v239, s[52:53]
	v_addc_co_u32_e64 v240, s[56:57], 0, v240, s[54:55]
	v_cmp_lt_u32_e64 s[48:49], s46, v237
	v_cmp_lt_u32_e64 s[50:51], s46, v238
	v_cmp_lt_u32_e64 s[52:53], s47, v237
	v_cmp_lt_u32_e64 s[54:55], s47, v238
	v_readlane_b32 s46, v237, 34
	v_readlane_b32 s47, v238, 34
	v_addc_co_u32_e64 v239, s[56:57], 0, v239, s[48:49]
	v_addc_co_u32_e64 v240, s[56:57], 0, v240, s[50:51]
; DEV void peer_gather_token(const Params& p, int tok) {
;     ...
;   const int e0 = p.eidx[(size_t)tok * 128 + lane], e1 = p.eidx[(size_t)tok * 128 + 64 + lane];
;   const int g0 = __builtin_bit_cast(int, p.gw[(size_t)tok * 128 + lane]), g1 = __builtin_bit_cast(int, p.gw[(size_t)tok * 128 + 64 + lane]);
;   u32x2 dn[4][3], up[4][3];
;   auto issue = [&](int k, int slot) {
;     const int e = (k < 64) ? __builtin_amdgcn_readlane(e0, k) : __builtin_amdgcn_readlane(e1, k - 64);
	v_addc_co_u32_e64 v239, s[56:57], 0, v239, s[52:53]
	v_addc_co_u32_e64 v240, s[56:57], 0, v240, s[54:55]
	v_cmp_lt_u32_e64 s[48:49], s46, v237
	v_cmp_lt_u32_e64 s[50:51], s46, v238
	v_cmp_lt_u32_e64 s[52:53], s47, v237
	v_cmp_lt_u32_e64 s[54:55], s47, v238
	v_readlane_b32 s46, v237, 35
	v_readlane_b32 s47, v238, 35
	v_addc_co_u32_e64 v239, s[56:57], 0, v239, s[48:49]
	v_addc_co_u32_e64 v240, s[56:57], 0, v240, s[50:51]
	v_addc_co_u32_e64 v239, s[56:57], 0, v239, s[52:53]
	v_addc_co_u32_e64 v240, s[56:57], 0, v240, s[54:55]
	v_cmp_lt_u32_e64 s[48:49], s46, v237
	v_cmp_lt_u32_e64 s[50:51], s46, v238
	v_cmp_lt_u32_e64 s[52:53], s47, v237
	v_cmp_lt_u32_e64 s[54:55], s47, v238
	v_readlane_b32 s46, v237, 36
	v_readlane_b32 s47, v238, 36
	v_addc_co_u32_e64 v239, s[56:57], 0, v239, s[48:49]
	v_addc_co_u32_e64 v240, s[56:57], 0, v240, s[50:51]
	v_addc_co_u32_e64 v239, s[56:57], 0, v239, s[52:53]
	v_addc_co_u32_e64 v240, s[56:57], 0, v240, s[54:55]
	v_cmp_lt_u32_e64 s[48:49], s46, v237
	v_cmp_lt_u32_e64 s[50:51], s46, v238
	v_cmp_lt_u32_e64 s[52:53], s47, v237
	v_cmp_lt_u32_e64 s[54:55], s47, v238
	v_readlane_b32 s46, v237, 37
	v_readlane_b32 s47, v238, 37
	v_addc_co_u32_e64 v239, s[56:57], 0, v239, s[48:49]
	v_addc_co_u32_e64 v240, s[56:57], 0, v240, s[50:51]
	v_addc_co_u32_e64 v239, s[56:57], 0, v239, s[52:53]
	v_addc_co_u32_e64 v240, s[56:57], 0, v240, s[54:55]
	v_cmp_lt_u32_e64 s[48:49], s46, v237
	v_cmp_lt_u32_e64 s[50:51], s46, v238
	v_cmp_lt_u32_e64 s[52:53], s47, v237
	v_cmp_lt_u32_e64 s[54:55], s47, v238
	v_readlane_b32 s46, v237, 38
	v_readlane_b32 s47, v238, 38
	v_addc_co_u32_e64 v239, s[56:57], 0, v239, s[48:49]
	v_addc_co_u32_e64 v240, s[56:57], 0, v240, s[50:51]
	v_addc_co_u32_e64 v239, s[56:57], 0, v239, s[52:53]
	v_addc_co_u32_e64 v240, s[56:57], 0, v240, s[54:55]
	v_cmp_lt_u32_e64 s[48:49], s46, v237
	v_cmp_lt_u32_e64 s[50:51], s46, v238
	v_cmp_lt_u32_e64 s[52:53], s47, v237
	v_cmp_lt_u32_e64 s[54:55], s47, v238
	v_readlane_b32 s46, v237, 39
	v_readlane_b32 s47, v238, 39
	v_addc_co_u32_e64 v239, s[56:57], 0, v239, s[48:49]
	v_addc_co_u32_e64 v240, s[56:57], 0, v240, s[50:51]
	v_addc_co_u32_e64 v239, s[56:57], 0, v239, s[52:53]
	v_addc_co_u32_e64 v240, s[56:57], 0, v240, s[54:55]
	v_cmp_lt_u32_e64 s[48:49], s46, v237
	v_cmp_lt_u32_e64 s[50:51], s46, v238
	v_cmp_lt_u32_e64 s[52:53], s47, v237
	v_cmp_lt_u32_e64 s[54:55], s47, v238
	v_readlane_b32 s46, v237, 40
	v_readlane_b32 s47, v238, 40
	v_addc_co_u32_e64 v239, s[56:57], 0, v239, s[48:49]
	v_addc_co_u32_e64 v240, s[56:57], 0, v240, s[50:51]
	v_addc_co_u32_e64 v239, s[56:57], 0, v239, s[52:53]
	v_addc_co_u32_e64 v240, s[56:57], 0, v240, s[54:55]
	v_cmp_lt_u32_e64 s[48:49], s46, v237
	v_cmp_lt_u32_e64 s[50:51], s46, v238
	v_cmp_lt_u32_e64 s[52:53], s47, v237
	v_cmp_lt_u32_e64 s[54:55], s47, v238
	v_readlane_b32 s46, v237, 41
	v_readlane_b32 s47, v238, 41
	v_addc_co_u32_e64 v239, s[56:57], 0, v239, s[48:49]
	v_addc_co_u32_e64 v240, s[56:57], 0, v240, s[50:51]
	v_addc_co_u32_e64 v239, s[56:57], 0, v239, s[52:53]
	v_addc_co_u32_e64 v240, s[56:57], 0, v240, s[54:55]
	v_cmp_lt_u32_e64 s[48:49], s46, v237
	v_cmp_lt_u32_e64 s[50:51], s46, v238
	v_cmp_lt_u32_e64 s[52:53], s47, v237
	v_cmp_lt_u32_e64 s[54:55], s47, v238
	v_readlane_b32 s46, v237, 42
	v_readlane_b32 s47, v238, 42
	v_addc_co_u32_e64 v239, s[56:57], 0, v239, s[48:49]
	v_addc_co_u32_e64 v240, s[56:57], 0, v240, s[50:51]
	v_addc_co_u32_e64 v239, s[56:57], 0, v239, s[52:53]
	v_addc_co_u32_e64 v240, s[56:57], 0, v240, s[54:55]
	v_cmp_lt_u32_e64 s[48:49], s46, v237
	v_cmp_lt_u32_e64 s[50:51], s46, v238
	v_cmp_lt_u32_e64 s[52:53], s47, v237
	v_cmp_lt_u32_e64 s[54:55], s47, v238
	v_readlane_b32 s46, v237, 43
	v_readlane_b32 s47, v238, 43
	v_addc_co_u32_e64 v239, s[56:57], 0, v239, s[48:49]
	v_addc_co_u32_e64 v240, s[56:57], 0, v240, s[50:51]
	v_addc_co_u32_e64 v239, s[56:57], 0, v239, s[52:53]
	v_addc_co_u32_e64 v240, s[56:57], 0, v240, s[54:55]
	v_cmp_lt_u32_e64 s[48:49], s46, v237
	v_cmp_lt_u32_e64 s[50:51], s46, v238
	v_cmp_lt_u32_e64 s[52:53], s47, v237
	v_cmp_lt_u32_e64 s[54:55], s47, v238
	v_readlane_b32 s46, v237, 44
	v_readlane_b32 s47, v238, 44
	v_addc_co_u32_e64 v239, s[56:57], 0, v239, s[48:49]
	v_addc_co_u32_e64 v240, s[56:57], 0, v240, s[50:51]
	v_addc_co_u32_e64 v239, s[56:57], 0, v239, s[52:53]
	v_addc_co_u32_e64 v240, s[56:57], 0, v240, s[54:55]
	v_cmp_lt_u32_e64 s[48:49], s46, v237
	v_cmp_lt_u32_e64 s[50:51], s46, v238
	v_cmp_lt_u32_e64 s[52:53], s47, v237
	v_cmp_lt_u32_e64 s[54:55], s47, v238
	v_readlane_b32 s46, v237, 45
	v_readlane_b32 s47, v238, 45
	v_addc_co_u32_e64 v239, s[56:57], 0, v239, s[48:49]
	v_addc_co_u32_e64 v240, s[56:57], 0, v240, s[50:51]
	v_addc_co_u32_e64 v239, s[56:57], 0, v239, s[52:53]
	v_addc_co_u32_e64 v240, s[56:57], 0, v240, s[54:55]
	v_cmp_lt_u32_e64 s[48:49], s46, v237
	v_cmp_lt_u32_e64 s[50:51], s46, v238
	v_cmp_lt_u32_e64 s[52:53], s47, v237
	v_cmp_lt_u32_e64 s[54:55], s47, v238
	v_readlane_b32 s46, v237, 46
	v_readlane_b32 s47, v238, 46
	v_addc_co_u32_e64 v239, s[56:57], 0, v239, s[48:49]
	v_addc_co_u32_e64 v240, s[56:57], 0, v240, s[50:51]
	v_addc_co_u32_e64 v239, s[56:57], 0, v239, s[52:53]
	v_addc_co_u32_e64 v240, s[56:57], 0, v240, s[54:55]
	v_cmp_lt_u32_e64 s[48:49], s46, v237
	v_cmp_lt_u32_e64 s[50:51], s46, v238
	v_cmp_lt_u32_e64 s[52:53], s47, v237
	v_cmp_lt_u32_e64 s[54:55], s47, v238
	v_readlane_b32 s46, v237, 47
	v_readlane_b32 s47, v238, 47
	v_addc_co_u32_e64 v239, s[56:57], 0, v239, s[48:49]
	v_addc_co_u32_e64 v240, s[56:57], 0, v240, s[50:51]
	v_addc_co_u32_e64 v239, s[56:57], 0, v239, s[52:53]
	v_addc_co_u32_e64 v240, s[56:57], 0, v240, s[54:55]
	v_cmp_lt_u32_e64 s[48:49], s46, v237
; DEV void peer_gather_token(const Params& p, int tok) {
;     ...
;   const int e0 = p.eidx[(size_t)tok * 128 + lane], e1 = p.eidx[(size_t)tok * 128 + 64 + lane];
;   const int g0 = __builtin_bit_cast(int, p.gw[(size_t)tok * 128 + lane]), g1 = __builtin_bit_cast(int, p.gw[(size_t)tok * 128 + 64 + lane]);
;   u32x2 dn[4][3], up[4][3];
;   auto issue = [&](int k, int slot) {
;     const int e = (k < 64) ? __builtin_amdgcn_readlane(e0, k) : __builtin_amdgcn_readlane(e1, k - 64);
	v_cmp_lt_u32_e64 s[50:51], s46, v238
	v_cmp_lt_u32_e64 s[52:53], s47, v237
	v_cmp_lt_u32_e64 s[54:55], s47, v238
	v_readlane_b32 s46, v237, 48
	v_readlane_b32 s47, v238, 48
	v_addc_co_u32_e64 v239, s[56:57], 0, v239, s[48:49]
	v_addc_co_u32_e64 v240, s[56:57], 0, v240, s[50:51]
	v_addc_co_u32_e64 v239, s[56:57], 0, v239, s[52:53]
	v_addc_co_u32_e64 v240, s[56:57], 0, v240, s[54:55]
	v_cmp_lt_u32_e64 s[48:49], s46, v237
	v_cmp_lt_u32_e64 s[50:51], s46, v238
	v_cmp_lt_u32_e64 s[52:53], s47, v237
	v_cmp_lt_u32_e64 s[54:55], s47, v238
	v_readlane_b32 s46, v237, 49
	v_readlane_b32 s47, v238, 49
	v_addc_co_u32_e64 v239, s[56:57], 0, v239, s[48:49]
	v_addc_co_u32_e64 v240, s[56:57], 0, v240, s[50:51]
	v_addc_co_u32_e64 v239, s[56:57], 0, v239, s[52:53]
	v_addc_co_u32_e64 v240, s[56:57], 0, v240, s[54:55]
	v_cmp_lt_u32_e64 s[48:49], s46, v237
	v_cmp_lt_u32_e64 s[50:51], s46, v238
	v_cmp_lt_u32_e64 s[52:53], s47, v237
	v_cmp_lt_u32_e64 s[54:55], s47, v238
	v_readlane_b32 s46, v237, 50
	v_readlane_b32 s47, v238, 50
	v_addc_co_u32_e64 v239, s[56:57], 0, v239, s[48:49]
	v_addc_co_u32_e64 v240, s[56:57], 0, v240, s[50:51]
	v_addc_co_u32_e64 v239, s[56:57], 0, v239, s[52:53]
	v_addc_co_u32_e64 v240, s[56:57], 0, v240, s[54:55]
	v_cmp_lt_u32_e64 s[48:49], s46, v237
	v_cmp_lt_u32_e64 s[50:51], s46, v238
	v_cmp_lt_u32_e64 s[52:53], s47, v237
	v_cmp_lt_u32_e64 s[54:55], s47, v238
	v_readlane_b32 s46, v237, 51
	v_readlane_b32 s47, v238, 51
	v_addc_co_u32_e64 v239, s[56:57], 0, v239, s[48:49]
	v_addc_co_u32_e64 v240, s[56:57], 0, v240, s[50:51]
	v_addc_co_u32_e64 v239, s[56:57], 0, v239, s[52:53]
	v_addc_co_u32_e64 v240, s[56:57], 0, v240, s[54:55]
	v_cmp_lt_u32_e64 s[48:49], s46, v237
	v_cmp_lt_u32_e64 s[50:51], s46, v238
	v_cmp_lt_u32_e64 s[52:53], s47, v237
	v_cmp_lt_u32_e64 s[54:55], s47, v238
	v_readlane_b32 s46, v237, 52
	v_readlane_b32 s47, v238, 52
	v_addc_co_u32_e64 v239, s[56:57], 0, v239, s[48:49]
	v_addc_co_u32_e64 v240, s[56:57], 0, v240, s[50:51]
	v_addc_co_u32_e64 v239, s[56:57], 0, v239, s[52:53]
	v_addc_co_u32_e64 v240, s[56:57], 0, v240, s[54:55]
	v_cmp_lt_u32_e64 s[48:49], s46, v237
	v_cmp_lt_u32_e64 s[50:51], s46, v238
	v_cmp_lt_u32_e64 s[52:53], s47, v237
	v_cmp_lt_u32_e64 s[54:55], s47, v238
	v_readlane_b32 s46, v237, 53
	v_readlane_b32 s47, v238, 53
	v_addc_co_u32_e64 v239, s[56:57], 0, v239, s[48:49]
	v_addc_co_u32_e64 v240, s[56:57], 0, v240, s[50:51]
	v_addc_co_u32_e64 v239, s[56:57], 0, v239, s[52:53]
	v_addc_co_u32_e64 v240, s[56:57], 0, v240, s[54:55]
	v_cmp_lt_u32_e64 s[48:49], s46, v237
	v_cmp_lt_u32_e64 s[50:51], s46, v238
	v_cmp_lt_u32_e64 s[52:53], s47, v237
	v_cmp_lt_u32_e64 s[54:55], s47, v238
	v_readlane_b32 s46, v237, 54
	v_readlane_b32 s47, v238, 54
	v_addc_co_u32_e64 v239, s[56:57], 0, v239, s[48:49]
	v_addc_co_u32_e64 v240, s[56:57], 0, v240, s[50:51]
	v_addc_co_u32_e64 v239, s[56:57], 0, v239, s[52:53]
	v_addc_co_u32_e64 v240, s[56:57], 0, v240, s[54:55]
	v_cmp_lt_u32_e64 s[48:49], s46, v237
	v_cmp_lt_u32_e64 s[50:51], s46, v238
	v_cmp_lt_u32_e64 s[52:53], s47, v237
	v_cmp_lt_u32_e64 s[54:55], s47, v238
	v_readlane_b32 s46, v237, 55
	v_readlane_b32 s47, v238, 55
	v_addc_co_u32_e64 v239, s[56:57], 0, v239, s[48:49]
	v_addc_co_u32_e64 v240, s[56:57], 0, v240, s[50:51]
	v_addc_co_u32_e64 v239, s[56:57], 0, v239, s[52:53]
	v_addc_co_u32_e64 v240, s[56:57], 0, v240, s[54:55]
	v_cmp_lt_u32_e64 s[48:49], s46, v237
	v_cmp_lt_u32_e64 s[50:51], s46, v238
	v_cmp_lt_u32_e64 s[52:53], s47, v237
	v_cmp_lt_u32_e64 s[54:55], s47, v238
	v_readlane_b32 s46, v237, 56
	v_readlane_b32 s47, v238, 56
	v_addc_co_u32_e64 v239, s[56:57], 0, v239, s[48:49]
	v_addc_co_u32_e64 v240, s[56:57], 0, v240, s[50:51]
	v_addc_co_u32_e64 v239, s[56:57], 0, v239, s[52:53]
	v_addc_co_u32_e64 v240, s[56:57], 0, v240, s[54:55]
	v_cmp_lt_u32_e64 s[48:49], s46, v237
; DEV void peer_gather_token(const Params& p, int tok) {
;     ...
;   const int e0 = p.eidx[(size_t)tok * 128 + lane], e1 = p.eidx[(size_t)tok * 128 + 64 + lane];
;   const int g0 = __builtin_bit_cast(int, p.gw[(size_t)tok * 128 + lane]), g1 = __builtin_bit_cast(int, p.gw[(size_t)tok * 128 + 64 + lane]);
;   u32x2 dn[4][3], up[4][3];
;   auto issue = [&](int k, int slot) {
;     const int e = (k < 64) ? __builtin_amdgcn_readlane(e0, k) : __builtin_amdgcn_readlane(e1, k - 64);
	v_cmp_lt_u32_e64 s[50:51], s46, v238
	v_cmp_lt_u32_e64 s[52:53], s47, v237
	v_cmp_lt_u32_e64 s[54:55], s47, v238
	v_readlane_b32 s46, v237, 57
	v_readlane_b32 s47, v238, 57
	v_addc_co_u32_e64 v239, s[56:57], 0, v239, s[48:49]
	v_addc_co_u32_e64 v240, s[56:57], 0, v240, s[50:51]
	v_addc_co_u32_e64 v239, s[56:57], 0, v239, s[52:53]
	v_addc_co_u32_e64 v240, s[56:57], 0, v240, s[54:55]
	v_cmp_lt_u32_e64 s[48:49], s46, v237
	v_cmp_lt_u32_e64 s[50:51], s46, v238
	v_cmp_lt_u32_e64 s[52:53], s47, v237
	v_cmp_lt_u32_e64 s[54:55], s47, v238
	v_readlane_b32 s46, v237, 58
	v_readlane_b32 s47, v238, 58
	v_addc_co_u32_e64 v239, s[56:57], 0, v239, s[48:49]
	v_addc_co_u32_e64 v240, s[56:57], 0, v240, s[50:51]
	v_addc_co_u32_e64 v239, s[56:57], 0, v239, s[52:53]
	v_addc_co_u32_e64 v240, s[56:57], 0, v240, s[54:55]
	v_cmp_lt_u32_e64 s[48:49], s46, v237
	v_cmp_lt_u32_e64 s[50:51], s46, v238
	v_cmp_lt_u32_e64 s[52:53], s47, v237
	v_cmp_lt_u32_e64 s[54:55], s47, v238
	v_readlane_b32 s46, v237, 59
	v_readlane_b32 s47, v238, 59
	v_addc_co_u32_e64 v239, s[56:57], 0, v239, s[48:49]
	v_addc_co_u32_e64 v240, s[56:57], 0, v240, s[50:51]
	v_addc_co_u32_e64 v239, s[56:57], 0, v239, s[52:53]
	v_addc_co_u32_e64 v240, s[56:57], 0, v240, s[54:55]
	v_cmp_lt_u32_e64 s[48:49], s46, v237
	v_cmp_lt_u32_e64 s[50:51], s46, v238
	v_cmp_lt_u32_e64 s[52:53], s47, v237
	v_cmp_lt_u32_e64 s[54:55], s47, v238
	v_readlane_b32 s46, v237, 60
	v_readlane_b32 s47, v238, 60
	v_addc_co_u32_e64 v239, s[56:57], 0, v239, s[48:49]
	v_addc_co_u32_e64 v240, s[56:57], 0, v240, s[50:51]
	v_addc_co_u32_e64 v239, s[56:57], 0, v239, s[52:53]
	v_addc_co_u32_e64 v240, s[56:57], 0, v240, s[54:55]
	v_cmp_lt_u32_e64 s[48:49], s46, v237
	v_cmp_lt_u32_e64 s[50:51], s46, v238
	v_cmp_lt_u32_e64 s[52:53], s47, v237
	v_cmp_lt_u32_e64 s[54:55], s47, v238
	v_readlane_b32 s46, v237, 61
	v_readlane_b32 s47, v238, 61
	v_addc_co_u32_e64 v239, s[56:57], 0, v239, s[48:49]
	v_addc_co_u32_e64 v240, s[56:57], 0, v240, s[50:51]
	v_addc_co_u32_e64 v239, s[56:57], 0, v239, s[52:53]
	v_addc_co_u32_e64 v240, s[56:57], 0, v240, s[54:55]
	v_cmp_lt_u32_e64 s[48:49], s46, v237
	v_cmp_lt_u32_e64 s[50:51], s46, v238
	v_cmp_lt_u32_e64 s[52:53], s47, v237
	v_cmp_lt_u32_e64 s[54:55], s47, v238
	v_readlane_b32 s46, v237, 62
	v_readlane_b32 s47, v238, 62
	v_addc_co_u32_e64 v239, s[56:57], 0, v239, s[48:49]
	v_addc_co_u32_e64 v240, s[56:57], 0, v240, s[50:51]
	v_addc_co_u32_e64 v239, s[56:57], 0, v239, s[52:53]
	v_addc_co_u32_e64 v240, s[56:57], 0, v240, s[54:55]
	v_cmp_lt_u32_e64 s[48:49], s46, v237
	v_cmp_lt_u32_e64 s[50:51], s46, v238
	v_cmp_lt_u32_e64 s[52:53], s47, v237
	v_cmp_lt_u32_e64 s[54:55], s47, v238
	v_readlane_b32 s46, v237, 63
	v_readlane_b32 s47, v238, 63
	v_addc_co_u32_e64 v239, s[56:57], 0, v239, s[48:49]
	v_addc_co_u32_e64 v240, s[56:57], 0, v240, s[50:51]
	v_addc_co_u32_e64 v239, s[56:57], 0, v239, s[52:53]
	v_addc_co_u32_e64 v240, s[56:57], 0, v240, s[54:55]
	v_cmp_lt_u32_e64 s[48:49], s46, v237
	v_cmp_lt_u32_e64 s[50:51], s46, v238
	v_cmp_lt_u32_e64 s[52:53], s47, v237
	v_cmp_lt_u32_e64 s[54:55], s47, v238
	s_nop 1
	v_addc_co_u32_e64 v239, s[56:57], 0, v239, s[48:49]
	v_addc_co_u32_e64 v240, s[56:57], 0, v240, s[50:51]
	v_addc_co_u32_e64 v239, s[56:57], 0, v239, s[52:53]
	v_addc_co_u32_e64 v240, s[56:57], 0, v240, s[54:55]
	v_xor_b32_e32 v239, s19, v239
	v_xor_b32_e32 v240, s19, v240
	s_xor_b32 s19, s19, 0x7f
	v_and_b32_e32 v237, 0xfffffc00, v241
	v_lshl_add_u32 v239, v239, 2, v237
	v_lshl_add_u32 v240, v240, 2, v237
	ds_write_b32 v239, v216
	ds_write_b32 v240, v217
	ds_write_b32 v239, v218 offset:512
	ds_write_b32 v240, v219 offset:512
	s_waitcnt lgkmcnt(0)
	ds_read_b32 v216, v241
	ds_read_b32 v217, v241 offset:256
	ds_read_b32 v218, v241 offset:512
	ds_read_b32 v219, v241 offset:768
	s_waitcnt lgkmcnt(0)
	s_branch .Lp12_switch

; DEV float gelu_exact(float v) { return 0.5f * v * (1.f + erff(v * 0.7071067811865476f)); }
; DEV void peer_gather_token(const Params& p, int tok) {
;     ...
;       if (k + 3 < 128) issue(k + 3, (s + 3) & 3);
;       const v6u dq = v6u{dn[s][0][0], dn[s][0][1], dn[s][1][0], dn[s][1][1], dn[s][2][0], dn[s][2][1]};
;       const v32f dv = __builtin_amdgcn_cvt_scalef32_pk32_f32_fp6(dq, 1.0f);
;       float d0 = 0.f, d1 = 0.f, d2 = 0.f, d3 = 0.f;
; #pragma unroll
;       for (int i = 0; i < 8; ++i) { d0 += dv[4 * i] * hx[4 * i]; d1 += dv[4 * i + 1] * hx[4 * i + 1]; d2 += dv[4 * i + 2] * hx[4 * i + 2]; d3 += dv[4 * i + 3] * hx[4 * i + 3]; }
;       const float d = wave_sum_fast((d0 + d1) + (d2 + d3)) * (1.f / DOWN_SCALE);
;       const float gk = __builtin_bit_cast(float, (k < 64) ? __builtin_amdgcn_readlane(g0, k) : __builtin_amdgcn_readlane(g1, k - 64));
;       const float act = gelu_exact(d) * gk * (1.f / UP_SCALE);
;       const v6u uq = v6u{up[s][0][0], up[s][0][1], up[s][1][0], up[s][1][1], up[s][2][0], up[s][2][1]};
;       const v32f uv = __builtin_amdgcn_cvt_scalef32_pk32_f32_fp6(uq, 1.0f);
; #pragma unroll
;       for (int i = 0; i < 32; ++i) acc[i] += act * uv[i];
.Ljn_1:
	v_bfi_b32 v209, s18, v210, v205
	v_mul_f32_e32 v208, 0.5, v204
	v_add_f32_e32 v209, 1.0, v209
	v_mul_f32_e32 v208, v208, v209
	v_mul_f32_e32 v208, s26, v208
	v_mul_f32_e32 v206, 0x3e800000, v208
	v_pk_fma_f32 v[66:67], v[2:3], v[206:207], v[66:67] op_sel_hi:[1,0,1]
	v_pk_fma_f32 v[68:69], v[4:5], v[206:207], v[68:69] op_sel_hi:[1,0,1]
	v_pk_fma_f32 v[70:71], v[6:7], v[206:207], v[70:71] op_sel_hi:[1,0,1]
	v_pk_fma_f32 v[72:73], v[8:9], v[206:207], v[72:73] op_sel_hi:[1,0,1]
	v_pk_fma_f32 v[74:75], v[10:11], v[206:207], v[74:75] op_sel_hi:[1,0,1]
	v_pk_fma_f32 v[76:77], v[12:13], v[206:207], v[76:77] op_sel_hi:[1,0,1]
	v_pk_fma_f32 v[78:79], v[14:15], v[206:207], v[78:79] op_sel_hi:[1,0,1]
	v_pk_fma_f32 v[80:81], v[16:17], v[206:207], v[80:81] op_sel_hi:[1,0,1]
	v_pk_fma_f32 v[82:83], v[18:19], v[206:207], v[82:83] op_sel_hi:[1,0,1]
	v_pk_fma_f32 v[84:85], v[20:21], v[206:207], v[84:85] op_sel_hi:[1,0,1]
	v_pk_fma_f32 v[86:87], v[22:23], v[206:207], v[86:87] op_sel_hi:[1,0,1]
	v_pk_fma_f32 v[88:89], v[24:25], v[206:207], v[88:89] op_sel_hi:[1,0,1]
	v_pk_fma_f32 v[90:91], v[26:27], v[206:207], v[90:91] op_sel_hi:[1,0,1]
	v_pk_fma_f32 v[92:93], v[28:29], v[206:207], v[92:93] op_sel_hi:[1,0,1]
	v_pk_fma_f32 v[94:95], v[30:31], v[206:207], v[94:95] op_sel_hi:[1,0,1]
	v_pk_fma_f32 v[96:97], v[32:33], v[206:207], v[96:97] op_sel_hi:[1,0,1]
	s_mul_i32 s40, s25, 0xc00
	s_cmp_lt_u32 s25, 0x1800
	s_cselect_b64 s[28:29], s[2:3], s[4:5]
	s_cmp_lt_u32 s25, 0x2800
	s_cselect_b64 s[28:29], s[28:29], s[62:63]
	s_add_u32 s28, s28, s40
	s_addc_u32 s29, s29, 0
	global_load_dwordx4 v[98:101], v1, s[28:29]
	global_load_dwordx4 v[102:105], v1, s[28:29] offset:2048
	global_load_dwordx4 v[106:109], v1, s[28:29] offset:1024
	s_waitcnt vmcnt(21)
	v_cvt_scalef32_pk32_f32_fp6 v[2:33], v[110:115], 1.0
	v_mul_f32_e32 v200, v2, v34
	v_mul_f32_e32 v201, v3, v35
	v_mul_f32_e32 v202, v4, v36
	v_mul_f32_e32 v203, v5, v37
	v_fmac_f32_e32 v200, v6, v38
	v_fmac_f32_e32 v201, v7, v39
	v_fmac_f32_e32 v202, v8, v40
	v_fmac_f32_e32 v203, v9, v41
	v_fmac_f32_e32 v200, v10, v42
	v_fmac_f32_e32 v201, v11, v43
	v_fmac_f32_e32 v202, v12, v44
	v_fmac_f32_e32 v203, v13, v45
	v_fmac_f32_e32 v200, v14, v46
	v_fmac_f32_e32 v201, v15, v47
	v_fmac_f32_e32 v202, v16, v48
	v_fmac_f32_e32 v203, v17, v49
	v_fmac_f32_e32 v200, v18, v50
	v_fmac_f32_e32 v201, v19, v51
	v_fmac_f32_e32 v202, v20, v52
	v_fmac_f32_e32 v203, v21, v53
	v_fmac_f32_e32 v200, v22, v54
	v_fmac_f32_e32 v201, v23, v55
	v_fmac_f32_e32 v202, v24, v56
	v_fmac_f32_e32 v203, v25, v57
	v_fmac_f32_e32 v200, v26, v58
	v_fmac_f32_e32 v201, v27, v59
	v_fmac_f32_e32 v202, v28, v60
	v_fmac_f32_e32 v203, v29, v61
	v_fmac_f32_e32 v200, v30, v62
	v_fmac_f32_e32 v201, v31, v63
	v_fmac_f32_e32 v202, v32, v64
	v_fmac_f32_e32 v203, v33, v65
	v_add_f32_e32 v200, v201, v200
	v_add_f32_e32 v202, v203, v202
	v_cvt_scalef32_pk32_f32_fp6 v[2:33], v[116:121], 1.0
	v_add_f32_e32 v200, v202, v200
	s_add_i32 s38, s24, 1
	v_readlane_b32 s26, v199, s38
	s_add_i32 s39, s23, 1
	v_readlane_b32 s25, v198, s39
	v_add_f32_dpp v200, v200, v200 quad_perm:[1,0,3,2] row_mask:0xf bank_mask:0xf bound_ctrl:1
	s_nop 1
	v_add_f32_dpp v200, v200, v200 quad_perm:[2,3,0,1] row_mask:0xf bank_mask:0xf bound_ctrl:1
	s_nop 1
	v_add_f32_dpp v200, v200, v200 row_half_mirror row_mask:0xf bank_mask:0xf bound_ctrl:1
	s_nop 1
	v_add_f32_dpp v200, v200, v200 row_mirror row_mask:0xf bank_mask:0xf bound_ctrl:1
	s_nop 1
	v_add_f32_dpp v200, v200, v200 row_bcast:15 row_mask:0xa bank_mask:0xf
	s_nop 1
	v_add_f32_dpp v200, v200, v200 row_bcast:31 row_mask:0xc bank_mask:0xf
	s_nop 0
	v_readlane_b32 s27, v200, 63
	v_mul_f32_e32 v204, s27, v212
	v_mul_f32_e32 v205, 0x3f3504f3, v204
	v_cmp_lt_f32_e64 s[32:33], |v205|, 1.0
	s_and_b64 vcc, exec, s[32:33]
	s_cbranch_vccnz .Lsm_3
	v_fma_f32 v208, |v205|, s9, v214
	v_fma_f32 v208, |v205|, v208, s10
	v_fma_f32 v208, |v205|, v208, s11
	v_fma_f32 v208, |v205|, v208, s12
	v_fma_f32 v208, |v205|, v208, s13
	v_fma_f32 v208, |v205|, v208, s14
	v_fma_f32 v208, |v205|, v208, |v205|
	v_mul_f32_e32 v209, 0xbfb8aa3b, v208
	v_fma_f32 v210, v208, s15, -v209
	v_rndne_f32_e32 v211, v209
	v_fmac_f32_e32 v210, 0xb2a5705f, v208
	v_sub_f32_e32 v209, v209, v211
	v_add_f32_e32 v209, v209, v210
	v_cvt_i32_f32_e32 v210, v211
	v_exp_f32_e32 v209, v209
	v_cmp_nlt_f32_e32 vcc, s16, v208
	v_ldexp_f32 v209, v209, v210
	s_nop 0
	v_cndmask_b32_e32 v209, 0, v209, vcc
	v_cmp_ngt_f32_e32 vcc, s17, v208
	s_nop 1
	v_cndmask_b32_e32 v208, v215, v209, vcc
	v_sub_f32_e32 v210, 1.0, v208
	s_branch .Ljn_3

; DEV float gelu_exact(float v) { return 0.5f * v * (1.f + erff(v * 0.7071067811865476f)); }
; DEV void peer_gather_token(const Params& p, int tok) {
;     ...
;       if (k + 3 < 128) issue(k + 3, (s + 3) & 3);
;       const v6u dq = v6u{dn[s][0][0], dn[s][0][1], dn[s][1][0], dn[s][1][1], dn[s][2][0], dn[s][2][1]};
;       const v32f dv = __builtin_amdgcn_cvt_scalef32_pk32_f32_fp6(dq, 1.0f);
;       float d0 = 0.f, d1 = 0.f, d2 = 0.f, d3 = 0.f;
; #pragma unroll
;       for (int i = 0; i < 8; ++i) { d0 += dv[4 * i] * hx[4 * i]; d1 += dv[4 * i + 1] * hx[4 * i + 1]; d2 += dv[4 * i + 2] * hx[4 * i + 2]; d3 += dv[4 * i + 3] * hx[4 * i + 3]; }
;       const float d = wave_sum_fast((d0 + d1) + (d2 + d3)) * (1.f / DOWN_SCALE);
;       const float gk = __builtin_bit_cast(float, (k < 64) ? __builtin_amdgcn_readlane(g0, k) : __builtin_amdgcn_readlane(g1, k - 64));
;       const float act = gelu_exact(d) * gk * (1.f / UP_SCALE);
;       const v6u uq = v6u{up[s][0][0], up[s][0][1], up[s][1][0], up[s][1][1], up[s][2][0], up[s][2][1]};
;       const v32f uv = __builtin_amdgcn_cvt_scalef32_pk32_f32_fp6(uq, 1.0f);
; #pragma unroll
;       for (int i = 0; i < 32; ++i) acc[i] += act * uv[i];
.Ljn_3:
	v_bfi_b32 v209, s18, v210, v205
	v_mul_f32_e32 v208, 0.5, v204
	v_add_f32_e32 v209, 1.0, v209
	v_mul_f32_e32 v208, v208, v209
	v_mul_f32_e32 v208, s26, v208
	v_mul_f32_e32 v206, 0x3e800000, v208
	v_pk_fma_f32 v[66:67], v[2:3], v[206:207], v[66:67] op_sel_hi:[1,0,1]
	v_pk_fma_f32 v[68:69], v[4:5], v[206:207], v[68:69] op_sel_hi:[1,0,1]
	v_pk_fma_f32 v[70:71], v[6:7], v[206:207], v[70:71] op_sel_hi:[1,0,1]
	v_pk_fma_f32 v[72:73], v[8:9], v[206:207], v[72:73] op_sel_hi:[1,0,1]
	v_pk_fma_f32 v[74:75], v[10:11], v[206:207], v[74:75] op_sel_hi:[1,0,1]
	v_pk_fma_f32 v[76:77], v[12:13], v[206:207], v[76:77] op_sel_hi:[1,0,1]
	v_pk_fma_f32 v[78:79], v[14:15], v[206:207], v[78:79] op_sel_hi:[1,0,1]
	v_pk_fma_f32 v[80:81], v[16:17], v[206:207], v[80:81] op_sel_hi:[1,0,1]
	v_pk_fma_f32 v[82:83], v[18:19], v[206:207], v[82:83] op_sel_hi:[1,0,1]
	v_pk_fma_f32 v[84:85], v[20:21], v[206:207], v[84:85] op_sel_hi:[1,0,1]
	v_pk_fma_f32 v[86:87], v[22:23], v[206:207], v[86:87] op_sel_hi:[1,0,1]
	v_pk_fma_f32 v[88:89], v[24:25], v[206:207], v[88:89] op_sel_hi:[1,0,1]
	v_pk_fma_f32 v[90:91], v[26:27], v[206:207], v[90:91] op_sel_hi:[1,0,1]
	v_pk_fma_f32 v[92:93], v[28:29], v[206:207], v[92:93] op_sel_hi:[1,0,1]
	v_pk_fma_f32 v[94:95], v[30:31], v[206:207], v[94:95] op_sel_hi:[1,0,1]
	v_pk_fma_f32 v[96:97], v[32:33], v[206:207], v[96:97] op_sel_hi:[1,0,1]
	s_mul_i32 s40, s25, 0xc00
	s_cmp_lt_u32 s25, 0x1800
	s_cselect_b64 s[28:29], s[2:3], s[4:5]
	s_cmp_lt_u32 s25, 0x2800
	s_cselect_b64 s[28:29], s[28:29], s[62:63]
	s_add_u32 s28, s28, s40
	s_addc_u32 s29, s29, 0
	global_load_dwordx4 v[110:113], v1, s[28:29]
	global_load_dwordx4 v[114:117], v1, s[28:29] offset:2048
	global_load_dwordx4 v[118:121], v1, s[28:29] offset:1024
	s_waitcnt vmcnt(21)
	v_cvt_scalef32_pk32_f32_fp6 v[2:33], v[122:127], 1.0
	v_mul_f32_e32 v200, v2, v34
	v_mul_f32_e32 v201, v3, v35
	v_mul_f32_e32 v202, v4, v36
	v_mul_f32_e32 v203, v5, v37
	v_fmac_f32_e32 v200, v6, v38
	v_fmac_f32_e32 v201, v7, v39
	v_fmac_f32_e32 v202, v8, v40
	v_fmac_f32_e32 v203, v9, v41
	v_fmac_f32_e32 v200, v10, v42
	v_fmac_f32_e32 v201, v11, v43
	v_fmac_f32_e32 v202, v12, v44
	v_fmac_f32_e32 v203, v13, v45
	v_fmac_f32_e32 v200, v14, v46
	v_fmac_f32_e32 v201, v15, v47
	v_fmac_f32_e32 v202, v16, v48
	v_fmac_f32_e32 v203, v17, v49
	v_fmac_f32_e32 v200, v18, v50
	v_fmac_f32_e32 v201, v19, v51
	v_fmac_f32_e32 v202, v20, v52
	v_fmac_f32_e32 v203, v21, v53
	v_fmac_f32_e32 v200, v22, v54
	v_fmac_f32_e32 v201, v23, v55
	v_fmac_f32_e32 v202, v24, v56
	v_fmac_f32_e32 v203, v25, v57
	v_fmac_f32_e32 v200, v26, v58
	v_fmac_f32_e32 v201, v27, v59
	v_fmac_f32_e32 v202, v28, v60
	v_fmac_f32_e32 v203, v29, v61
	v_fmac_f32_e32 v200, v30, v62
	v_fmac_f32_e32 v201, v31, v63
	v_fmac_f32_e32 v202, v32, v64
	v_fmac_f32_e32 v203, v33, v65
	v_add_f32_e32 v200, v201, v200
	v_add_f32_e32 v202, v203, v202
	v_cvt_scalef32_pk32_f32_fp6 v[2:33], v[128:133], 1.0
	v_add_f32_e32 v200, v202, v200
	s_add_i32 s38, s24, 2
	v_readlane_b32 s26, v199, s38
	s_add_i32 s39, s23, 2
	v_readlane_b32 s25, v198, s39
	v_add_f32_dpp v200, v200, v200 quad_perm:[1,0,3,2] row_mask:0xf bank_mask:0xf bound_ctrl:1
	s_nop 1
	v_add_f32_dpp v200, v200, v200 quad_perm:[2,3,0,1] row_mask:0xf bank_mask:0xf bound_ctrl:1
	s_nop 1
	v_add_f32_dpp v200, v200, v200 row_half_mirror row_mask:0xf bank_mask:0xf bound_ctrl:1
	s_nop 1
	v_add_f32_dpp v200, v200, v200 row_mirror row_mask:0xf bank_mask:0xf bound_ctrl:1
	s_nop 1
	v_add_f32_dpp v200, v200, v200 row_bcast:15 row_mask:0xa bank_mask:0xf
	s_nop 1
	v_add_f32_dpp v200, v200, v200 row_bcast:31 row_mask:0xc bank_mask:0xf
	s_nop 0
	v_readlane_b32 s27, v200, 63
	v_mul_f32_e32 v204, s27, v212
	v_mul_f32_e32 v205, 0x3f3504f3, v204
	v_cmp_lt_f32_e64 s[32:33], |v205|, 1.0
	s_and_b64 vcc, exec, s[32:33]
	s_cbranch_vccnz .Lsm_5
	v_fma_f32 v208, |v205|, s9, v214
	v_fma_f32 v208, |v205|, v208, s10
	v_fma_f32 v208, |v205|, v208, s11
	v_fma_f32 v208, |v205|, v208, s12
	v_fma_f32 v208, |v205|, v208, s13
	v_fma_f32 v208, |v205|, v208, s14
	v_fma_f32 v208, |v205|, v208, |v205|
	v_mul_f32_e32 v209, 0xbfb8aa3b, v208
	v_fma_f32 v210, v208, s15, -v209
	v_rndne_f32_e32 v211, v209
	v_fmac_f32_e32 v210, 0xb2a5705f, v208
	v_sub_f32_e32 v209, v209, v211
	v_add_f32_e32 v209, v209, v210
	v_cvt_i32_f32_e32 v210, v211
	v_exp_f32_e32 v209, v209
	v_cmp_nlt_f32_e32 vcc, s16, v208
	v_ldexp_f32 v209, v209, v210
	s_nop 0
	v_cndmask_b32_e32 v209, 0, v209, vcc
	v_cmp_ngt_f32_e32 vcc, s17, v208
	s_nop 1
	v_cndmask_b32_e32 v208, v215, v209, vcc
	v_sub_f32_e32 v210, 1.0, v208
	s_branch .Ljn_5

; DEV float gelu_exact(float v) { return 0.5f * v * (1.f + erff(v * 0.7071067811865476f)); }
; DEV void peer_gather_token(const Params& p, int tok) {
;     ...
;       if (k + 3 < 128) issue(k + 3, (s + 3) & 3);
;       const v6u dq = v6u{dn[s][0][0], dn[s][0][1], dn[s][1][0], dn[s][1][1], dn[s][2][0], dn[s][2][1]};
;       const v32f dv = __builtin_amdgcn_cvt_scalef32_pk32_f32_fp6(dq, 1.0f);
;       float d0 = 0.f, d1 = 0.f, d2 = 0.f, d3 = 0.f;
; #pragma unroll
;       for (int i = 0; i < 8; ++i) { d0 += dv[4 * i] * hx[4 * i]; d1 += dv[4 * i + 1] * hx[4 * i + 1]; d2 += dv[4 * i + 2] * hx[4 * i + 2]; d3 += dv[4 * i + 3] * hx[4 * i + 3]; }
;       const float d = wave_sum_fast((d0 + d1) + (d2 + d3)) * (1.f / DOWN_SCALE);
;       const float gk = __builtin_bit_cast(float, (k < 64) ? __builtin_amdgcn_readlane(g0, k) : __builtin_amdgcn_readlane(g1, k - 64));
;       const float act = gelu_exact(d) * gk * (1.f / UP_SCALE);
;       const v6u uq = v6u{up[s][0][0], up[s][0][1], up[s][1][0], up[s][1][1], up[s][2][0], up[s][2][1]};
;       const v32f uv = __builtin_amdgcn_cvt_scalef32_pk32_f32_fp6(uq, 1.0f);
; #pragma unroll
;       for (int i = 0; i < 32; ++i) acc[i] += act * uv[i];
.Ljn_5:
	v_bfi_b32 v209, s18, v210, v205
	v_mul_f32_e32 v208, 0.5, v204
	v_add_f32_e32 v209, 1.0, v209
	v_mul_f32_e32 v208, v208, v209
	v_mul_f32_e32 v208, s26, v208
	v_mul_f32_e32 v206, 0x3e800000, v208
	v_pk_fma_f32 v[66:67], v[2:3], v[206:207], v[66:67] op_sel_hi:[1,0,1]
	v_pk_fma_f32 v[68:69], v[4:5], v[206:207], v[68:69] op_sel_hi:[1,0,1]
	v_pk_fma_f32 v[70:71], v[6:7], v[206:207], v[70:71] op_sel_hi:[1,0,1]
	v_pk_fma_f32 v[72:73], v[8:9], v[206:207], v[72:73] op_sel_hi:[1,0,1]
	v_pk_fma_f32 v[74:75], v[10:11], v[206:207], v[74:75] op_sel_hi:[1,0,1]
	v_pk_fma_f32 v[76:77], v[12:13], v[206:207], v[76:77] op_sel_hi:[1,0,1]
	v_pk_fma_f32 v[78:79], v[14:15], v[206:207], v[78:79] op_sel_hi:[1,0,1]
	v_pk_fma_f32 v[80:81], v[16:17], v[206:207], v[80:81] op_sel_hi:[1,0,1]
	v_pk_fma_f32 v[82:83], v[18:19], v[206:207], v[82:83] op_sel_hi:[1,0,1]
	v_pk_fma_f32 v[84:85], v[20:21], v[206:207], v[84:85] op_sel_hi:[1,0,1]
	v_pk_fma_f32 v[86:87], v[22:23], v[206:207], v[86:87] op_sel_hi:[1,0,1]
	v_pk_fma_f32 v[88:89], v[24:25], v[206:207], v[88:89] op_sel_hi:[1,0,1]
	v_pk_fma_f32 v[90:91], v[26:27], v[206:207], v[90:91] op_sel_hi:[1,0,1]
	v_pk_fma_f32 v[92:93], v[28:29], v[206:207], v[92:93] op_sel_hi:[1,0,1]
	v_pk_fma_f32 v[94:95], v[30:31], v[206:207], v[94:95] op_sel_hi:[1,0,1]
	v_pk_fma_f32 v[96:97], v[32:33], v[206:207], v[96:97] op_sel_hi:[1,0,1]
	s_mul_i32 s40, s25, 0xc00
	s_cmp_lt_u32 s25, 0x1800
	s_cselect_b64 s[28:29], s[2:3], s[4:5]
	s_cmp_lt_u32 s25, 0x2800
	s_cselect_b64 s[28:29], s[28:29], s[62:63]
	s_add_u32 s28, s28, s40
	s_addc_u32 s29, s29, 0
	global_load_dwordx4 v[122:125], v1, s[28:29]
	global_load_dwordx4 v[126:129], v1, s[28:29] offset:2048
	global_load_dwordx4 v[130:133], v1, s[28:29] offset:1024
	s_waitcnt vmcnt(21)
	v_cvt_scalef32_pk32_f32_fp6 v[2:33], v[134:139], 1.0
	v_mul_f32_e32 v200, v2, v34
	v_mul_f32_e32 v201, v3, v35
	v_mul_f32_e32 v202, v4, v36
	v_mul_f32_e32 v203, v5, v37
	v_fmac_f32_e32 v200, v6, v38
	v_fmac_f32_e32 v201, v7, v39
	v_fmac_f32_e32 v202, v8, v40
	v_fmac_f32_e32 v203, v9, v41
	v_fmac_f32_e32 v200, v10, v42
	v_fmac_f32_e32 v201, v11, v43
	v_fmac_f32_e32 v202, v12, v44
	v_fmac_f32_e32 v203, v13, v45
	v_fmac_f32_e32 v200, v14, v46
	v_fmac_f32_e32 v201, v15, v47
	v_fmac_f32_e32 v202, v16, v48
	v_fmac_f32_e32 v203, v17, v49
	v_fmac_f32_e32 v200, v18, v50
	v_fmac_f32_e32 v201, v19, v51
	v_fmac_f32_e32 v202, v20, v52
	v_fmac_f32_e32 v203, v21, v53
	v_fmac_f32_e32 v200, v22, v54
	v_fmac_f32_e32 v201, v23, v55
	v_fmac_f32_e32 v202, v24, v56
	v_fmac_f32_e32 v203, v25, v57
	v_fmac_f32_e32 v200, v26, v58
	v_fmac_f32_e32 v201, v27, v59
	v_fmac_f32_e32 v202, v28, v60
	v_fmac_f32_e32 v203, v29, v61
	v_fmac_f32_e32 v200, v30, v62
	v_fmac_f32_e32 v201, v31, v63
	v_fmac_f32_e32 v202, v32, v64
	v_fmac_f32_e32 v203, v33, v65
	v_add_f32_e32 v200, v201, v200
	v_add_f32_e32 v202, v203, v202
	v_cvt_scalef32_pk32_f32_fp6 v[2:33], v[140:145], 1.0
	v_add_f32_e32 v200, v202, v200
	s_add_i32 s38, s24, 3
	v_readlane_b32 s26, v199, s38
	s_add_i32 s39, s23, 3
	v_readlane_b32 s25, v198, s39
	v_add_f32_dpp v200, v200, v200 quad_perm:[1,0,3,2] row_mask:0xf bank_mask:0xf bound_ctrl:1
	s_nop 1
	v_add_f32_dpp v200, v200, v200 quad_perm:[2,3,0,1] row_mask:0xf bank_mask:0xf bound_ctrl:1
	s_nop 1
	v_add_f32_dpp v200, v200, v200 row_half_mirror row_mask:0xf bank_mask:0xf bound_ctrl:1
	s_nop 1
	v_add_f32_dpp v200, v200, v200 row_mirror row_mask:0xf bank_mask:0xf bound_ctrl:1
	s_nop 1
	v_add_f32_dpp v200, v200, v200 row_bcast:15 row_mask:0xa bank_mask:0xf
	s_nop 1
	v_add_f32_dpp v200, v200, v200 row_bcast:31 row_mask:0xc bank_mask:0xf
	s_nop 0
	v_readlane_b32 s27, v200, 63
	v_mul_f32_e32 v204, s27, v212
	v_mul_f32_e32 v205, 0x3f3504f3, v204
	v_cmp_lt_f32_e64 s[32:33], |v205|, 1.0
	s_and_b64 vcc, exec, s[32:33]
	s_cbranch_vccnz .Lsm_7
	v_fma_f32 v208, |v205|, s9, v214
	v_fma_f32 v208, |v205|, v208, s10
	v_fma_f32 v208, |v205|, v208, s11
	v_fma_f32 v208, |v205|, v208, s12
	v_fma_f32 v208, |v205|, v208, s13
	v_fma_f32 v208, |v205|, v208, s14
	v_fma_f32 v208, |v205|, v208, |v205|
	v_mul_f32_e32 v209, 0xbfb8aa3b, v208
	v_fma_f32 v210, v208, s15, -v209
	v_rndne_f32_e32 v211, v209
	v_fmac_f32_e32 v210, 0xb2a5705f, v208
	v_sub_f32_e32 v209, v209, v211
	v_add_f32_e32 v209, v209, v210
	v_cvt_i32_f32_e32 v210, v211
	v_exp_f32_e32 v209, v209
	v_cmp_nlt_f32_e32 vcc, s16, v208
	v_ldexp_f32 v209, v209, v210
	s_nop 0
	v_cndmask_b32_e32 v209, 0, v209, vcc
	v_cmp_ngt_f32_e32 vcc, s17, v208
	s_nop 1
	v_cndmask_b32_e32 v208, v215, v209, vcc
	v_sub_f32_e32 v210, 1.0, v208
	s_branch .Ljn_7

; DEV float gelu_exact(float v) { return 0.5f * v * (1.f + erff(v * 0.7071067811865476f)); }
; DEV void peer_gather_token(const Params& p, int tok) {
;     ...
;       if (k + 3 < 128) issue(k + 3, (s + 3) & 3);
;       const v6u dq = v6u{dn[s][0][0], dn[s][0][1], dn[s][1][0], dn[s][1][1], dn[s][2][0], dn[s][2][1]};
;       const v32f dv = __builtin_amdgcn_cvt_scalef32_pk32_f32_fp6(dq, 1.0f);
;       float d0 = 0.f, d1 = 0.f, d2 = 0.f, d3 = 0.f;
; #pragma unroll
;       for (int i = 0; i < 8; ++i) { d0 += dv[4 * i] * hx[4 * i]; d1 += dv[4 * i + 1] * hx[4 * i + 1]; d2 += dv[4 * i + 2] * hx[4 * i + 2]; d3 += dv[4 * i + 3] * hx[4 * i + 3]; }
;       const float d = wave_sum_fast((d0 + d1) + (d2 + d3)) * (1.f / DOWN_SCALE);
;       const float gk = __builtin_bit_cast(float, (k < 64) ? __builtin_amdgcn_readlane(g0, k) : __builtin_amdgcn_readlane(g1, k - 64));
;       const float act = gelu_exact(d) * gk * (1.f / UP_SCALE);
;       const v6u uq = v6u{up[s][0][0], up[s][0][1], up[s][1][0], up[s][1][1], up[s][2][0], up[s][2][1]};
;       const v32f uv = __builtin_amdgcn_cvt_scalef32_pk32_f32_fp6(uq, 1.0f);
; #pragma unroll
;       for (int i = 0; i < 32; ++i) acc[i] += act * uv[i];
.Ljn_7:
	v_bfi_b32 v209, s18, v210, v205
	v_mul_f32_e32 v208, 0.5, v204
	v_add_f32_e32 v209, 1.0, v209
	v_mul_f32_e32 v208, v208, v209
	v_mul_f32_e32 v208, s26, v208
	v_mul_f32_e32 v206, 0x3e800000, v208
	v_pk_fma_f32 v[66:67], v[2:3], v[206:207], v[66:67] op_sel_hi:[1,0,1]
	v_pk_fma_f32 v[68:69], v[4:5], v[206:207], v[68:69] op_sel_hi:[1,0,1]
	v_pk_fma_f32 v[70:71], v[6:7], v[206:207], v[70:71] op_sel_hi:[1,0,1]
	v_pk_fma_f32 v[72:73], v[8:9], v[206:207], v[72:73] op_sel_hi:[1,0,1]
	v_pk_fma_f32 v[74:75], v[10:11], v[206:207], v[74:75] op_sel_hi:[1,0,1]
	v_pk_fma_f32 v[76:77], v[12:13], v[206:207], v[76:77] op_sel_hi:[1,0,1]
	v_pk_fma_f32 v[78:79], v[14:15], v[206:207], v[78:79] op_sel_hi:[1,0,1]
	v_pk_fma_f32 v[80:81], v[16:17], v[206:207], v[80:81] op_sel_hi:[1,0,1]
	v_pk_fma_f32 v[82:83], v[18:19], v[206:207], v[82:83] op_sel_hi:[1,0,1]
	v_pk_fma_f32 v[84:85], v[20:21], v[206:207], v[84:85] op_sel_hi:[1,0,1]
	v_pk_fma_f32 v[86:87], v[22:23], v[206:207], v[86:87] op_sel_hi:[1,0,1]
	v_pk_fma_f32 v[88:89], v[24:25], v[206:207], v[88:89] op_sel_hi:[1,0,1]
	v_pk_fma_f32 v[90:91], v[26:27], v[206:207], v[90:91] op_sel_hi:[1,0,1]
	v_pk_fma_f32 v[92:93], v[28:29], v[206:207], v[92:93] op_sel_hi:[1,0,1]
	v_pk_fma_f32 v[94:95], v[30:31], v[206:207], v[94:95] op_sel_hi:[1,0,1]
	v_pk_fma_f32 v[96:97], v[32:33], v[206:207], v[96:97] op_sel_hi:[1,0,1]
	s_mul_i32 s40, s25, 0xc00
	s_cmp_lt_u32 s25, 0x1800
	s_cselect_b64 s[28:29], s[2:3], s[4:5]
	s_cmp_lt_u32 s25, 0x2800
	s_cselect_b64 s[28:29], s[28:29], s[62:63]
	s_add_u32 s28, s28, s40
	s_addc_u32 s29, s29, 0
	global_load_dwordx4 v[134:137], v1, s[28:29]
	global_load_dwordx4 v[138:141], v1, s[28:29] offset:2048
	global_load_dwordx4 v[142:145], v1, s[28:29] offset:1024
	s_waitcnt vmcnt(21)
	v_cvt_scalef32_pk32_f32_fp6 v[2:33], v[146:151], 1.0
	v_mul_f32_e32 v200, v2, v34
	v_mul_f32_e32 v201, v3, v35
	v_mul_f32_e32 v202, v4, v36
	v_mul_f32_e32 v203, v5, v37
	v_fmac_f32_e32 v200, v6, v38
	v_fmac_f32_e32 v201, v7, v39
	v_fmac_f32_e32 v202, v8, v40
	v_fmac_f32_e32 v203, v9, v41
	v_fmac_f32_e32 v200, v10, v42
	v_fmac_f32_e32 v201, v11, v43
	v_fmac_f32_e32 v202, v12, v44
	v_fmac_f32_e32 v203, v13, v45
	v_fmac_f32_e32 v200, v14, v46
	v_fmac_f32_e32 v201, v15, v47
	v_fmac_f32_e32 v202, v16, v48
	v_fmac_f32_e32 v203, v17, v49
	v_fmac_f32_e32 v200, v18, v50
	v_fmac_f32_e32 v201, v19, v51
	v_fmac_f32_e32 v202, v20, v52
	v_fmac_f32_e32 v203, v21, v53
	v_fmac_f32_e32 v200, v22, v54
	v_fmac_f32_e32 v201, v23, v55
	v_fmac_f32_e32 v202, v24, v56
	v_fmac_f32_e32 v203, v25, v57
	v_fmac_f32_e32 v200, v26, v58
	v_fmac_f32_e32 v201, v27, v59
	v_fmac_f32_e32 v202, v28, v60
	v_fmac_f32_e32 v203, v29, v61
	v_fmac_f32_e32 v200, v30, v62
	v_fmac_f32_e32 v201, v31, v63
	v_fmac_f32_e32 v202, v32, v64
	v_fmac_f32_e32 v203, v33, v65
	v_add_f32_e32 v200, v201, v200
	v_add_f32_e32 v202, v203, v202
	v_cvt_scalef32_pk32_f32_fp6 v[2:33], v[152:157], 1.0
	v_add_f32_e32 v200, v202, v200
	s_add_i32 s38, s24, 4
	v_readlane_b32 s26, v199, s38
	s_add_i32 s39, s23, 4
	v_readlane_b32 s25, v198, s39
	v_add_f32_dpp v200, v200, v200 quad_perm:[1,0,3,2] row_mask:0xf bank_mask:0xf bound_ctrl:1
	s_nop 1
	v_add_f32_dpp v200, v200, v200 quad_perm:[2,3,0,1] row_mask:0xf bank_mask:0xf bound_ctrl:1
	s_nop 1
	v_add_f32_dpp v200, v200, v200 row_half_mirror row_mask:0xf bank_mask:0xf bound_ctrl:1
	s_nop 1
	v_add_f32_dpp v200, v200, v200 row_mirror row_mask:0xf bank_mask:0xf bound_ctrl:1
	s_nop 1
	v_add_f32_dpp v200, v200, v200 row_bcast:15 row_mask:0xa bank_mask:0xf
	s_nop 1
	v_add_f32_dpp v200, v200, v200 row_bcast:31 row_mask:0xc bank_mask:0xf
	s_nop 0
	v_readlane_b32 s27, v200, 63
	v_mul_f32_e32 v204, s27, v212
	v_mul_f32_e32 v205, 0x3f3504f3, v204
	v_cmp_lt_f32_e64 s[32:33], |v205|, 1.0
	s_and_b64 vcc, exec, s[32:33]
	s_cbranch_vccnz .Lsm_9
	v_fma_f32 v208, |v205|, s9, v214
	v_fma_f32 v208, |v205|, v208, s10
	v_fma_f32 v208, |v205|, v208, s11
	v_fma_f32 v208, |v205|, v208, s12
	v_fma_f32 v208, |v205|, v208, s13
	v_fma_f32 v208, |v205|, v208, s14
	v_fma_f32 v208, |v205|, v208, |v205|
	v_mul_f32_e32 v209, 0xbfb8aa3b, v208
	v_fma_f32 v210, v208, s15, -v209
	v_rndne_f32_e32 v211, v209
	v_fmac_f32_e32 v210, 0xb2a5705f, v208
	v_sub_f32_e32 v209, v209, v211
	v_add_f32_e32 v209, v209, v210
	v_cvt_i32_f32_e32 v210, v211
	v_exp_f32_e32 v209, v209
	v_cmp_nlt_f32_e32 vcc, s16, v208
	v_ldexp_f32 v209, v209, v210
	s_nop 0
	v_cndmask_b32_e32 v209, 0, v209, vcc
	v_cmp_ngt_f32_e32 vcc, s17, v208
	s_nop 1
	v_cndmask_b32_e32 v208, v215, v209, vcc
	v_sub_f32_e32 v210, 1.0, v208
	s_branch .Ljn_9

; DEV float gelu_exact(float v) { return 0.5f * v * (1.f + erff(v * 0.7071067811865476f)); }
; DEV void peer_gather_token(const Params& p, int tok) {
;     ...
;       if (k + 3 < 128) issue(k + 3, (s + 3) & 3);
;       const v6u dq = v6u{dn[s][0][0], dn[s][0][1], dn[s][1][0], dn[s][1][1], dn[s][2][0], dn[s][2][1]};
;       const v32f dv = __builtin_amdgcn_cvt_scalef32_pk32_f32_fp6(dq, 1.0f);
;       float d0 = 0.f, d1 = 0.f, d2 = 0.f, d3 = 0.f;
; #pragma unroll
;       for (int i = 0; i < 8; ++i) { d0 += dv[4 * i] * hx[4 * i]; d1 += dv[4 * i + 1] * hx[4 * i + 1]; d2 += dv[4 * i + 2] * hx[4 * i + 2]; d3 += dv[4 * i + 3] * hx[4 * i + 3]; }
;       const float d = wave_sum_fast((d0 + d1) + (d2 + d3)) * (1.f / DOWN_SCALE);
;       const float gk = __builtin_bit_cast(float, (k < 64) ? __builtin_amdgcn_readlane(g0, k) : __builtin_amdgcn_readlane(g1, k - 64));
;       const float act = gelu_exact(d) * gk * (1.f / UP_SCALE);
;       const v6u uq = v6u{up[s][0][0], up[s][0][1], up[s][1][0], up[s][1][1], up[s][2][0], up[s][2][1]};
;       const v32f uv = __builtin_amdgcn_cvt_scalef32_pk32_f32_fp6(uq, 1.0f);
; #pragma unroll
;       for (int i = 0; i < 32; ++i) acc[i] += act * uv[i];
.Ljn_9:
	v_bfi_b32 v209, s18, v210, v205
	v_mul_f32_e32 v208, 0.5, v204
	v_add_f32_e32 v209, 1.0, v209
	v_mul_f32_e32 v208, v208, v209
	v_mul_f32_e32 v208, s26, v208
	v_mul_f32_e32 v206, 0x3e800000, v208
	v_pk_fma_f32 v[66:67], v[2:3], v[206:207], v[66:67] op_sel_hi:[1,0,1]
	v_pk_fma_f32 v[68:69], v[4:5], v[206:207], v[68:69] op_sel_hi:[1,0,1]
	v_pk_fma_f32 v[70:71], v[6:7], v[206:207], v[70:71] op_sel_hi:[1,0,1]
	v_pk_fma_f32 v[72:73], v[8:9], v[206:207], v[72:73] op_sel_hi:[1,0,1]
	v_pk_fma_f32 v[74:75], v[10:11], v[206:207], v[74:75] op_sel_hi:[1,0,1]
	v_pk_fma_f32 v[76:77], v[12:13], v[206:207], v[76:77] op_sel_hi:[1,0,1]
	v_pk_fma_f32 v[78:79], v[14:15], v[206:207], v[78:79] op_sel_hi:[1,0,1]
	v_pk_fma_f32 v[80:81], v[16:17], v[206:207], v[80:81] op_sel_hi:[1,0,1]
	v_pk_fma_f32 v[82:83], v[18:19], v[206:207], v[82:83] op_sel_hi:[1,0,1]
	v_pk_fma_f32 v[84:85], v[20:21], v[206:207], v[84:85] op_sel_hi:[1,0,1]
	v_pk_fma_f32 v[86:87], v[22:23], v[206:207], v[86:87] op_sel_hi:[1,0,1]
	v_pk_fma_f32 v[88:89], v[24:25], v[206:207], v[88:89] op_sel_hi:[1,0,1]
	v_pk_fma_f32 v[90:91], v[26:27], v[206:207], v[90:91] op_sel_hi:[1,0,1]
	v_pk_fma_f32 v[92:93], v[28:29], v[206:207], v[92:93] op_sel_hi:[1,0,1]
	v_pk_fma_f32 v[94:95], v[30:31], v[206:207], v[94:95] op_sel_hi:[1,0,1]
	v_pk_fma_f32 v[96:97], v[32:33], v[206:207], v[96:97] op_sel_hi:[1,0,1]
	s_mul_i32 s40, s25, 0xc00
	s_cmp_lt_u32 s25, 0x1800
	s_cselect_b64 s[28:29], s[2:3], s[4:5]
	s_cmp_lt_u32 s25, 0x2800
	s_cselect_b64 s[28:29], s[28:29], s[62:63]
	s_add_u32 s28, s28, s40
	s_addc_u32 s29, s29, 0
	global_load_dwordx4 v[146:149], v1, s[28:29]
	global_load_dwordx4 v[150:153], v1, s[28:29] offset:2048
	global_load_dwordx4 v[154:157], v1, s[28:29] offset:1024
	s_waitcnt vmcnt(21)
	v_cvt_scalef32_pk32_f32_fp6 v[2:33], v[158:163], 1.0
	v_mul_f32_e32 v200, v2, v34
	v_mul_f32_e32 v201, v3, v35
	v_mul_f32_e32 v202, v4, v36
	v_mul_f32_e32 v203, v5, v37
	v_fmac_f32_e32 v200, v6, v38
	v_fmac_f32_e32 v201, v7, v39
	v_fmac_f32_e32 v202, v8, v40
	v_fmac_f32_e32 v203, v9, v41
	v_fmac_f32_e32 v200, v10, v42
	v_fmac_f32_e32 v201, v11, v43
	v_fmac_f32_e32 v202, v12, v44
	v_fmac_f32_e32 v203, v13, v45
	v_fmac_f32_e32 v200, v14, v46
	v_fmac_f32_e32 v201, v15, v47
	v_fmac_f32_e32 v202, v16, v48
	v_fmac_f32_e32 v203, v17, v49
	v_fmac_f32_e32 v200, v18, v50
	v_fmac_f32_e32 v201, v19, v51
	v_fmac_f32_e32 v202, v20, v52
	v_fmac_f32_e32 v203, v21, v53
	v_fmac_f32_e32 v200, v22, v54
	v_fmac_f32_e32 v201, v23, v55
	v_fmac_f32_e32 v202, v24, v56
	v_fmac_f32_e32 v203, v25, v57
	v_fmac_f32_e32 v200, v26, v58
	v_fmac_f32_e32 v201, v27, v59
	v_fmac_f32_e32 v202, v28, v60
	v_fmac_f32_e32 v203, v29, v61
	v_fmac_f32_e32 v200, v30, v62
	v_fmac_f32_e32 v201, v31, v63
	v_fmac_f32_e32 v202, v32, v64
	v_fmac_f32_e32 v203, v33, v65
	v_add_f32_e32 v200, v201, v200
	v_add_f32_e32 v202, v203, v202
	v_cvt_scalef32_pk32_f32_fp6 v[2:33], v[164:169], 1.0
	v_add_f32_e32 v200, v202, v200
	s_add_i32 s38, s24, 5
	v_readlane_b32 s26, v199, s38
	s_add_i32 s39, s23, 5
	v_readlane_b32 s25, v198, s39
	v_add_f32_dpp v200, v200, v200 quad_perm:[1,0,3,2] row_mask:0xf bank_mask:0xf bound_ctrl:1
	s_nop 1
	v_add_f32_dpp v200, v200, v200 quad_perm:[2,3,0,1] row_mask:0xf bank_mask:0xf bound_ctrl:1
	s_nop 1
	v_add_f32_dpp v200, v200, v200 row_half_mirror row_mask:0xf bank_mask:0xf bound_ctrl:1
	s_nop 1
	v_add_f32_dpp v200, v200, v200 row_mirror row_mask:0xf bank_mask:0xf bound_ctrl:1
	s_nop 1
	v_add_f32_dpp v200, v200, v200 row_bcast:15 row_mask:0xa bank_mask:0xf
	s_nop 1
	v_add_f32_dpp v200, v200, v200 row_bcast:31 row_mask:0xc bank_mask:0xf
	s_nop 0
	v_readlane_b32 s27, v200, 63
	v_mul_f32_e32 v204, s27, v212
	v_mul_f32_e32 v205, 0x3f3504f3, v204
	v_cmp_lt_f32_e64 s[32:33], |v205|, 1.0
	s_and_b64 vcc, exec, s[32:33]
	s_cbranch_vccnz .Lsm_11
	v_fma_f32 v208, |v205|, s9, v214
	v_fma_f32 v208, |v205|, v208, s10
	v_fma_f32 v208, |v205|, v208, s11
	v_fma_f32 v208, |v205|, v208, s12
	v_fma_f32 v208, |v205|, v208, s13
	v_fma_f32 v208, |v205|, v208, s14
	v_fma_f32 v208, |v205|, v208, |v205|
	v_mul_f32_e32 v209, 0xbfb8aa3b, v208
	v_fma_f32 v210, v208, s15, -v209
	v_rndne_f32_e32 v211, v209
	v_fmac_f32_e32 v210, 0xb2a5705f, v208
	v_sub_f32_e32 v209, v209, v211
	v_add_f32_e32 v209, v209, v210
	v_cvt_i32_f32_e32 v210, v211
	v_exp_f32_e32 v209, v209
	v_cmp_nlt_f32_e32 vcc, s16, v208
	v_ldexp_f32 v209, v209, v210
	s_nop 0
	v_cndmask_b32_e32 v209, 0, v209, vcc
	v_cmp_ngt_f32_e32 vcc, s17, v208
	s_nop 1
	v_cndmask_b32_e32 v208, v215, v209, vcc
	v_sub_f32_e32 v210, 1.0, v208
	s_branch .Ljn_11

; DEV float gelu_exact(float v) { return 0.5f * v * (1.f + erff(v * 0.7071067811865476f)); }
; DEV void peer_gather_token(const Params& p, int tok) {
;     ...
;       if (k + 3 < 128) issue(k + 3, (s + 3) & 3);
;       const v6u dq = v6u{dn[s][0][0], dn[s][0][1], dn[s][1][0], dn[s][1][1], dn[s][2][0], dn[s][2][1]};
;       const v32f dv = __builtin_amdgcn_cvt_scalef32_pk32_f32_fp6(dq, 1.0f);
;       float d0 = 0.f, d1 = 0.f, d2 = 0.f, d3 = 0.f;
; #pragma unroll
;       for (int i = 0; i < 8; ++i) { d0 += dv[4 * i] * hx[4 * i]; d1 += dv[4 * i + 1] * hx[4 * i + 1]; d2 += dv[4 * i + 2] * hx[4 * i + 2]; d3 += dv[4 * i + 3] * hx[4 * i + 3]; }
;       const float d = wave_sum_fast((d0 + d1) + (d2 + d3)) * (1.f / DOWN_SCALE);
;       const float gk = __builtin_bit_cast(float, (k < 64) ? __builtin_amdgcn_readlane(g0, k) : __builtin_amdgcn_readlane(g1, k - 64));
;       const float act = gelu_exact(d) * gk * (1.f / UP_SCALE);
;       const v6u uq = v6u{up[s][0][0], up[s][0][1], up[s][1][0], up[s][1][1], up[s][2][0], up[s][2][1]};
;       const v32f uv = __builtin_amdgcn_cvt_scalef32_pk32_f32_fp6(uq, 1.0f);
; #pragma unroll
;       for (int i = 0; i < 32; ++i) acc[i] += act * uv[i];
.Ljn_11:
	v_bfi_b32 v209, s18, v210, v205
	v_mul_f32_e32 v208, 0.5, v204
	v_add_f32_e32 v209, 1.0, v209
	v_mul_f32_e32 v208, v208, v209
	v_mul_f32_e32 v208, s26, v208
	v_mul_f32_e32 v206, 0x3e800000, v208
	v_pk_fma_f32 v[66:67], v[2:3], v[206:207], v[66:67] op_sel_hi:[1,0,1]
	v_pk_fma_f32 v[68:69], v[4:5], v[206:207], v[68:69] op_sel_hi:[1,0,1]
	v_pk_fma_f32 v[70:71], v[6:7], v[206:207], v[70:71] op_sel_hi:[1,0,1]
	v_pk_fma_f32 v[72:73], v[8:9], v[206:207], v[72:73] op_sel_hi:[1,0,1]
	v_pk_fma_f32 v[74:75], v[10:11], v[206:207], v[74:75] op_sel_hi:[1,0,1]
	v_pk_fma_f32 v[76:77], v[12:13], v[206:207], v[76:77] op_sel_hi:[1,0,1]
	v_pk_fma_f32 v[78:79], v[14:15], v[206:207], v[78:79] op_sel_hi:[1,0,1]
	v_pk_fma_f32 v[80:81], v[16:17], v[206:207], v[80:81] op_sel_hi:[1,0,1]
	v_pk_fma_f32 v[82:83], v[18:19], v[206:207], v[82:83] op_sel_hi:[1,0,1]
	v_pk_fma_f32 v[84:85], v[20:21], v[206:207], v[84:85] op_sel_hi:[1,0,1]
	v_pk_fma_f32 v[86:87], v[22:23], v[206:207], v[86:87] op_sel_hi:[1,0,1]
	v_pk_fma_f32 v[88:89], v[24:25], v[206:207], v[88:89] op_sel_hi:[1,0,1]
	v_pk_fma_f32 v[90:91], v[26:27], v[206:207], v[90:91] op_sel_hi:[1,0,1]
	v_pk_fma_f32 v[92:93], v[28:29], v[206:207], v[92:93] op_sel_hi:[1,0,1]
	v_pk_fma_f32 v[94:95], v[30:31], v[206:207], v[94:95] op_sel_hi:[1,0,1]
	v_pk_fma_f32 v[96:97], v[32:33], v[206:207], v[96:97] op_sel_hi:[1,0,1]
	s_mul_i32 s40, s25, 0xc00
	s_cmp_lt_u32 s25, 0x1800
	s_cselect_b64 s[28:29], s[2:3], s[4:5]
	s_cmp_lt_u32 s25, 0x2800
	s_cselect_b64 s[28:29], s[28:29], s[62:63]
	s_add_u32 s28, s28, s40
	s_addc_u32 s29, s29, 0
	global_load_dwordx4 v[158:161], v1, s[28:29]
	global_load_dwordx4 v[162:165], v1, s[28:29] offset:2048
	global_load_dwordx4 v[166:169], v1, s[28:29] offset:1024
	s_waitcnt vmcnt(21)
	v_cvt_scalef32_pk32_f32_fp6 v[2:33], v[170:175], 1.0
	v_mul_f32_e32 v200, v2, v34
	v_mul_f32_e32 v201, v3, v35
	v_mul_f32_e32 v202, v4, v36
	v_mul_f32_e32 v203, v5, v37
	v_fmac_f32_e32 v200, v6, v38
	v_fmac_f32_e32 v201, v7, v39
	v_fmac_f32_e32 v202, v8, v40
	v_fmac_f32_e32 v203, v9, v41
	v_fmac_f32_e32 v200, v10, v42
	v_fmac_f32_e32 v201, v11, v43
	v_fmac_f32_e32 v202, v12, v44
	v_fmac_f32_e32 v203, v13, v45
	v_fmac_f32_e32 v200, v14, v46
	v_fmac_f32_e32 v201, v15, v47
	v_fmac_f32_e32 v202, v16, v48
	v_fmac_f32_e32 v203, v17, v49
	v_fmac_f32_e32 v200, v18, v50
	v_fmac_f32_e32 v201, v19, v51
	v_fmac_f32_e32 v202, v20, v52
	v_fmac_f32_e32 v203, v21, v53
	v_fmac_f32_e32 v200, v22, v54
	v_fmac_f32_e32 v201, v23, v55
	v_fmac_f32_e32 v202, v24, v56
	v_fmac_f32_e32 v203, v25, v57
	v_fmac_f32_e32 v200, v26, v58
	v_fmac_f32_e32 v201, v27, v59
	v_fmac_f32_e32 v202, v28, v60
	v_fmac_f32_e32 v203, v29, v61
	v_fmac_f32_e32 v200, v30, v62
	v_fmac_f32_e32 v201, v31, v63
	v_fmac_f32_e32 v202, v32, v64
	v_fmac_f32_e32 v203, v33, v65
	v_add_f32_e32 v200, v201, v200
	v_add_f32_e32 v202, v203, v202
	v_cvt_scalef32_pk32_f32_fp6 v[2:33], v[176:181], 1.0
	v_add_f32_e32 v200, v202, v200
	s_add_i32 s38, s24, 6
	v_readlane_b32 s26, v199, s38
	s_add_i32 s39, s23, 6
	v_readlane_b32 s25, v198, s39
	v_add_f32_dpp v200, v200, v200 quad_perm:[1,0,3,2] row_mask:0xf bank_mask:0xf bound_ctrl:1
	s_nop 1
	v_add_f32_dpp v200, v200, v200 quad_perm:[2,3,0,1] row_mask:0xf bank_mask:0xf bound_ctrl:1
	s_nop 1
	v_add_f32_dpp v200, v200, v200 row_half_mirror row_mask:0xf bank_mask:0xf bound_ctrl:1
	s_nop 1
	v_add_f32_dpp v200, v200, v200 row_mirror row_mask:0xf bank_mask:0xf bound_ctrl:1
	s_nop 1
	v_add_f32_dpp v200, v200, v200 row_bcast:15 row_mask:0xa bank_mask:0xf
	s_nop 1
	v_add_f32_dpp v200, v200, v200 row_bcast:31 row_mask:0xc bank_mask:0xf
	s_nop 0
	v_readlane_b32 s27, v200, 63
	v_mul_f32_e32 v204, s27, v212
	v_mul_f32_e32 v205, 0x3f3504f3, v204
	v_cmp_lt_f32_e64 s[32:33], |v205|, 1.0
	s_and_b64 vcc, exec, s[32:33]
	s_cbranch_vccnz .Lsm_13
	v_fma_f32 v208, |v205|, s9, v214
	v_fma_f32 v208, |v205|, v208, s10
	v_fma_f32 v208, |v205|, v208, s11
	v_fma_f32 v208, |v205|, v208, s12
	v_fma_f32 v208, |v205|, v208, s13
	v_fma_f32 v208, |v205|, v208, s14
	v_fma_f32 v208, |v205|, v208, |v205|
	v_mul_f32_e32 v209, 0xbfb8aa3b, v208
	v_fma_f32 v210, v208, s15, -v209
	v_rndne_f32_e32 v211, v209
	v_fmac_f32_e32 v210, 0xb2a5705f, v208
	v_sub_f32_e32 v209, v209, v211
	v_add_f32_e32 v209, v209, v210
	v_cvt_i32_f32_e32 v210, v211
	v_exp_f32_e32 v209, v209
	v_cmp_nlt_f32_e32 vcc, s16, v208
	v_ldexp_f32 v209, v209, v210
	s_nop 0
	v_cndmask_b32_e32 v209, 0, v209, vcc
	v_cmp_ngt_f32_e32 vcc, s17, v208
	s_nop 1
	v_cndmask_b32_e32 v208, v215, v209, vcc
	v_sub_f32_e32 v210, 1.0, v208
	s_branch .Ljn_13

; DEV float gelu_exact(float v) { return 0.5f * v * (1.f + erff(v * 0.7071067811865476f)); }
; DEV void peer_gather_token(const Params& p, int tok) {
;     ...
;       if (k + 3 < 128) issue(k + 3, (s + 3) & 3);
;       const v6u dq = v6u{dn[s][0][0], dn[s][0][1], dn[s][1][0], dn[s][1][1], dn[s][2][0], dn[s][2][1]};
;       const v32f dv = __builtin_amdgcn_cvt_scalef32_pk32_f32_fp6(dq, 1.0f);
;       float d0 = 0.f, d1 = 0.f, d2 = 0.f, d3 = 0.f;
; #pragma unroll
;       for (int i = 0; i < 8; ++i) { d0 += dv[4 * i] * hx[4 * i]; d1 += dv[4 * i + 1] * hx[4 * i + 1]; d2 += dv[4 * i + 2] * hx[4 * i + 2]; d3 += dv[4 * i + 3] * hx[4 * i + 3]; }
;       const float d = wave_sum_fast((d0 + d1) + (d2 + d3)) * (1.f / DOWN_SCALE);
;       const float gk = __builtin_bit_cast(float, (k < 64) ? __builtin_amdgcn_readlane(g0, k) : __builtin_amdgcn_readlane(g1, k - 64));
;       const float act = gelu_exact(d) * gk * (1.f / UP_SCALE);
;       const v6u uq = v6u{up[s][0][0], up[s][0][1], up[s][1][0], up[s][1][1], up[s][2][0], up[s][2][1]};
;       const v32f uv = __builtin_amdgcn_cvt_scalef32_pk32_f32_fp6(uq, 1.0f);
; #pragma unroll
;       for (int i = 0; i < 32; ++i) acc[i] += act * uv[i];
.Ljn_13:
	v_bfi_b32 v209, s18, v210, v205
	v_mul_f32_e32 v208, 0.5, v204
	v_add_f32_e32 v209, 1.0, v209
	v_mul_f32_e32 v208, v208, v209
	v_mul_f32_e32 v208, s26, v208
	v_mul_f32_e32 v206, 0x3e800000, v208
	v_pk_fma_f32 v[66:67], v[2:3], v[206:207], v[66:67] op_sel_hi:[1,0,1]
	v_pk_fma_f32 v[68:69], v[4:5], v[206:207], v[68:69] op_sel_hi:[1,0,1]
	v_pk_fma_f32 v[70:71], v[6:7], v[206:207], v[70:71] op_sel_hi:[1,0,1]
	v_pk_fma_f32 v[72:73], v[8:9], v[206:207], v[72:73] op_sel_hi:[1,0,1]
	v_pk_fma_f32 v[74:75], v[10:11], v[206:207], v[74:75] op_sel_hi:[1,0,1]
	v_pk_fma_f32 v[76:77], v[12:13], v[206:207], v[76:77] op_sel_hi:[1,0,1]
	v_pk_fma_f32 v[78:79], v[14:15], v[206:207], v[78:79] op_sel_hi:[1,0,1]
	v_pk_fma_f32 v[80:81], v[16:17], v[206:207], v[80:81] op_sel_hi:[1,0,1]
	v_pk_fma_f32 v[82:83], v[18:19], v[206:207], v[82:83] op_sel_hi:[1,0,1]
	v_pk_fma_f32 v[84:85], v[20:21], v[206:207], v[84:85] op_sel_hi:[1,0,1]
	v_pk_fma_f32 v[86:87], v[22:23], v[206:207], v[86:87] op_sel_hi:[1,0,1]
	v_pk_fma_f32 v[88:89], v[24:25], v[206:207], v[88:89] op_sel_hi:[1,0,1]
	v_pk_fma_f32 v[90:91], v[26:27], v[206:207], v[90:91] op_sel_hi:[1,0,1]
	v_pk_fma_f32 v[92:93], v[28:29], v[206:207], v[92:93] op_sel_hi:[1,0,1]
	v_pk_fma_f32 v[94:95], v[30:31], v[206:207], v[94:95] op_sel_hi:[1,0,1]
	v_pk_fma_f32 v[96:97], v[32:33], v[206:207], v[96:97] op_sel_hi:[1,0,1]
	s_mul_i32 s40, s25, 0xc00
	s_cmp_lt_u32 s25, 0x1800
	s_cselect_b64 s[28:29], s[2:3], s[4:5]
	s_cmp_lt_u32 s25, 0x2800
	s_cselect_b64 s[28:29], s[28:29], s[62:63]
	s_add_u32 s28, s28, s40
	s_addc_u32 s29, s29, 0
	global_load_dwordx4 v[170:173], v1, s[28:29]
	global_load_dwordx4 v[174:177], v1, s[28:29] offset:2048
	global_load_dwordx4 v[178:181], v1, s[28:29] offset:1024
	s_waitcnt vmcnt(21)
	v_cvt_scalef32_pk32_f32_fp6 v[2:33], v[182:187], 1.0
	v_mul_f32_e32 v200, v2, v34
	v_mul_f32_e32 v201, v3, v35
	v_mul_f32_e32 v202, v4, v36
	v_mul_f32_e32 v203, v5, v37
	v_fmac_f32_e32 v200, v6, v38
	v_fmac_f32_e32 v201, v7, v39
	v_fmac_f32_e32 v202, v8, v40
	v_fmac_f32_e32 v203, v9, v41
	v_fmac_f32_e32 v200, v10, v42
	v_fmac_f32_e32 v201, v11, v43
	v_fmac_f32_e32 v202, v12, v44
	v_fmac_f32_e32 v203, v13, v45
	v_fmac_f32_e32 v200, v14, v46
	v_fmac_f32_e32 v201, v15, v47
	v_fmac_f32_e32 v202, v16, v48
	v_fmac_f32_e32 v203, v17, v49
	v_fmac_f32_e32 v200, v18, v50
	v_fmac_f32_e32 v201, v19, v51
	v_fmac_f32_e32 v202, v20, v52
	v_fmac_f32_e32 v203, v21, v53
	v_fmac_f32_e32 v200, v22, v54
	v_fmac_f32_e32 v201, v23, v55
	v_fmac_f32_e32 v202, v24, v56
	v_fmac_f32_e32 v203, v25, v57
	v_fmac_f32_e32 v200, v26, v58
	v_fmac_f32_e32 v201, v27, v59
	v_fmac_f32_e32 v202, v28, v60
	v_fmac_f32_e32 v203, v29, v61
	v_fmac_f32_e32 v200, v30, v62
	v_fmac_f32_e32 v201, v31, v63
	v_fmac_f32_e32 v202, v32, v64
	v_fmac_f32_e32 v203, v33, v65
	v_add_f32_e32 v200, v201, v200
	v_add_f32_e32 v202, v203, v202
	v_cvt_scalef32_pk32_f32_fp6 v[2:33], v[188:193], 1.0
	v_add_f32_e32 v200, v202, v200
	s_add_i32 s38, s24, 7
	v_readlane_b32 s26, v199, s38
	s_add_i32 s39, s23, 7
	v_readlane_b32 s25, v198, s39
	v_add_f32_dpp v200, v200, v200 quad_perm:[1,0,3,2] row_mask:0xf bank_mask:0xf bound_ctrl:1
	s_nop 1
	v_add_f32_dpp v200, v200, v200 quad_perm:[2,3,0,1] row_mask:0xf bank_mask:0xf bound_ctrl:1
	s_nop 1
	v_add_f32_dpp v200, v200, v200 row_half_mirror row_mask:0xf bank_mask:0xf bound_ctrl:1
	s_nop 1
	v_add_f32_dpp v200, v200, v200 row_mirror row_mask:0xf bank_mask:0xf bound_ctrl:1
	s_nop 1
	v_add_f32_dpp v200, v200, v200 row_bcast:15 row_mask:0xa bank_mask:0xf
	s_nop 1
	v_add_f32_dpp v200, v200, v200 row_bcast:31 row_mask:0xc bank_mask:0xf
	s_nop 0
	v_readlane_b32 s27, v200, 63
	v_mul_f32_e32 v204, s27, v212
	v_mul_f32_e32 v205, 0x3f3504f3, v204
	v_cmp_lt_f32_e64 s[32:33], |v205|, 1.0
	s_and_b64 vcc, exec, s[32:33]
	s_cbranch_vccnz .Lsm_15
	v_fma_f32 v208, |v205|, s9, v214
	v_fma_f32 v208, |v205|, v208, s10
	v_fma_f32 v208, |v205|, v208, s11
	v_fma_f32 v208, |v205|, v208, s12
	v_fma_f32 v208, |v205|, v208, s13
	v_fma_f32 v208, |v205|, v208, s14
	v_fma_f32 v208, |v205|, v208, |v205|
	v_mul_f32_e32 v209, 0xbfb8aa3b, v208
	v_fma_f32 v210, v208, s15, -v209
	v_rndne_f32_e32 v211, v209
	v_fmac_f32_e32 v210, 0xb2a5705f, v208
	v_sub_f32_e32 v209, v209, v211
	v_add_f32_e32 v209, v209, v210
	v_cvt_i32_f32_e32 v210, v211
	v_exp_f32_e32 v209, v209
	v_cmp_nlt_f32_e32 vcc, s16, v208
	v_ldexp_f32 v209, v209, v210
	s_nop 0
	v_cndmask_b32_e32 v209, 0, v209, vcc
	v_cmp_ngt_f32_e32 vcc, s17, v208
	s_nop 1
	v_cndmask_b32_e32 v208, v215, v209, vcc
	v_sub_f32_e32 v210, 1.0, v208
	s_branch .Ljn_15

; DEV float bflo(unsigned u) { return __uint_as_float(u << 16); }
; DEV float bfhi(unsigned u) { return __uint_as_float(u & 0xffff0000u); }
; DEV float gelu_exact(float v) { return 0.5f * v * (1.f + erff(v * 0.7071067811865476f)); }
; DEV void peer_gather_token(const Params& p, int tok) {
;     ...
;     const u16* hr = p.h + (size_t)tok * 2048 + lane * 32;
; #pragma unroll
;     for (int q = 0; q < 4; ++q) {
;       u32x4 v = *(const u32x4*)(hr + q * 8);
; #pragma unroll
;       for (int e = 0; e < 4; ++e) { hx[q * 8 + 2 * e] = bflo(v[e]); hx[q * 8 + 2 * e + 1] = bfhi(v[e]); }
;     }
;   }
; #pragma unroll
;   for (int e = 0; e < 32; ++e) acc[e] = 0.f;
;   const int e0 = p.eidx[(size_t)tok * 128 + lane], e1 = p.eidx[(size_t)tok * 128 + 64 + lane];
;   const int g0 = __builtin_bit_cast(int, p.gw[(size_t)tok * 128 + lane]), g1 = __builtin_bit_cast(int, p.gw[(size_t)tok * 128 + 64 + lane]);
;     ...
;       if (k + 3 < 128) issue(k + 3, (s + 3) & 3);
;       const v6u dq = v6u{dn[s][0][0], dn[s][0][1], dn[s][1][0], dn[s][1][1], dn[s][2][0], dn[s][2][1]};
;       const v32f dv = __builtin_amdgcn_cvt_scalef32_pk32_f32_fp6(dq, 1.0f);
;       float d0 = 0.f, d1 = 0.f, d2 = 0.f, d3 = 0.f;
; #pragma unroll
;       for (int i = 0; i < 8; ++i) { d0 += dv[4 * i] * hx[4 * i]; d1 += dv[4 * i + 1] * hx[4 * i + 1]; d2 += dv[4 * i + 2] * hx[4 * i + 2]; d3 += dv[4 * i + 3] * hx[4 * i + 3]; }
;       const float d = wave_sum_fast((d0 + d1) + (d2 + d3)) * (1.f / DOWN_SCALE);
;       const float gk = __builtin_bit_cast(float, (k < 64) ? __builtin_amdgcn_readlane(g0, k) : __builtin_amdgcn_readlane(g1, k - 64));
;       const float act = gelu_exact(d) * gk * (1.f / UP_SCALE);
;       const v6u uq = v6u{up[s][0][0], up[s][0][1], up[s][1][0], up[s][1][1], up[s][2][0], up[s][2][1]};
;       const v32f uv = __builtin_amdgcn_cvt_scalef32_pk32_f32_fp6(uq, 1.0f);
; #pragma unroll
;       for (int i = 0; i < 32; ++i) acc[i] += act * uv[i];
.Ljn_15:
	v_bfi_b32 v209, s18, v210, v205
	v_mul_f32_e32 v208, 0.5, v204
	v_add_f32_e32 v209, 1.0, v209
	v_mul_f32_e32 v208, v208, v209
	v_mul_f32_e32 v208, s26, v208
	v_mul_f32_e32 v206, 0x3e800000, v208
	v_pk_fma_f32 v[66:67], v[2:3], v[206:207], v[66:67] op_sel_hi:[1,0,1]
	v_pk_fma_f32 v[68:69], v[4:5], v[206:207], v[68:69] op_sel_hi:[1,0,1]
	v_pk_fma_f32 v[70:71], v[6:7], v[206:207], v[70:71] op_sel_hi:[1,0,1]
	v_pk_fma_f32 v[72:73], v[8:9], v[206:207], v[72:73] op_sel_hi:[1,0,1]
	v_pk_fma_f32 v[74:75], v[10:11], v[206:207], v[74:75] op_sel_hi:[1,0,1]
	v_pk_fma_f32 v[76:77], v[12:13], v[206:207], v[76:77] op_sel_hi:[1,0,1]
	v_pk_fma_f32 v[78:79], v[14:15], v[206:207], v[78:79] op_sel_hi:[1,0,1]
	v_pk_fma_f32 v[80:81], v[16:17], v[206:207], v[80:81] op_sel_hi:[1,0,1]
	v_pk_fma_f32 v[82:83], v[18:19], v[206:207], v[82:83] op_sel_hi:[1,0,1]
	v_pk_fma_f32 v[84:85], v[20:21], v[206:207], v[84:85] op_sel_hi:[1,0,1]
	v_pk_fma_f32 v[86:87], v[22:23], v[206:207], v[86:87] op_sel_hi:[1,0,1]
	v_pk_fma_f32 v[88:89], v[24:25], v[206:207], v[88:89] op_sel_hi:[1,0,1]
	v_pk_fma_f32 v[90:91], v[26:27], v[206:207], v[90:91] op_sel_hi:[1,0,1]
	v_pk_fma_f32 v[92:93], v[28:29], v[206:207], v[92:93] op_sel_hi:[1,0,1]
	v_pk_fma_f32 v[94:95], v[30:31], v[206:207], v[94:95] op_sel_hi:[1,0,1]
	v_pk_fma_f32 v[96:97], v[32:33], v[206:207], v[96:97] op_sel_hi:[1,0,1]
	s_mul_i32 s40, s25, 0xc00
	s_cmp_lt_u32 s25, 0x1800
	s_cselect_b64 s[28:29], s[2:3], s[4:5]
	s_cmp_lt_u32 s25, 0x2800
	s_cselect_b64 s[28:29], s[28:29], s[62:63]
	s_add_u32 s28, s28, s40
	s_addc_u32 s29, s29, 0
	global_load_dwordx4 v[182:185], v1, s[28:29]
	global_load_dwordx4 v[186:189], v1, s[28:29] offset:2048
	global_load_dwordx4 v[190:193], v1, s[28:29] offset:1024
	s_add_i32 s22, s22, 1
	s_add_i32 s23, s23, 8
	s_and_b32 s23, s23, 63
	s_add_i32 s24, s24, 8
	s_and_b32 s24, s24, 63
	s_cmp_lt_u32 s22, 14
	s_cbranch_scc1 .Lp12_main
	s_add_i32 s60, s20, s21
	s_cmpk_lt_u32 s60, 0x4000
	s_cselect_b32 s60, s60, s20
	s_lshl_b32 s38, s60, 9
	s_add_u32 s58, s66, s38
	s_addc_u32 s59, s67, 0
	global_load_dword v216, v242, s[58:59]
	global_load_dword v217, v242, s[58:59] offset:256
	s_add_u32 s58, s68, s38
	s_addc_u32 s59, s69, 0
	global_load_dword v218, v242, s[58:59]
	global_load_dword v219, v242, s[58:59] offset:256
	s_lshl_b32 s38, s60, 6
	s_add_u32 s58, s80, s38
	s_addc_u32 s59, s81, 0
	global_load_dwordx2 v[220:221], v246, s[58:59]
	global_load_dwordx2 v[222:223], v247, s[58:59]
	global_load_dwordx2 v[224:225], v248, s[58:59]
	global_load_dwordx2 v[226:227], v249, s[58:59]
	global_load_dwordx2 v[228:229], v250, s[58:59]
	global_load_dwordx2 v[230:231], v251, s[58:59]
	global_load_dwordx2 v[232:233], v252, s[58:59]
	global_load_dwordx2 v[234:235], v253, s[58:59]
	s_waitcnt vmcnt(33)
	v_cvt_scalef32_pk32_f32_fp6 v[2:33], v[98:103], 1.0
	v_mul_f32_e32 v200, v2, v34
	v_mul_f32_e32 v201, v3, v35
	v_mul_f32_e32 v202, v4, v36
	v_mul_f32_e32 v203, v5, v37
	v_fmac_f32_e32 v200, v6, v38
	v_fmac_f32_e32 v201, v7, v39
	v_fmac_f32_e32 v202, v8, v40
	v_fmac_f32_e32 v203, v9, v41
	v_fmac_f32_e32 v200, v10, v42
	v_fmac_f32_e32 v201, v11, v43
	v_fmac_f32_e32 v202, v12, v44
	v_fmac_f32_e32 v203, v13, v45
	v_fmac_f32_e32 v200, v14, v46
	v_fmac_f32_e32 v201, v15, v47
	v_fmac_f32_e32 v202, v16, v48
	v_fmac_f32_e32 v203, v17, v49
	v_fmac_f32_e32 v200, v18, v50
	v_fmac_f32_e32 v201, v19, v51
	v_fmac_f32_e32 v202, v20, v52
	v_fmac_f32_e32 v203, v21, v53
	v_fmac_f32_e32 v200, v22, v54
	v_fmac_f32_e32 v201, v23, v55
	v_fmac_f32_e32 v202, v24, v56
	v_fmac_f32_e32 v203, v25, v57
	v_fmac_f32_e32 v200, v26, v58
	v_fmac_f32_e32 v201, v27, v59
	v_fmac_f32_e32 v202, v28, v60
	v_fmac_f32_e32 v203, v29, v61
	v_fmac_f32_e32 v200, v30, v62
	v_fmac_f32_e32 v201, v31, v63
	v_fmac_f32_e32 v202, v32, v64
	v_fmac_f32_e32 v203, v33, v65
	v_add_f32_e32 v200, v201, v200
	v_add_f32_e32 v202, v203, v202
	v_cvt_scalef32_pk32_f32_fp6 v[2:33], v[104:109], 1.0
	v_add_f32_e32 v200, v202, v200
	s_add_i32 s38, s24, 0
	v_readlane_b32 s26, v199, s38
	s_add_i32 s39, s23, 0
	v_readlane_b32 s25, v198, s39
	v_add_f32_dpp v200, v200, v200 quad_perm:[1,0,3,2] row_mask:0xf bank_mask:0xf bound_ctrl:1
	s_nop 1
	v_add_f32_dpp v200, v200, v200 quad_perm:[2,3,0,1] row_mask:0xf bank_mask:0xf bound_ctrl:1
	s_nop 1
	v_add_f32_dpp v200, v200, v200 row_half_mirror row_mask:0xf bank_mask:0xf bound_ctrl:1
	s_nop 1
	v_add_f32_dpp v200, v200, v200 row_mirror row_mask:0xf bank_mask:0xf bound_ctrl:1
	s_nop 1
	v_add_f32_dpp v200, v200, v200 row_bcast:15 row_mask:0xa bank_mask:0xf
	s_nop 1
	v_add_f32_dpp v200, v200, v200 row_bcast:31 row_mask:0xc bank_mask:0xf
	s_nop 0
	v_readlane_b32 s27, v200, 63
	v_mul_f32_e32 v204, s27, v212
	v_mul_f32_e32 v205, 0x3f3504f3, v204
	v_cmp_lt_f32_e64 s[32:33], |v205|, 1.0
	s_and_b64 vcc, exec, s[32:33]
	s_cbranch_vccnz .Lsm_17
	v_fma_f32 v208, |v205|, s9, v214
	v_fma_f32 v208, |v205|, v208, s10
	v_fma_f32 v208, |v205|, v208, s11
	v_fma_f32 v208, |v205|, v208, s12
	v_fma_f32 v208, |v205|, v208, s13
	v_fma_f32 v208, |v205|, v208, s14
	v_fma_f32 v208, |v205|, v208, |v205|
	v_mul_f32_e32 v209, 0xbfb8aa3b, v208
	v_fma_f32 v210, v208, s15, -v209
	v_rndne_f32_e32 v211, v209
	v_fmac_f32_e32 v210, 0xb2a5705f, v208
	v_sub_f32_e32 v209, v209, v211
	v_add_f32_e32 v209, v209, v210
	v_cvt_i32_f32_e32 v210, v211
	v_exp_f32_e32 v209, v209
	v_cmp_nlt_f32_e32 vcc, s16, v208
	v_ldexp_f32 v209, v209, v210
	s_nop 0
	v_cndmask_b32_e32 v209, 0, v209, vcc
	v_cmp_ngt_f32_e32 vcc, s17, v208
	s_nop 1
	v_cndmask_b32_e32 v208, v215, v209, vcc
	v_sub_f32_e32 v210, 1.0, v208
	s_branch .Ljn_17

; DEV float gelu_exact(float v) { return 0.5f * v * (1.f + erff(v * 0.7071067811865476f)); }
; DEV void peer_gather_token(const Params& p, int tok) {
;     ...
;       if (k + 3 < 128) issue(k + 3, (s + 3) & 3);
;       const v6u dq = v6u{dn[s][0][0], dn[s][0][1], dn[s][1][0], dn[s][1][1], dn[s][2][0], dn[s][2][1]};
;       const v32f dv = __builtin_amdgcn_cvt_scalef32_pk32_f32_fp6(dq, 1.0f);
;       float d0 = 0.f, d1 = 0.f, d2 = 0.f, d3 = 0.f;
; #pragma unroll
;       for (int i = 0; i < 8; ++i) { d0 += dv[4 * i] * hx[4 * i]; d1 += dv[4 * i + 1] * hx[4 * i + 1]; d2 += dv[4 * i + 2] * hx[4 * i + 2]; d3 += dv[4 * i + 3] * hx[4 * i + 3]; }
;       const float d = wave_sum_fast((d0 + d1) + (d2 + d3)) * (1.f / DOWN_SCALE);
;       const float gk = __builtin_bit_cast(float, (k < 64) ? __builtin_amdgcn_readlane(g0, k) : __builtin_amdgcn_readlane(g1, k - 64));
;       const float act = gelu_exact(d) * gk * (1.f / UP_SCALE);
;       const v6u uq = v6u{up[s][0][0], up[s][0][1], up[s][1][0], up[s][1][1], up[s][2][0], up[s][2][1]};
;       const v32f uv = __builtin_amdgcn_cvt_scalef32_pk32_f32_fp6(uq, 1.0f);
; #pragma unroll
;       for (int i = 0; i < 32; ++i) acc[i] += act * uv[i];
.Ljn_17:
	v_bfi_b32 v209, s18, v210, v205
	v_mul_f32_e32 v208, 0.5, v204
	v_add_f32_e32 v209, 1.0, v209
	v_mul_f32_e32 v208, v208, v209
	v_mul_f32_e32 v208, s26, v208
	v_mul_f32_e32 v206, 0x3e800000, v208
	v_pk_fma_f32 v[66:67], v[2:3], v[206:207], v[66:67] op_sel_hi:[1,0,1]
	v_pk_fma_f32 v[68:69], v[4:5], v[206:207], v[68:69] op_sel_hi:[1,0,1]
	v_pk_fma_f32 v[70:71], v[6:7], v[206:207], v[70:71] op_sel_hi:[1,0,1]
	v_pk_fma_f32 v[72:73], v[8:9], v[206:207], v[72:73] op_sel_hi:[1,0,1]
	v_pk_fma_f32 v[74:75], v[10:11], v[206:207], v[74:75] op_sel_hi:[1,0,1]
	v_pk_fma_f32 v[76:77], v[12:13], v[206:207], v[76:77] op_sel_hi:[1,0,1]
	v_pk_fma_f32 v[78:79], v[14:15], v[206:207], v[78:79] op_sel_hi:[1,0,1]
	v_pk_fma_f32 v[80:81], v[16:17], v[206:207], v[80:81] op_sel_hi:[1,0,1]
	v_pk_fma_f32 v[82:83], v[18:19], v[206:207], v[82:83] op_sel_hi:[1,0,1]
	v_pk_fma_f32 v[84:85], v[20:21], v[206:207], v[84:85] op_sel_hi:[1,0,1]
	v_pk_fma_f32 v[86:87], v[22:23], v[206:207], v[86:87] op_sel_hi:[1,0,1]
	v_pk_fma_f32 v[88:89], v[24:25], v[206:207], v[88:89] op_sel_hi:[1,0,1]
	v_pk_fma_f32 v[90:91], v[26:27], v[206:207], v[90:91] op_sel_hi:[1,0,1]
	v_pk_fma_f32 v[92:93], v[28:29], v[206:207], v[92:93] op_sel_hi:[1,0,1]
	v_pk_fma_f32 v[94:95], v[30:31], v[206:207], v[94:95] op_sel_hi:[1,0,1]
	v_pk_fma_f32 v[96:97], v[32:33], v[206:207], v[96:97] op_sel_hi:[1,0,1]
	s_mul_i32 s40, s25, 0xc00
	s_cmp_lt_u32 s25, 0x1800
	s_cselect_b64 s[28:29], s[2:3], s[4:5]
	s_cmp_lt_u32 s25, 0x2800
	s_cselect_b64 s[28:29], s[28:29], s[62:63]
	s_add_u32 s28, s28, s40
	s_addc_u32 s29, s29, 0
	global_load_dwordx4 v[98:101], v1, s[28:29]
	global_load_dwordx4 v[102:105], v1, s[28:29] offset:2048
	global_load_dwordx4 v[106:109], v1, s[28:29] offset:1024
	s_waitcnt vmcnt(33)
	v_cvt_scalef32_pk32_f32_fp6 v[2:33], v[110:115], 1.0
	v_mul_f32_e32 v200, v2, v34
	v_mul_f32_e32 v201, v3, v35
	v_mul_f32_e32 v202, v4, v36
	v_mul_f32_e32 v203, v5, v37
	v_fmac_f32_e32 v200, v6, v38
	v_fmac_f32_e32 v201, v7, v39
	v_fmac_f32_e32 v202, v8, v40
	v_fmac_f32_e32 v203, v9, v41
	v_fmac_f32_e32 v200, v10, v42
	v_fmac_f32_e32 v201, v11, v43
	v_fmac_f32_e32 v202, v12, v44
	v_fmac_f32_e32 v203, v13, v45
	v_fmac_f32_e32 v200, v14, v46
	v_fmac_f32_e32 v201, v15, v47
	v_fmac_f32_e32 v202, v16, v48
	v_fmac_f32_e32 v203, v17, v49
	v_fmac_f32_e32 v200, v18, v50
	v_fmac_f32_e32 v201, v19, v51
	v_fmac_f32_e32 v202, v20, v52
	v_fmac_f32_e32 v203, v21, v53
	v_fmac_f32_e32 v200, v22, v54
	v_fmac_f32_e32 v201, v23, v55
	v_fmac_f32_e32 v202, v24, v56
	v_fmac_f32_e32 v203, v25, v57
	v_fmac_f32_e32 v200, v26, v58
	v_fmac_f32_e32 v201, v27, v59
	v_fmac_f32_e32 v202, v28, v60
	v_fmac_f32_e32 v203, v29, v61
	v_fmac_f32_e32 v200, v30, v62
	v_fmac_f32_e32 v201, v31, v63
	v_fmac_f32_e32 v202, v32, v64
	v_fmac_f32_e32 v203, v33, v65
	v_add_f32_e32 v200, v201, v200
	v_add_f32_e32 v202, v203, v202
	v_cvt_scalef32_pk32_f32_fp6 v[2:33], v[116:121], 1.0
	v_add_f32_e32 v200, v202, v200
	s_add_i32 s38, s24, 1
	v_readlane_b32 s26, v199, s38
	s_add_i32 s39, s23, 1
	v_readlane_b32 s25, v198, s39
	v_add_f32_dpp v200, v200, v200 quad_perm:[1,0,3,2] row_mask:0xf bank_mask:0xf bound_ctrl:1
	s_nop 1
	v_add_f32_dpp v200, v200, v200 quad_perm:[2,3,0,1] row_mask:0xf bank_mask:0xf bound_ctrl:1
	s_nop 1
	v_add_f32_dpp v200, v200, v200 row_half_mirror row_mask:0xf bank_mask:0xf bound_ctrl:1
	s_nop 1
	v_add_f32_dpp v200, v200, v200 row_mirror row_mask:0xf bank_mask:0xf bound_ctrl:1
	s_nop 1
	v_add_f32_dpp v200, v200, v200 row_bcast:15 row_mask:0xa bank_mask:0xf
	s_nop 1
	v_add_f32_dpp v200, v200, v200 row_bcast:31 row_mask:0xc bank_mask:0xf
	s_nop 0
	v_readlane_b32 s27, v200, 63
	v_mul_f32_e32 v204, s27, v212
	v_mul_f32_e32 v205, 0x3f3504f3, v204
	v_cmp_lt_f32_e64 s[32:33], |v205|, 1.0
	s_and_b64 vcc, exec, s[32:33]
	s_cbranch_vccnz .Lsm_19
	v_fma_f32 v208, |v205|, s9, v214
	v_fma_f32 v208, |v205|, v208, s10
	v_fma_f32 v208, |v205|, v208, s11
	v_fma_f32 v208, |v205|, v208, s12
	v_fma_f32 v208, |v205|, v208, s13
	v_fma_f32 v208, |v205|, v208, s14
	v_fma_f32 v208, |v205|, v208, |v205|
	v_mul_f32_e32 v209, 0xbfb8aa3b, v208
	v_fma_f32 v210, v208, s15, -v209
	v_rndne_f32_e32 v211, v209
	v_fmac_f32_e32 v210, 0xb2a5705f, v208
	v_sub_f32_e32 v209, v209, v211
	v_add_f32_e32 v209, v209, v210
	v_cvt_i32_f32_e32 v210, v211
	v_exp_f32_e32 v209, v209
	v_cmp_nlt_f32_e32 vcc, s16, v208
	v_ldexp_f32 v209, v209, v210
	s_nop 0
	v_cndmask_b32_e32 v209, 0, v209, vcc
	v_cmp_ngt_f32_e32 vcc, s17, v208
	s_nop 1
	v_cndmask_b32_e32 v208, v215, v209, vcc
	v_sub_f32_e32 v210, 1.0, v208
	s_branch .Ljn_19

; DEV float gelu_exact(float v) { return 0.5f * v * (1.f + erff(v * 0.7071067811865476f)); }
; DEV void peer_gather_token(const Params& p, int tok) {
;     ...
;       if (k + 3 < 128) issue(k + 3, (s + 3) & 3);
;       const v6u dq = v6u{dn[s][0][0], dn[s][0][1], dn[s][1][0], dn[s][1][1], dn[s][2][0], dn[s][2][1]};
;       const v32f dv = __builtin_amdgcn_cvt_scalef32_pk32_f32_fp6(dq, 1.0f);
;       float d0 = 0.f, d1 = 0.f, d2 = 0.f, d3 = 0.f;
; #pragma unroll
;       for (int i = 0; i < 8; ++i) { d0 += dv[4 * i] * hx[4 * i]; d1 += dv[4 * i + 1] * hx[4 * i + 1]; d2 += dv[4 * i + 2] * hx[4 * i + 2]; d3 += dv[4 * i + 3] * hx[4 * i + 3]; }
;       const float d = wave_sum_fast((d0 + d1) + (d2 + d3)) * (1.f / DOWN_SCALE);
;       const float gk = __builtin_bit_cast(float, (k < 64) ? __builtin_amdgcn_readlane(g0, k) : __builtin_amdgcn_readlane(g1, k - 64));
;       const float act = gelu_exact(d) * gk * (1.f / UP_SCALE);
;       const v6u uq = v6u{up[s][0][0], up[s][0][1], up[s][1][0], up[s][1][1], up[s][2][0], up[s][2][1]};
;       const v32f uv = __builtin_amdgcn_cvt_scalef32_pk32_f32_fp6(uq, 1.0f);
; #pragma unroll
;       for (int i = 0; i < 32; ++i) acc[i] += act * uv[i];
.Ljn_19:
	v_bfi_b32 v209, s18, v210, v205
	v_mul_f32_e32 v208, 0.5, v204
	v_add_f32_e32 v209, 1.0, v209
	v_mul_f32_e32 v208, v208, v209
	v_mul_f32_e32 v208, s26, v208
	v_mul_f32_e32 v206, 0x3e800000, v208
	v_pk_fma_f32 v[66:67], v[2:3], v[206:207], v[66:67] op_sel_hi:[1,0,1]
	v_pk_fma_f32 v[68:69], v[4:5], v[206:207], v[68:69] op_sel_hi:[1,0,1]
	v_pk_fma_f32 v[70:71], v[6:7], v[206:207], v[70:71] op_sel_hi:[1,0,1]
	v_pk_fma_f32 v[72:73], v[8:9], v[206:207], v[72:73] op_sel_hi:[1,0,1]
	v_pk_fma_f32 v[74:75], v[10:11], v[206:207], v[74:75] op_sel_hi:[1,0,1]
	v_pk_fma_f32 v[76:77], v[12:13], v[206:207], v[76:77] op_sel_hi:[1,0,1]
	v_pk_fma_f32 v[78:79], v[14:15], v[206:207], v[78:79] op_sel_hi:[1,0,1]
	v_pk_fma_f32 v[80:81], v[16:17], v[206:207], v[80:81] op_sel_hi:[1,0,1]
	v_pk_fma_f32 v[82:83], v[18:19], v[206:207], v[82:83] op_sel_hi:[1,0,1]
	v_pk_fma_f32 v[84:85], v[20:21], v[206:207], v[84:85] op_sel_hi:[1,0,1]
	v_pk_fma_f32 v[86:87], v[22:23], v[206:207], v[86:87] op_sel_hi:[1,0,1]
	v_pk_fma_f32 v[88:89], v[24:25], v[206:207], v[88:89] op_sel_hi:[1,0,1]
	v_pk_fma_f32 v[90:91], v[26:27], v[206:207], v[90:91] op_sel_hi:[1,0,1]
	v_pk_fma_f32 v[92:93], v[28:29], v[206:207], v[92:93] op_sel_hi:[1,0,1]
	v_pk_fma_f32 v[94:95], v[30:31], v[206:207], v[94:95] op_sel_hi:[1,0,1]
	v_pk_fma_f32 v[96:97], v[32:33], v[206:207], v[96:97] op_sel_hi:[1,0,1]
	s_mul_i32 s40, s25, 0xc00
	s_cmp_lt_u32 s25, 0x1800
	s_cselect_b64 s[28:29], s[2:3], s[4:5]
	s_cmp_lt_u32 s25, 0x2800
	s_cselect_b64 s[28:29], s[28:29], s[62:63]
	s_add_u32 s28, s28, s40
	s_addc_u32 s29, s29, 0
	global_load_dwordx4 v[110:113], v1, s[28:29]
	global_load_dwordx4 v[114:117], v1, s[28:29] offset:2048
	global_load_dwordx4 v[118:121], v1, s[28:29] offset:1024
	s_waitcnt vmcnt(33)
	v_cvt_scalef32_pk32_f32_fp6 v[2:33], v[122:127], 1.0
	v_mul_f32_e32 v200, v2, v34
	v_mul_f32_e32 v201, v3, v35
	v_mul_f32_e32 v202, v4, v36
	v_mul_f32_e32 v203, v5, v37
	v_fmac_f32_e32 v200, v6, v38
	v_fmac_f32_e32 v201, v7, v39
	v_fmac_f32_e32 v202, v8, v40
	v_fmac_f32_e32 v203, v9, v41
	v_fmac_f32_e32 v200, v10, v42
	v_fmac_f32_e32 v201, v11, v43
	v_fmac_f32_e32 v202, v12, v44
	v_fmac_f32_e32 v203, v13, v45
	v_fmac_f32_e32 v200, v14, v46
	v_fmac_f32_e32 v201, v15, v47
	v_fmac_f32_e32 v202, v16, v48
	v_fmac_f32_e32 v203, v17, v49
	v_fmac_f32_e32 v200, v18, v50
	v_fmac_f32_e32 v201, v19, v51
	v_fmac_f32_e32 v202, v20, v52
	v_fmac_f32_e32 v203, v21, v53
	v_fmac_f32_e32 v200, v22, v54
	v_fmac_f32_e32 v201, v23, v55
	v_fmac_f32_e32 v202, v24, v56
	v_fmac_f32_e32 v203, v25, v57
	v_fmac_f32_e32 v200, v26, v58
	v_fmac_f32_e32 v201, v27, v59
	v_fmac_f32_e32 v202, v28, v60
	v_fmac_f32_e32 v203, v29, v61
	v_fmac_f32_e32 v200, v30, v62
	v_fmac_f32_e32 v201, v31, v63
	v_fmac_f32_e32 v202, v32, v64
	v_fmac_f32_e32 v203, v33, v65
	v_add_f32_e32 v200, v201, v200
	v_add_f32_e32 v202, v203, v202
	v_cvt_scalef32_pk32_f32_fp6 v[2:33], v[128:133], 1.0
	v_add_f32_e32 v200, v202, v200
	s_add_i32 s38, s24, 2
	v_readlane_b32 s26, v199, s38
	s_add_i32 s39, s23, 2
	v_readlane_b32 s25, v198, s39
	v_add_f32_dpp v200, v200, v200 quad_perm:[1,0,3,2] row_mask:0xf bank_mask:0xf bound_ctrl:1
	s_nop 1
	v_add_f32_dpp v200, v200, v200 quad_perm:[2,3,0,1] row_mask:0xf bank_mask:0xf bound_ctrl:1
	s_nop 1
	v_add_f32_dpp v200, v200, v200 row_half_mirror row_mask:0xf bank_mask:0xf bound_ctrl:1
	s_nop 1
	v_add_f32_dpp v200, v200, v200 row_mirror row_mask:0xf bank_mask:0xf bound_ctrl:1
	s_nop 1
	v_add_f32_dpp v200, v200, v200 row_bcast:15 row_mask:0xa bank_mask:0xf
	s_nop 1
	v_add_f32_dpp v200, v200, v200 row_bcast:31 row_mask:0xc bank_mask:0xf
	s_nop 0
	v_readlane_b32 s27, v200, 63
	v_mul_f32_e32 v204, s27, v212
	v_mul_f32_e32 v205, 0x3f3504f3, v204
	v_cmp_lt_f32_e64 s[32:33], |v205|, 1.0
	s_and_b64 vcc, exec, s[32:33]
	s_cbranch_vccnz .Lsm_21
	v_fma_f32 v208, |v205|, s9, v214
	v_fma_f32 v208, |v205|, v208, s10
	v_fma_f32 v208, |v205|, v208, s11
	v_fma_f32 v208, |v205|, v208, s12
	v_fma_f32 v208, |v205|, v208, s13
	v_fma_f32 v208, |v205|, v208, s14
	v_fma_f32 v208, |v205|, v208, |v205|
	v_mul_f32_e32 v209, 0xbfb8aa3b, v208
	v_fma_f32 v210, v208, s15, -v209
	v_rndne_f32_e32 v211, v209
	v_fmac_f32_e32 v210, 0xb2a5705f, v208
	v_sub_f32_e32 v209, v209, v211
	v_add_f32_e32 v209, v209, v210
	v_cvt_i32_f32_e32 v210, v211
	v_exp_f32_e32 v209, v209
	v_cmp_nlt_f32_e32 vcc, s16, v208
	v_ldexp_f32 v209, v209, v210
	s_nop 0
	v_cndmask_b32_e32 v209, 0, v209, vcc
	v_cmp_ngt_f32_e32 vcc, s17, v208
	s_nop 1
	v_cndmask_b32_e32 v208, v215, v209, vcc
	v_sub_f32_e32 v210, 1.0, v208
	s_branch .Ljn_21

; DEV float gelu_exact(float v) { return 0.5f * v * (1.f + erff(v * 0.7071067811865476f)); }
; DEV void peer_gather_token(const Params& p, int tok) {
;     ...
;       if (k + 3 < 128) issue(k + 3, (s + 3) & 3);
;       const v6u dq = v6u{dn[s][0][0], dn[s][0][1], dn[s][1][0], dn[s][1][1], dn[s][2][0], dn[s][2][1]};
;       const v32f dv = __builtin_amdgcn_cvt_scalef32_pk32_f32_fp6(dq, 1.0f);
;       float d0 = 0.f, d1 = 0.f, d2 = 0.f, d3 = 0.f;
; #pragma unroll
;       for (int i = 0; i < 8; ++i) { d0 += dv[4 * i] * hx[4 * i]; d1 += dv[4 * i + 1] * hx[4 * i + 1]; d2 += dv[4 * i + 2] * hx[4 * i + 2]; d3 += dv[4 * i + 3] * hx[4 * i + 3]; }
;       const float d = wave_sum_fast((d0 + d1) + (d2 + d3)) * (1.f / DOWN_SCALE);
;       const float gk = __builtin_bit_cast(float, (k < 64) ? __builtin_amdgcn_readlane(g0, k) : __builtin_amdgcn_readlane(g1, k - 64));
;       const float act = gelu_exact(d) * gk * (1.f / UP_SCALE);
;       const v6u uq = v6u{up[s][0][0], up[s][0][1], up[s][1][0], up[s][1][1], up[s][2][0], up[s][2][1]};
;       const v32f uv = __builtin_amdgcn_cvt_scalef32_pk32_f32_fp6(uq, 1.0f);
; #pragma unroll
;       for (int i = 0; i < 32; ++i) acc[i] += act * uv[i];
.Ljn_21:
	v_bfi_b32 v209, s18, v210, v205
	v_mul_f32_e32 v208, 0.5, v204
	v_add_f32_e32 v209, 1.0, v209
	v_mul_f32_e32 v208, v208, v209
	v_mul_f32_e32 v208, s26, v208
	v_mul_f32_e32 v206, 0x3e800000, v208
	v_pk_fma_f32 v[66:67], v[2:3], v[206:207], v[66:67] op_sel_hi:[1,0,1]
	v_pk_fma_f32 v[68:69], v[4:5], v[206:207], v[68:69] op_sel_hi:[1,0,1]
	v_pk_fma_f32 v[70:71], v[6:7], v[206:207], v[70:71] op_sel_hi:[1,0,1]
	v_pk_fma_f32 v[72:73], v[8:9], v[206:207], v[72:73] op_sel_hi:[1,0,1]
	v_pk_fma_f32 v[74:75], v[10:11], v[206:207], v[74:75] op_sel_hi:[1,0,1]
	v_pk_fma_f32 v[76:77], v[12:13], v[206:207], v[76:77] op_sel_hi:[1,0,1]
	v_pk_fma_f32 v[78:79], v[14:15], v[206:207], v[78:79] op_sel_hi:[1,0,1]
	v_pk_fma_f32 v[80:81], v[16:17], v[206:207], v[80:81] op_sel_hi:[1,0,1]
	v_pk_fma_f32 v[82:83], v[18:19], v[206:207], v[82:83] op_sel_hi:[1,0,1]
	v_pk_fma_f32 v[84:85], v[20:21], v[206:207], v[84:85] op_sel_hi:[1,0,1]
	v_pk_fma_f32 v[86:87], v[22:23], v[206:207], v[86:87] op_sel_hi:[1,0,1]
	v_pk_fma_f32 v[88:89], v[24:25], v[206:207], v[88:89] op_sel_hi:[1,0,1]
	v_pk_fma_f32 v[90:91], v[26:27], v[206:207], v[90:91] op_sel_hi:[1,0,1]
	v_pk_fma_f32 v[92:93], v[28:29], v[206:207], v[92:93] op_sel_hi:[1,0,1]
	v_pk_fma_f32 v[94:95], v[30:31], v[206:207], v[94:95] op_sel_hi:[1,0,1]
	v_pk_fma_f32 v[96:97], v[32:33], v[206:207], v[96:97] op_sel_hi:[1,0,1]
	s_mul_i32 s40, s25, 0xc00
	s_cmp_lt_u32 s25, 0x1800
	s_cselect_b64 s[28:29], s[2:3], s[4:5]
	s_cmp_lt_u32 s25, 0x2800
	s_cselect_b64 s[28:29], s[28:29], s[62:63]
	s_add_u32 s28, s28, s40
	s_addc_u32 s29, s29, 0
	global_load_dwordx4 v[122:125], v1, s[28:29]
	global_load_dwordx4 v[126:129], v1, s[28:29] offset:2048
	global_load_dwordx4 v[130:133], v1, s[28:29] offset:1024
	s_waitcnt vmcnt(33)
	v_cvt_scalef32_pk32_f32_fp6 v[2:33], v[134:139], 1.0
	v_mul_f32_e32 v200, v2, v34
	v_mul_f32_e32 v201, v3, v35
	v_mul_f32_e32 v202, v4, v36
	v_mul_f32_e32 v203, v5, v37
	v_fmac_f32_e32 v200, v6, v38
	v_fmac_f32_e32 v201, v7, v39
	v_fmac_f32_e32 v202, v8, v40
	v_fmac_f32_e32 v203, v9, v41
	v_fmac_f32_e32 v200, v10, v42
	v_fmac_f32_e32 v201, v11, v43
	v_fmac_f32_e32 v202, v12, v44
	v_fmac_f32_e32 v203, v13, v45
	v_fmac_f32_e32 v200, v14, v46
	v_fmac_f32_e32 v201, v15, v47
	v_fmac_f32_e32 v202, v16, v48
	v_fmac_f32_e32 v203, v17, v49
	v_fmac_f32_e32 v200, v18, v50
	v_fmac_f32_e32 v201, v19, v51
	v_fmac_f32_e32 v202, v20, v52
	v_fmac_f32_e32 v203, v21, v53
	v_fmac_f32_e32 v200, v22, v54
	v_fmac_f32_e32 v201, v23, v55
	v_fmac_f32_e32 v202, v24, v56
	v_fmac_f32_e32 v203, v25, v57
	v_fmac_f32_e32 v200, v26, v58
	v_fmac_f32_e32 v201, v27, v59
	v_fmac_f32_e32 v202, v28, v60
	v_fmac_f32_e32 v203, v29, v61
	v_fmac_f32_e32 v200, v30, v62
	v_fmac_f32_e32 v201, v31, v63
	v_fmac_f32_e32 v202, v32, v64
	v_fmac_f32_e32 v203, v33, v65
	v_add_f32_e32 v200, v201, v200
	v_add_f32_e32 v202, v203, v202
	v_cvt_scalef32_pk32_f32_fp6 v[2:33], v[140:145], 1.0
	v_add_f32_e32 v200, v202, v200
	s_add_i32 s38, s24, 3
	v_readlane_b32 s26, v199, s38
	s_add_i32 s39, s23, 3
	v_readlane_b32 s25, v198, s39
	v_add_f32_dpp v200, v200, v200 quad_perm:[1,0,3,2] row_mask:0xf bank_mask:0xf bound_ctrl:1
	s_nop 1
	v_add_f32_dpp v200, v200, v200 quad_perm:[2,3,0,1] row_mask:0xf bank_mask:0xf bound_ctrl:1
	s_nop 1
	v_add_f32_dpp v200, v200, v200 row_half_mirror row_mask:0xf bank_mask:0xf bound_ctrl:1
	s_nop 1
	v_add_f32_dpp v200, v200, v200 row_mirror row_mask:0xf bank_mask:0xf bound_ctrl:1
	s_nop 1
	v_add_f32_dpp v200, v200, v200 row_bcast:15 row_mask:0xa bank_mask:0xf
	s_nop 1
	v_add_f32_dpp v200, v200, v200 row_bcast:31 row_mask:0xc bank_mask:0xf
	s_nop 0
	v_readlane_b32 s27, v200, 63
	v_mul_f32_e32 v204, s27, v212
	v_mul_f32_e32 v205, 0x3f3504f3, v204
	v_cmp_lt_f32_e64 s[32:33], |v205|, 1.0
	s_and_b64 vcc, exec, s[32:33]
	s_cbranch_vccnz .Lsm_23
	v_fma_f32 v208, |v205|, s9, v214
	v_fma_f32 v208, |v205|, v208, s10
	v_fma_f32 v208, |v205|, v208, s11
	v_fma_f32 v208, |v205|, v208, s12
	v_fma_f32 v208, |v205|, v208, s13
	v_fma_f32 v208, |v205|, v208, s14
	v_fma_f32 v208, |v205|, v208, |v205|
	v_mul_f32_e32 v209, 0xbfb8aa3b, v208
	v_fma_f32 v210, v208, s15, -v209
	v_rndne_f32_e32 v211, v209
	v_fmac_f32_e32 v210, 0xb2a5705f, v208
	v_sub_f32_e32 v209, v209, v211
	v_add_f32_e32 v209, v209, v210
	v_cvt_i32_f32_e32 v210, v211
	v_exp_f32_e32 v209, v209
	v_cmp_nlt_f32_e32 vcc, s16, v208
	v_ldexp_f32 v209, v209, v210
	s_nop 0
	v_cndmask_b32_e32 v209, 0, v209, vcc
	v_cmp_ngt_f32_e32 vcc, s17, v208
	s_nop 1
	v_cndmask_b32_e32 v208, v215, v209, vcc
	v_sub_f32_e32 v210, 1.0, v208
	s_branch .Ljn_23

; DEV float gelu_exact(float v) { return 0.5f * v * (1.f + erff(v * 0.7071067811865476f)); }
; DEV void peer_gather_token(const Params& p, int tok) {
;     ...
;       if (k + 3 < 128) issue(k + 3, (s + 3) & 3);
;       const v6u dq = v6u{dn[s][0][0], dn[s][0][1], dn[s][1][0], dn[s][1][1], dn[s][2][0], dn[s][2][1]};
;       const v32f dv = __builtin_amdgcn_cvt_scalef32_pk32_f32_fp6(dq, 1.0f);
;       float d0 = 0.f, d1 = 0.f, d2 = 0.f, d3 = 0.f;
; #pragma unroll
;       for (int i = 0; i < 8; ++i) { d0 += dv[4 * i] * hx[4 * i]; d1 += dv[4 * i + 1] * hx[4 * i + 1]; d2 += dv[4 * i + 2] * hx[4 * i + 2]; d3 += dv[4 * i + 3] * hx[4 * i + 3]; }
;       const float d = wave_sum_fast((d0 + d1) + (d2 + d3)) * (1.f / DOWN_SCALE);
;       const float gk = __builtin_bit_cast(float, (k < 64) ? __builtin_amdgcn_readlane(g0, k) : __builtin_amdgcn_readlane(g1, k - 64));
;       const float act = gelu_exact(d) * gk * (1.f / UP_SCALE);
;       const v6u uq = v6u{up[s][0][0], up[s][0][1], up[s][1][0], up[s][1][1], up[s][2][0], up[s][2][1]};
;       const v32f uv = __builtin_amdgcn_cvt_scalef32_pk32_f32_fp6(uq, 1.0f);
; #pragma unroll
;       for (int i = 0; i < 32; ++i) acc[i] += act * uv[i];
.Ljn_23:
	v_bfi_b32 v209, s18, v210, v205
	v_mul_f32_e32 v208, 0.5, v204
	v_add_f32_e32 v209, 1.0, v209
	v_mul_f32_e32 v208, v208, v209
	v_mul_f32_e32 v208, s26, v208
	v_mul_f32_e32 v206, 0x3e800000, v208
	v_pk_fma_f32 v[66:67], v[2:3], v[206:207], v[66:67] op_sel_hi:[1,0,1]
	v_pk_fma_f32 v[68:69], v[4:5], v[206:207], v[68:69] op_sel_hi:[1,0,1]
	v_pk_fma_f32 v[70:71], v[6:7], v[206:207], v[70:71] op_sel_hi:[1,0,1]
	v_pk_fma_f32 v[72:73], v[8:9], v[206:207], v[72:73] op_sel_hi:[1,0,1]
	v_pk_fma_f32 v[74:75], v[10:11], v[206:207], v[74:75] op_sel_hi:[1,0,1]
	v_pk_fma_f32 v[76:77], v[12:13], v[206:207], v[76:77] op_sel_hi:[1,0,1]
	v_pk_fma_f32 v[78:79], v[14:15], v[206:207], v[78:79] op_sel_hi:[1,0,1]
	v_pk_fma_f32 v[80:81], v[16:17], v[206:207], v[80:81] op_sel_hi:[1,0,1]
	v_pk_fma_f32 v[82:83], v[18:19], v[206:207], v[82:83] op_sel_hi:[1,0,1]
	v_pk_fma_f32 v[84:85], v[20:21], v[206:207], v[84:85] op_sel_hi:[1,0,1]
	v_pk_fma_f32 v[86:87], v[22:23], v[206:207], v[86:87] op_sel_hi:[1,0,1]
	v_pk_fma_f32 v[88:89], v[24:25], v[206:207], v[88:89] op_sel_hi:[1,0,1]
	v_pk_fma_f32 v[90:91], v[26:27], v[206:207], v[90:91] op_sel_hi:[1,0,1]
	v_pk_fma_f32 v[92:93], v[28:29], v[206:207], v[92:93] op_sel_hi:[1,0,1]
	v_pk_fma_f32 v[94:95], v[30:31], v[206:207], v[94:95] op_sel_hi:[1,0,1]
	v_pk_fma_f32 v[96:97], v[32:33], v[206:207], v[96:97] op_sel_hi:[1,0,1]
	s_mul_i32 s40, s25, 0xc00
	s_cmp_lt_u32 s25, 0x1800
	s_cselect_b64 s[28:29], s[2:3], s[4:5]
	s_cmp_lt_u32 s25, 0x2800
	s_cselect_b64 s[28:29], s[28:29], s[62:63]
	s_add_u32 s28, s28, s40
	s_addc_u32 s29, s29, 0
	global_load_dwordx4 v[134:137], v1, s[28:29]
	global_load_dwordx4 v[138:141], v1, s[28:29] offset:2048
	global_load_dwordx4 v[142:145], v1, s[28:29] offset:1024
	s_waitcnt vmcnt(33)
	v_cvt_scalef32_pk32_f32_fp6 v[2:33], v[146:151], 1.0
	v_mul_f32_e32 v200, v2, v34
	v_mul_f32_e32 v201, v3, v35
	v_mul_f32_e32 v202, v4, v36
	v_mul_f32_e32 v203, v5, v37
	v_fmac_f32_e32 v200, v6, v38
	v_fmac_f32_e32 v201, v7, v39
	v_fmac_f32_e32 v202, v8, v40
	v_fmac_f32_e32 v203, v9, v41
	v_fmac_f32_e32 v200, v10, v42
	v_fmac_f32_e32 v201, v11, v43
	v_fmac_f32_e32 v202, v12, v44
	v_fmac_f32_e32 v203, v13, v45
	v_fmac_f32_e32 v200, v14, v46
	v_fmac_f32_e32 v201, v15, v47
	v_fmac_f32_e32 v202, v16, v48
	v_fmac_f32_e32 v203, v17, v49
	v_fmac_f32_e32 v200, v18, v50
	v_fmac_f32_e32 v201, v19, v51
	v_fmac_f32_e32 v202, v20, v52
	v_fmac_f32_e32 v203, v21, v53
	v_fmac_f32_e32 v200, v22, v54
	v_fmac_f32_e32 v201, v23, v55
	v_fmac_f32_e32 v202, v24, v56
	v_fmac_f32_e32 v203, v25, v57
	v_fmac_f32_e32 v200, v26, v58
	v_fmac_f32_e32 v201, v27, v59
	v_fmac_f32_e32 v202, v28, v60
	v_fmac_f32_e32 v203, v29, v61
	v_fmac_f32_e32 v200, v30, v62
	v_fmac_f32_e32 v201, v31, v63
	v_fmac_f32_e32 v202, v32, v64
	v_fmac_f32_e32 v203, v33, v65
	v_add_f32_e32 v200, v201, v200
	v_add_f32_e32 v202, v203, v202
	v_cvt_scalef32_pk32_f32_fp6 v[2:33], v[152:157], 1.0
	v_add_f32_e32 v200, v202, v200
	s_add_i32 s38, s24, 4
	v_readlane_b32 s26, v199, s38
	s_add_i32 s39, s23, 4
	v_readlane_b32 s25, v198, s39
	v_add_f32_dpp v200, v200, v200 quad_perm:[1,0,3,2] row_mask:0xf bank_mask:0xf bound_ctrl:1
	s_nop 1
	v_add_f32_dpp v200, v200, v200 quad_perm:[2,3,0,1] row_mask:0xf bank_mask:0xf bound_ctrl:1
	s_nop 1
	v_add_f32_dpp v200, v200, v200 row_half_mirror row_mask:0xf bank_mask:0xf bound_ctrl:1
	s_nop 1
	v_add_f32_dpp v200, v200, v200 row_mirror row_mask:0xf bank_mask:0xf bound_ctrl:1
	s_nop 1
	v_add_f32_dpp v200, v200, v200 row_bcast:15 row_mask:0xa bank_mask:0xf
	s_nop 1
	v_add_f32_dpp v200, v200, v200 row_bcast:31 row_mask:0xc bank_mask:0xf
	s_nop 0
	v_readlane_b32 s27, v200, 63
	v_mul_f32_e32 v204, s27, v212
	v_mul_f32_e32 v205, 0x3f3504f3, v204
	v_cmp_lt_f32_e64 s[32:33], |v205|, 1.0
	s_and_b64 vcc, exec, s[32:33]
	s_cbranch_vccnz .Lsm_25
	v_fma_f32 v208, |v205|, s9, v214
	v_fma_f32 v208, |v205|, v208, s10
	v_fma_f32 v208, |v205|, v208, s11
	v_fma_f32 v208, |v205|, v208, s12
	v_fma_f32 v208, |v205|, v208, s13
	v_fma_f32 v208, |v205|, v208, s14
	v_fma_f32 v208, |v205|, v208, |v205|
	v_mul_f32_e32 v209, 0xbfb8aa3b, v208
	v_fma_f32 v210, v208, s15, -v209
	v_rndne_f32_e32 v211, v209
	v_fmac_f32_e32 v210, 0xb2a5705f, v208
	v_sub_f32_e32 v209, v209, v211
	v_add_f32_e32 v209, v209, v210
	v_cvt_i32_f32_e32 v210, v211
	v_exp_f32_e32 v209, v209
	v_cmp_nlt_f32_e32 vcc, s16, v208
	v_ldexp_f32 v209, v209, v210
	s_nop 0
	v_cndmask_b32_e32 v209, 0, v209, vcc
	v_cmp_ngt_f32_e32 vcc, s17, v208
	s_nop 1
	v_cndmask_b32_e32 v208, v215, v209, vcc
	v_sub_f32_e32 v210, 1.0, v208
	s_branch .Ljn_25

; DEV float gelu_exact(float v) { return 0.5f * v * (1.f + erff(v * 0.7071067811865476f)); }
; DEV void peer_gather_token(const Params& p, int tok) {
;     ...
;       if (k + 3 < 128) issue(k + 3, (s + 3) & 3);
;       const v6u dq = v6u{dn[s][0][0], dn[s][0][1], dn[s][1][0], dn[s][1][1], dn[s][2][0], dn[s][2][1]};
;       const v32f dv = __builtin_amdgcn_cvt_scalef32_pk32_f32_fp6(dq, 1.0f);
;       float d0 = 0.f, d1 = 0.f, d2 = 0.f, d3 = 0.f;
; #pragma unroll
;       for (int i = 0; i < 8; ++i) { d0 += dv[4 * i] * hx[4 * i]; d1 += dv[4 * i + 1] * hx[4 * i + 1]; d2 += dv[4 * i + 2] * hx[4 * i + 2]; d3 += dv[4 * i + 3] * hx[4 * i + 3]; }
;       const float d = wave_sum_fast((d0 + d1) + (d2 + d3)) * (1.f / DOWN_SCALE);
;       const float gk = __builtin_bit_cast(float, (k < 64) ? __builtin_amdgcn_readlane(g0, k) : __builtin_amdgcn_readlane(g1, k - 64));
;       const float act = gelu_exact(d) * gk * (1.f / UP_SCALE);
;       const v6u uq = v6u{up[s][0][0], up[s][0][1], up[s][1][0], up[s][1][1], up[s][2][0], up[s][2][1]};
;       const v32f uv = __builtin_amdgcn_cvt_scalef32_pk32_f32_fp6(uq, 1.0f);
; #pragma unroll
;       for (int i = 0; i < 32; ++i) acc[i] += act * uv[i];
.Ljn_25:
	v_bfi_b32 v209, s18, v210, v205
	v_mul_f32_e32 v208, 0.5, v204
	v_add_f32_e32 v209, 1.0, v209
	v_mul_f32_e32 v208, v208, v209
	v_mul_f32_e32 v208, s26, v208
	v_mul_f32_e32 v206, 0x3e800000, v208
	v_pk_fma_f32 v[66:67], v[2:3], v[206:207], v[66:67] op_sel_hi:[1,0,1]
	v_pk_fma_f32 v[68:69], v[4:5], v[206:207], v[68:69] op_sel_hi:[1,0,1]
	v_pk_fma_f32 v[70:71], v[6:7], v[206:207], v[70:71] op_sel_hi:[1,0,1]
	v_pk_fma_f32 v[72:73], v[8:9], v[206:207], v[72:73] op_sel_hi:[1,0,1]
	v_pk_fma_f32 v[74:75], v[10:11], v[206:207], v[74:75] op_sel_hi:[1,0,1]
	v_pk_fma_f32 v[76:77], v[12:13], v[206:207], v[76:77] op_sel_hi:[1,0,1]
	v_pk_fma_f32 v[78:79], v[14:15], v[206:207], v[78:79] op_sel_hi:[1,0,1]
	v_pk_fma_f32 v[80:81], v[16:17], v[206:207], v[80:81] op_sel_hi:[1,0,1]
	v_pk_fma_f32 v[82:83], v[18:19], v[206:207], v[82:83] op_sel_hi:[1,0,1]
	v_pk_fma_f32 v[84:85], v[20:21], v[206:207], v[84:85] op_sel_hi:[1,0,1]
	v_pk_fma_f32 v[86:87], v[22:23], v[206:207], v[86:87] op_sel_hi:[1,0,1]
	v_pk_fma_f32 v[88:89], v[24:25], v[206:207], v[88:89] op_sel_hi:[1,0,1]
	v_pk_fma_f32 v[90:91], v[26:27], v[206:207], v[90:91] op_sel_hi:[1,0,1]
	v_pk_fma_f32 v[92:93], v[28:29], v[206:207], v[92:93] op_sel_hi:[1,0,1]
	v_pk_fma_f32 v[94:95], v[30:31], v[206:207], v[94:95] op_sel_hi:[1,0,1]
	v_pk_fma_f32 v[96:97], v[32:33], v[206:207], v[96:97] op_sel_hi:[1,0,1]
	s_mul_i32 s40, s25, 0xc00
	s_cmp_lt_u32 s25, 0x1800
	s_cselect_b64 s[28:29], s[2:3], s[4:5]
	s_cmp_lt_u32 s25, 0x2800
	s_cselect_b64 s[28:29], s[28:29], s[62:63]
	s_add_u32 s28, s28, s40
	s_addc_u32 s29, s29, 0
	global_load_dwordx4 v[146:149], v1, s[28:29]
	global_load_dwordx4 v[150:153], v1, s[28:29] offset:2048
	global_load_dwordx4 v[154:157], v1, s[28:29] offset:1024
	s_waitcnt vmcnt(33)
	v_cvt_scalef32_pk32_f32_fp6 v[2:33], v[158:163], 1.0
	v_mul_f32_e32 v200, v2, v34
	v_mul_f32_e32 v201, v3, v35
	v_mul_f32_e32 v202, v4, v36
	v_mul_f32_e32 v203, v5, v37
	v_fmac_f32_e32 v200, v6, v38
	v_fmac_f32_e32 v201, v7, v39
	v_fmac_f32_e32 v202, v8, v40
	v_fmac_f32_e32 v203, v9, v41
	v_fmac_f32_e32 v200, v10, v42
	v_fmac_f32_e32 v201, v11, v43
	v_fmac_f32_e32 v202, v12, v44
	v_fmac_f32_e32 v203, v13, v45
	v_fmac_f32_e32 v200, v14, v46
	v_fmac_f32_e32 v201, v15, v47
	v_fmac_f32_e32 v202, v16, v48
	v_fmac_f32_e32 v203, v17, v49
	v_fmac_f32_e32 v200, v18, v50
	v_fmac_f32_e32 v201, v19, v51
	v_fmac_f32_e32 v202, v20, v52
	v_fmac_f32_e32 v203, v21, v53
	v_fmac_f32_e32 v200, v22, v54
	v_fmac_f32_e32 v201, v23, v55
	v_fmac_f32_e32 v202, v24, v56
	v_fmac_f32_e32 v203, v25, v57
	v_fmac_f32_e32 v200, v26, v58
	v_fmac_f32_e32 v201, v27, v59
	v_fmac_f32_e32 v202, v28, v60
	v_fmac_f32_e32 v203, v29, v61
	v_fmac_f32_e32 v200, v30, v62
	v_fmac_f32_e32 v201, v31, v63
	v_fmac_f32_e32 v202, v32, v64
	v_fmac_f32_e32 v203, v33, v65
	v_add_f32_e32 v200, v201, v200
	v_add_f32_e32 v202, v203, v202
	v_cvt_scalef32_pk32_f32_fp6 v[2:33], v[164:169], 1.0
	v_add_f32_e32 v200, v202, v200
	s_add_i32 s38, s24, 5
	v_readlane_b32 s26, v199, s38
	s_add_i32 s39, s23, 5
	v_readlane_b32 s25, v198, s39
	v_add_f32_dpp v200, v200, v200 quad_perm:[1,0,3,2] row_mask:0xf bank_mask:0xf bound_ctrl:1
	s_nop 1
	v_add_f32_dpp v200, v200, v200 quad_perm:[2,3,0,1] row_mask:0xf bank_mask:0xf bound_ctrl:1
	s_nop 1
	v_add_f32_dpp v200, v200, v200 row_half_mirror row_mask:0xf bank_mask:0xf bound_ctrl:1
	s_nop 1
	v_add_f32_dpp v200, v200, v200 row_mirror row_mask:0xf bank_mask:0xf bound_ctrl:1
	s_nop 1
	v_add_f32_dpp v200, v200, v200 row_bcast:15 row_mask:0xa bank_mask:0xf
	s_nop 1
	v_add_f32_dpp v200, v200, v200 row_bcast:31 row_mask:0xc bank_mask:0xf
	s_nop 0
	v_readlane_b32 s27, v200, 63
	v_mul_f32_e32 v204, s27, v212
	v_mul_f32_e32 v205, 0x3f3504f3, v204
	v_cmp_lt_f32_e64 s[32:33], |v205|, 1.0
	s_and_b64 vcc, exec, s[32:33]
	s_cbranch_vccnz .Lsm_27
	v_fma_f32 v208, |v205|, s9, v214
	v_fma_f32 v208, |v205|, v208, s10
	v_fma_f32 v208, |v205|, v208, s11
	v_fma_f32 v208, |v205|, v208, s12
	v_fma_f32 v208, |v205|, v208, s13
	v_fma_f32 v208, |v205|, v208, s14
	v_fma_f32 v208, |v205|, v208, |v205|
	v_mul_f32_e32 v209, 0xbfb8aa3b, v208
	v_fma_f32 v210, v208, s15, -v209
	v_rndne_f32_e32 v211, v209
	v_fmac_f32_e32 v210, 0xb2a5705f, v208
	v_sub_f32_e32 v209, v209, v211
	v_add_f32_e32 v209, v209, v210
	v_cvt_i32_f32_e32 v210, v211
	v_exp_f32_e32 v209, v209
	v_cmp_nlt_f32_e32 vcc, s16, v208
	v_ldexp_f32 v209, v209, v210
	s_nop 0
	v_cndmask_b32_e32 v209, 0, v209, vcc
	v_cmp_ngt_f32_e32 vcc, s17, v208
	s_nop 1
	v_cndmask_b32_e32 v208, v215, v209, vcc
	v_sub_f32_e32 v210, 1.0, v208
	s_branch .Ljn_27

; DEV float gelu_exact(float v) { return 0.5f * v * (1.f + erff(v * 0.7071067811865476f)); }
; DEV void peer_gather_token(const Params& p, int tok) {
;     ...
;       if (k + 3 < 128) issue(k + 3, (s + 3) & 3);
;       const v6u dq = v6u{dn[s][0][0], dn[s][0][1], dn[s][1][0], dn[s][1][1], dn[s][2][0], dn[s][2][1]};
;       const v32f dv = __builtin_amdgcn_cvt_scalef32_pk32_f32_fp6(dq, 1.0f);
;       float d0 = 0.f, d1 = 0.f, d2 = 0.f, d3 = 0.f;
; #pragma unroll
;       for (int i = 0; i < 8; ++i) { d0 += dv[4 * i] * hx[4 * i]; d1 += dv[4 * i + 1] * hx[4 * i + 1]; d2 += dv[4 * i + 2] * hx[4 * i + 2]; d3 += dv[4 * i + 3] * hx[4 * i + 3]; }
;       const float d = wave_sum_fast((d0 + d1) + (d2 + d3)) * (1.f / DOWN_SCALE);
;       const float gk = __builtin_bit_cast(float, (k < 64) ? __builtin_amdgcn_readlane(g0, k) : __builtin_amdgcn_readlane(g1, k - 64));
;       const float act = gelu_exact(d) * gk * (1.f / UP_SCALE);
;       const v6u uq = v6u{up[s][0][0], up[s][0][1], up[s][1][0], up[s][1][1], up[s][2][0], up[s][2][1]};
;       const v32f uv = __builtin_amdgcn_cvt_scalef32_pk32_f32_fp6(uq, 1.0f);
; #pragma unroll
;       for (int i = 0; i < 32; ++i) acc[i] += act * uv[i];
.Ljn_27:
	v_bfi_b32 v209, s18, v210, v205
	v_mul_f32_e32 v208, 0.5, v204
	v_add_f32_e32 v209, 1.0, v209
	v_mul_f32_e32 v208, v208, v209
	v_mul_f32_e32 v208, s26, v208
	v_mul_f32_e32 v206, 0x3e800000, v208
	v_pk_fma_f32 v[66:67], v[2:3], v[206:207], v[66:67] op_sel_hi:[1,0,1]
	v_pk_fma_f32 v[68:69], v[4:5], v[206:207], v[68:69] op_sel_hi:[1,0,1]
	v_pk_fma_f32 v[70:71], v[6:7], v[206:207], v[70:71] op_sel_hi:[1,0,1]
	v_pk_fma_f32 v[72:73], v[8:9], v[206:207], v[72:73] op_sel_hi:[1,0,1]
	v_pk_fma_f32 v[74:75], v[10:11], v[206:207], v[74:75] op_sel_hi:[1,0,1]
	v_pk_fma_f32 v[76:77], v[12:13], v[206:207], v[76:77] op_sel_hi:[1,0,1]
	v_pk_fma_f32 v[78:79], v[14:15], v[206:207], v[78:79] op_sel_hi:[1,0,1]
	v_pk_fma_f32 v[80:81], v[16:17], v[206:207], v[80:81] op_sel_hi:[1,0,1]
	v_pk_fma_f32 v[82:83], v[18:19], v[206:207], v[82:83] op_sel_hi:[1,0,1]
	v_pk_fma_f32 v[84:85], v[20:21], v[206:207], v[84:85] op_sel_hi:[1,0,1]
	v_pk_fma_f32 v[86:87], v[22:23], v[206:207], v[86:87] op_sel_hi:[1,0,1]
	v_pk_fma_f32 v[88:89], v[24:25], v[206:207], v[88:89] op_sel_hi:[1,0,1]
	v_pk_fma_f32 v[90:91], v[26:27], v[206:207], v[90:91] op_sel_hi:[1,0,1]
	v_pk_fma_f32 v[92:93], v[28:29], v[206:207], v[92:93] op_sel_hi:[1,0,1]
	v_pk_fma_f32 v[94:95], v[30:31], v[206:207], v[94:95] op_sel_hi:[1,0,1]
	v_pk_fma_f32 v[96:97], v[32:33], v[206:207], v[96:97] op_sel_hi:[1,0,1]
	s_mul_i32 s40, s25, 0xc00
	s_cmp_lt_u32 s25, 0x1800
	s_cselect_b64 s[28:29], s[2:3], s[4:5]
	s_cmp_lt_u32 s25, 0x2800
	s_cselect_b64 s[28:29], s[28:29], s[62:63]
	s_add_u32 s28, s28, s40
	s_addc_u32 s29, s29, 0
	global_load_dwordx4 v[158:161], v1, s[28:29]
	global_load_dwordx4 v[162:165], v1, s[28:29] offset:2048
	global_load_dwordx4 v[166:169], v1, s[28:29] offset:1024
	s_waitcnt vmcnt(33)
	v_cvt_scalef32_pk32_f32_fp6 v[2:33], v[170:175], 1.0
	v_mul_f32_e32 v200, v2, v34
	v_mul_f32_e32 v201, v3, v35
	v_mul_f32_e32 v202, v4, v36
	v_mul_f32_e32 v203, v5, v37
	v_fmac_f32_e32 v200, v6, v38
	v_fmac_f32_e32 v201, v7, v39
	v_fmac_f32_e32 v202, v8, v40
	v_fmac_f32_e32 v203, v9, v41
	v_fmac_f32_e32 v200, v10, v42
	v_fmac_f32_e32 v201, v11, v43
	v_fmac_f32_e32 v202, v12, v44
	v_fmac_f32_e32 v203, v13, v45
	v_fmac_f32_e32 v200, v14, v46
	v_fmac_f32_e32 v201, v15, v47
	v_fmac_f32_e32 v202, v16, v48
	v_fmac_f32_e32 v203, v17, v49
	v_fmac_f32_e32 v200, v18, v50
	v_fmac_f32_e32 v201, v19, v51
	v_fmac_f32_e32 v202, v20, v52
	v_fmac_f32_e32 v203, v21, v53
	v_fmac_f32_e32 v200, v22, v54
	v_fmac_f32_e32 v201, v23, v55
	v_fmac_f32_e32 v202, v24, v56
	v_fmac_f32_e32 v203, v25, v57
	v_fmac_f32_e32 v200, v26, v58
	v_fmac_f32_e32 v201, v27, v59
	v_fmac_f32_e32 v202, v28, v60
	v_fmac_f32_e32 v203, v29, v61
	v_fmac_f32_e32 v200, v30, v62
	v_fmac_f32_e32 v201, v31, v63
	v_fmac_f32_e32 v202, v32, v64
	v_fmac_f32_e32 v203, v33, v65
	v_add_f32_e32 v200, v201, v200
	v_add_f32_e32 v202, v203, v202
	v_cvt_scalef32_pk32_f32_fp6 v[2:33], v[176:181], 1.0
	v_add_f32_e32 v200, v202, v200
	s_add_i32 s38, s24, 6
	v_readlane_b32 s26, v199, s38
	s_add_i32 s39, s23, 6
	v_readlane_b32 s25, v198, s39
	v_add_f32_dpp v200, v200, v200 quad_perm:[1,0,3,2] row_mask:0xf bank_mask:0xf bound_ctrl:1
	s_nop 1
	v_add_f32_dpp v200, v200, v200 quad_perm:[2,3,0,1] row_mask:0xf bank_mask:0xf bound_ctrl:1
	s_nop 1
	v_add_f32_dpp v200, v200, v200 row_half_mirror row_mask:0xf bank_mask:0xf bound_ctrl:1
	s_nop 1
	v_add_f32_dpp v200, v200, v200 row_mirror row_mask:0xf bank_mask:0xf bound_ctrl:1
	s_nop 1
	v_add_f32_dpp v200, v200, v200 row_bcast:15 row_mask:0xa bank_mask:0xf
	s_nop 1
	v_add_f32_dpp v200, v200, v200 row_bcast:31 row_mask:0xc bank_mask:0xf
	s_nop 0
	v_readlane_b32 s27, v200, 63
	v_mul_f32_e32 v204, s27, v212
	v_mul_f32_e32 v205, 0x3f3504f3, v204
	v_cmp_lt_f32_e64 s[32:33], |v205|, 1.0
	s_and_b64 vcc, exec, s[32:33]
	s_cbranch_vccnz .Lsm_29
	v_fma_f32 v208, |v205|, s9, v214
	v_fma_f32 v208, |v205|, v208, s10
	v_fma_f32 v208, |v205|, v208, s11
	v_fma_f32 v208, |v205|, v208, s12
	v_fma_f32 v208, |v205|, v208, s13
	v_fma_f32 v208, |v205|, v208, s14
	v_fma_f32 v208, |v205|, v208, |v205|
	v_mul_f32_e32 v209, 0xbfb8aa3b, v208
	v_fma_f32 v210, v208, s15, -v209
	v_rndne_f32_e32 v211, v209
	v_fmac_f32_e32 v210, 0xb2a5705f, v208
	v_sub_f32_e32 v209, v209, v211
	v_add_f32_e32 v209, v209, v210
	v_cvt_i32_f32_e32 v210, v211
	v_exp_f32_e32 v209, v209
	v_cmp_nlt_f32_e32 vcc, s16, v208
	v_ldexp_f32 v209, v209, v210
	s_nop 0
	v_cndmask_b32_e32 v209, 0, v209, vcc
	v_cmp_ngt_f32_e32 vcc, s17, v208
	s_nop 1
	v_cndmask_b32_e32 v208, v215, v209, vcc
	v_sub_f32_e32 v210, 1.0, v208
	s_branch .Ljn_29

; DEV float gelu_exact(float v) { return 0.5f * v * (1.f + erff(v * 0.7071067811865476f)); }
; DEV void peer_gather_token(const Params& p, int tok) {
;     ...
;       if (k + 3 < 128) issue(k + 3, (s + 3) & 3);
;       const v6u dq = v6u{dn[s][0][0], dn[s][0][1], dn[s][1][0], dn[s][1][1], dn[s][2][0], dn[s][2][1]};
;       const v32f dv = __builtin_amdgcn_cvt_scalef32_pk32_f32_fp6(dq, 1.0f);
;       float d0 = 0.f, d1 = 0.f, d2 = 0.f, d3 = 0.f;
; #pragma unroll
;       for (int i = 0; i < 8; ++i) { d0 += dv[4 * i] * hx[4 * i]; d1 += dv[4 * i + 1] * hx[4 * i + 1]; d2 += dv[4 * i + 2] * hx[4 * i + 2]; d3 += dv[4 * i + 3] * hx[4 * i + 3]; }
;       const float d = wave_sum_fast((d0 + d1) + (d2 + d3)) * (1.f / DOWN_SCALE);
;       const float gk = __builtin_bit_cast(float, (k < 64) ? __builtin_amdgcn_readlane(g0, k) : __builtin_amdgcn_readlane(g1, k - 64));
;       const float act = gelu_exact(d) * gk * (1.f / UP_SCALE);
;       const v6u uq = v6u{up[s][0][0], up[s][0][1], up[s][1][0], up[s][1][1], up[s][2][0], up[s][2][1]};
;       const v32f uv = __builtin_amdgcn_cvt_scalef32_pk32_f32_fp6(uq, 1.0f);
; #pragma unroll
;       for (int i = 0; i < 32; ++i) acc[i] += act * uv[i];
.Ljn_29:
	v_bfi_b32 v209, s18, v210, v205
	v_mul_f32_e32 v208, 0.5, v204
	v_add_f32_e32 v209, 1.0, v209
	v_mul_f32_e32 v208, v208, v209
	v_mul_f32_e32 v208, s26, v208
	v_mul_f32_e32 v206, 0x3e800000, v208
	v_pk_fma_f32 v[66:67], v[2:3], v[206:207], v[66:67] op_sel_hi:[1,0,1]
	v_pk_fma_f32 v[68:69], v[4:5], v[206:207], v[68:69] op_sel_hi:[1,0,1]
	v_pk_fma_f32 v[70:71], v[6:7], v[206:207], v[70:71] op_sel_hi:[1,0,1]
	v_pk_fma_f32 v[72:73], v[8:9], v[206:207], v[72:73] op_sel_hi:[1,0,1]
	v_pk_fma_f32 v[74:75], v[10:11], v[206:207], v[74:75] op_sel_hi:[1,0,1]
	v_pk_fma_f32 v[76:77], v[12:13], v[206:207], v[76:77] op_sel_hi:[1,0,1]
	v_pk_fma_f32 v[78:79], v[14:15], v[206:207], v[78:79] op_sel_hi:[1,0,1]
	v_pk_fma_f32 v[80:81], v[16:17], v[206:207], v[80:81] op_sel_hi:[1,0,1]
	v_pk_fma_f32 v[82:83], v[18:19], v[206:207], v[82:83] op_sel_hi:[1,0,1]
	v_pk_fma_f32 v[84:85], v[20:21], v[206:207], v[84:85] op_sel_hi:[1,0,1]
	v_pk_fma_f32 v[86:87], v[22:23], v[206:207], v[86:87] op_sel_hi:[1,0,1]
	v_pk_fma_f32 v[88:89], v[24:25], v[206:207], v[88:89] op_sel_hi:[1,0,1]
	v_pk_fma_f32 v[90:91], v[26:27], v[206:207], v[90:91] op_sel_hi:[1,0,1]
	v_pk_fma_f32 v[92:93], v[28:29], v[206:207], v[92:93] op_sel_hi:[1,0,1]
	v_pk_fma_f32 v[94:95], v[30:31], v[206:207], v[94:95] op_sel_hi:[1,0,1]
	v_pk_fma_f32 v[96:97], v[32:33], v[206:207], v[96:97] op_sel_hi:[1,0,1]
	s_mul_i32 s40, s25, 0xc00
	s_cmp_lt_u32 s25, 0x1800
	s_cselect_b64 s[28:29], s[2:3], s[4:5]
	s_cmp_lt_u32 s25, 0x2800
	s_cselect_b64 s[28:29], s[28:29], s[62:63]
	s_add_u32 s28, s28, s40
	s_addc_u32 s29, s29, 0
	global_load_dwordx4 v[170:173], v1, s[28:29]
	global_load_dwordx4 v[174:177], v1, s[28:29] offset:2048
	global_load_dwordx4 v[178:181], v1, s[28:29] offset:1024
	s_waitcnt vmcnt(33)
	v_cvt_scalef32_pk32_f32_fp6 v[2:33], v[182:187], 1.0
	v_mul_f32_e32 v200, v2, v34
	v_mul_f32_e32 v201, v3, v35
	v_mul_f32_e32 v202, v4, v36
	v_mul_f32_e32 v203, v5, v37
	v_fmac_f32_e32 v200, v6, v38
	v_fmac_f32_e32 v201, v7, v39
	v_fmac_f32_e32 v202, v8, v40
	v_fmac_f32_e32 v203, v9, v41
	v_fmac_f32_e32 v200, v10, v42
	v_fmac_f32_e32 v201, v11, v43
	v_fmac_f32_e32 v202, v12, v44
	v_fmac_f32_e32 v203, v13, v45
	v_fmac_f32_e32 v200, v14, v46
	v_fmac_f32_e32 v201, v15, v47
	v_fmac_f32_e32 v202, v16, v48
	v_fmac_f32_e32 v203, v17, v49
	v_fmac_f32_e32 v200, v18, v50
	v_fmac_f32_e32 v201, v19, v51
	v_fmac_f32_e32 v202, v20, v52
	v_fmac_f32_e32 v203, v21, v53
	v_fmac_f32_e32 v200, v22, v54
	v_fmac_f32_e32 v201, v23, v55
	v_fmac_f32_e32 v202, v24, v56
	v_fmac_f32_e32 v203, v25, v57
	v_fmac_f32_e32 v200, v26, v58
	v_fmac_f32_e32 v201, v27, v59
	v_fmac_f32_e32 v202, v28, v60
	v_fmac_f32_e32 v203, v29, v61
	v_fmac_f32_e32 v200, v30, v62
	v_fmac_f32_e32 v201, v31, v63
	v_fmac_f32_e32 v202, v32, v64
	v_fmac_f32_e32 v203, v33, v65
	v_add_f32_e32 v200, v201, v200
	v_add_f32_e32 v202, v203, v202
	v_cvt_scalef32_pk32_f32_fp6 v[2:33], v[188:193], 1.0
	v_add_f32_e32 v200, v202, v200
	s_add_i32 s38, s24, 7
	v_readlane_b32 s26, v199, s38
	s_add_i32 s39, s23, 7
	v_readlane_b32 s25, v198, s39
	v_add_f32_dpp v200, v200, v200 quad_perm:[1,0,3,2] row_mask:0xf bank_mask:0xf bound_ctrl:1
	s_nop 1
	v_add_f32_dpp v200, v200, v200 quad_perm:[2,3,0,1] row_mask:0xf bank_mask:0xf bound_ctrl:1
	s_nop 1
	v_add_f32_dpp v200, v200, v200 row_half_mirror row_mask:0xf bank_mask:0xf bound_ctrl:1
	s_nop 1
	v_add_f32_dpp v200, v200, v200 row_mirror row_mask:0xf bank_mask:0xf bound_ctrl:1
	s_nop 1
	v_add_f32_dpp v200, v200, v200 row_bcast:15 row_mask:0xa bank_mask:0xf
	s_nop 1
	v_add_f32_dpp v200, v200, v200 row_bcast:31 row_mask:0xc bank_mask:0xf
	s_nop 0
	v_readlane_b32 s27, v200, 63
	v_mul_f32_e32 v204, s27, v212
	v_mul_f32_e32 v205, 0x3f3504f3, v204
	v_cmp_lt_f32_e64 s[32:33], |v205|, 1.0
	s_and_b64 vcc, exec, s[32:33]
	s_cbranch_vccnz .Lsm_31
	v_fma_f32 v208, |v205|, s9, v214
	v_fma_f32 v208, |v205|, v208, s10
	v_fma_f32 v208, |v205|, v208, s11
	v_fma_f32 v208, |v205|, v208, s12
	v_fma_f32 v208, |v205|, v208, s13
	v_fma_f32 v208, |v205|, v208, s14
	v_fma_f32 v208, |v205|, v208, |v205|
	v_mul_f32_e32 v209, 0xbfb8aa3b, v208
	v_fma_f32 v210, v208, s15, -v209
	v_rndne_f32_e32 v211, v209
	v_fmac_f32_e32 v210, 0xb2a5705f, v208
	v_sub_f32_e32 v209, v209, v211
	v_add_f32_e32 v209, v209, v210
	v_cvt_i32_f32_e32 v210, v211
	v_exp_f32_e32 v209, v209
	v_cmp_nlt_f32_e32 vcc, s16, v208
	v_ldexp_f32 v209, v209, v210
	s_nop 0
	v_cndmask_b32_e32 v209, 0, v209, vcc
	v_cmp_ngt_f32_e32 vcc, s17, v208
	s_nop 1
	v_cndmask_b32_e32 v208, v215, v209, vcc
	v_sub_f32_e32 v210, 1.0, v208
	s_branch .Ljn_31

; DEV float gelu_exact(float v) { return 0.5f * v * (1.f + erff(v * 0.7071067811865476f)); }
; DEV void peer_gather_token(const Params& p, int tok) {
;     ...
;   const int e0 = p.eidx[(size_t)tok * 128 + lane], e1 = p.eidx[(size_t)tok * 128 + 64 + lane];
;   const int g0 = __builtin_bit_cast(int, p.gw[(size_t)tok * 128 + lane]), g1 = __builtin_bit_cast(int, p.gw[(size_t)tok * 128 + 64 + lane]);
;   u32x2 dn[4][3], up[4][3];
;   auto issue = [&](int k, int slot) {
;     const int e = (k < 64) ? __builtin_amdgcn_readlane(e0, k) : __builtin_amdgcn_readlane(e1, k - 64);
;     ...
;       if (k + 3 < 128) issue(k + 3, (s + 3) & 3);
;       const v6u dq = v6u{dn[s][0][0], dn[s][0][1], dn[s][1][0], dn[s][1][1], dn[s][2][0], dn[s][2][1]};
;       const v32f dv = __builtin_amdgcn_cvt_scalef32_pk32_f32_fp6(dq, 1.0f);
;       float d0 = 0.f, d1 = 0.f, d2 = 0.f, d3 = 0.f;
; #pragma unroll
;       for (int i = 0; i < 8; ++i) { d0 += dv[4 * i] * hx[4 * i]; d1 += dv[4 * i + 1] * hx[4 * i + 1]; d2 += dv[4 * i + 2] * hx[4 * i + 2]; d3 += dv[4 * i + 3] * hx[4 * i + 3]; }
;       const float d = wave_sum_fast((d0 + d1) + (d2 + d3)) * (1.f / DOWN_SCALE);
;       const float gk = __builtin_bit_cast(float, (k < 64) ? __builtin_amdgcn_readlane(g0, k) : __builtin_amdgcn_readlane(g1, k - 64));
;       const float act = gelu_exact(d) * gk * (1.f / UP_SCALE);
;       const v6u uq = v6u{up[s][0][0], up[s][0][1], up[s][1][0], up[s][1][1], up[s][2][0], up[s][2][1]};
;       const v32f uv = __builtin_amdgcn_cvt_scalef32_pk32_f32_fp6(uq, 1.0f);
; #pragma unroll
;       for (int i = 0; i < 32; ++i) acc[i] += act * uv[i];
.Ljn_31:
	v_bfi_b32 v209, s18, v210, v205
	v_mul_f32_e32 v208, 0.5, v204
	v_add_f32_e32 v209, 1.0, v209
	v_mul_f32_e32 v208, v208, v209
	v_mul_f32_e32 v208, s26, v208
	v_mul_f32_e32 v206, 0x3e800000, v208
	v_pk_fma_f32 v[66:67], v[2:3], v[206:207], v[66:67] op_sel_hi:[1,0,1]
	v_pk_fma_f32 v[68:69], v[4:5], v[206:207], v[68:69] op_sel_hi:[1,0,1]
	v_pk_fma_f32 v[70:71], v[6:7], v[206:207], v[70:71] op_sel_hi:[1,0,1]
	v_pk_fma_f32 v[72:73], v[8:9], v[206:207], v[72:73] op_sel_hi:[1,0,1]
	v_pk_fma_f32 v[74:75], v[10:11], v[206:207], v[74:75] op_sel_hi:[1,0,1]
	v_pk_fma_f32 v[76:77], v[12:13], v[206:207], v[76:77] op_sel_hi:[1,0,1]
	v_pk_fma_f32 v[78:79], v[14:15], v[206:207], v[78:79] op_sel_hi:[1,0,1]
	v_pk_fma_f32 v[80:81], v[16:17], v[206:207], v[80:81] op_sel_hi:[1,0,1]
	v_pk_fma_f32 v[82:83], v[18:19], v[206:207], v[82:83] op_sel_hi:[1,0,1]
	v_pk_fma_f32 v[84:85], v[20:21], v[206:207], v[84:85] op_sel_hi:[1,0,1]
	v_pk_fma_f32 v[86:87], v[22:23], v[206:207], v[86:87] op_sel_hi:[1,0,1]
	v_pk_fma_f32 v[88:89], v[24:25], v[206:207], v[88:89] op_sel_hi:[1,0,1]
	v_pk_fma_f32 v[90:91], v[26:27], v[206:207], v[90:91] op_sel_hi:[1,0,1]
	v_pk_fma_f32 v[92:93], v[28:29], v[206:207], v[92:93] op_sel_hi:[1,0,1]
	v_pk_fma_f32 v[94:95], v[30:31], v[206:207], v[94:95] op_sel_hi:[1,0,1]
	v_pk_fma_f32 v[96:97], v[32:33], v[206:207], v[96:97] op_sel_hi:[1,0,1]
	s_mul_i32 s40, s25, 0xc00
	s_cmp_lt_u32 s25, 0x1800
	s_cselect_b64 s[28:29], s[2:3], s[4:5]
	s_cmp_lt_u32 s25, 0x2800
	s_cselect_b64 s[28:29], s[28:29], s[62:63]
	s_add_u32 s28, s28, s40
	s_addc_u32 s29, s29, 0
	global_load_dwordx4 v[182:185], v1, s[28:29]
	global_load_dwordx4 v[186:189], v1, s[28:29] offset:2048
	global_load_dwordx4 v[190:193], v1, s[28:29] offset:1024
	s_add_i32 s24, s24, 8
	s_and_b32 s24, s24, 63
	s_waitcnt vmcnt(21)
	v_and_b32_e32 v236, 63, v0
	v_lshrrev_b32_e32 v241, 6, v0
	v_lshl_or_b32 v237, v216, 7, v236
	v_or_b32_e32 v238, 64, v236
	v_lshl_or_b32 v238, v217, 7, v238
	v_mov_b32_e32 v239, 0
	v_mov_b32_e32 v240, 0
	v_lshlrev_b32_e32 v241, 10, v241
	v_lshl_add_u32 v241, v236, 2, v241
	v_readlane_b32 s46, v237, 0
	v_readlane_b32 s47, v238, 0
	s_nop 1
	v_cmp_lt_u32_e64 s[48:49], s46, v237
	v_cmp_lt_u32_e64 s[50:51], s46, v238
	v_cmp_lt_u32_e64 s[52:53], s47, v237
	v_cmp_lt_u32_e64 s[54:55], s47, v238
	v_readlane_b32 s46, v237, 1
	v_readlane_b32 s47, v238, 1
	v_addc_co_u32_e64 v239, s[56:57], 0, v239, s[48:49]
	v_addc_co_u32_e64 v240, s[56:57], 0, v240, s[50:51]
	v_addc_co_u32_e64 v239, s[56:57], 0, v239, s[52:53]
	v_addc_co_u32_e64 v240, s[56:57], 0, v240, s[54:55]
	v_cmp_lt_u32_e64 s[48:49], s46, v237
	v_cmp_lt_u32_e64 s[50:51], s46, v238
	v_cmp_lt_u32_e64 s[52:53], s47, v237
	v_cmp_lt_u32_e64 s[54:55], s47, v238
	v_readlane_b32 s46, v237, 2
	v_readlane_b32 s47, v238, 2
	v_addc_co_u32_e64 v239, s[56:57], 0, v239, s[48:49]
	v_addc_co_u32_e64 v240, s[56:57], 0, v240, s[50:51]
	v_addc_co_u32_e64 v239, s[56:57], 0, v239, s[52:53]
	v_addc_co_u32_e64 v240, s[56:57], 0, v240, s[54:55]
	v_cmp_lt_u32_e64 s[48:49], s46, v237
	v_cmp_lt_u32_e64 s[50:51], s46, v238
	v_cmp_lt_u32_e64 s[52:53], s47, v237
	v_cmp_lt_u32_e64 s[54:55], s47, v238
	v_readlane_b32 s46, v237, 3
	v_readlane_b32 s47, v238, 3
	v_addc_co_u32_e64 v239, s[56:57], 0, v239, s[48:49]
	v_addc_co_u32_e64 v240, s[56:57], 0, v240, s[50:51]
	v_addc_co_u32_e64 v239, s[56:57], 0, v239, s[52:53]
	v_addc_co_u32_e64 v240, s[56:57], 0, v240, s[54:55]
	v_cmp_lt_u32_e64 s[48:49], s46, v237
	v_cmp_lt_u32_e64 s[50:51], s46, v238
	v_cmp_lt_u32_e64 s[52:53], s47, v237
	v_cmp_lt_u32_e64 s[54:55], s47, v238
	v_readlane_b32 s46, v237, 4
	v_readlane_b32 s47, v238, 4
	v_addc_co_u32_e64 v239, s[56:57], 0, v239, s[48:49]
	v_addc_co_u32_e64 v240, s[56:57], 0, v240, s[50:51]
	v_addc_co_u32_e64 v239, s[56:57], 0, v239, s[52:53]
	v_addc_co_u32_e64 v240, s[56:57], 0, v240, s[54:55]
	v_cmp_lt_u32_e64 s[48:49], s46, v237
	v_cmp_lt_u32_e64 s[50:51], s46, v238
	v_cmp_lt_u32_e64 s[52:53], s47, v237
	v_cmp_lt_u32_e64 s[54:55], s47, v238
	v_readlane_b32 s46, v237, 5
	v_readlane_b32 s47, v238, 5
	v_addc_co_u32_e64 v239, s[56:57], 0, v239, s[48:49]
	v_addc_co_u32_e64 v240, s[56:57], 0, v240, s[50:51]
	v_addc_co_u32_e64 v239, s[56:57], 0, v239, s[52:53]
	v_addc_co_u32_e64 v240, s[56:57], 0, v240, s[54:55]
	v_cmp_lt_u32_e64 s[48:49], s46, v237
	v_cmp_lt_u32_e64 s[50:51], s46, v238
	v_cmp_lt_u32_e64 s[52:53], s47, v237
	v_cmp_lt_u32_e64 s[54:55], s47, v238
	v_readlane_b32 s46, v237, 6
	v_readlane_b32 s47, v238, 6
	v_addc_co_u32_e64 v239, s[56:57], 0, v239, s[48:49]
	v_addc_co_u32_e64 v240, s[56:57], 0, v240, s[50:51]
	v_addc_co_u32_e64 v239, s[56:57], 0, v239, s[52:53]
	v_addc_co_u32_e64 v240, s[56:57], 0, v240, s[54:55]
	v_cmp_lt_u32_e64 s[48:49], s46, v237
	v_cmp_lt_u32_e64 s[50:51], s46, v238
	v_cmp_lt_u32_e64 s[52:53], s47, v237
	v_cmp_lt_u32_e64 s[54:55], s47, v238
	v_readlane_b32 s46, v237, 7
	v_readlane_b32 s47, v238, 7
	v_addc_co_u32_e64 v239, s[56:57], 0, v239, s[48:49]
	v_addc_co_u32_e64 v240, s[56:57], 0, v240, s[50:51]
	v_addc_co_u32_e64 v239, s[56:57], 0, v239, s[52:53]
	v_addc_co_u32_e64 v240, s[56:57], 0, v240, s[54:55]
	v_cmp_lt_u32_e64 s[48:49], s46, v237
	v_cmp_lt_u32_e64 s[50:51], s46, v238
	v_cmp_lt_u32_e64 s[52:53], s47, v237
	v_cmp_lt_u32_e64 s[54:55], s47, v238
	v_readlane_b32 s46, v237, 8
	v_readlane_b32 s47, v238, 8
	v_addc_co_u32_e64 v239, s[56:57], 0, v239, s[48:49]
	v_addc_co_u32_e64 v240, s[56:57], 0, v240, s[50:51]
	v_addc_co_u32_e64 v239, s[56:57], 0, v239, s[52:53]
	v_addc_co_u32_e64 v240, s[56:57], 0, v240, s[54:55]
	v_cmp_lt_u32_e64 s[48:49], s46, v237
	v_cmp_lt_u32_e64 s[50:51], s46, v238
	v_cmp_lt_u32_e64 s[52:53], s47, v237
; DEV void peer_gather_token(const Params& p, int tok) {
;     ...
;   const int e0 = p.eidx[(size_t)tok * 128 + lane], e1 = p.eidx[(size_t)tok * 128 + 64 + lane];
;   const int g0 = __builtin_bit_cast(int, p.gw[(size_t)tok * 128 + lane]), g1 = __builtin_bit_cast(int, p.gw[(size_t)tok * 128 + 64 + lane]);
;   u32x2 dn[4][3], up[4][3];
;   auto issue = [&](int k, int slot) {
;     const int e = (k < 64) ? __builtin_amdgcn_readlane(e0, k) : __builtin_amdgcn_readlane(e1, k - 64);
	v_cmp_lt_u32_e64 s[54:55], s47, v238
	v_readlane_b32 s46, v237, 9
	v_readlane_b32 s47, v238, 9
	v_addc_co_u32_e64 v239, s[56:57], 0, v239, s[48:49]
	v_addc_co_u32_e64 v240, s[56:57], 0, v240, s[50:51]
	v_addc_co_u32_e64 v239, s[56:57], 0, v239, s[52:53]
	v_addc_co_u32_e64 v240, s[56:57], 0, v240, s[54:55]
	v_cmp_lt_u32_e64 s[48:49], s46, v237
	v_cmp_lt_u32_e64 s[50:51], s46, v238
	v_cmp_lt_u32_e64 s[52:53], s47, v237
	v_cmp_lt_u32_e64 s[54:55], s47, v238
	v_readlane_b32 s46, v237, 10
	v_readlane_b32 s47, v238, 10
	v_addc_co_u32_e64 v239, s[56:57], 0, v239, s[48:49]
	v_addc_co_u32_e64 v240, s[56:57], 0, v240, s[50:51]
	v_addc_co_u32_e64 v239, s[56:57], 0, v239, s[52:53]
	v_addc_co_u32_e64 v240, s[56:57], 0, v240, s[54:55]
	v_cmp_lt_u32_e64 s[48:49], s46, v237
	v_cmp_lt_u32_e64 s[50:51], s46, v238
	v_cmp_lt_u32_e64 s[52:53], s47, v237
	v_cmp_lt_u32_e64 s[54:55], s47, v238
	v_readlane_b32 s46, v237, 11
	v_readlane_b32 s47, v238, 11
	v_addc_co_u32_e64 v239, s[56:57], 0, v239, s[48:49]
	v_addc_co_u32_e64 v240, s[56:57], 0, v240, s[50:51]
	v_addc_co_u32_e64 v239, s[56:57], 0, v239, s[52:53]
	v_addc_co_u32_e64 v240, s[56:57], 0, v240, s[54:55]
	v_cmp_lt_u32_e64 s[48:49], s46, v237
	v_cmp_lt_u32_e64 s[50:51], s46, v238
	v_cmp_lt_u32_e64 s[52:53], s47, v237
	v_cmp_lt_u32_e64 s[54:55], s47, v238
	v_readlane_b32 s46, v237, 12
	v_readlane_b32 s47, v238, 12
	v_addc_co_u32_e64 v239, s[56:57], 0, v239, s[48:49]
	v_addc_co_u32_e64 v240, s[56:57], 0, v240, s[50:51]
	v_addc_co_u32_e64 v239, s[56:57], 0, v239, s[52:53]
	v_addc_co_u32_e64 v240, s[56:57], 0, v240, s[54:55]
	v_cmp_lt_u32_e64 s[48:49], s46, v237
	v_cmp_lt_u32_e64 s[50:51], s46, v238
	v_cmp_lt_u32_e64 s[52:53], s47, v237
	v_cmp_lt_u32_e64 s[54:55], s47, v238
	v_readlane_b32 s46, v237, 13
	v_readlane_b32 s47, v238, 13
	v_addc_co_u32_e64 v239, s[56:57], 0, v239, s[48:49]
	v_addc_co_u32_e64 v240, s[56:57], 0, v240, s[50:51]
	v_addc_co_u32_e64 v239, s[56:57], 0, v239, s[52:53]
	v_addc_co_u32_e64 v240, s[56:57], 0, v240, s[54:55]
	v_cmp_lt_u32_e64 s[48:49], s46, v237
	v_cmp_lt_u32_e64 s[50:51], s46, v238
	v_cmp_lt_u32_e64 s[52:53], s47, v237
	v_cmp_lt_u32_e64 s[54:55], s47, v238
	v_readlane_b32 s46, v237, 14
	v_readlane_b32 s47, v238, 14
	v_addc_co_u32_e64 v239, s[56:57], 0, v239, s[48:49]
	v_addc_co_u32_e64 v240, s[56:57], 0, v240, s[50:51]
	v_addc_co_u32_e64 v239, s[56:57], 0, v239, s[52:53]
	v_addc_co_u32_e64 v240, s[56:57], 0, v240, s[54:55]
	v_cmp_lt_u32_e64 s[48:49], s46, v237
	v_cmp_lt_u32_e64 s[50:51], s46, v238
	v_cmp_lt_u32_e64 s[52:53], s47, v237
	v_cmp_lt_u32_e64 s[54:55], s47, v238
	v_readlane_b32 s46, v237, 15
	v_readlane_b32 s47, v238, 15
	v_addc_co_u32_e64 v239, s[56:57], 0, v239, s[48:49]
	v_addc_co_u32_e64 v240, s[56:57], 0, v240, s[50:51]
	v_addc_co_u32_e64 v239, s[56:57], 0, v239, s[52:53]
	v_addc_co_u32_e64 v240, s[56:57], 0, v240, s[54:55]
	v_cmp_lt_u32_e64 s[48:49], s46, v237
	v_cmp_lt_u32_e64 s[50:51], s46, v238
	v_cmp_lt_u32_e64 s[52:53], s47, v237
	v_cmp_lt_u32_e64 s[54:55], s47, v238
	v_readlane_b32 s46, v237, 16
	v_readlane_b32 s47, v238, 16
	v_addc_co_u32_e64 v239, s[56:57], 0, v239, s[48:49]
	v_addc_co_u32_e64 v240, s[56:57], 0, v240, s[50:51]
	v_addc_co_u32_e64 v239, s[56:57], 0, v239, s[52:53]
	v_addc_co_u32_e64 v240, s[56:57], 0, v240, s[54:55]
	v_cmp_lt_u32_e64 s[48:49], s46, v237
	v_cmp_lt_u32_e64 s[50:51], s46, v238
	v_cmp_lt_u32_e64 s[52:53], s47, v237
	v_cmp_lt_u32_e64 s[54:55], s47, v238
	v_readlane_b32 s46, v237, 17
	v_readlane_b32 s47, v238, 17
	v_addc_co_u32_e64 v239, s[56:57], 0, v239, s[48:49]
	v_addc_co_u32_e64 v240, s[56:57], 0, v240, s[50:51]
	v_addc_co_u32_e64 v239, s[56:57], 0, v239, s[52:53]
	v_addc_co_u32_e64 v240, s[56:57], 0, v240, s[54:55]
	v_cmp_lt_u32_e64 s[48:49], s46, v237
	v_cmp_lt_u32_e64 s[50:51], s46, v238
	v_cmp_lt_u32_e64 s[52:53], s47, v237
	v_cmp_lt_u32_e64 s[54:55], s47, v238
	v_readlane_b32 s46, v237, 18
	v_readlane_b32 s47, v238, 18
	v_addc_co_u32_e64 v239, s[56:57], 0, v239, s[48:49]
	v_addc_co_u32_e64 v240, s[56:57], 0, v240, s[50:51]
	v_addc_co_u32_e64 v239, s[56:57], 0, v239, s[52:53]
	v_addc_co_u32_e64 v240, s[56:57], 0, v240, s[54:55]
	v_cmp_lt_u32_e64 s[48:49], s46, v237
	v_cmp_lt_u32_e64 s[50:51], s46, v238
	v_cmp_lt_u32_e64 s[52:53], s47, v237
	v_cmp_lt_u32_e64 s[54:55], s47, v238
	v_readlane_b32 s46, v237, 19
	v_readlane_b32 s47, v238, 19
	v_addc_co_u32_e64 v239, s[56:57], 0, v239, s[48:49]
	v_addc_co_u32_e64 v240, s[56:57], 0, v240, s[50:51]
	v_addc_co_u32_e64 v239, s[56:57], 0, v239, s[52:53]
	v_addc_co_u32_e64 v240, s[56:57], 0, v240, s[54:55]
	v_cmp_lt_u32_e64 s[48:49], s46, v237
	v_cmp_lt_u32_e64 s[50:51], s46, v238
	v_cmp_lt_u32_e64 s[52:53], s47, v237
	v_cmp_lt_u32_e64 s[54:55], s47, v238
	v_readlane_b32 s46, v237, 20
	v_readlane_b32 s47, v238, 20
	v_addc_co_u32_e64 v239, s[56:57], 0, v239, s[48:49]
	v_addc_co_u32_e64 v240, s[56:57], 0, v240, s[50:51]
	v_addc_co_u32_e64 v239, s[56:57], 0, v239, s[52:53]
	v_addc_co_u32_e64 v240, s[56:57], 0, v240, s[54:55]
	v_cmp_lt_u32_e64 s[48:49], s46, v237
	v_cmp_lt_u32_e64 s[50:51], s46, v238
	v_cmp_lt_u32_e64 s[52:53], s47, v237
	v_cmp_lt_u32_e64 s[54:55], s47, v238
	v_readlane_b32 s46, v237, 21
	v_readlane_b32 s47, v238, 21
	v_addc_co_u32_e64 v239, s[56:57], 0, v239, s[48:49]
	v_addc_co_u32_e64 v240, s[56:57], 0, v240, s[50:51]
	v_addc_co_u32_e64 v239, s[56:57], 0, v239, s[52:53]
	v_addc_co_u32_e64 v240, s[56:57], 0, v240, s[54:55]
	v_cmp_lt_u32_e64 s[48:49], s46, v237
	v_cmp_lt_u32_e64 s[50:51], s46, v238
	v_cmp_lt_u32_e64 s[52:53], s47, v237
	v_cmp_lt_u32_e64 s[54:55], s47, v238
	v_readlane_b32 s46, v237, 22
	v_readlane_b32 s47, v238, 22
	v_addc_co_u32_e64 v239, s[56:57], 0, v239, s[48:49]
; DEV void peer_gather_token(const Params& p, int tok) {
;     ...
;   const int e0 = p.eidx[(size_t)tok * 128 + lane], e1 = p.eidx[(size_t)tok * 128 + 64 + lane];
;   const int g0 = __builtin_bit_cast(int, p.gw[(size_t)tok * 128 + lane]), g1 = __builtin_bit_cast(int, p.gw[(size_t)tok * 128 + 64 + lane]);
;   u32x2 dn[4][3], up[4][3];
;   auto issue = [&](int k, int slot) {
;     const int e = (k < 64) ? __builtin_amdgcn_readlane(e0, k) : __builtin_amdgcn_readlane(e1, k - 64);
	v_addc_co_u32_e64 v240, s[56:57], 0, v240, s[50:51]
	v_addc_co_u32_e64 v239, s[56:57], 0, v239, s[52:53]
	v_addc_co_u32_e64 v240, s[56:57], 0, v240, s[54:55]
	v_cmp_lt_u32_e64 s[48:49], s46, v237
	v_cmp_lt_u32_e64 s[50:51], s46, v238
	v_cmp_lt_u32_e64 s[52:53], s47, v237
	v_cmp_lt_u32_e64 s[54:55], s47, v238
	v_readlane_b32 s46, v237, 23
	v_readlane_b32 s47, v238, 23
	v_addc_co_u32_e64 v239, s[56:57], 0, v239, s[48:49]
	v_addc_co_u32_e64 v240, s[56:57], 0, v240, s[50:51]
	v_addc_co_u32_e64 v239, s[56:57], 0, v239, s[52:53]
	v_addc_co_u32_e64 v240, s[56:57], 0, v240, s[54:55]
	v_cmp_lt_u32_e64 s[48:49], s46, v237
	v_cmp_lt_u32_e64 s[50:51], s46, v238
	v_cmp_lt_u32_e64 s[52:53], s47, v237
	v_cmp_lt_u32_e64 s[54:55], s47, v238
	v_readlane_b32 s46, v237, 24
	v_readlane_b32 s47, v238, 24
	v_addc_co_u32_e64 v239, s[56:57], 0, v239, s[48:49]
	v_addc_co_u32_e64 v240, s[56:57], 0, v240, s[50:51]
	v_addc_co_u32_e64 v239, s[56:57], 0, v239, s[52:53]
	v_addc_co_u32_e64 v240, s[56:57], 0, v240, s[54:55]
	v_cmp_lt_u32_e64 s[48:49], s46, v237
	v_cmp_lt_u32_e64 s[50:51], s46, v238
	v_cmp_lt_u32_e64 s[52:53], s47, v237
	v_cmp_lt_u32_e64 s[54:55], s47, v238
	v_readlane_b32 s46, v237, 25
	v_readlane_b32 s47, v238, 25
	v_addc_co_u32_e64 v239, s[56:57], 0, v239, s[48:49]
	v_addc_co_u32_e64 v240, s[56:57], 0, v240, s[50:51]
	v_addc_co_u32_e64 v239, s[56:57], 0, v239, s[52:53]
	v_addc_co_u32_e64 v240, s[56:57], 0, v240, s[54:55]
	v_cmp_lt_u32_e64 s[48:49], s46, v237
	v_cmp_lt_u32_e64 s[50:51], s46, v238
	v_cmp_lt_u32_e64 s[52:53], s47, v237
	v_cmp_lt_u32_e64 s[54:55], s47, v238
	v_readlane_b32 s46, v237, 26
	v_readlane_b32 s47, v238, 26
	v_addc_co_u32_e64 v239, s[56:57], 0, v239, s[48:49]
	v_addc_co_u32_e64 v240, s[56:57], 0, v240, s[50:51]
	v_addc_co_u32_e64 v239, s[56:57], 0, v239, s[52:53]
	v_addc_co_u32_e64 v240, s[56:57], 0, v240, s[54:55]
	v_cmp_lt_u32_e64 s[48:49], s46, v237
	v_cmp_lt_u32_e64 s[50:51], s46, v238
	v_cmp_lt_u32_e64 s[52:53], s47, v237
	v_cmp_lt_u32_e64 s[54:55], s47, v238
	v_readlane_b32 s46, v237, 27
	v_readlane_b32 s47, v238, 27
	v_addc_co_u32_e64 v239, s[56:57], 0, v239, s[48:49]
	v_addc_co_u32_e64 v240, s[56:57], 0, v240, s[50:51]
	v_addc_co_u32_e64 v239, s[56:57], 0, v239, s[52:53]
	v_addc_co_u32_e64 v240, s[56:57], 0, v240, s[54:55]
	v_cmp_lt_u32_e64 s[48:49], s46, v237
	v_cmp_lt_u32_e64 s[50:51], s46, v238
	v_cmp_lt_u32_e64 s[52:53], s47, v237
	v_cmp_lt_u32_e64 s[54:55], s47, v238
	v_readlane_b32 s46, v237, 28
	v_readlane_b32 s47, v238, 28
	v_addc_co_u32_e64 v239, s[56:57], 0, v239, s[48:49]
	v_addc_co_u32_e64 v240, s[56:57], 0, v240, s[50:51]
	v_addc_co_u32_e64 v239, s[56:57], 0, v239, s[52:53]
	v_addc_co_u32_e64 v240, s[56:57], 0, v240, s[54:55]
	v_cmp_lt_u32_e64 s[48:49], s46, v237
	v_cmp_lt_u32_e64 s[50:51], s46, v238
	v_cmp_lt_u32_e64 s[52:53], s47, v237
	v_cmp_lt_u32_e64 s[54:55], s47, v238
	v_readlane_b32 s46, v237, 29
	v_readlane_b32 s47, v238, 29
	v_addc_co_u32_e64 v239, s[56:57], 0, v239, s[48:49]
	v_addc_co_u32_e64 v240, s[56:57], 0, v240, s[50:51]
	v_addc_co_u32_e64 v239, s[56:57], 0, v239, s[52:53]
	v_addc_co_u32_e64 v240, s[56:57], 0, v240, s[54:55]
	v_cmp_lt_u32_e64 s[48:49], s46, v237
	v_cmp_lt_u32_e64 s[50:51], s46, v238
	v_cmp_lt_u32_e64 s[52:53], s47, v237
	v_cmp_lt_u32_e64 s[54:55], s47, v238
	v_readlane_b32 s46, v237, 30
	v_readlane_b32 s47, v238, 30
	v_addc_co_u32_e64 v239, s[56:57], 0, v239, s[48:49]
	v_addc_co_u32_e64 v240, s[56:57], 0, v240, s[50:51]
	v_addc_co_u32_e64 v239, s[56:57], 0, v239, s[52:53]
	v_addc_co_u32_e64 v240, s[56:57], 0, v240, s[54:55]
	v_cmp_lt_u32_e64 s[48:49], s46, v237
	v_cmp_lt_u32_e64 s[50:51], s46, v238
	v_cmp_lt_u32_e64 s[52:53], s47, v237
	v_cmp_lt_u32_e64 s[54:55], s47, v238
	v_readlane_b32 s46, v237, 31
	v_readlane_b32 s47, v238, 31
	v_addc_co_u32_e64 v239, s[56:57], 0, v239, s[48:49]
	v_addc_co_u32_e64 v240, s[56:57], 0, v240, s[50:51]
	v_addc_co_u32_e64 v239, s[56:57], 0, v239, s[52:53]
	v_addc_co_u32_e64 v240, s[56:57], 0, v240, s[54:55]
	v_cmp_lt_u32_e64 s[48:49], s46, v237
	v_cmp_lt_u32_e64 s[50:51], s46, v238
	v_cmp_lt_u32_e64 s[52:53], s47, v237
	v_cmp_lt_u32_e64 s[54:55], s47, v238
	v_readlane_b32 s46, v237, 32
	v_readlane_b32 s47, v238, 32
	v_addc_co_u32_e64 v239, s[56:57], 0, v239, s[48:49]
	v_addc_co_u32_e64 v240, s[56:57], 0, v240, s[50:51]
	v_addc_co_u32_e64 v239, s[56:57], 0, v239, s[52:53]
	v_addc_co_u32_e64 v240, s[56:57], 0, v240, s[54:55]
	v_cmp_lt_u32_e64 s[48:49], s46, v237
	v_cmp_lt_u32_e64 s[50:51], s46, v238
	v_cmp_lt_u32_e64 s[52:53], s47, v237
	v_cmp_lt_u32_e64 s[54:55], s47, v238
	v_readlane_b32 s46, v237, 33
	v_readlane_b32 s47, v238, 33
	v_addc_co_u32_e64 v239, s[56:57], 0, v239, s[48:49]
	v_addc_co_u32_e64 v240, s[56:57], 0, v240, s[50:51]
	v_addc_co_u32_e64 v239, s[56:57], 0, v239, s[52:53]
	v_addc_co_u32_e64 v240, s[56:57], 0, v240, s[54:55]
	v_cmp_lt_u32_e64 s[48:49], s46, v237
	v_cmp_lt_u32_e64 s[50:51], s46, v238
	v_cmp_lt_u32_e64 s[52:53], s47, v237
	v_cmp_lt_u32_e64 s[54:55], s47, v238
	v_readlane_b32 s46, v237, 34
	v_readlane_b32 s47, v238, 34
	v_addc_co_u32_e64 v239, s[56:57], 0, v239, s[48:49]
	v_addc_co_u32_e64 v240, s[56:57], 0, v240, s[50:51]
	v_addc_co_u32_e64 v239, s[56:57], 0, v239, s[52:53]
	v_addc_co_u32_e64 v240, s[56:57], 0, v240, s[54:55]
	v_cmp_lt_u32_e64 s[48:49], s46, v237
	v_cmp_lt_u32_e64 s[50:51], s46, v238
	v_cmp_lt_u32_e64 s[52:53], s47, v237
	v_cmp_lt_u32_e64 s[54:55], s47, v238
	v_readlane_b32 s46, v237, 35
	v_readlane_b32 s47, v238, 35
	v_addc_co_u32_e64 v239, s[56:57], 0, v239, s[48:49]
	v_addc_co_u32_e64 v240, s[56:57], 0, v240, s[50:51]
	v_addc_co_u32_e64 v239, s[56:57], 0, v239, s[52:53]
; DEV void peer_gather_token(const Params& p, int tok) {
;     ...
;   const int e0 = p.eidx[(size_t)tok * 128 + lane], e1 = p.eidx[(size_t)tok * 128 + 64 + lane];
;   const int g0 = __builtin_bit_cast(int, p.gw[(size_t)tok * 128 + lane]), g1 = __builtin_bit_cast(int, p.gw[(size_t)tok * 128 + 64 + lane]);
;   u32x2 dn[4][3], up[4][3];
;   auto issue = [&](int k, int slot) {
;     const int e = (k < 64) ? __builtin_amdgcn_readlane(e0, k) : __builtin_amdgcn_readlane(e1, k - 64);
	v_addc_co_u32_e64 v240, s[56:57], 0, v240, s[54:55]
	v_cmp_lt_u32_e64 s[48:49], s46, v237
	v_cmp_lt_u32_e64 s[50:51], s46, v238
	v_cmp_lt_u32_e64 s[52:53], s47, v237
	v_cmp_lt_u32_e64 s[54:55], s47, v238
	v_readlane_b32 s46, v237, 36
	v_readlane_b32 s47, v238, 36
	v_addc_co_u32_e64 v239, s[56:57], 0, v239, s[48:49]
	v_addc_co_u32_e64 v240, s[56:57], 0, v240, s[50:51]
	v_addc_co_u32_e64 v239, s[56:57], 0, v239, s[52:53]
	v_addc_co_u32_e64 v240, s[56:57], 0, v240, s[54:55]
	v_cmp_lt_u32_e64 s[48:49], s46, v237
	v_cmp_lt_u32_e64 s[50:51], s46, v238
	v_cmp_lt_u32_e64 s[52:53], s47, v237
	v_cmp_lt_u32_e64 s[54:55], s47, v238
	v_readlane_b32 s46, v237, 37
	v_readlane_b32 s47, v238, 37
	v_addc_co_u32_e64 v239, s[56:57], 0, v239, s[48:49]
	v_addc_co_u32_e64 v240, s[56:57], 0, v240, s[50:51]
	v_addc_co_u32_e64 v239, s[56:57], 0, v239, s[52:53]
	v_addc_co_u32_e64 v240, s[56:57], 0, v240, s[54:55]
	v_cmp_lt_u32_e64 s[48:49], s46, v237
	v_cmp_lt_u32_e64 s[50:51], s46, v238
	v_cmp_lt_u32_e64 s[52:53], s47, v237
	v_cmp_lt_u32_e64 s[54:55], s47, v238
	v_readlane_b32 s46, v237, 38
	v_readlane_b32 s47, v238, 38
	v_addc_co_u32_e64 v239, s[56:57], 0, v239, s[48:49]
	v_addc_co_u32_e64 v240, s[56:57], 0, v240, s[50:51]
	v_addc_co_u32_e64 v239, s[56:57], 0, v239, s[52:53]
	v_addc_co_u32_e64 v240, s[56:57], 0, v240, s[54:55]
	v_cmp_lt_u32_e64 s[48:49], s46, v237
	v_cmp_lt_u32_e64 s[50:51], s46, v238
	v_cmp_lt_u32_e64 s[52:53], s47, v237
	v_cmp_lt_u32_e64 s[54:55], s47, v238
	v_readlane_b32 s46, v237, 39
	v_readlane_b32 s47, v238, 39
	v_addc_co_u32_e64 v239, s[56:57], 0, v239, s[48:49]
	v_addc_co_u32_e64 v240, s[56:57], 0, v240, s[50:51]
	v_addc_co_u32_e64 v239, s[56:57], 0, v239, s[52:53]
	v_addc_co_u32_e64 v240, s[56:57], 0, v240, s[54:55]
	v_cmp_lt_u32_e64 s[48:49], s46, v237
	v_cmp_lt_u32_e64 s[50:51], s46, v238
	v_cmp_lt_u32_e64 s[52:53], s47, v237
	v_cmp_lt_u32_e64 s[54:55], s47, v238
	v_readlane_b32 s46, v237, 40
	v_readlane_b32 s47, v238, 40
	v_addc_co_u32_e64 v239, s[56:57], 0, v239, s[48:49]
	v_addc_co_u32_e64 v240, s[56:57], 0, v240, s[50:51]
	v_addc_co_u32_e64 v239, s[56:57], 0, v239, s[52:53]
	v_addc_co_u32_e64 v240, s[56:57], 0, v240, s[54:55]
	v_cmp_lt_u32_e64 s[48:49], s46, v237
	v_cmp_lt_u32_e64 s[50:51], s46, v238
	v_cmp_lt_u32_e64 s[52:53], s47, v237
	v_cmp_lt_u32_e64 s[54:55], s47, v238
	v_readlane_b32 s46, v237, 41
	v_readlane_b32 s47, v238, 41
	v_addc_co_u32_e64 v239, s[56:57], 0, v239, s[48:49]
	v_addc_co_u32_e64 v240, s[56:57], 0, v240, s[50:51]
	v_addc_co_u32_e64 v239, s[56:57], 0, v239, s[52:53]
	v_addc_co_u32_e64 v240, s[56:57], 0, v240, s[54:55]
	v_cmp_lt_u32_e64 s[48:49], s46, v237
	v_cmp_lt_u32_e64 s[50:51], s46, v238
	v_cmp_lt_u32_e64 s[52:53], s47, v237
	v_cmp_lt_u32_e64 s[54:55], s47, v238
	v_readlane_b32 s46, v237, 42
	v_readlane_b32 s47, v238, 42
	v_addc_co_u32_e64 v239, s[56:57], 0, v239, s[48:49]
	v_addc_co_u32_e64 v240, s[56:57], 0, v240, s[50:51]
	v_addc_co_u32_e64 v239, s[56:57], 0, v239, s[52:53]
	v_addc_co_u32_e64 v240, s[56:57], 0, v240, s[54:55]
	v_cmp_lt_u32_e64 s[48:49], s46, v237
	v_cmp_lt_u32_e64 s[50:51], s46, v238
	v_cmp_lt_u32_e64 s[52:53], s47, v237
	v_cmp_lt_u32_e64 s[54:55], s47, v238
	v_readlane_b32 s46, v237, 43
	v_readlane_b32 s47, v238, 43
	v_addc_co_u32_e64 v239, s[56:57], 0, v239, s[48:49]
	v_addc_co_u32_e64 v240, s[56:57], 0, v240, s[50:51]
	v_addc_co_u32_e64 v239, s[56:57], 0, v239, s[52:53]
	v_addc_co_u32_e64 v240, s[56:57], 0, v240, s[54:55]
	v_cmp_lt_u32_e64 s[48:49], s46, v237
	v_cmp_lt_u32_e64 s[50:51], s46, v238
	v_cmp_lt_u32_e64 s[52:53], s47, v237
	v_cmp_lt_u32_e64 s[54:55], s47, v238
	v_readlane_b32 s46, v237, 44
	v_readlane_b32 s47, v238, 44
	v_addc_co_u32_e64 v239, s[56:57], 0, v239, s[48:49]
	v_addc_co_u32_e64 v240, s[56:57], 0, v240, s[50:51]
	v_addc_co_u32_e64 v239, s[56:57], 0, v239, s[52:53]
	v_addc_co_u32_e64 v240, s[56:57], 0, v240, s[54:55]
	v_cmp_lt_u32_e64 s[48:49], s46, v237
	v_cmp_lt_u32_e64 s[50:51], s46, v238
	v_cmp_lt_u32_e64 s[52:53], s47, v237
	v_cmp_lt_u32_e64 s[54:55], s47, v238
	v_readlane_b32 s46, v237, 45
	v_readlane_b32 s47, v238, 45
	v_addc_co_u32_e64 v239, s[56:57], 0, v239, s[48:49]
	v_addc_co_u32_e64 v240, s[56:57], 0, v240, s[50:51]
	v_addc_co_u32_e64 v239, s[56:57], 0, v239, s[52:53]
	v_addc_co_u32_e64 v240, s[56:57], 0, v240, s[54:55]
	v_cmp_lt_u32_e64 s[48:49], s46, v237
	v_cmp_lt_u32_e64 s[50:51], s46, v238
	v_cmp_lt_u32_e64 s[52:53], s47, v237
	v_cmp_lt_u32_e64 s[54:55], s47, v238
	v_readlane_b32 s46, v237, 46
	v_readlane_b32 s47, v238, 46
	v_addc_co_u32_e64 v239, s[56:57], 0, v239, s[48:49]
	v_addc_co_u32_e64 v240, s[56:57], 0, v240, s[50:51]
	v_addc_co_u32_e64 v239, s[56:57], 0, v239, s[52:53]
	v_addc_co_u32_e64 v240, s[56:57], 0, v240, s[54:55]
	v_cmp_lt_u32_e64 s[48:49], s46, v237
	v_cmp_lt_u32_e64 s[50:51], s46, v238
	v_cmp_lt_u32_e64 s[52:53], s47, v237
	v_cmp_lt_u32_e64 s[54:55], s47, v238
	v_readlane_b32 s46, v237, 47
	v_readlane_b32 s47, v238, 47
	v_addc_co_u32_e64 v239, s[56:57], 0, v239, s[48:49]
	v_addc_co_u32_e64 v240, s[56:57], 0, v240, s[50:51]
	v_addc_co_u32_e64 v239, s[56:57], 0, v239, s[52:53]
	v_addc_co_u32_e64 v240, s[56:57], 0, v240, s[54:55]
	v_cmp_lt_u32_e64 s[48:49], s46, v237
	v_cmp_lt_u32_e64 s[50:51], s46, v238
	v_cmp_lt_u32_e64 s[52:53], s47, v237
	v_cmp_lt_u32_e64 s[54:55], s47, v238
	v_readlane_b32 s46, v237, 48
	v_readlane_b32 s47, v238, 48
	v_addc_co_u32_e64 v239, s[56:57], 0, v239, s[48:49]
	v_addc_co_u32_e64 v240, s[56:57], 0, v240, s[50:51]
	v_addc_co_u32_e64 v239, s[56:57], 0, v239, s[52:53]
	v_addc_co_u32_e64 v240, s[56:57], 0, v240, s[54:55]
	v_cmp_lt_u32_e64 s[48:49], s46, v237
	v_cmp_lt_u32_e64 s[50:51], s46, v238
; DEV void peer_gather_token(const Params& p, int tok) {
;     ...
;   const int e0 = p.eidx[(size_t)tok * 128 + lane], e1 = p.eidx[(size_t)tok * 128 + 64 + lane];
;   const int g0 = __builtin_bit_cast(int, p.gw[(size_t)tok * 128 + lane]), g1 = __builtin_bit_cast(int, p.gw[(size_t)tok * 128 + 64 + lane]);
;   u32x2 dn[4][3], up[4][3];
;   auto issue = [&](int k, int slot) {
;     const int e = (k < 64) ? __builtin_amdgcn_readlane(e0, k) : __builtin_amdgcn_readlane(e1, k - 64);
	v_cmp_lt_u32_e64 s[52:53], s47, v237
	v_cmp_lt_u32_e64 s[54:55], s47, v238
	v_readlane_b32 s46, v237, 49
	v_readlane_b32 s47, v238, 49
	v_addc_co_u32_e64 v239, s[56:57], 0, v239, s[48:49]
	v_addc_co_u32_e64 v240, s[56:57], 0, v240, s[50:51]
	v_addc_co_u32_e64 v239, s[56:57], 0, v239, s[52:53]
	v_addc_co_u32_e64 v240, s[56:57], 0, v240, s[54:55]
	v_cmp_lt_u32_e64 s[48:49], s46, v237
	v_cmp_lt_u32_e64 s[50:51], s46, v238
	v_cmp_lt_u32_e64 s[52:53], s47, v237
	v_cmp_lt_u32_e64 s[54:55], s47, v238
	v_readlane_b32 s46, v237, 50
	v_readlane_b32 s47, v238, 50
	v_addc_co_u32_e64 v239, s[56:57], 0, v239, s[48:49]
	v_addc_co_u32_e64 v240, s[56:57], 0, v240, s[50:51]
	v_addc_co_u32_e64 v239, s[56:57], 0, v239, s[52:53]
	v_addc_co_u32_e64 v240, s[56:57], 0, v240, s[54:55]
	v_cmp_lt_u32_e64 s[48:49], s46, v237
	v_cmp_lt_u32_e64 s[50:51], s46, v238
	v_cmp_lt_u32_e64 s[52:53], s47, v237
	v_cmp_lt_u32_e64 s[54:55], s47, v238
	v_readlane_b32 s46, v237, 51
	v_readlane_b32 s47, v238, 51
	v_addc_co_u32_e64 v239, s[56:57], 0, v239, s[48:49]
	v_addc_co_u32_e64 v240, s[56:57], 0, v240, s[50:51]
	v_addc_co_u32_e64 v239, s[56:57], 0, v239, s[52:53]
	v_addc_co_u32_e64 v240, s[56:57], 0, v240, s[54:55]
	v_cmp_lt_u32_e64 s[48:49], s46, v237
	v_cmp_lt_u32_e64 s[50:51], s46, v238
	v_cmp_lt_u32_e64 s[52:53], s47, v237
	v_cmp_lt_u32_e64 s[54:55], s47, v238
	v_readlane_b32 s46, v237, 52
	v_readlane_b32 s47, v238, 52
	v_addc_co_u32_e64 v239, s[56:57], 0, v239, s[48:49]
	v_addc_co_u32_e64 v240, s[56:57], 0, v240, s[50:51]
	v_addc_co_u32_e64 v239, s[56:57], 0, v239, s[52:53]
	v_addc_co_u32_e64 v240, s[56:57], 0, v240, s[54:55]
	v_cmp_lt_u32_e64 s[48:49], s46, v237
	v_cmp_lt_u32_e64 s[50:51], s46, v238
	v_cmp_lt_u32_e64 s[52:53], s47, v237
	v_cmp_lt_u32_e64 s[54:55], s47, v238
	v_readlane_b32 s46, v237, 53
	v_readlane_b32 s47, v238, 53
	v_addc_co_u32_e64 v239, s[56:57], 0, v239, s[48:49]
	v_addc_co_u32_e64 v240, s[56:57], 0, v240, s[50:51]
	v_addc_co_u32_e64 v239, s[56:57], 0, v239, s[52:53]
	v_addc_co_u32_e64 v240, s[56:57], 0, v240, s[54:55]
	v_cmp_lt_u32_e64 s[48:49], s46, v237
	v_cmp_lt_u32_e64 s[50:51], s46, v238
	v_cmp_lt_u32_e64 s[52:53], s47, v237
	v_cmp_lt_u32_e64 s[54:55], s47, v238
	v_readlane_b32 s46, v237, 54
	v_readlane_b32 s47, v238, 54
	v_addc_co_u32_e64 v239, s[56:57], 0, v239, s[48:49]
	v_addc_co_u32_e64 v240, s[56:57], 0, v240, s[50:51]
	v_addc_co_u32_e64 v239, s[56:57], 0, v239, s[52:53]
	v_addc_co_u32_e64 v240, s[56:57], 0, v240, s[54:55]
	v_cmp_lt_u32_e64 s[48:49], s46, v237
	v_cmp_lt_u32_e64 s[50:51], s46, v238
	v_cmp_lt_u32_e64 s[52:53], s47, v237
	v_cmp_lt_u32_e64 s[54:55], s47, v238
	v_readlane_b32 s46, v237, 55
	v_readlane_b32 s47, v238, 55
	v_addc_co_u32_e64 v239, s[56:57], 0, v239, s[48:49]
	v_addc_co_u32_e64 v240, s[56:57], 0, v240, s[50:51]
	v_addc_co_u32_e64 v239, s[56:57], 0, v239, s[52:53]
	v_addc_co_u32_e64 v240, s[56:57], 0, v240, s[54:55]
	v_cmp_lt_u32_e64 s[48:49], s46, v237
	v_cmp_lt_u32_e64 s[50:51], s46, v238
	v_cmp_lt_u32_e64 s[52:53], s47, v237
	v_cmp_lt_u32_e64 s[54:55], s47, v238
	v_readlane_b32 s46, v237, 56
	v_readlane_b32 s47, v238, 56
	v_addc_co_u32_e64 v239, s[56:57], 0, v239, s[48:49]
	v_addc_co_u32_e64 v240, s[56:57], 0, v240, s[50:51]
	v_addc_co_u32_e64 v239, s[56:57], 0, v239, s[52:53]
	v_addc_co_u32_e64 v240, s[56:57], 0, v240, s[54:55]
	v_cmp_lt_u32_e64 s[48:49], s46, v237
	v_cmp_lt_u32_e64 s[50:51], s46, v238
	v_cmp_lt_u32_e64 s[52:53], s47, v237
	v_cmp_lt_u32_e64 s[54:55], s47, v238
	v_readlane_b32 s46, v237, 57
	v_readlane_b32 s47, v238, 57
	v_addc_co_u32_e64 v239, s[56:57], 0, v239, s[48:49]
	v_addc_co_u32_e64 v240, s[56:57], 0, v240, s[50:51]
	v_addc_co_u32_e64 v239, s[56:57], 0, v239, s[52:53]
	v_addc_co_u32_e64 v240, s[56:57], 0, v240, s[54:55]
	v_cmp_lt_u32_e64 s[48:49], s46, v237
	v_cmp_lt_u32_e64 s[50:51], s46, v238
	v_cmp_lt_u32_e64 s[52:53], s47, v237
	v_cmp_lt_u32_e64 s[54:55], s47, v238
	v_readlane_b32 s46, v237, 58
	v_readlane_b32 s47, v238, 58
	v_addc_co_u32_e64 v239, s[56:57], 0, v239, s[48:49]
	v_addc_co_u32_e64 v240, s[56:57], 0, v240, s[50:51]
	v_addc_co_u32_e64 v239, s[56:57], 0, v239, s[52:53]
	v_addc_co_u32_e64 v240, s[56:57], 0, v240, s[54:55]
	v_cmp_lt_u32_e64 s[48:49], s46, v237
	v_cmp_lt_u32_e64 s[50:51], s46, v238
	v_cmp_lt_u32_e64 s[52:53], s47, v237
	v_cmp_lt_u32_e64 s[54:55], s47, v238
	v_readlane_b32 s46, v237, 59
	v_readlane_b32 s47, v238, 59
	v_addc_co_u32_e64 v239, s[56:57], 0, v239, s[48:49]
	v_addc_co_u32_e64 v240, s[56:57], 0, v240, s[50:51]
	v_addc_co_u32_e64 v239, s[56:57], 0, v239, s[52:53]
	v_addc_co_u32_e64 v240, s[56:57], 0, v240, s[54:55]
	v_cmp_lt_u32_e64 s[48:49], s46, v237
	v_cmp_lt_u32_e64 s[50:51], s46, v238
	v_cmp_lt_u32_e64 s[52:53], s47, v237
	v_cmp_lt_u32_e64 s[54:55], s47, v238
	v_readlane_b32 s46, v237, 60
	v_readlane_b32 s47, v238, 60
	v_addc_co_u32_e64 v239, s[56:57], 0, v239, s[48:49]
	v_addc_co_u32_e64 v240, s[56:57], 0, v240, s[50:51]
	v_addc_co_u32_e64 v239, s[56:57], 0, v239, s[52:53]
	v_addc_co_u32_e64 v240, s[56:57], 0, v240, s[54:55]
	v_cmp_lt_u32_e64 s[48:49], s46, v237
	v_cmp_lt_u32_e64 s[50:51], s46, v238
	v_cmp_lt_u32_e64 s[52:53], s47, v237
	v_cmp_lt_u32_e64 s[54:55], s47, v238
	v_readlane_b32 s46, v237, 61
	v_readlane_b32 s47, v238, 61
	v_addc_co_u32_e64 v239, s[56:57], 0, v239, s[48:49]
	v_addc_co_u32_e64 v240, s[56:57], 0, v240, s[50:51]
	v_addc_co_u32_e64 v239, s[56:57], 0, v239, s[52:53]
	v_addc_co_u32_e64 v240, s[56:57], 0, v240, s[54:55]
	v_cmp_lt_u32_e64 s[48:49], s46, v237
	v_cmp_lt_u32_e64 s[50:51], s46, v238
	v_cmp_lt_u32_e64 s[52:53], s47, v237
	v_cmp_lt_u32_e64 s[54:55], s47, v238
	v_readlane_b32 s46, v237, 62
	v_readlane_b32 s47, v238, 62
	v_addc_co_u32_e64 v239, s[56:57], 0, v239, s[48:49]
	v_addc_co_u32_e64 v240, s[56:57], 0, v240, s[50:51]
	v_addc_co_u32_e64 v239, s[56:57], 0, v239, s[52:53]
	v_addc_co_u32_e64 v240, s[56:57], 0, v240, s[54:55]
	v_cmp_lt_u32_e64 s[48:49], s46, v237
	v_cmp_lt_u32_e64 s[50:51], s46, v238
	v_cmp_lt_u32_e64 s[52:53], s47, v237
	v_cmp_lt_u32_e64 s[54:55], s47, v238
	v_readlane_b32 s46, v237, 63
	v_readlane_b32 s47, v238, 63
	v_addc_co_u32_e64 v239, s[56:57], 0, v239, s[48:49]
	v_addc_co_u32_e64 v240, s[56:57], 0, v240, s[50:51]
	v_addc_co_u32_e64 v239, s[56:57], 0, v239, s[52:53]
	v_addc_co_u32_e64 v240, s[56:57], 0, v240, s[54:55]
	v_cmp_lt_u32_e64 s[48:49], s46, v237
	v_cmp_lt_u32_e64 s[50:51], s46, v238
	v_cmp_lt_u32_e64 s[52:53], s47, v237
	v_cmp_lt_u32_e64 s[54:55], s47, v238
	s_nop 1
	v_addc_co_u32_e64 v239, s[56:57], 0, v239, s[48:49]
	v_addc_co_u32_e64 v240, s[56:57], 0, v240, s[50:51]
	v_addc_co_u32_e64 v239, s[56:57], 0, v239, s[52:53]
	v_addc_co_u32_e64 v240, s[56:57], 0, v240, s[54:55]
	v_xor_b32_e32 v239, s19, v239
	v_xor_b32_e32 v240, s19, v240
	s_xor_b32 s19, s19, 0x7f
	v_and_b32_e32 v237, 0xfffffc00, v241
	v_lshl_add_u32 v239, v239, 2, v237
	v_lshl_add_u32 v240, v240, 2, v237
	ds_write_b32 v239, v216
	ds_write_b32 v240, v217
	ds_write_b32 v239, v218 offset:512
	ds_write_b32 v240, v219 offset:512
	s_waitcnt lgkmcnt(0)
; DEV float gelu_exact(float v) { return 0.5f * v * (1.f + erff(v * 0.7071067811865476f)); }
; DEV void peer_gather_token(const Params& p, int tok) {
;     ...
;   const int e0 = p.eidx[(size_t)tok * 128 + lane], e1 = p.eidx[(size_t)tok * 128 + 64 + lane];
;   const int g0 = __builtin_bit_cast(int, p.gw[(size_t)tok * 128 + lane]), g1 = __builtin_bit_cast(int, p.gw[(size_t)tok * 128 + 64 + lane]);
;   u32x2 dn[4][3], up[4][3];
;   auto issue = [&](int k, int slot) {
;     const int e = (k < 64) ? __builtin_amdgcn_readlane(e0, k) : __builtin_amdgcn_readlane(e1, k - 64);
;     ...
;       if (k + 3 < 128) issue(k + 3, (s + 3) & 3);
;       const v6u dq = v6u{dn[s][0][0], dn[s][0][1], dn[s][1][0], dn[s][1][1], dn[s][2][0], dn[s][2][1]};
;       const v32f dv = __builtin_amdgcn_cvt_scalef32_pk32_f32_fp6(dq, 1.0f);
;       float d0 = 0.f, d1 = 0.f, d2 = 0.f, d3 = 0.f;
; #pragma unroll
;       for (int i = 0; i < 8; ++i) { d0 += dv[4 * i] * hx[4 * i]; d1 += dv[4 * i + 1] * hx[4 * i + 1]; d2 += dv[4 * i + 2] * hx[4 * i + 2]; d3 += dv[4 * i + 3] * hx[4 * i + 3]; }
;       const float d = wave_sum_fast((d0 + d1) + (d2 + d3)) * (1.f / DOWN_SCALE);
;       const float gk = __builtin_bit_cast(float, (k < 64) ? __builtin_amdgcn_readlane(g0, k) : __builtin_amdgcn_readlane(g1, k - 64));
;       const float act = gelu_exact(d) * gk * (1.f / UP_SCALE);
;       const v6u uq = v6u{up[s][0][0], up[s][0][1], up[s][1][0], up[s][1][1], up[s][2][0], up[s][2][1]};
;       const v32f uv = __builtin_amdgcn_cvt_scalef32_pk32_f32_fp6(uq, 1.0f);
; #pragma unroll
;       for (int i = 0; i < 32; ++i) acc[i] += act * uv[i];
	ds_read_b32 v216, v241
	ds_read_b32 v217, v241 offset:256
	ds_read_b32 v218, v241 offset:512
	ds_read_b32 v219, v241 offset:768
	s_waitcnt lgkmcnt(0)
	v_cvt_scalef32_pk32_f32_fp6 v[2:33], v[98:103], 1.0
	v_mul_f32_e32 v200, v2, v34
	v_mul_f32_e32 v201, v3, v35
	v_mul_f32_e32 v202, v4, v36
	v_mul_f32_e32 v203, v5, v37
	v_fmac_f32_e32 v200, v6, v38
	v_fmac_f32_e32 v201, v7, v39
	v_fmac_f32_e32 v202, v8, v40
	v_fmac_f32_e32 v203, v9, v41
	v_fmac_f32_e32 v200, v10, v42
	v_fmac_f32_e32 v201, v11, v43
	v_fmac_f32_e32 v202, v12, v44
	v_fmac_f32_e32 v203, v13, v45
	v_fmac_f32_e32 v200, v14, v46
	v_fmac_f32_e32 v201, v15, v47
	v_fmac_f32_e32 v202, v16, v48
	v_fmac_f32_e32 v203, v17, v49
	v_fmac_f32_e32 v200, v18, v50
	v_fmac_f32_e32 v201, v19, v51
	v_fmac_f32_e32 v202, v20, v52
	v_fmac_f32_e32 v203, v21, v53
	v_fmac_f32_e32 v200, v22, v54
	v_fmac_f32_e32 v201, v23, v55
	v_fmac_f32_e32 v202, v24, v56
	v_fmac_f32_e32 v203, v25, v57
	v_fmac_f32_e32 v200, v26, v58
	v_fmac_f32_e32 v201, v27, v59
	v_fmac_f32_e32 v202, v28, v60
	v_fmac_f32_e32 v203, v29, v61
	v_fmac_f32_e32 v200, v30, v62
	v_fmac_f32_e32 v201, v31, v63
	v_fmac_f32_e32 v202, v32, v64
	v_fmac_f32_e32 v203, v33, v65
	v_add_f32_e32 v200, v201, v200
	v_add_f32_e32 v202, v203, v202
	v_cvt_scalef32_pk32_f32_fp6 v[2:33], v[104:109], 1.0
	v_add_f32_e32 v200, v202, v200
	s_add_i32 s38, s24, 0
	v_readlane_b32 s26, v199, s38
	s_mov_b32 s39, 0
	v_readlane_b32 s25, v216, s39
	v_add_f32_dpp v200, v200, v200 quad_perm:[1,0,3,2] row_mask:0xf bank_mask:0xf bound_ctrl:1
	s_nop 1
	v_add_f32_dpp v200, v200, v200 quad_perm:[2,3,0,1] row_mask:0xf bank_mask:0xf bound_ctrl:1
	s_nop 1
	v_add_f32_dpp v200, v200, v200 row_half_mirror row_mask:0xf bank_mask:0xf bound_ctrl:1
	s_nop 1
	v_add_f32_dpp v200, v200, v200 row_mirror row_mask:0xf bank_mask:0xf bound_ctrl:1
	s_nop 1
	v_add_f32_dpp v200, v200, v200 row_bcast:15 row_mask:0xa bank_mask:0xf
	s_nop 1
	v_add_f32_dpp v200, v200, v200 row_bcast:31 row_mask:0xc bank_mask:0xf
	s_nop 0
	v_readlane_b32 s27, v200, 63
	v_mul_f32_e32 v204, s27, v212
	v_mul_f32_e32 v205, 0x3f3504f3, v204
	v_cmp_lt_f32_e64 s[32:33], |v205|, 1.0
	s_and_b64 vcc, exec, s[32:33]
	s_cbranch_vccnz .Lsm_33
	v_fma_f32 v208, |v205|, s9, v214
	v_fma_f32 v208, |v205|, v208, s10
	v_fma_f32 v208, |v205|, v208, s11
	v_fma_f32 v208, |v205|, v208, s12
	v_fma_f32 v208, |v205|, v208, s13
	v_fma_f32 v208, |v205|, v208, s14
	v_fma_f32 v208, |v205|, v208, |v205|
	v_mul_f32_e32 v209, 0xbfb8aa3b, v208
	v_fma_f32 v210, v208, s15, -v209
	v_rndne_f32_e32 v211, v209
	v_fmac_f32_e32 v210, 0xb2a5705f, v208
	v_sub_f32_e32 v209, v209, v211
	v_add_f32_e32 v209, v209, v210
	v_cvt_i32_f32_e32 v210, v211
	v_exp_f32_e32 v209, v209
	v_cmp_nlt_f32_e32 vcc, s16, v208
	v_ldexp_f32 v209, v209, v210
	s_nop 0
	v_cndmask_b32_e32 v209, 0, v209, vcc
	v_cmp_ngt_f32_e32 vcc, s17, v208
	s_nop 1
	v_cndmask_b32_e32 v208, v215, v209, vcc
	v_sub_f32_e32 v210, 1.0, v208
	s_branch .Ljn_33

; DEV float gelu_exact(float v) { return 0.5f * v * (1.f + erff(v * 0.7071067811865476f)); }
; DEV void peer_gather_token(const Params& p, int tok) {
;     ...
;       if (k + 3 < 128) issue(k + 3, (s + 3) & 3);
;       const v6u dq = v6u{dn[s][0][0], dn[s][0][1], dn[s][1][0], dn[s][1][1], dn[s][2][0], dn[s][2][1]};
;       const v32f dv = __builtin_amdgcn_cvt_scalef32_pk32_f32_fp6(dq, 1.0f);
;       float d0 = 0.f, d1 = 0.f, d2 = 0.f, d3 = 0.f;
; #pragma unroll
;       for (int i = 0; i < 8; ++i) { d0 += dv[4 * i] * hx[4 * i]; d1 += dv[4 * i + 1] * hx[4 * i + 1]; d2 += dv[4 * i + 2] * hx[4 * i + 2]; d3 += dv[4 * i + 3] * hx[4 * i + 3]; }
;       const float d = wave_sum_fast((d0 + d1) + (d2 + d3)) * (1.f / DOWN_SCALE);
;       const float gk = __builtin_bit_cast(float, (k < 64) ? __builtin_amdgcn_readlane(g0, k) : __builtin_amdgcn_readlane(g1, k - 64));
;       const float act = gelu_exact(d) * gk * (1.f / UP_SCALE);
;       const v6u uq = v6u{up[s][0][0], up[s][0][1], up[s][1][0], up[s][1][1], up[s][2][0], up[s][2][1]};
;       const v32f uv = __builtin_amdgcn_cvt_scalef32_pk32_f32_fp6(uq, 1.0f);
; #pragma unroll
;       for (int i = 0; i < 32; ++i) acc[i] += act * uv[i];
.Ljn_33:
	v_bfi_b32 v209, s18, v210, v205
	v_mul_f32_e32 v208, 0.5, v204
	v_add_f32_e32 v209, 1.0, v209
	v_mul_f32_e32 v208, v208, v209
	v_mul_f32_e32 v208, s26, v208
	v_mul_f32_e32 v206, 0x3e800000, v208
	v_pk_fma_f32 v[66:67], v[2:3], v[206:207], v[66:67] op_sel_hi:[1,0,1]
	v_pk_fma_f32 v[68:69], v[4:5], v[206:207], v[68:69] op_sel_hi:[1,0,1]
	v_pk_fma_f32 v[70:71], v[6:7], v[206:207], v[70:71] op_sel_hi:[1,0,1]
	v_pk_fma_f32 v[72:73], v[8:9], v[206:207], v[72:73] op_sel_hi:[1,0,1]
	v_pk_fma_f32 v[74:75], v[10:11], v[206:207], v[74:75] op_sel_hi:[1,0,1]
	v_pk_fma_f32 v[76:77], v[12:13], v[206:207], v[76:77] op_sel_hi:[1,0,1]
	v_pk_fma_f32 v[78:79], v[14:15], v[206:207], v[78:79] op_sel_hi:[1,0,1]
	v_pk_fma_f32 v[80:81], v[16:17], v[206:207], v[80:81] op_sel_hi:[1,0,1]
	v_pk_fma_f32 v[82:83], v[18:19], v[206:207], v[82:83] op_sel_hi:[1,0,1]
	v_pk_fma_f32 v[84:85], v[20:21], v[206:207], v[84:85] op_sel_hi:[1,0,1]
	v_pk_fma_f32 v[86:87], v[22:23], v[206:207], v[86:87] op_sel_hi:[1,0,1]
	v_pk_fma_f32 v[88:89], v[24:25], v[206:207], v[88:89] op_sel_hi:[1,0,1]
	v_pk_fma_f32 v[90:91], v[26:27], v[206:207], v[90:91] op_sel_hi:[1,0,1]
	v_pk_fma_f32 v[92:93], v[28:29], v[206:207], v[92:93] op_sel_hi:[1,0,1]
	v_pk_fma_f32 v[94:95], v[30:31], v[206:207], v[94:95] op_sel_hi:[1,0,1]
	v_pk_fma_f32 v[96:97], v[32:33], v[206:207], v[96:97] op_sel_hi:[1,0,1]
	s_mul_i32 s40, s25, 0xc00
	s_cmp_lt_u32 s25, 0x1800
	s_cselect_b64 s[28:29], s[2:3], s[4:5]
	s_cmp_lt_u32 s25, 0x2800
	s_cselect_b64 s[28:29], s[28:29], s[62:63]
	s_add_u32 s28, s28, s40
	s_addc_u32 s29, s29, 0
	global_load_dwordx4 v[98:101], v1, s[28:29]
	global_load_dwordx4 v[102:105], v1, s[28:29] offset:2048
	global_load_dwordx4 v[106:109], v1, s[28:29] offset:1024
	s_waitcnt vmcnt(21)
	v_cvt_scalef32_pk32_f32_fp6 v[2:33], v[110:115], 1.0
	v_mul_f32_e32 v200, v2, v34
	v_mul_f32_e32 v201, v3, v35
	v_mul_f32_e32 v202, v4, v36
	v_mul_f32_e32 v203, v5, v37
	v_fmac_f32_e32 v200, v6, v38
	v_fmac_f32_e32 v201, v7, v39
	v_fmac_f32_e32 v202, v8, v40
	v_fmac_f32_e32 v203, v9, v41
	v_fmac_f32_e32 v200, v10, v42
	v_fmac_f32_e32 v201, v11, v43
	v_fmac_f32_e32 v202, v12, v44
	v_fmac_f32_e32 v203, v13, v45
	v_fmac_f32_e32 v200, v14, v46
	v_fmac_f32_e32 v201, v15, v47
	v_fmac_f32_e32 v202, v16, v48
	v_fmac_f32_e32 v203, v17, v49
	v_fmac_f32_e32 v200, v18, v50
	v_fmac_f32_e32 v201, v19, v51
	v_fmac_f32_e32 v202, v20, v52
	v_fmac_f32_e32 v203, v21, v53
	v_fmac_f32_e32 v200, v22, v54
	v_fmac_f32_e32 v201, v23, v55
	v_fmac_f32_e32 v202, v24, v56
	v_fmac_f32_e32 v203, v25, v57
	v_fmac_f32_e32 v200, v26, v58
	v_fmac_f32_e32 v201, v27, v59
	v_fmac_f32_e32 v202, v28, v60
	v_fmac_f32_e32 v203, v29, v61
	v_fmac_f32_e32 v200, v30, v62
	v_fmac_f32_e32 v201, v31, v63
	v_fmac_f32_e32 v202, v32, v64
	v_fmac_f32_e32 v203, v33, v65
	v_add_f32_e32 v200, v201, v200
	v_add_f32_e32 v202, v203, v202
	v_cvt_scalef32_pk32_f32_fp6 v[2:33], v[116:121], 1.0
	v_add_f32_e32 v200, v202, v200
	s_add_i32 s38, s24, 1
	v_readlane_b32 s26, v199, s38
	s_mov_b32 s39, 1
	v_readlane_b32 s25, v216, s39
	v_add_f32_dpp v200, v200, v200 quad_perm:[1,0,3,2] row_mask:0xf bank_mask:0xf bound_ctrl:1
	s_nop 1
	v_add_f32_dpp v200, v200, v200 quad_perm:[2,3,0,1] row_mask:0xf bank_mask:0xf bound_ctrl:1
	s_nop 1
	v_add_f32_dpp v200, v200, v200 row_half_mirror row_mask:0xf bank_mask:0xf bound_ctrl:1
	s_nop 1
	v_add_f32_dpp v200, v200, v200 row_mirror row_mask:0xf bank_mask:0xf bound_ctrl:1
	s_nop 1
	v_add_f32_dpp v200, v200, v200 row_bcast:15 row_mask:0xa bank_mask:0xf
	s_nop 1
	v_add_f32_dpp v200, v200, v200 row_bcast:31 row_mask:0xc bank_mask:0xf
	s_nop 0
	v_readlane_b32 s27, v200, 63
	v_mul_f32_e32 v204, s27, v212
	v_mul_f32_e32 v205, 0x3f3504f3, v204
	v_cmp_lt_f32_e64 s[32:33], |v205|, 1.0
	s_and_b64 vcc, exec, s[32:33]
	s_cbranch_vccnz .Lsm_35
	v_fma_f32 v208, |v205|, s9, v214
	v_fma_f32 v208, |v205|, v208, s10
	v_fma_f32 v208, |v205|, v208, s11
	v_fma_f32 v208, |v205|, v208, s12
	v_fma_f32 v208, |v205|, v208, s13
	v_fma_f32 v208, |v205|, v208, s14
	v_fma_f32 v208, |v205|, v208, |v205|
	v_mul_f32_e32 v209, 0xbfb8aa3b, v208
	v_fma_f32 v210, v208, s15, -v209
	v_rndne_f32_e32 v211, v209
	v_fmac_f32_e32 v210, 0xb2a5705f, v208
	v_sub_f32_e32 v209, v209, v211
	v_add_f32_e32 v209, v209, v210
	v_cvt_i32_f32_e32 v210, v211
	v_exp_f32_e32 v209, v209
	v_cmp_nlt_f32_e32 vcc, s16, v208
	v_ldexp_f32 v209, v209, v210
	s_nop 0
	v_cndmask_b32_e32 v209, 0, v209, vcc
	v_cmp_ngt_f32_e32 vcc, s17, v208
	s_nop 1
	v_cndmask_b32_e32 v208, v215, v209, vcc
	v_sub_f32_e32 v210, 1.0, v208
	s_branch .Ljn_35

; DEV float gelu_exact(float v) { return 0.5f * v * (1.f + erff(v * 0.7071067811865476f)); }
; DEV void peer_gather_token(const Params& p, int tok) {
;     ...
;       if (k + 3 < 128) issue(k + 3, (s + 3) & 3);
;       const v6u dq = v6u{dn[s][0][0], dn[s][0][1], dn[s][1][0], dn[s][1][1], dn[s][2][0], dn[s][2][1]};
;       const v32f dv = __builtin_amdgcn_cvt_scalef32_pk32_f32_fp6(dq, 1.0f);
;       float d0 = 0.f, d1 = 0.f, d2 = 0.f, d3 = 0.f;
; #pragma unroll
;       for (int i = 0; i < 8; ++i) { d0 += dv[4 * i] * hx[4 * i]; d1 += dv[4 * i + 1] * hx[4 * i + 1]; d2 += dv[4 * i + 2] * hx[4 * i + 2]; d3 += dv[4 * i + 3] * hx[4 * i + 3]; }
;       const float d = wave_sum_fast((d0 + d1) + (d2 + d3)) * (1.f / DOWN_SCALE);
;       const float gk = __builtin_bit_cast(float, (k < 64) ? __builtin_amdgcn_readlane(g0, k) : __builtin_amdgcn_readlane(g1, k - 64));
;       const float act = gelu_exact(d) * gk * (1.f / UP_SCALE);
;       const v6u uq = v6u{up[s][0][0], up[s][0][1], up[s][1][0], up[s][1][1], up[s][2][0], up[s][2][1]};
;       const v32f uv = __builtin_amdgcn_cvt_scalef32_pk32_f32_fp6(uq, 1.0f);
; #pragma unroll
;       for (int i = 0; i < 32; ++i) acc[i] += act * uv[i];
.Ljn_35:
	v_bfi_b32 v209, s18, v210, v205
	v_mul_f32_e32 v208, 0.5, v204
	v_add_f32_e32 v209, 1.0, v209
	v_mul_f32_e32 v208, v208, v209
	v_mul_f32_e32 v208, s26, v208
	v_mul_f32_e32 v206, 0x3e800000, v208
	v_pk_fma_f32 v[66:67], v[2:3], v[206:207], v[66:67] op_sel_hi:[1,0,1]
	v_pk_fma_f32 v[68:69], v[4:5], v[206:207], v[68:69] op_sel_hi:[1,0,1]
	v_pk_fma_f32 v[70:71], v[6:7], v[206:207], v[70:71] op_sel_hi:[1,0,1]
	v_pk_fma_f32 v[72:73], v[8:9], v[206:207], v[72:73] op_sel_hi:[1,0,1]
	v_pk_fma_f32 v[74:75], v[10:11], v[206:207], v[74:75] op_sel_hi:[1,0,1]
	v_pk_fma_f32 v[76:77], v[12:13], v[206:207], v[76:77] op_sel_hi:[1,0,1]
	v_pk_fma_f32 v[78:79], v[14:15], v[206:207], v[78:79] op_sel_hi:[1,0,1]
	v_pk_fma_f32 v[80:81], v[16:17], v[206:207], v[80:81] op_sel_hi:[1,0,1]
	v_pk_fma_f32 v[82:83], v[18:19], v[206:207], v[82:83] op_sel_hi:[1,0,1]
	v_pk_fma_f32 v[84:85], v[20:21], v[206:207], v[84:85] op_sel_hi:[1,0,1]
	v_pk_fma_f32 v[86:87], v[22:23], v[206:207], v[86:87] op_sel_hi:[1,0,1]
	v_pk_fma_f32 v[88:89], v[24:25], v[206:207], v[88:89] op_sel_hi:[1,0,1]
	v_pk_fma_f32 v[90:91], v[26:27], v[206:207], v[90:91] op_sel_hi:[1,0,1]
	v_pk_fma_f32 v[92:93], v[28:29], v[206:207], v[92:93] op_sel_hi:[1,0,1]
	v_pk_fma_f32 v[94:95], v[30:31], v[206:207], v[94:95] op_sel_hi:[1,0,1]
	v_pk_fma_f32 v[96:97], v[32:33], v[206:207], v[96:97] op_sel_hi:[1,0,1]
	s_mul_i32 s40, s25, 0xc00
	s_cmp_lt_u32 s25, 0x1800
	s_cselect_b64 s[28:29], s[2:3], s[4:5]
	s_cmp_lt_u32 s25, 0x2800
	s_cselect_b64 s[28:29], s[28:29], s[62:63]
	s_add_u32 s28, s28, s40
	s_addc_u32 s29, s29, 0
	global_load_dwordx4 v[110:113], v1, s[28:29]
	global_load_dwordx4 v[114:117], v1, s[28:29] offset:2048
	global_load_dwordx4 v[118:121], v1, s[28:29] offset:1024
	s_waitcnt vmcnt(21)
	v_cvt_scalef32_pk32_f32_fp6 v[2:33], v[122:127], 1.0
	v_mul_f32_e32 v200, v2, v34
	v_mul_f32_e32 v201, v3, v35
	v_mul_f32_e32 v202, v4, v36
	v_mul_f32_e32 v203, v5, v37
	v_fmac_f32_e32 v200, v6, v38
	v_fmac_f32_e32 v201, v7, v39
	v_fmac_f32_e32 v202, v8, v40
	v_fmac_f32_e32 v203, v9, v41
	v_fmac_f32_e32 v200, v10, v42
	v_fmac_f32_e32 v201, v11, v43
	v_fmac_f32_e32 v202, v12, v44
	v_fmac_f32_e32 v203, v13, v45
	v_fmac_f32_e32 v200, v14, v46
	v_fmac_f32_e32 v201, v15, v47
	v_fmac_f32_e32 v202, v16, v48
	v_fmac_f32_e32 v203, v17, v49
	v_fmac_f32_e32 v200, v18, v50
	v_fmac_f32_e32 v201, v19, v51
	v_fmac_f32_e32 v202, v20, v52
	v_fmac_f32_e32 v203, v21, v53
	v_fmac_f32_e32 v200, v22, v54
	v_fmac_f32_e32 v201, v23, v55
	v_fmac_f32_e32 v202, v24, v56
	v_fmac_f32_e32 v203, v25, v57
	v_fmac_f32_e32 v200, v26, v58
	v_fmac_f32_e32 v201, v27, v59
	v_fmac_f32_e32 v202, v28, v60
	v_fmac_f32_e32 v203, v29, v61
	v_fmac_f32_e32 v200, v30, v62
	v_fmac_f32_e32 v201, v31, v63
	v_fmac_f32_e32 v202, v32, v64
	v_fmac_f32_e32 v203, v33, v65
	v_add_f32_e32 v200, v201, v200
	v_add_f32_e32 v202, v203, v202
	v_cvt_scalef32_pk32_f32_fp6 v[2:33], v[128:133], 1.0
	v_add_f32_e32 v200, v202, v200
	s_add_i32 s38, s24, 2
	v_readlane_b32 s26, v199, s38
	s_mov_b32 s39, 2
	v_readlane_b32 s25, v216, s39
	v_add_f32_dpp v200, v200, v200 quad_perm:[1,0,3,2] row_mask:0xf bank_mask:0xf bound_ctrl:1
	s_nop 1
	v_add_f32_dpp v200, v200, v200 quad_perm:[2,3,0,1] row_mask:0xf bank_mask:0xf bound_ctrl:1
	s_nop 1
	v_add_f32_dpp v200, v200, v200 row_half_mirror row_mask:0xf bank_mask:0xf bound_ctrl:1
	s_nop 1
	v_add_f32_dpp v200, v200, v200 row_mirror row_mask:0xf bank_mask:0xf bound_ctrl:1
	s_nop 1
	v_add_f32_dpp v200, v200, v200 row_bcast:15 row_mask:0xa bank_mask:0xf
	s_nop 1
	v_add_f32_dpp v200, v200, v200 row_bcast:31 row_mask:0xc bank_mask:0xf
	s_nop 0
	v_readlane_b32 s27, v200, 63
	v_mul_f32_e32 v204, s27, v212
	v_mul_f32_e32 v205, 0x3f3504f3, v204
	v_cmp_lt_f32_e64 s[32:33], |v205|, 1.0
	s_and_b64 vcc, exec, s[32:33]
	s_cbranch_vccnz .Lsm_37
	v_fma_f32 v208, |v205|, s9, v214
	v_fma_f32 v208, |v205|, v208, s10
	v_fma_f32 v208, |v205|, v208, s11
	v_fma_f32 v208, |v205|, v208, s12
	v_fma_f32 v208, |v205|, v208, s13
	v_fma_f32 v208, |v205|, v208, s14
	v_fma_f32 v208, |v205|, v208, |v205|
	v_mul_f32_e32 v209, 0xbfb8aa3b, v208
	v_fma_f32 v210, v208, s15, -v209
	v_rndne_f32_e32 v211, v209
	v_fmac_f32_e32 v210, 0xb2a5705f, v208
	v_sub_f32_e32 v209, v209, v211
	v_add_f32_e32 v209, v209, v210
	v_cvt_i32_f32_e32 v210, v211
	v_exp_f32_e32 v209, v209
	v_cmp_nlt_f32_e32 vcc, s16, v208
	v_ldexp_f32 v209, v209, v210
	s_nop 0
	v_cndmask_b32_e32 v209, 0, v209, vcc
	v_cmp_ngt_f32_e32 vcc, s17, v208
	s_nop 1
	v_cndmask_b32_e32 v208, v215, v209, vcc
	v_sub_f32_e32 v210, 1.0, v208
	s_branch .Ljn_37

; DEV float gelu_exact(float v) { return 0.5f * v * (1.f + erff(v * 0.7071067811865476f)); }
; DEV void peer_gather_token(const Params& p, int tok) {
;     ...
;       if (k + 3 < 128) issue(k + 3, (s + 3) & 3);
;       const v6u dq = v6u{dn[s][0][0], dn[s][0][1], dn[s][1][0], dn[s][1][1], dn[s][2][0], dn[s][2][1]};
;       const v32f dv = __builtin_amdgcn_cvt_scalef32_pk32_f32_fp6(dq, 1.0f);
;       float d0 = 0.f, d1 = 0.f, d2 = 0.f, d3 = 0.f;
; #pragma unroll
;       for (int i = 0; i < 8; ++i) { d0 += dv[4 * i] * hx[4 * i]; d1 += dv[4 * i + 1] * hx[4 * i + 1]; d2 += dv[4 * i + 2] * hx[4 * i + 2]; d3 += dv[4 * i + 3] * hx[4 * i + 3]; }
;       const float d = wave_sum_fast((d0 + d1) + (d2 + d3)) * (1.f / DOWN_SCALE);
;       const float gk = __builtin_bit_cast(float, (k < 64) ? __builtin_amdgcn_readlane(g0, k) : __builtin_amdgcn_readlane(g1, k - 64));
;       const float act = gelu_exact(d) * gk * (1.f / UP_SCALE);
;       const v6u uq = v6u{up[s][0][0], up[s][0][1], up[s][1][0], up[s][1][1], up[s][2][0], up[s][2][1]};
;       const v32f uv = __builtin_amdgcn_cvt_scalef32_pk32_f32_fp6(uq, 1.0f);
; #pragma unroll
;       for (int i = 0; i < 32; ++i) acc[i] += act * uv[i];
.Ljn_37:
	v_bfi_b32 v209, s18, v210, v205
	v_mul_f32_e32 v208, 0.5, v204
	v_add_f32_e32 v209, 1.0, v209
	v_mul_f32_e32 v208, v208, v209
	v_mul_f32_e32 v208, s26, v208
	v_mul_f32_e32 v206, 0x3e800000, v208
	v_pk_fma_f32 v[66:67], v[2:3], v[206:207], v[66:67] op_sel_hi:[1,0,1]
	v_pk_fma_f32 v[68:69], v[4:5], v[206:207], v[68:69] op_sel_hi:[1,0,1]
	v_pk_fma_f32 v[70:71], v[6:7], v[206:207], v[70:71] op_sel_hi:[1,0,1]
	v_pk_fma_f32 v[72:73], v[8:9], v[206:207], v[72:73] op_sel_hi:[1,0,1]
	v_pk_fma_f32 v[74:75], v[10:11], v[206:207], v[74:75] op_sel_hi:[1,0,1]
	v_pk_fma_f32 v[76:77], v[12:13], v[206:207], v[76:77] op_sel_hi:[1,0,1]
	v_pk_fma_f32 v[78:79], v[14:15], v[206:207], v[78:79] op_sel_hi:[1,0,1]
	v_pk_fma_f32 v[80:81], v[16:17], v[206:207], v[80:81] op_sel_hi:[1,0,1]
	v_pk_fma_f32 v[82:83], v[18:19], v[206:207], v[82:83] op_sel_hi:[1,0,1]
	v_pk_fma_f32 v[84:85], v[20:21], v[206:207], v[84:85] op_sel_hi:[1,0,1]
	v_pk_fma_f32 v[86:87], v[22:23], v[206:207], v[86:87] op_sel_hi:[1,0,1]
	v_pk_fma_f32 v[88:89], v[24:25], v[206:207], v[88:89] op_sel_hi:[1,0,1]
	v_pk_fma_f32 v[90:91], v[26:27], v[206:207], v[90:91] op_sel_hi:[1,0,1]
	v_pk_fma_f32 v[92:93], v[28:29], v[206:207], v[92:93] op_sel_hi:[1,0,1]
	v_pk_fma_f32 v[94:95], v[30:31], v[206:207], v[94:95] op_sel_hi:[1,0,1]
	v_pk_fma_f32 v[96:97], v[32:33], v[206:207], v[96:97] op_sel_hi:[1,0,1]
	s_mul_i32 s40, s25, 0xc00
	s_cmp_lt_u32 s25, 0x1800
	s_cselect_b64 s[28:29], s[2:3], s[4:5]
	s_cmp_lt_u32 s25, 0x2800
	s_cselect_b64 s[28:29], s[28:29], s[62:63]
	s_add_u32 s28, s28, s40
	s_addc_u32 s29, s29, 0
	global_load_dwordx4 v[122:125], v1, s[28:29]
	global_load_dwordx4 v[126:129], v1, s[28:29] offset:2048
	global_load_dwordx4 v[130:133], v1, s[28:29] offset:1024
	s_waitcnt vmcnt(21)
	v_cvt_scalef32_pk32_f32_fp6 v[2:33], v[134:139], 1.0
	v_mul_f32_e32 v200, v2, v34
	v_mul_f32_e32 v201, v3, v35
	v_mul_f32_e32 v202, v4, v36
	v_mul_f32_e32 v203, v5, v37
	v_fmac_f32_e32 v200, v6, v38
	v_fmac_f32_e32 v201, v7, v39
	v_fmac_f32_e32 v202, v8, v40
	v_fmac_f32_e32 v203, v9, v41
	v_fmac_f32_e32 v200, v10, v42
	v_fmac_f32_e32 v201, v11, v43
	v_fmac_f32_e32 v202, v12, v44
	v_fmac_f32_e32 v203, v13, v45
	v_fmac_f32_e32 v200, v14, v46
	v_fmac_f32_e32 v201, v15, v47
	v_fmac_f32_e32 v202, v16, v48
	v_fmac_f32_e32 v203, v17, v49
	v_fmac_f32_e32 v200, v18, v50
	v_fmac_f32_e32 v201, v19, v51
	v_fmac_f32_e32 v202, v20, v52
	v_fmac_f32_e32 v203, v21, v53
	v_fmac_f32_e32 v200, v22, v54
	v_fmac_f32_e32 v201, v23, v55
	v_fmac_f32_e32 v202, v24, v56
	v_fmac_f32_e32 v203, v25, v57
	v_fmac_f32_e32 v200, v26, v58
	v_fmac_f32_e32 v201, v27, v59
	v_fmac_f32_e32 v202, v28, v60
	v_fmac_f32_e32 v203, v29, v61
	v_fmac_f32_e32 v200, v30, v62
	v_fmac_f32_e32 v201, v31, v63
	v_fmac_f32_e32 v202, v32, v64
	v_fmac_f32_e32 v203, v33, v65
	v_add_f32_e32 v200, v201, v200
	v_add_f32_e32 v202, v203, v202
	v_cvt_scalef32_pk32_f32_fp6 v[2:33], v[140:145], 1.0
	v_add_f32_e32 v200, v202, v200
	s_add_i32 s38, s24, 3
	v_readlane_b32 s26, v199, s38
	s_mov_b32 s39, 3
	v_readlane_b32 s25, v216, s39
	v_add_f32_dpp v200, v200, v200 quad_perm:[1,0,3,2] row_mask:0xf bank_mask:0xf bound_ctrl:1
	s_nop 1
	v_add_f32_dpp v200, v200, v200 quad_perm:[2,3,0,1] row_mask:0xf bank_mask:0xf bound_ctrl:1
	s_nop 1
	v_add_f32_dpp v200, v200, v200 row_half_mirror row_mask:0xf bank_mask:0xf bound_ctrl:1
	s_nop 1
	v_add_f32_dpp v200, v200, v200 row_mirror row_mask:0xf bank_mask:0xf bound_ctrl:1
	s_nop 1
	v_add_f32_dpp v200, v200, v200 row_bcast:15 row_mask:0xa bank_mask:0xf
	s_nop 1
	v_add_f32_dpp v200, v200, v200 row_bcast:31 row_mask:0xc bank_mask:0xf
	s_nop 0
	v_readlane_b32 s27, v200, 63
	v_mul_f32_e32 v204, s27, v212
	v_mul_f32_e32 v205, 0x3f3504f3, v204
	v_cmp_lt_f32_e64 s[32:33], |v205|, 1.0
	s_and_b64 vcc, exec, s[32:33]
	s_cbranch_vccnz .Lsm_39
	v_fma_f32 v208, |v205|, s9, v214
	v_fma_f32 v208, |v205|, v208, s10
	v_fma_f32 v208, |v205|, v208, s11
	v_fma_f32 v208, |v205|, v208, s12
	v_fma_f32 v208, |v205|, v208, s13
	v_fma_f32 v208, |v205|, v208, s14
	v_fma_f32 v208, |v205|, v208, |v205|
	v_mul_f32_e32 v209, 0xbfb8aa3b, v208
	v_fma_f32 v210, v208, s15, -v209
	v_rndne_f32_e32 v211, v209
	v_fmac_f32_e32 v210, 0xb2a5705f, v208
	v_sub_f32_e32 v209, v209, v211
	v_add_f32_e32 v209, v209, v210
	v_cvt_i32_f32_e32 v210, v211
	v_exp_f32_e32 v209, v209
	v_cmp_nlt_f32_e32 vcc, s16, v208
	v_ldexp_f32 v209, v209, v210
	s_nop 0
	v_cndmask_b32_e32 v209, 0, v209, vcc
	v_cmp_ngt_f32_e32 vcc, s17, v208
	s_nop 1
	v_cndmask_b32_e32 v208, v215, v209, vcc
	v_sub_f32_e32 v210, 1.0, v208
	s_branch .Ljn_39

; DEV float gelu_exact(float v) { return 0.5f * v * (1.f + erff(v * 0.7071067811865476f)); }
; DEV void peer_gather_token(const Params& p, int tok) {
;     ...
;   auto issue = [&](int k, int slot) {
;     const int e = (k < 64) ? __builtin_amdgcn_readlane(e0, k) : __builtin_amdgcn_readlane(e1, k - 64);
;     const unsigned char* dr = p.down8 + (size_t)e * ROW6 + lane * 24;
;     const unsigned char* ur = p.up8 + (size_t)e * ROW6 + lane * 24;
; #pragma unroll
;     for (int i = 0; i < 3; ++i) { dn[slot][i] = *(const u32x2*)(dr + i * 8); up[slot][i] = *(const u32x2*)(ur + i * 8); }
;   };
;   issue(0, 0); issue(1, 1); issue(2, 2);
; #pragma unroll 1
;   for (int k4 = 0; k4 < 128; k4 += 4) {
; #pragma unroll
;     for (int s = 0; s < 4; ++s) {
;       const int k = k4 + s;
;       if (k + 3 < 128) issue(k + 3, (s + 3) & 3);
;       const v6u dq = v6u{dn[s][0][0], dn[s][0][1], dn[s][1][0], dn[s][1][1], dn[s][2][0], dn[s][2][1]};
;       const v32f dv = __builtin_amdgcn_cvt_scalef32_pk32_f32_fp6(dq, 1.0f);
;       float d0 = 0.f, d1 = 0.f, d2 = 0.f, d3 = 0.f;
; #pragma unroll
;       for (int i = 0; i < 8; ++i) { d0 += dv[4 * i] * hx[4 * i]; d1 += dv[4 * i + 1] * hx[4 * i + 1]; d2 += dv[4 * i + 2] * hx[4 * i + 2]; d3 += dv[4 * i + 3] * hx[4 * i + 3]; }
;       const float d = wave_sum_fast((d0 + d1) + (d2 + d3)) * (1.f / DOWN_SCALE);
;       const float gk = __builtin_bit_cast(float, (k < 64) ? __builtin_amdgcn_readlane(g0, k) : __builtin_amdgcn_readlane(g1, k - 64));
;       const float act = gelu_exact(d) * gk * (1.f / UP_SCALE);
;       const v6u uq = v6u{up[s][0][0], up[s][0][1], up[s][1][0], up[s][1][1], up[s][2][0], up[s][2][1]};
;       const v32f uv = __builtin_amdgcn_cvt_scalef32_pk32_f32_fp6(uq, 1.0f);
; #pragma unroll
;       for (int i = 0; i < 32; ++i) acc[i] += act * uv[i];
.Ljn_39:
	v_bfi_b32 v209, s18, v210, v205
	v_mul_f32_e32 v208, 0.5, v204
	v_add_f32_e32 v209, 1.0, v209
	v_mul_f32_e32 v208, v208, v209
	v_mul_f32_e32 v208, s26, v208
	v_mul_f32_e32 v206, 0x3e800000, v208
	v_pk_fma_f32 v[66:67], v[2:3], v[206:207], v[66:67] op_sel_hi:[1,0,1]
	v_pk_fma_f32 v[68:69], v[4:5], v[206:207], v[68:69] op_sel_hi:[1,0,1]
	v_pk_fma_f32 v[70:71], v[6:7], v[206:207], v[70:71] op_sel_hi:[1,0,1]
	v_pk_fma_f32 v[72:73], v[8:9], v[206:207], v[72:73] op_sel_hi:[1,0,1]
	v_pk_fma_f32 v[74:75], v[10:11], v[206:207], v[74:75] op_sel_hi:[1,0,1]
	v_pk_fma_f32 v[76:77], v[12:13], v[206:207], v[76:77] op_sel_hi:[1,0,1]
	v_pk_fma_f32 v[78:79], v[14:15], v[206:207], v[78:79] op_sel_hi:[1,0,1]
	v_pk_fma_f32 v[80:81], v[16:17], v[206:207], v[80:81] op_sel_hi:[1,0,1]
	v_pk_fma_f32 v[82:83], v[18:19], v[206:207], v[82:83] op_sel_hi:[1,0,1]
	v_pk_fma_f32 v[84:85], v[20:21], v[206:207], v[84:85] op_sel_hi:[1,0,1]
	v_pk_fma_f32 v[86:87], v[22:23], v[206:207], v[86:87] op_sel_hi:[1,0,1]
	v_pk_fma_f32 v[88:89], v[24:25], v[206:207], v[88:89] op_sel_hi:[1,0,1]
	v_pk_fma_f32 v[90:91], v[26:27], v[206:207], v[90:91] op_sel_hi:[1,0,1]
	v_pk_fma_f32 v[92:93], v[28:29], v[206:207], v[92:93] op_sel_hi:[1,0,1]
	v_pk_fma_f32 v[94:95], v[30:31], v[206:207], v[94:95] op_sel_hi:[1,0,1]
	v_pk_fma_f32 v[96:97], v[32:33], v[206:207], v[96:97] op_sel_hi:[1,0,1]
	s_mul_i32 s40, s25, 0xc00
	s_cmp_lt_u32 s25, 0x1800
	s_cselect_b64 s[28:29], s[2:3], s[4:5]
	s_cmp_lt_u32 s25, 0x2800
	s_cselect_b64 s[28:29], s[28:29], s[62:63]
	s_add_u32 s28, s28, s40
	s_addc_u32 s29, s29, 0
	global_load_dwordx4 v[134:137], v1, s[28:29]
	global_load_dwordx4 v[138:141], v1, s[28:29] offset:2048
	global_load_dwordx4 v[142:145], v1, s[28:29] offset:1024
	s_waitcnt vmcnt(21)
	v_cvt_scalef32_pk32_f32_fp6 v[2:33], v[146:151], 1.0
	v_mul_f32_e32 v200, v2, v34
	v_mul_f32_e32 v201, v3, v35
	v_mul_f32_e32 v202, v4, v36
	v_mul_f32_e32 v203, v5, v37
	v_fmac_f32_e32 v200, v6, v38
	v_fmac_f32_e32 v201, v7, v39
	v_fmac_f32_e32 v202, v8, v40
	v_fmac_f32_e32 v203, v9, v41
	v_fmac_f32_e32 v200, v10, v42
	v_fmac_f32_e32 v201, v11, v43
	v_fmac_f32_e32 v202, v12, v44
	v_fmac_f32_e32 v203, v13, v45
	v_fmac_f32_e32 v200, v14, v46
	v_fmac_f32_e32 v201, v15, v47
	v_fmac_f32_e32 v202, v16, v48
	v_fmac_f32_e32 v203, v17, v49
	v_fmac_f32_e32 v200, v18, v50
	v_fmac_f32_e32 v201, v19, v51
	v_fmac_f32_e32 v202, v20, v52
	v_fmac_f32_e32 v203, v21, v53
	v_fmac_f32_e32 v200, v22, v54
	v_fmac_f32_e32 v201, v23, v55
	v_fmac_f32_e32 v202, v24, v56
	v_fmac_f32_e32 v203, v25, v57
	v_fmac_f32_e32 v200, v26, v58
	v_fmac_f32_e32 v201, v27, v59
	v_fmac_f32_e32 v202, v28, v60
	v_fmac_f32_e32 v203, v29, v61
	v_fmac_f32_e32 v200, v30, v62
	v_fmac_f32_e32 v201, v31, v63
	v_fmac_f32_e32 v202, v32, v64
	v_fmac_f32_e32 v203, v33, v65
	v_add_f32_e32 v200, v201, v200
	v_add_f32_e32 v202, v203, v202
	v_cvt_scalef32_pk32_f32_fp6 v[2:33], v[152:157], 1.0
	v_add_f32_e32 v200, v202, v200
	s_add_i32 s38, s24, 4
	v_readlane_b32 s26, v199, s38
	s_mov_b32 s39, 4
	v_readlane_b32 s25, v216, s39
	v_add_f32_dpp v200, v200, v200 quad_perm:[1,0,3,2] row_mask:0xf bank_mask:0xf bound_ctrl:1
	s_nop 1
	v_add_f32_dpp v200, v200, v200 quad_perm:[2,3,0,1] row_mask:0xf bank_mask:0xf bound_ctrl:1
	s_nop 1
	v_add_f32_dpp v200, v200, v200 row_half_mirror row_mask:0xf bank_mask:0xf bound_ctrl:1
	s_nop 1
	v_add_f32_dpp v200, v200, v200 row_mirror row_mask:0xf bank_mask:0xf bound_ctrl:1
	s_nop 1
	v_add_f32_dpp v200, v200, v200 row_bcast:15 row_mask:0xa bank_mask:0xf
	s_nop 1
	v_add_f32_dpp v200, v200, v200 row_bcast:31 row_mask:0xc bank_mask:0xf
	s_nop 0
	v_readlane_b32 s27, v200, 63
	v_mul_f32_e32 v204, s27, v212
	v_mul_f32_e32 v205, 0x3f3504f3, v204
	v_cmp_lt_f32_e64 s[32:33], |v205|, 1.0
	s_and_b64 vcc, exec, s[32:33]
	s_cbranch_vccnz .Lsm_41
	v_fma_f32 v208, |v205|, s9, v214
	v_fma_f32 v208, |v205|, v208, s10
	v_fma_f32 v208, |v205|, v208, s11
	v_fma_f32 v208, |v205|, v208, s12
	v_fma_f32 v208, |v205|, v208, s13
	v_fma_f32 v208, |v205|, v208, s14
	v_fma_f32 v208, |v205|, v208, |v205|
	v_mul_f32_e32 v209, 0xbfb8aa3b, v208
	v_fma_f32 v210, v208, s15, -v209
	v_rndne_f32_e32 v211, v209
	v_fmac_f32_e32 v210, 0xb2a5705f, v208
	v_sub_f32_e32 v209, v209, v211
	v_add_f32_e32 v209, v209, v210
	v_cvt_i32_f32_e32 v210, v211
	v_exp_f32_e32 v209, v209
	v_cmp_nlt_f32_e32 vcc, s16, v208
	v_ldexp_f32 v209, v209, v210
	s_nop 0
	v_cndmask_b32_e32 v209, 0, v209, vcc
	v_cmp_ngt_f32_e32 vcc, s17, v208
	s_nop 1
	v_cndmask_b32_e32 v208, v215, v209, vcc
	v_sub_f32_e32 v210, 1.0, v208
	s_branch .Ljn_41

; DEV float gelu_exact(float v) { return 0.5f * v * (1.f + erff(v * 0.7071067811865476f)); }
; DEV void peer_gather_token(const Params& p, int tok) {
;     ...
;   auto issue = [&](int k, int slot) {
;     const int e = (k < 64) ? __builtin_amdgcn_readlane(e0, k) : __builtin_amdgcn_readlane(e1, k - 64);
;     const unsigned char* dr = p.down8 + (size_t)e * ROW6 + lane * 24;
;     const unsigned char* ur = p.up8 + (size_t)e * ROW6 + lane * 24;
; #pragma unroll
;     for (int i = 0; i < 3; ++i) { dn[slot][i] = *(const u32x2*)(dr + i * 8); up[slot][i] = *(const u32x2*)(ur + i * 8); }
;   };
;   issue(0, 0); issue(1, 1); issue(2, 2);
; #pragma unroll 1
;   for (int k4 = 0; k4 < 128; k4 += 4) {
; #pragma unroll
;     for (int s = 0; s < 4; ++s) {
;       const int k = k4 + s;
;       if (k + 3 < 128) issue(k + 3, (s + 3) & 3);
;       const v6u dq = v6u{dn[s][0][0], dn[s][0][1], dn[s][1][0], dn[s][1][1], dn[s][2][0], dn[s][2][1]};
;       const v32f dv = __builtin_amdgcn_cvt_scalef32_pk32_f32_fp6(dq, 1.0f);
;       float d0 = 0.f, d1 = 0.f, d2 = 0.f, d3 = 0.f;
; #pragma unroll
;       for (int i = 0; i < 8; ++i) { d0 += dv[4 * i] * hx[4 * i]; d1 += dv[4 * i + 1] * hx[4 * i + 1]; d2 += dv[4 * i + 2] * hx[4 * i + 2]; d3 += dv[4 * i + 3] * hx[4 * i + 3]; }
;       const float d = wave_sum_fast((d0 + d1) + (d2 + d3)) * (1.f / DOWN_SCALE);
;       const float gk = __builtin_bit_cast(float, (k < 64) ? __builtin_amdgcn_readlane(g0, k) : __builtin_amdgcn_readlane(g1, k - 64));
;       const float act = gelu_exact(d) * gk * (1.f / UP_SCALE);
;       const v6u uq = v6u{up[s][0][0], up[s][0][1], up[s][1][0], up[s][1][1], up[s][2][0], up[s][2][1]};
;       const v32f uv = __builtin_amdgcn_cvt_scalef32_pk32_f32_fp6(uq, 1.0f);
; #pragma unroll
;       for (int i = 0; i < 32; ++i) acc[i] += act * uv[i];
.Ljn_41:
	v_bfi_b32 v209, s18, v210, v205
	v_mul_f32_e32 v208, 0.5, v204
	v_add_f32_e32 v209, 1.0, v209
	v_mul_f32_e32 v208, v208, v209
	v_mul_f32_e32 v208, s26, v208
	v_mul_f32_e32 v206, 0x3e800000, v208
	v_pk_fma_f32 v[66:67], v[2:3], v[206:207], v[66:67] op_sel_hi:[1,0,1]
	v_pk_fma_f32 v[68:69], v[4:5], v[206:207], v[68:69] op_sel_hi:[1,0,1]
	v_pk_fma_f32 v[70:71], v[6:7], v[206:207], v[70:71] op_sel_hi:[1,0,1]
	v_pk_fma_f32 v[72:73], v[8:9], v[206:207], v[72:73] op_sel_hi:[1,0,1]
	v_pk_fma_f32 v[74:75], v[10:11], v[206:207], v[74:75] op_sel_hi:[1,0,1]
	v_pk_fma_f32 v[76:77], v[12:13], v[206:207], v[76:77] op_sel_hi:[1,0,1]
	v_pk_fma_f32 v[78:79], v[14:15], v[206:207], v[78:79] op_sel_hi:[1,0,1]
	v_pk_fma_f32 v[80:81], v[16:17], v[206:207], v[80:81] op_sel_hi:[1,0,1]
	v_pk_fma_f32 v[82:83], v[18:19], v[206:207], v[82:83] op_sel_hi:[1,0,1]
	v_pk_fma_f32 v[84:85], v[20:21], v[206:207], v[84:85] op_sel_hi:[1,0,1]
	v_pk_fma_f32 v[86:87], v[22:23], v[206:207], v[86:87] op_sel_hi:[1,0,1]
	v_pk_fma_f32 v[88:89], v[24:25], v[206:207], v[88:89] op_sel_hi:[1,0,1]
	v_pk_fma_f32 v[90:91], v[26:27], v[206:207], v[90:91] op_sel_hi:[1,0,1]
	v_pk_fma_f32 v[92:93], v[28:29], v[206:207], v[92:93] op_sel_hi:[1,0,1]
	v_pk_fma_f32 v[94:95], v[30:31], v[206:207], v[94:95] op_sel_hi:[1,0,1]
	v_pk_fma_f32 v[96:97], v[32:33], v[206:207], v[96:97] op_sel_hi:[1,0,1]
	s_mul_i32 s40, s25, 0xc00
	s_cmp_lt_u32 s25, 0x1800
	s_cselect_b64 s[28:29], s[2:3], s[4:5]
	s_cmp_lt_u32 s25, 0x2800
	s_cselect_b64 s[28:29], s[28:29], s[62:63]
	s_add_u32 s28, s28, s40
	s_addc_u32 s29, s29, 0
	global_load_dwordx4 v[146:149], v1, s[28:29]
	global_load_dwordx4 v[150:153], v1, s[28:29] offset:2048
	global_load_dwordx4 v[154:157], v1, s[28:29] offset:1024
	s_waitcnt vmcnt(21)
	v_cvt_scalef32_pk32_f32_fp6 v[2:33], v[158:163], 1.0
	v_mul_f32_e32 v200, v2, v34
	v_mul_f32_e32 v201, v3, v35
	v_mul_f32_e32 v202, v4, v36
	v_mul_f32_e32 v203, v5, v37
	v_fmac_f32_e32 v200, v6, v38
	v_fmac_f32_e32 v201, v7, v39
	v_fmac_f32_e32 v202, v8, v40
	v_fmac_f32_e32 v203, v9, v41
	v_fmac_f32_e32 v200, v10, v42
	v_fmac_f32_e32 v201, v11, v43
	v_fmac_f32_e32 v202, v12, v44
	v_fmac_f32_e32 v203, v13, v45
	v_fmac_f32_e32 v200, v14, v46
	v_fmac_f32_e32 v201, v15, v47
	v_fmac_f32_e32 v202, v16, v48
	v_fmac_f32_e32 v203, v17, v49
	v_fmac_f32_e32 v200, v18, v50
	v_fmac_f32_e32 v201, v19, v51
	v_fmac_f32_e32 v202, v20, v52
	v_fmac_f32_e32 v203, v21, v53
	v_fmac_f32_e32 v200, v22, v54
	v_fmac_f32_e32 v201, v23, v55
	v_fmac_f32_e32 v202, v24, v56
	v_fmac_f32_e32 v203, v25, v57
	v_fmac_f32_e32 v200, v26, v58
	v_fmac_f32_e32 v201, v27, v59
	v_fmac_f32_e32 v202, v28, v60
	v_fmac_f32_e32 v203, v29, v61
	v_fmac_f32_e32 v200, v30, v62
	v_fmac_f32_e32 v201, v31, v63
	v_fmac_f32_e32 v202, v32, v64
	v_fmac_f32_e32 v203, v33, v65
	v_add_f32_e32 v200, v201, v200
	v_add_f32_e32 v202, v203, v202
	v_cvt_scalef32_pk32_f32_fp6 v[2:33], v[164:169], 1.0
	v_add_f32_e32 v200, v202, v200
	s_add_i32 s38, s24, 5
	v_readlane_b32 s26, v199, s38
	s_mov_b32 s39, 5
	v_readlane_b32 s25, v216, s39
	v_add_f32_dpp v200, v200, v200 quad_perm:[1,0,3,2] row_mask:0xf bank_mask:0xf bound_ctrl:1
	s_nop 1
	v_add_f32_dpp v200, v200, v200 quad_perm:[2,3,0,1] row_mask:0xf bank_mask:0xf bound_ctrl:1
	s_nop 1
	v_add_f32_dpp v200, v200, v200 row_half_mirror row_mask:0xf bank_mask:0xf bound_ctrl:1
	s_nop 1
	v_add_f32_dpp v200, v200, v200 row_mirror row_mask:0xf bank_mask:0xf bound_ctrl:1
	s_nop 1
	v_add_f32_dpp v200, v200, v200 row_bcast:15 row_mask:0xa bank_mask:0xf
	s_nop 1
	v_add_f32_dpp v200, v200, v200 row_bcast:31 row_mask:0xc bank_mask:0xf
	s_nop 0
	v_readlane_b32 s27, v200, 63
	v_mul_f32_e32 v204, s27, v212
	v_mul_f32_e32 v205, 0x3f3504f3, v204
	v_cmp_lt_f32_e64 s[32:33], |v205|, 1.0
	s_and_b64 vcc, exec, s[32:33]
	s_cbranch_vccnz .Lsm_43
	v_fma_f32 v208, |v205|, s9, v214
	v_fma_f32 v208, |v205|, v208, s10
	v_fma_f32 v208, |v205|, v208, s11
	v_fma_f32 v208, |v205|, v208, s12
	v_fma_f32 v208, |v205|, v208, s13
	v_fma_f32 v208, |v205|, v208, s14
	v_fma_f32 v208, |v205|, v208, |v205|
	v_mul_f32_e32 v209, 0xbfb8aa3b, v208
	v_fma_f32 v210, v208, s15, -v209
	v_rndne_f32_e32 v211, v209
	v_fmac_f32_e32 v210, 0xb2a5705f, v208
	v_sub_f32_e32 v209, v209, v211
	v_add_f32_e32 v209, v209, v210
	v_cvt_i32_f32_e32 v210, v211
	v_exp_f32_e32 v209, v209
	v_cmp_nlt_f32_e32 vcc, s16, v208
	v_ldexp_f32 v209, v209, v210
	s_nop 0
	v_cndmask_b32_e32 v209, 0, v209, vcc
	v_cmp_ngt_f32_e32 vcc, s17, v208
	s_nop 1
	v_cndmask_b32_e32 v208, v215, v209, vcc
	v_sub_f32_e32 v210, 1.0, v208
	s_branch .Ljn_43

; DEV float gelu_exact(float v) { return 0.5f * v * (1.f + erff(v * 0.7071067811865476f)); }
; DEV void peer_gather_token(const Params& p, int tok) {
;     ...
;   auto issue = [&](int k, int slot) {
;     const int e = (k < 64) ? __builtin_amdgcn_readlane(e0, k) : __builtin_amdgcn_readlane(e1, k - 64);
;     const unsigned char* dr = p.down8 + (size_t)e * ROW6 + lane * 24;
;     const unsigned char* ur = p.up8 + (size_t)e * ROW6 + lane * 24;
; #pragma unroll
;     for (int i = 0; i < 3; ++i) { dn[slot][i] = *(const u32x2*)(dr + i * 8); up[slot][i] = *(const u32x2*)(ur + i * 8); }
;   };
;   issue(0, 0); issue(1, 1); issue(2, 2);
; #pragma unroll 1
;   for (int k4 = 0; k4 < 128; k4 += 4) {
; #pragma unroll
;     for (int s = 0; s < 4; ++s) {
;       const int k = k4 + s;
;       if (k + 3 < 128) issue(k + 3, (s + 3) & 3);
;       const v6u dq = v6u{dn[s][0][0], dn[s][0][1], dn[s][1][0], dn[s][1][1], dn[s][2][0], dn[s][2][1]};
;       const v32f dv = __builtin_amdgcn_cvt_scalef32_pk32_f32_fp6(dq, 1.0f);
;       float d0 = 0.f, d1 = 0.f, d2 = 0.f, d3 = 0.f;
; #pragma unroll
;       for (int i = 0; i < 8; ++i) { d0 += dv[4 * i] * hx[4 * i]; d1 += dv[4 * i + 1] * hx[4 * i + 1]; d2 += dv[4 * i + 2] * hx[4 * i + 2]; d3 += dv[4 * i + 3] * hx[4 * i + 3]; }
;       const float d = wave_sum_fast((d0 + d1) + (d2 + d3)) * (1.f / DOWN_SCALE);
;       const float gk = __builtin_bit_cast(float, (k < 64) ? __builtin_amdgcn_readlane(g0, k) : __builtin_amdgcn_readlane(g1, k - 64));
;       const float act = gelu_exact(d) * gk * (1.f / UP_SCALE);
;       const v6u uq = v6u{up[s][0][0], up[s][0][1], up[s][1][0], up[s][1][1], up[s][2][0], up[s][2][1]};
;       const v32f uv = __builtin_amdgcn_cvt_scalef32_pk32_f32_fp6(uq, 1.0f);
; #pragma unroll
;       for (int i = 0; i < 32; ++i) acc[i] += act * uv[i];
.Ljn_43:
	v_bfi_b32 v209, s18, v210, v205
	v_mul_f32_e32 v208, 0.5, v204
	v_add_f32_e32 v209, 1.0, v209
	v_mul_f32_e32 v208, v208, v209
	v_mul_f32_e32 v208, s26, v208
	v_mul_f32_e32 v206, 0x3e800000, v208
	v_pk_fma_f32 v[66:67], v[2:3], v[206:207], v[66:67] op_sel_hi:[1,0,1]
	v_pk_fma_f32 v[68:69], v[4:5], v[206:207], v[68:69] op_sel_hi:[1,0,1]
	v_pk_fma_f32 v[70:71], v[6:7], v[206:207], v[70:71] op_sel_hi:[1,0,1]
	v_pk_fma_f32 v[72:73], v[8:9], v[206:207], v[72:73] op_sel_hi:[1,0,1]
	v_pk_fma_f32 v[74:75], v[10:11], v[206:207], v[74:75] op_sel_hi:[1,0,1]
	v_pk_fma_f32 v[76:77], v[12:13], v[206:207], v[76:77] op_sel_hi:[1,0,1]
	v_pk_fma_f32 v[78:79], v[14:15], v[206:207], v[78:79] op_sel_hi:[1,0,1]
	v_pk_fma_f32 v[80:81], v[16:17], v[206:207], v[80:81] op_sel_hi:[1,0,1]
	v_pk_fma_f32 v[82:83], v[18:19], v[206:207], v[82:83] op_sel_hi:[1,0,1]
	v_pk_fma_f32 v[84:85], v[20:21], v[206:207], v[84:85] op_sel_hi:[1,0,1]
	v_pk_fma_f32 v[86:87], v[22:23], v[206:207], v[86:87] op_sel_hi:[1,0,1]
	v_pk_fma_f32 v[88:89], v[24:25], v[206:207], v[88:89] op_sel_hi:[1,0,1]
	v_pk_fma_f32 v[90:91], v[26:27], v[206:207], v[90:91] op_sel_hi:[1,0,1]
	v_pk_fma_f32 v[92:93], v[28:29], v[206:207], v[92:93] op_sel_hi:[1,0,1]
	v_pk_fma_f32 v[94:95], v[30:31], v[206:207], v[94:95] op_sel_hi:[1,0,1]
	v_pk_fma_f32 v[96:97], v[32:33], v[206:207], v[96:97] op_sel_hi:[1,0,1]
	s_mul_i32 s40, s25, 0xc00
	s_cmp_lt_u32 s25, 0x1800
	s_cselect_b64 s[28:29], s[2:3], s[4:5]
	s_cmp_lt_u32 s25, 0x2800
	s_cselect_b64 s[28:29], s[28:29], s[62:63]
	s_add_u32 s28, s28, s40
	s_addc_u32 s29, s29, 0
	global_load_dwordx4 v[158:161], v1, s[28:29]
	global_load_dwordx4 v[162:165], v1, s[28:29] offset:2048
	global_load_dwordx4 v[166:169], v1, s[28:29] offset:1024
	s_waitcnt vmcnt(21)
	v_cvt_scalef32_pk32_f32_fp6 v[2:33], v[170:175], 1.0
	v_mul_f32_e32 v200, v2, v34
	v_mul_f32_e32 v201, v3, v35
	v_mul_f32_e32 v202, v4, v36
	v_mul_f32_e32 v203, v5, v37
	v_fmac_f32_e32 v200, v6, v38
	v_fmac_f32_e32 v201, v7, v39
	v_fmac_f32_e32 v202, v8, v40
	v_fmac_f32_e32 v203, v9, v41
	v_fmac_f32_e32 v200, v10, v42
	v_fmac_f32_e32 v201, v11, v43
	v_fmac_f32_e32 v202, v12, v44
	v_fmac_f32_e32 v203, v13, v45
	v_fmac_f32_e32 v200, v14, v46
	v_fmac_f32_e32 v201, v15, v47
	v_fmac_f32_e32 v202, v16, v48
	v_fmac_f32_e32 v203, v17, v49
	v_fmac_f32_e32 v200, v18, v50
	v_fmac_f32_e32 v201, v19, v51
	v_fmac_f32_e32 v202, v20, v52
	v_fmac_f32_e32 v203, v21, v53
	v_fmac_f32_e32 v200, v22, v54
	v_fmac_f32_e32 v201, v23, v55
	v_fmac_f32_e32 v202, v24, v56
	v_fmac_f32_e32 v203, v25, v57
	v_fmac_f32_e32 v200, v26, v58
	v_fmac_f32_e32 v201, v27, v59
	v_fmac_f32_e32 v202, v28, v60
	v_fmac_f32_e32 v203, v29, v61
	v_fmac_f32_e32 v200, v30, v62
	v_fmac_f32_e32 v201, v31, v63
	v_fmac_f32_e32 v202, v32, v64
	v_fmac_f32_e32 v203, v33, v65
	v_add_f32_e32 v200, v201, v200
	v_add_f32_e32 v202, v203, v202
	v_cvt_scalef32_pk32_f32_fp6 v[2:33], v[176:181], 1.0
	v_add_f32_e32 v200, v202, v200
	s_add_i32 s38, s24, 6
	v_readlane_b32 s26, v199, s38
	s_mov_b32 s39, 6
	v_readlane_b32 s25, v216, s39
	v_add_f32_dpp v200, v200, v200 quad_perm:[1,0,3,2] row_mask:0xf bank_mask:0xf bound_ctrl:1
	s_nop 1
	v_add_f32_dpp v200, v200, v200 quad_perm:[2,3,0,1] row_mask:0xf bank_mask:0xf bound_ctrl:1
	s_nop 1
	v_add_f32_dpp v200, v200, v200 row_half_mirror row_mask:0xf bank_mask:0xf bound_ctrl:1
	s_nop 1
	v_add_f32_dpp v200, v200, v200 row_mirror row_mask:0xf bank_mask:0xf bound_ctrl:1
	s_nop 1
	v_add_f32_dpp v200, v200, v200 row_bcast:15 row_mask:0xa bank_mask:0xf
	s_nop 1
	v_add_f32_dpp v200, v200, v200 row_bcast:31 row_mask:0xc bank_mask:0xf
	s_nop 0
	v_readlane_b32 s27, v200, 63
	v_mul_f32_e32 v204, s27, v212
	v_mul_f32_e32 v205, 0x3f3504f3, v204
	v_cmp_lt_f32_e64 s[32:33], |v205|, 1.0
	s_and_b64 vcc, exec, s[32:33]
	s_cbranch_vccnz .Lsm_45
	v_fma_f32 v208, |v205|, s9, v214
	v_fma_f32 v208, |v205|, v208, s10
	v_fma_f32 v208, |v205|, v208, s11
	v_fma_f32 v208, |v205|, v208, s12
	v_fma_f32 v208, |v205|, v208, s13
	v_fma_f32 v208, |v205|, v208, s14
	v_fma_f32 v208, |v205|, v208, |v205|
	v_mul_f32_e32 v209, 0xbfb8aa3b, v208
	v_fma_f32 v210, v208, s15, -v209
	v_rndne_f32_e32 v211, v209
	v_fmac_f32_e32 v210, 0xb2a5705f, v208
	v_sub_f32_e32 v209, v209, v211
	v_add_f32_e32 v209, v209, v210
	v_cvt_i32_f32_e32 v210, v211
	v_exp_f32_e32 v209, v209
	v_cmp_nlt_f32_e32 vcc, s16, v208
	v_ldexp_f32 v209, v209, v210
	s_nop 0
	v_cndmask_b32_e32 v209, 0, v209, vcc
	v_cmp_ngt_f32_e32 vcc, s17, v208
	s_nop 1
	v_cndmask_b32_e32 v208, v215, v209, vcc
	v_sub_f32_e32 v210, 1.0, v208
	s_branch .Ljn_45

; DEV float gelu_exact(float v) { return 0.5f * v * (1.f + erff(v * 0.7071067811865476f)); }
; DEV void peer_gather_token(const Params& p, int tok) {
;     ...
;   auto issue = [&](int k, int slot) {
;     const int e = (k < 64) ? __builtin_amdgcn_readlane(e0, k) : __builtin_amdgcn_readlane(e1, k - 64);
;     const unsigned char* dr = p.down8 + (size_t)e * ROW6 + lane * 24;
;     const unsigned char* ur = p.up8 + (size_t)e * ROW6 + lane * 24;
; #pragma unroll
;     for (int i = 0; i < 3; ++i) { dn[slot][i] = *(const u32x2*)(dr + i * 8); up[slot][i] = *(const u32x2*)(ur + i * 8); }
;   };
;   issue(0, 0); issue(1, 1); issue(2, 2);
; #pragma unroll 1
;   for (int k4 = 0; k4 < 128; k4 += 4) {
; #pragma unroll
;     for (int s = 0; s < 4; ++s) {
;       const int k = k4 + s;
;       if (k + 3 < 128) issue(k + 3, (s + 3) & 3);
;       const v6u dq = v6u{dn[s][0][0], dn[s][0][1], dn[s][1][0], dn[s][1][1], dn[s][2][0], dn[s][2][1]};
;       const v32f dv = __builtin_amdgcn_cvt_scalef32_pk32_f32_fp6(dq, 1.0f);
;       float d0 = 0.f, d1 = 0.f, d2 = 0.f, d3 = 0.f;
; #pragma unroll
;       for (int i = 0; i < 8; ++i) { d0 += dv[4 * i] * hx[4 * i]; d1 += dv[4 * i + 1] * hx[4 * i + 1]; d2 += dv[4 * i + 2] * hx[4 * i + 2]; d3 += dv[4 * i + 3] * hx[4 * i + 3]; }
;       const float d = wave_sum_fast((d0 + d1) + (d2 + d3)) * (1.f / DOWN_SCALE);
;       const float gk = __builtin_bit_cast(float, (k < 64) ? __builtin_amdgcn_readlane(g0, k) : __builtin_amdgcn_readlane(g1, k - 64));
;       const float act = gelu_exact(d) * gk * (1.f / UP_SCALE);
;       const v6u uq = v6u{up[s][0][0], up[s][0][1], up[s][1][0], up[s][1][1], up[s][2][0], up[s][2][1]};
;       const v32f uv = __builtin_amdgcn_cvt_scalef32_pk32_f32_fp6(uq, 1.0f);
; #pragma unroll
;       for (int i = 0; i < 32; ++i) acc[i] += act * uv[i];
.Ljn_45:
	v_bfi_b32 v209, s18, v210, v205
	v_mul_f32_e32 v208, 0.5, v204
	v_add_f32_e32 v209, 1.0, v209
	v_mul_f32_e32 v208, v208, v209
	v_mul_f32_e32 v208, s26, v208
	v_mul_f32_e32 v206, 0x3e800000, v208
	v_pk_fma_f32 v[66:67], v[2:3], v[206:207], v[66:67] op_sel_hi:[1,0,1]
	v_pk_fma_f32 v[68:69], v[4:5], v[206:207], v[68:69] op_sel_hi:[1,0,1]
	v_pk_fma_f32 v[70:71], v[6:7], v[206:207], v[70:71] op_sel_hi:[1,0,1]
	v_pk_fma_f32 v[72:73], v[8:9], v[206:207], v[72:73] op_sel_hi:[1,0,1]
	v_pk_fma_f32 v[74:75], v[10:11], v[206:207], v[74:75] op_sel_hi:[1,0,1]
	v_pk_fma_f32 v[76:77], v[12:13], v[206:207], v[76:77] op_sel_hi:[1,0,1]
	v_pk_fma_f32 v[78:79], v[14:15], v[206:207], v[78:79] op_sel_hi:[1,0,1]
	v_pk_fma_f32 v[80:81], v[16:17], v[206:207], v[80:81] op_sel_hi:[1,0,1]
	v_pk_fma_f32 v[82:83], v[18:19], v[206:207], v[82:83] op_sel_hi:[1,0,1]
	v_pk_fma_f32 v[84:85], v[20:21], v[206:207], v[84:85] op_sel_hi:[1,0,1]
	v_pk_fma_f32 v[86:87], v[22:23], v[206:207], v[86:87] op_sel_hi:[1,0,1]
	v_pk_fma_f32 v[88:89], v[24:25], v[206:207], v[88:89] op_sel_hi:[1,0,1]
	v_pk_fma_f32 v[90:91], v[26:27], v[206:207], v[90:91] op_sel_hi:[1,0,1]
	v_pk_fma_f32 v[92:93], v[28:29], v[206:207], v[92:93] op_sel_hi:[1,0,1]
	v_pk_fma_f32 v[94:95], v[30:31], v[206:207], v[94:95] op_sel_hi:[1,0,1]
	v_pk_fma_f32 v[96:97], v[32:33], v[206:207], v[96:97] op_sel_hi:[1,0,1]
	s_mul_i32 s40, s25, 0xc00
	s_cmp_lt_u32 s25, 0x1800
	s_cselect_b64 s[28:29], s[2:3], s[4:5]
	s_cmp_lt_u32 s25, 0x2800
	s_cselect_b64 s[28:29], s[28:29], s[62:63]
	s_add_u32 s28, s28, s40
	s_addc_u32 s29, s29, 0
	global_load_dwordx4 v[170:173], v1, s[28:29]
	global_load_dwordx4 v[174:177], v1, s[28:29] offset:2048
	global_load_dwordx4 v[178:181], v1, s[28:29] offset:1024
	s_waitcnt vmcnt(21)
	v_cvt_scalef32_pk32_f32_fp6 v[2:33], v[182:187], 1.0
	v_mul_f32_e32 v200, v2, v34
	v_mul_f32_e32 v201, v3, v35
	v_mul_f32_e32 v202, v4, v36
	v_mul_f32_e32 v203, v5, v37
	v_fmac_f32_e32 v200, v6, v38
	v_fmac_f32_e32 v201, v7, v39
	v_fmac_f32_e32 v202, v8, v40
	v_fmac_f32_e32 v203, v9, v41
	v_fmac_f32_e32 v200, v10, v42
	v_fmac_f32_e32 v201, v11, v43
	v_fmac_f32_e32 v202, v12, v44
	v_fmac_f32_e32 v203, v13, v45
	v_fmac_f32_e32 v200, v14, v46
	v_fmac_f32_e32 v201, v15, v47
	v_fmac_f32_e32 v202, v16, v48
	v_fmac_f32_e32 v203, v17, v49
	v_fmac_f32_e32 v200, v18, v50
	v_fmac_f32_e32 v201, v19, v51
	v_fmac_f32_e32 v202, v20, v52
	v_fmac_f32_e32 v203, v21, v53
	v_fmac_f32_e32 v200, v22, v54
	v_fmac_f32_e32 v201, v23, v55
	v_fmac_f32_e32 v202, v24, v56
	v_fmac_f32_e32 v203, v25, v57
	v_fmac_f32_e32 v200, v26, v58
	v_fmac_f32_e32 v201, v27, v59
	v_fmac_f32_e32 v202, v28, v60
	v_fmac_f32_e32 v203, v29, v61
	v_fmac_f32_e32 v200, v30, v62
	v_fmac_f32_e32 v201, v31, v63
	v_fmac_f32_e32 v202, v32, v64
	v_fmac_f32_e32 v203, v33, v65
	v_add_f32_e32 v200, v201, v200
	v_add_f32_e32 v202, v203, v202
	v_cvt_scalef32_pk32_f32_fp6 v[2:33], v[188:193], 1.0
	v_add_f32_e32 v200, v202, v200
	s_add_i32 s38, s24, 7
	v_readlane_b32 s26, v199, s38
	s_mov_b32 s39, 7
	v_readlane_b32 s25, v216, s39
	v_add_f32_dpp v200, v200, v200 quad_perm:[1,0,3,2] row_mask:0xf bank_mask:0xf bound_ctrl:1
	s_nop 1
	v_add_f32_dpp v200, v200, v200 quad_perm:[2,3,0,1] row_mask:0xf bank_mask:0xf bound_ctrl:1
	s_nop 1
	v_add_f32_dpp v200, v200, v200 row_half_mirror row_mask:0xf bank_mask:0xf bound_ctrl:1
	s_nop 1
	v_add_f32_dpp v200, v200, v200 row_mirror row_mask:0xf bank_mask:0xf bound_ctrl:1
	s_nop 1
	v_add_f32_dpp v200, v200, v200 row_bcast:15 row_mask:0xa bank_mask:0xf
	s_nop 1
	v_add_f32_dpp v200, v200, v200 row_bcast:31 row_mask:0xc bank_mask:0xf
	s_nop 0
	v_readlane_b32 s27, v200, 63
	v_mul_f32_e32 v204, s27, v212
	v_mul_f32_e32 v205, 0x3f3504f3, v204
	v_cmp_lt_f32_e64 s[32:33], |v205|, 1.0
	s_and_b64 vcc, exec, s[32:33]
	s_cbranch_vccnz .Lsm_47
	v_fma_f32 v208, |v205|, s9, v214
	v_fma_f32 v208, |v205|, v208, s10
	v_fma_f32 v208, |v205|, v208, s11
	v_fma_f32 v208, |v205|, v208, s12
	v_fma_f32 v208, |v205|, v208, s13
	v_fma_f32 v208, |v205|, v208, s14
	v_fma_f32 v208, |v205|, v208, |v205|
	v_mul_f32_e32 v209, 0xbfb8aa3b, v208
	v_fma_f32 v210, v208, s15, -v209
	v_rndne_f32_e32 v211, v209
	v_fmac_f32_e32 v210, 0xb2a5705f, v208
	v_sub_f32_e32 v209, v209, v211
	v_add_f32_e32 v209, v209, v210
	v_cvt_i32_f32_e32 v210, v211
	v_exp_f32_e32 v209, v209
	v_cmp_nlt_f32_e32 vcc, s16, v208
	v_ldexp_f32 v209, v209, v210
	s_nop 0
	v_cndmask_b32_e32 v209, 0, v209, vcc
	v_cmp_ngt_f32_e32 vcc, s17, v208
	s_nop 1
	v_cndmask_b32_e32 v208, v215, v209, vcc
	v_sub_f32_e32 v210, 1.0, v208
	s_branch .Ljn_47

; DEV float gelu_exact(float v) { return 0.5f * v * (1.f + erff(v * 0.7071067811865476f)); }
; DEV void peer_gather_token(const Params& p, int tok) {
;     ...
;   auto issue = [&](int k, int slot) {
;     const int e = (k < 64) ? __builtin_amdgcn_readlane(e0, k) : __builtin_amdgcn_readlane(e1, k - 64);
;     const unsigned char* dr = p.down8 + (size_t)e * ROW6 + lane * 24;
;     const unsigned char* ur = p.up8 + (size_t)e * ROW6 + lane * 24;
; #pragma unroll
;     for (int i = 0; i < 3; ++i) { dn[slot][i] = *(const u32x2*)(dr + i * 8); up[slot][i] = *(const u32x2*)(ur + i * 8); }
;   };
;   issue(0, 0); issue(1, 1); issue(2, 2);
; #pragma unroll 1
;   for (int k4 = 0; k4 < 128; k4 += 4) {
; #pragma unroll
;     for (int s = 0; s < 4; ++s) {
;       const int k = k4 + s;
;       if (k + 3 < 128) issue(k + 3, (s + 3) & 3);
;       const v6u dq = v6u{dn[s][0][0], dn[s][0][1], dn[s][1][0], dn[s][1][1], dn[s][2][0], dn[s][2][1]};
;       const v32f dv = __builtin_amdgcn_cvt_scalef32_pk32_f32_fp6(dq, 1.0f);
;       float d0 = 0.f, d1 = 0.f, d2 = 0.f, d3 = 0.f;
; #pragma unroll
;       for (int i = 0; i < 8; ++i) { d0 += dv[4 * i] * hx[4 * i]; d1 += dv[4 * i + 1] * hx[4 * i + 1]; d2 += dv[4 * i + 2] * hx[4 * i + 2]; d3 += dv[4 * i + 3] * hx[4 * i + 3]; }
;       const float d = wave_sum_fast((d0 + d1) + (d2 + d3)) * (1.f / DOWN_SCALE);
;       const float gk = __builtin_bit_cast(float, (k < 64) ? __builtin_amdgcn_readlane(g0, k) : __builtin_amdgcn_readlane(g1, k - 64));
;       const float act = gelu_exact(d) * gk * (1.f / UP_SCALE);
;       const v6u uq = v6u{up[s][0][0], up[s][0][1], up[s][1][0], up[s][1][1], up[s][2][0], up[s][2][1]};
;       const v32f uv = __builtin_amdgcn_cvt_scalef32_pk32_f32_fp6(uq, 1.0f);
; #pragma unroll
;       for (int i = 0; i < 32; ++i) acc[i] += act * uv[i];
;     }
;   }
;   const float* gt2 = p.mod + (size_t)b * 12288 + 10240;
;   float* orow = p.out + (size_t)tok * 2048;
; #pragma unroll
;   for (int q = 0; q < 8; ++q) {
;     const int col = lane * 32 + q * 4;
;     float4 x0 = *(const float4*)(orow + col);
;     float4 ga = *(const float4*)(gt2 + col);
;     x0.x += ga.x * acc[q * 4 + 0]; x0.y += ga.y * acc[q * 4 + 1]; x0.z += ga.z * acc[q * 4 + 2]; x0.w += ga.w * acc[q * 4 + 3];
;     *(float4*)(orow + col) = x0;
;   }
.Ljn_47:
	v_bfi_b32 v209, s18, v210, v205
	v_mul_f32_e32 v208, 0.5, v204
	v_add_f32_e32 v209, 1.0, v209
	v_mul_f32_e32 v208, v208, v209
	v_mul_f32_e32 v208, s26, v208
	v_mul_f32_e32 v206, 0x3e800000, v208
	v_pk_fma_f32 v[66:67], v[2:3], v[206:207], v[66:67] op_sel_hi:[1,0,1]
	v_pk_fma_f32 v[68:69], v[4:5], v[206:207], v[68:69] op_sel_hi:[1,0,1]
	v_pk_fma_f32 v[70:71], v[6:7], v[206:207], v[70:71] op_sel_hi:[1,0,1]
	v_pk_fma_f32 v[72:73], v[8:9], v[206:207], v[72:73] op_sel_hi:[1,0,1]
	v_pk_fma_f32 v[74:75], v[10:11], v[206:207], v[74:75] op_sel_hi:[1,0,1]
	v_pk_fma_f32 v[76:77], v[12:13], v[206:207], v[76:77] op_sel_hi:[1,0,1]
	v_pk_fma_f32 v[78:79], v[14:15], v[206:207], v[78:79] op_sel_hi:[1,0,1]
	v_pk_fma_f32 v[80:81], v[16:17], v[206:207], v[80:81] op_sel_hi:[1,0,1]
	v_pk_fma_f32 v[82:83], v[18:19], v[206:207], v[82:83] op_sel_hi:[1,0,1]
	v_pk_fma_f32 v[84:85], v[20:21], v[206:207], v[84:85] op_sel_hi:[1,0,1]
	v_pk_fma_f32 v[86:87], v[22:23], v[206:207], v[86:87] op_sel_hi:[1,0,1]
	v_pk_fma_f32 v[88:89], v[24:25], v[206:207], v[88:89] op_sel_hi:[1,0,1]
	v_pk_fma_f32 v[90:91], v[26:27], v[206:207], v[90:91] op_sel_hi:[1,0,1]
	v_pk_fma_f32 v[92:93], v[28:29], v[206:207], v[92:93] op_sel_hi:[1,0,1]
	v_pk_fma_f32 v[94:95], v[30:31], v[206:207], v[94:95] op_sel_hi:[1,0,1]
	v_pk_fma_f32 v[96:97], v[32:33], v[206:207], v[96:97] op_sel_hi:[1,0,1]
	s_mul_i32 s40, s25, 0xc00
	s_cmp_lt_u32 s25, 0x1800
	s_cselect_b64 s[28:29], s[2:3], s[4:5]
	s_cmp_lt_u32 s25, 0x2800
	s_cselect_b64 s[28:29], s[28:29], s[62:63]
	s_add_u32 s28, s28, s40
	s_addc_u32 s29, s29, 0
	global_load_dwordx4 v[182:185], v1, s[28:29]
	global_load_dwordx4 v[186:189], v1, s[28:29] offset:2048
	global_load_dwordx4 v[190:193], v1, s[28:29] offset:1024
	s_lshr_b32 s38, s20, 11
	s_mul_i32 s38, s38, 0xc000
	s_add_u32 s38, s38, 0xa000
	s_add_u32 s58, s78, s38
	s_addc_u32 s59, s79, 0
	global_load_dwordx4 v[34:37], v244, s[58:59]
	global_load_dwordx4 v[38:41], v244, s[58:59] offset:1024
	global_load_dwordx4 v[42:45], v244, s[58:59] offset:2048
	global_load_dwordx4 v[46:49], v244, s[58:59] offset:3072
	global_load_dwordx4 v[50:53], v245, s[58:59]
	global_load_dwordx4 v[54:57], v245, s[58:59] offset:1024
	global_load_dwordx4 v[58:61], v245, s[58:59] offset:2048
	global_load_dwordx4 v[62:65], v245, s[58:59] offset:3072
	s_lshl_b32 s38, s20, 13
	s_add_u32 s58, s44, s38
	s_addc_u32 s59, s45, 0
	global_load_dwordx4 v[2:5], v244, s[58:59]
	global_load_dwordx4 v[6:9], v244, s[58:59] offset:1024
	global_load_dwordx4 v[10:13], v244, s[58:59] offset:2048
	global_load_dwordx4 v[14:17], v244, s[58:59] offset:3072
	global_load_dwordx4 v[18:21], v245, s[58:59]
	global_load_dwordx4 v[22:25], v245, s[58:59] offset:1024
	global_load_dwordx4 v[26:29], v245, s[58:59] offset:2048
	global_load_dwordx4 v[30:33], v245, s[58:59] offset:3072
	s_waitcnt vmcnt(0)
	v_fmac_f32_e32 v2, v34, v66
	v_fmac_f32_e32 v3, v35, v67
	v_fmac_f32_e32 v4, v36, v68
	v_fmac_f32_e32 v5, v37, v69
	v_fmac_f32_e32 v6, v38, v70
	v_fmac_f32_e32 v7, v39, v71
	v_fmac_f32_e32 v8, v40, v72
	v_fmac_f32_e32 v9, v41, v73
	v_fmac_f32_e32 v10, v42, v74
	v_fmac_f32_e32 v11, v43, v75
	v_fmac_f32_e32 v12, v44, v76
	v_fmac_f32_e32 v13, v45, v77
	v_fmac_f32_e32 v14, v46, v78
	v_fmac_f32_e32 v15, v47, v79
	v_fmac_f32_e32 v16, v48, v80
	v_fmac_f32_e32 v17, v49, v81
	v_fmac_f32_e32 v18, v50, v82
	v_fmac_f32_e32 v19, v51, v83
	v_fmac_f32_e32 v20, v52, v84
	v_fmac_f32_e32 v21, v53, v85
	v_fmac_f32_e32 v22, v54, v86
	v_fmac_f32_e32 v23, v55, v87
	v_fmac_f32_e32 v24, v56, v88
	v_fmac_f32_e32 v25, v57, v89
	v_fmac_f32_e32 v26, v58, v90
	v_fmac_f32_e32 v27, v59, v91
	v_fmac_f32_e32 v28, v60, v92
	v_fmac_f32_e32 v29, v61, v93
	v_fmac_f32_e32 v30, v62, v94
	v_fmac_f32_e32 v31, v63, v95
	v_fmac_f32_e32 v32, v64, v96
	v_fmac_f32_e32 v33, v65, v97
	global_store_dwordx4 v244, v[2:5], s[58:59]
	global_store_dwordx4 v244, v[6:9], s[58:59] offset:1024
	global_store_dwordx4 v244, v[10:13], s[58:59] offset:2048
	global_store_dwordx4 v244, v[14:17], s[58:59] offset:3072
	global_store_dwordx4 v245, v[18:21], s[58:59]
	global_store_dwordx4 v245, v[22:25], s[58:59] offset:1024
	global_store_dwordx4 v245, v[26:29], s[58:59] offset:2048
	global_store_dwordx4 v245, v[30:33], s[58:59] offset:3072
	s_add_i32 s20, s20, s21
	s_cmpk_lt_u32 s20, 0x4000
	s_cbranch_scc0 .Lp12_end
; DEV int ltid() { int t = threadIdx.x; asm volatile("" : "+v"(t)); return t; }
; DEV float bflo(unsigned u) { return __uint_as_float(u << 16); }
; DEV float bfhi(unsigned u) { return __uint_as_float(u & 0xffff0000u); }
; DEV void peer_gather_token(const Params& p, int tok) {
;   const int lane = ltid() & 63, b = tok >> 11;
;   float hx[32], acc[32];
;   {
;     const u16* hr = p.h + (size_t)tok * 2048 + lane * 32;
; #pragma unroll
;     for (int q = 0; q < 4; ++q) {
;       u32x4 v = *(const u32x4*)(hr + q * 8);
; #pragma unroll
;       for (int e = 0; e < 4; ++e) { hx[q * 8 + 2 * e] = bflo(v[e]); hx[q * 8 + 2 * e + 1] = bfhi(v[e]); }
;     }
;   }
; #pragma unroll
;   for (int e = 0; e < 32; ++e) acc[e] = 0.f;
;   const int e0 = p.eidx[(size_t)tok * 128 + lane], e1 = p.eidx[(size_t)tok * 128 + 64 + lane];
;   const int g0 = __builtin_bit_cast(int, p.gw[(size_t)tok * 128 + lane]), g1 = __builtin_bit_cast(int, p.gw[(size_t)tok * 128 + 64 + lane]);
;   u32x2 dn[4][3], up[4][3];
;   auto issue = [&](int k, int slot) {
;     const int e = (k < 64) ? __builtin_amdgcn_readlane(e0, k) : __builtin_amdgcn_readlane(e1, k - 64);
;     const unsigned char* dr = p.down8 + (size_t)e * ROW6 + lane * 24;
;     const unsigned char* ur = p.up8 + (size_t)e * ROW6 + lane * 24;
; #pragma unroll
;     for (int i = 0; i < 3; ++i) { dn[slot][i] = *(const u32x2*)(dr + i * 8); up[slot][i] = *(const u32x2*)(ur + i * 8); }
;   };
;   issue(0, 0); issue(1, 1); issue(2, 2);
.Lp12_switch:
	v_mov_b32_e32 v194, v216
	v_mov_b32_e32 v195, v217
	v_mov_b32_e32 v196, v218
	v_mov_b32_e32 v197, v219
	v_mov_b32_e32 v198, v216
	v_mov_b32_e32 v199, v218
	v_lshlrev_b32_e32 v34, 16, v220
	v_and_b32_e32 v35, 0xffff0000, v220
	v_lshlrev_b32_e32 v36, 16, v221
	v_and_b32_e32 v37, 0xffff0000, v221
	v_lshlrev_b32_e32 v38, 16, v222
	v_and_b32_e32 v39, 0xffff0000, v222
	v_lshlrev_b32_e32 v40, 16, v223
	v_and_b32_e32 v41, 0xffff0000, v223
	v_lshlrev_b32_e32 v42, 16, v224
	v_and_b32_e32 v43, 0xffff0000, v224
	v_lshlrev_b32_e32 v44, 16, v225
	v_and_b32_e32 v45, 0xffff0000, v225
	v_lshlrev_b32_e32 v46, 16, v226
	v_and_b32_e32 v47, 0xffff0000, v226
	v_lshlrev_b32_e32 v48, 16, v227
	v_and_b32_e32 v49, 0xffff0000, v227
	v_lshlrev_b32_e32 v50, 16, v228
	v_and_b32_e32 v51, 0xffff0000, v228
	v_lshlrev_b32_e32 v52, 16, v229
	v_and_b32_e32 v53, 0xffff0000, v229
	v_lshlrev_b32_e32 v54, 16, v230
	v_and_b32_e32 v55, 0xffff0000, v230
	v_lshlrev_b32_e32 v56, 16, v231
	v_and_b32_e32 v57, 0xffff0000, v231
	v_lshlrev_b32_e32 v58, 16, v232
	v_and_b32_e32 v59, 0xffff0000, v232
	v_lshlrev_b32_e32 v60, 16, v233
	v_and_b32_e32 v61, 0xffff0000, v233
	v_lshlrev_b32_e32 v62, 16, v234
	v_and_b32_e32 v63, 0xffff0000, v234
	v_lshlrev_b32_e32 v64, 16, v235
	v_and_b32_e32 v65, 0xffff0000, v235
	v_mov_b32_e32 v66, 0
	v_mov_b32_e32 v67, 0
	v_mov_b32_e32 v68, 0
	v_mov_b32_e32 v69, 0
	v_mov_b32_e32 v70, 0
	v_mov_b32_e32 v71, 0
	v_mov_b32_e32 v72, 0
	v_mov_b32_e32 v73, 0
	v_mov_b32_e32 v74, 0
	v_mov_b32_e32 v75, 0
	v_mov_b32_e32 v76, 0
	v_mov_b32_e32 v77, 0
	v_mov_b32_e32 v78, 0
	v_mov_b32_e32 v79, 0
	v_mov_b32_e32 v80, 0
	v_mov_b32_e32 v81, 0
	v_mov_b32_e32 v82, 0
	v_mov_b32_e32 v83, 0
	v_mov_b32_e32 v84, 0
	v_mov_b32_e32 v85, 0
	v_mov_b32_e32 v86, 0
	v_mov_b32_e32 v87, 0
	v_mov_b32_e32 v88, 0
	v_mov_b32_e32 v89, 0
	v_mov_b32_e32 v90, 0
	v_mov_b32_e32 v91, 0
	v_mov_b32_e32 v92, 0
	v_mov_b32_e32 v93, 0
	v_mov_b32_e32 v94, 0
	v_mov_b32_e32 v95, 0
	v_mov_b32_e32 v96, 0
	v_mov_b32_e32 v97, 0
	s_mov_b32 s22, 0
	s_mov_b32 s23, 8
	s_mov_b32 s24, 0
	s_cmp_eq_u32 s43, 0
	s_cbranch_scc1 .Lp12_token
	s_mov_b32 s43, 0
	v_readlane_b32 s25, v194, 0
	s_mul_i32 s40, s25, 0xc00
	s_cmp_lt_u32 s25, 0x1800
	s_cselect_b64 s[28:29], s[2:3], s[4:5]
	s_cmp_lt_u32 s25, 0x2800
	s_cselect_b64 s[28:29], s[28:29], s[62:63]
	s_add_u32 s28, s28, s40
	s_addc_u32 s29, s29, 0
	global_load_dwordx4 v[98:101], v1, s[28:29]
	global_load_dwordx4 v[102:105], v1, s[28:29] offset:2048
	global_load_dwordx4 v[106:109], v1, s[28:29] offset:1024
	v_readlane_b32 s25, v194, 1
	s_mul_i32 s40, s25, 0xc00
	s_cmp_lt_u32 s25, 0x1800
	s_cselect_b64 s[28:29], s[2:3], s[4:5]
	s_cmp_lt_u32 s25, 0x2800
	s_cselect_b64 s[28:29], s[28:29], s[62:63]
	s_add_u32 s28, s28, s40
	s_addc_u32 s29, s29, 0
	global_load_dwordx4 v[110:113], v1, s[28:29]
	global_load_dwordx4 v[114:117], v1, s[28:29] offset:2048
	global_load_dwordx4 v[118:121], v1, s[28:29] offset:1024
	v_readlane_b32 s25, v194, 2
	s_mul_i32 s40, s25, 0xc00
	s_cmp_lt_u32 s25, 0x1800
	s_cselect_b64 s[28:29], s[2:3], s[4:5]
	s_cmp_lt_u32 s25, 0x2800
	s_cselect_b64 s[28:29], s[28:29], s[62:63]
	s_add_u32 s28, s28, s40
	s_addc_u32 s29, s29, 0
	global_load_dwordx4 v[122:125], v1, s[28:29]
	global_load_dwordx4 v[126:129], v1, s[28:29] offset:2048
	global_load_dwordx4 v[130:133], v1, s[28:29] offset:1024
	v_readlane_b32 s25, v194, 3
	s_mul_i32 s40, s25, 0xc00
	s_cmp_lt_u32 s25, 0x1800
	s_cselect_b64 s[28:29], s[2:3], s[4:5]
	s_cmp_lt_u32 s25, 0x2800
	s_cselect_b64 s[28:29], s[28:29], s[62:63]
	s_add_u32 s28, s28, s40
	s_addc_u32 s29, s29, 0
	global_load_dwordx4 v[134:137], v1, s[28:29]
	global_load_dwordx4 v[138:141], v1, s[28:29] offset:2048
	global_load_dwordx4 v[142:145], v1, s[28:29] offset:1024
	v_readlane_b32 s25, v194, 4
	s_mul_i32 s40, s25, 0xc00
	s_cmp_lt_u32 s25, 0x1800
	s_cselect_b64 s[28:29], s[2:3], s[4:5]
	s_cmp_lt_u32 s25, 0x2800
	s_cselect_b64 s[28:29], s[28:29], s[62:63]
	s_add_u32 s28, s28, s40
	s_addc_u32 s29, s29, 0
	global_load_dwordx4 v[146:149], v1, s[28:29]
	global_load_dwordx4 v[150:153], v1, s[28:29] offset:2048
	global_load_dwordx4 v[154:157], v1, s[28:29] offset:1024
	v_readlane_b32 s25, v194, 5
	s_mul_i32 s40, s25, 0xc00
	s_cmp_lt_u32 s25, 0x1800
	s_cselect_b64 s[28:29], s[2:3], s[4:5]
	s_cmp_lt_u32 s25, 0x2800
	s_cselect_b64 s[28:29], s[28:29], s[62:63]
	s_add_u32 s28, s28, s40
	s_addc_u32 s29, s29, 0
	global_load_dwordx4 v[158:161], v1, s[28:29]
	global_load_dwordx4 v[162:165], v1, s[28:29] offset:2048
	global_load_dwordx4 v[166:169], v1, s[28:29] offset:1024
	v_readlane_b32 s25, v194, 6
	s_mul_i32 s40, s25, 0xc00
	s_cmp_lt_u32 s25, 0x1800
	s_cselect_b64 s[28:29], s[2:3], s[4:5]
	s_cmp_lt_u32 s25, 0x2800
	s_cselect_b64 s[28:29], s[28:29], s[62:63]
	s_add_u32 s28, s28, s40
	s_addc_u32 s29, s29, 0
	global_load_dwordx4 v[170:173], v1, s[28:29]
	global_load_dwordx4 v[174:177], v1, s[28:29] offset:2048
	global_load_dwordx4 v[178:181], v1, s[28:29] offset:1024
	v_readlane_b32 s25, v194, 7
	s_mul_i32 s40, s25, 0xc00
	s_cmp_lt_u32 s25, 0x1800
	s_cselect_b64 s[28:29], s[2:3], s[4:5]
	s_cmp_lt_u32 s25, 0x2800
	s_cselect_b64 s[28:29], s[28:29], s[62:63]
	s_add_u32 s28, s28, s40
	s_addc_u32 s29, s29, 0
	global_load_dwordx4 v[182:185], v1, s[28:29]
	global_load_dwordx4 v[186:189], v1, s[28:29] offset:2048
	global_load_dwordx4 v[190:193], v1, s[28:29] offset:1024
	s_branch .Lp12_token
